# GEMM phases: per-MMA-block s_setprio flips deleted, one static priority raise for waves 4-7; plus nosync+cvt4
# baseline (speedup 1.0000x reference)
; __device__ __forceinline__ void wconv_phase(KP Pk, int L, unsigned char* lds, int G, int blk) {
;     ...
;     int tid_l = threadIdx.x; asm volatile("" : "+v"(tid_l)); const int tid = tid_l, lane = tid & 63, wid = __builtin_amdgcn_readfirstlane(tid >> 6), j = L >> 1; const bool att = (L & 1) == 0;
;     float* scr = (float*)(lds + wid * 16384);
;     unsigned char* ws = P.ws;
;     bf16_t *WIN = (bf16_t*)(ws + WS_WIN), *WOUT = (bf16_t*)(ws + WS_WOUT), *W1 = (bf16_t*)(ws + WS_W1), *W2 = (bf16_t*)(ws + WS_W2), *WG = (bf16_t*)(ws + WS_WG), *WP = (bf16_t*)(ws + WS_WP);
;     float* vecp = (float*)(ws + WS_VECP);
;     const int nin = att ? NQKV / 32 : HIN / 32;
;     const int I0 = nin * 16, I1 = I0 + 32 * 16, I2 = I1 + 176 * 16, I3 = I2 + 32 * 44, I4 = I3 + 32 * 16, I5 = I4 + 32 * 4;
;     for (int it = wid * G + blk; it < I5; it += 8 * G) {
;         if (it < I0) { const int nb = it >> 4, kb = it & 15; if (att) conv_item<1, false>(P.att_wqkv + (size_t)j * D * NQKV, D, NQKV, WIN, nb * 32, kb * 64, 64, nullptr, nullptr, nullptr, nullptr, scr, lane);
.LBB0_5:
	s_or_b64 exec, exec, s[4:5]
	s_or_b64 exec, exec, s[4:5]
	s_setprio 0
	s_mov_b64 s[14:15], s[0:1]
	s_mov_b32 s10, s2
	s_mov_b32 s8, s74
	v_mov_b32_e32 v0, v254
	s_barrier
	s_load_dwordx2 s[12:13], s[14:15], 0x90
	v_readfirstlane_b32 s3, v0
	s_ashr_i32 s3, s3, 6
	s_mul_i32 s4, s3, s8
	s_add_i32 s9, s4, s10
	s_cmpk_gt_i32 s9, 0x17ff
	s_cbranch_scc1 .LBB0_54
	s_waitcnt lgkmcnt(0)
	s_add_u32 s11, s12, 0x1fd00000
	v_lshlrev_b32_e32 v18, 3, v0
	s_addc_u32 s22, s13, 0
	s_lshl_b32 s3, s3, 14
	v_and_b32_e32 v4, 56, v18
	v_bfe_u32 v3, v0, 3, 3
	s_add_i32 s4, s3, 0
	v_mul_u32_u24_e32 v5, 0x84, v4
	v_lshlrev_b32_e32 v6, 2, v3
	v_add3_u32 v48, s4, v5, v6
	v_lshlrev_b32_e32 v4, 1, v4
	v_mov_b32_e32 v5, 0
	v_bfe_u32 v2, v0, 5, 1
	v_lshl_add_u64 v[6:7], s[12:13], 0, v[4:5]
	s_mov_b64 s[4:5], 0x1f00000
	v_and_b32_e32 v4, 1, v0
	v_and_b32_e32 v12, 63, v0
	v_and_b32_e32 v1, 31, v0
	v_lshl_add_u64 v[8:9], v[6:7], 0, s[4:5]
	s_mov_b64 s[4:5], 0x1d00000
	s_mov_b64 s[6:7], 0x1700000
	v_cmp_eq_u32_e32 vcc, 1, v4
	v_mul_u32_u24_e32 v4, 0x84, v2
	v_lshl_add_u64 v[10:11], v[6:7], 0, s[4:5]
	v_cmp_gt_u32_e64 s[4:5], 32, v12
	v_lshl_add_u64 v[12:13], v[6:7], 0, s[6:7]
	v_mov_b32_e32 v14, 0xb00
	s_mov_b64 s[6:7], 0xc00000
	v_and_b32_e32 v53, 8, v18
	v_or_b32_e32 v4, s3, v4
	v_lshlrev_b32_e32 v18, 2, v1
	v_cndmask_b32_e32 v52, 0, v14, vcc
	v_lshl_add_u64 v[14:15], v[6:7], 0, s[6:7]
	s_mov_b64 s[6:7], 0xa00000
	v_add3_u32 v54, v4, v18, 0
	s_lshl_b32 s3, s9, 3
	s_add_i32 s30, s9, 0xfffffb00
	v_mbcnt_lo_u32_b32 v4, -1, 0
	s_mov_b32 s17, 0
	v_or_b32_e32 v49, 8, v3
	v_or_b32_e32 v50, 16, v3
	v_or_b32_e32 v51, 24, v3
	v_lshl_add_u64 v[16:17], v[6:7], 0, s[6:7]
	s_lshl_b32 s23, s8, 3
	s_add_i32 s24, s3, 0xffff4400
	s_lshl_b32 s25, s8, 6
	v_or_b32_e32 v55, 14, v2
	s_lshl_b32 s26, s9, 6
	s_lshl_b32 s27, s8, 9
	v_or_b32_e32 v56, 12, v2
	v_or_b32_e32 v57, 10, v2
	v_or_b32_e32 v58, 8, v2
	v_or_b32_e32 v59, 6, v2
	v_or_b32_e32 v60, 4, v2
	v_or_b32_e32 v61, 2, v2
	v_or_b32_e32 v62, 0xffffd500, v1
	s_lshl_b32 s28, s9, 1
	s_lshl_b32 s29, s8, 4
	v_lshlrev_b32_e32 v18, 2, v2
	v_mov_b32_e32 v19, v5
	s_lshl_b32 s31, s30, 1
	v_or_b32_e32 v63, 0xfffffa00, v1
	s_mov_b64 s[18:19], 0x10000
	s_mov_b64 s[20:21], 0x58000
	s_movk_i32 s34, 0x1800
	s_movk_i32 s35, 0x500
	v_mbcnt_hi_u32_b32 v64, -1, v4
	s_mov_b32 s36, s9
	s_branch .LBB0_18

; __device__ __forceinline__ void vec_finalize(unsigned char* ws, int G, int blk) {
;     const float* vecp = (const float*)(ws + WS_VECP); float* vec = (float*)(ws + WS_VEC);
;     for (int i = blk * 512 + threadIdx.x; i < 13312; i += G * 512) { float a = 0.f;
; #pragma unroll
;         for (int kb = 0; kb < 16; ++kb) a += vecp[(size_t)kb * 13312 + i];
;         vec[i] = a; }
.LBB0_115:
	s_or_b64 exec, exec, s[4:5]
	v_readfirstlane_b32 s98, v254
	s_lshr_b32 s98, s98, 6
	s_setprio 0
	s_cmp_ge_u32 s98, 4
	s_cbranch_scc0 .Lprio_qkv0
	s_setprio 1
.Lprio_qkv0:
	s_mov_b32 s44, s2
	s_mov_b32 s45, s74
	s_mov_b64 s[4:5], s[0:1]
	s_waitcnt lgkmcnt(0)
	s_barrier
	s_load_dwordx2 s[8:9], s[4:5], 0x90
	v_lshl_add_u32 v0, s44, 9, v254
	s_movk_i32 s3, 0x3400
	v_cmp_gt_i32_e32 vcc, s3, v0
	s_and_saveexec_b64 s[4:5], vcc
	s_cbranch_execz .LBB0_118
	s_lshl_b32 s6, s45, 9
	v_ashrrev_i32_e32 v1, 31, v0
	s_waitcnt lgkmcnt(0)
	v_lshl_add_u64 v[2:3], v[0:1], 2, s[8:9]
	s_mov_b64 s[10:11], 0x1fdc3000
	s_ashr_i32 s7, s6, 31
	v_lshl_add_u64 v[2:3], v[2:3], 0, s[10:11]
	s_lshl_b64 s[10:11], s[6:7], 2
	s_mov_b64 s[12:13], 0
	s_movk_i32 s3, 0x33ff

; #define PG8_STAGE(bufoff, gbase, voff) do { _Pragma("unroll") for (int _i = 0; _i < 2; ++_i) \
;         __builtin_amdgcn_global_load_lds((const unsigned*)((const char*)(gbase) + (voff)[_i]), (PG8_LAS unsigned*)(lds + (bufoff) + ldsw + _i * 8192), 16, 0, 0); } while (0)
; #define PG8_LDA(dst, b, h) do { _Pragma("unroll") for (int m = 0; m < 4; ++m) _Pragma("unroll") for (int k = 0; k < 2; ++k) dst[m][k] = *(const PG8_LAS bf16x8*)(lds + PG8_SA(b, h) + aoff + m * 2048 + k * 1024); } while (0)
; #define PG8_LDB(dst, b, h) do { _Pragma("unroll") for (int n = 0; n < 2; ++n) _Pragma("unroll") for (int k = 0; k < 2; ++k) dst[n][k] = *(const PG8_LAS bf16x8*)(lds + PG8_SB(b, h) + boff + n * 2048 + k * 1024); } while (0)
; #define PG8_MMA(ai, bj, At, Bt) do { __builtin_amdgcn_s_setprio(1); _Pragma("unroll") for (int m = 0; m < 4; ++m) _Pragma("unroll") for (int n = 0; n < 2; ++n) _Pragma("unroll") for (int k = 0; k < 2; ++k) \
;         acc[ai][bj][m][n] = __builtin_amdgcn_mfma_f32_16x16x32_bf16(Bt[n][k], At[m][k], acc[ai][bj][m][n], 0, 0, 0); __builtin_amdgcn_s_setprio(0); } while (0)
; #define PG8_WAIT_V(n) asm volatile("s_waitcnt vmcnt(" #n ")" ::: "memory")
; #define PG8_WAIT_L(n) asm volatile("s_waitcnt lgkmcnt(" #n ")" ::: "memory")
; #define PG8_BAR __builtin_amdgcn_s_barrier()
; #define PG8_SCHED __builtin_amdgcn_sched_barrier(0)
; template <class Epi, class Sched, bool ALIGN_EPI = false, bool SP2 = false>
; __device__ __forceinline__ void gemm_phase(PG8_LAS unsigned char* lds, const Gemm g, const Sched& S, const Epi& E) {
;     ...
;         for (int t = 0; t < nt; t += 2) {
;             const bool last = (t == nt - 2);
;             const char* a1 = cA + PG8_AK(t + 1);
;             const char* a2 = last ? nA : cA + PG8_AK(t + 2); const char* b2 = last ? nB : cB + (size_t)(t + 2) * kstep;
;             const char* a3 = last ? nA + PG8_AK(1) : cA + PG8_AK(t + 3); const char* b3 = b2 + kstep;
;             if (last && has_next) S.a_ready(nxt);
;             if constexpr (SP2) {
;             PG8_LDB(B0, 0, 0); PG8_LDB(B1, 0, 1); PG8_SCHED; PG8_LDA(At, 0, 0); PG8_STAGE(PG8_SA(1, 1), a1 + hstepA, voffA);
;             PG8_WAIT_V(8); PG8_WAIT_L(0); PG8_BAR; PG8_MMA(0, 0, At, B0); PG8_MMA(0, 1, At, B1); PG8_BAR; PG8_SCHED;
;             PG8_LDA(At, 0, 1); PG8_STAGE(PG8_SB(0, 0), b2, voffB); PG8_STAGE(PG8_SB(0, 1), b2 + hstepB, voffB); PG8_STAGE(PG8_SA(0, 0), a2, voffA);
.LBB0_129:
	ds_read_b128 v[132:135], v172
	ds_read_b128 v[158:161], v172 offset:1024
	ds_read_b128 v[176:179], v172 offset:2048
	ds_read_b128 v[180:183], v172 offset:3072
	ds_read_b128 v[184:187], v173
	ds_read_b128 v[188:191], v173 offset:1024
	ds_read_b128 v[192:195], v173 offset:2048
	ds_read_b128 v[196:199], v173 offset:3072
	s_add_u32 s38, s28, s34
	s_addc_u32 s39, s29, s35
	s_add_u32 s42, s38, 0x100
	s_addc_u32 s43, s39, 0
	s_add_u32 s40, s62, s34
	s_addc_u32 s41, s63, s35
	s_add_u32 s38, s38, 0x180
	s_addc_u32 s39, s39, 0
	s_cmpk_eq_i32 s34, 0x700
	s_cselect_b32 s39, s37, s39
	s_cselect_b32 s38, s31, s38
	s_cselect_b32 s41, s21, s41
	s_cselect_b32 s40, s23, s40
	s_cselect_b32 s43, s3, s43
	s_cselect_b32 s42, s10, s42
	v_lshl_add_u64 v[204:205], v[130:131], 0, s[34:35]
	s_add_i32 m0, s49, 0xc000
	ds_read_b128 v[200:203], v174
	ds_read_b128 v[208:211], v174 offset:1024
	ds_read_b128 v[212:215], v174 offset:2048
	ds_read_b128 v[216:219], v174 offset:3072
	ds_read_b128 v[220:223], v174 offset:4096
	ds_read_b128 v[224:227], v174 offset:5120
	ds_read_b128 v[228:231], v174 offset:6144
	ds_read_b128 v[232:235], v174 offset:7168
	global_load_lds_dwordx4 v[204:205], off
	v_lshl_add_u64 v[204:205], v[128:129], 0, s[34:35]
	s_add_i32 m0, s49, 0xe000
	s_nop 0
	global_load_lds_dwordx4 v[204:205], off
	s_waitcnt vmcnt(8)
	s_waitcnt lgkmcnt(0)
	s_barrier
	s_waitcnt lgkmcnt(0)
	v_mfma_f32_16x16x32_bf16 v[124:127], v[132:135], v[200:203], v[124:127]
	v_mfma_f32_16x16x32_bf16 v[120:123], v[176:179], v[200:203], v[120:123]
	v_mfma_f32_16x16x32_bf16 v[108:111], v[132:135], v[212:215], v[108:111]
	v_mfma_f32_16x16x32_bf16 v[104:107], v[176:179], v[212:215], v[104:107]
	v_mfma_f32_16x16x32_bf16 v[92:95], v[132:135], v[220:223], v[92:95]
	v_mfma_f32_16x16x32_bf16 v[88:91], v[176:179], v[220:223], v[88:91]
	v_mfma_f32_16x16x32_bf16 v[76:79], v[132:135], v[228:231], v[76:79]
	v_mfma_f32_16x16x32_bf16 v[72:75], v[176:179], v[228:231], v[72:75]
	v_mfma_f32_16x16x32_bf16 v[124:127], v[158:161], v[208:211], v[124:127]
	v_mfma_f32_16x16x32_bf16 v[120:123], v[180:183], v[208:211], v[120:123]
	v_mfma_f32_16x16x32_bf16 v[108:111], v[158:161], v[216:219], v[108:111]
	v_mfma_f32_16x16x32_bf16 v[104:107], v[180:183], v[216:219], v[104:107]
	v_mfma_f32_16x16x32_bf16 v[92:95], v[158:161], v[224:227], v[92:95]
	v_mfma_f32_16x16x32_bf16 v[88:91], v[180:183], v[224:227], v[88:91]
	v_mfma_f32_16x16x32_bf16 v[76:79], v[158:161], v[232:235], v[76:79]
	v_mfma_f32_16x16x32_bf16 v[72:75], v[180:183], v[232:235], v[72:75]
	v_mfma_f32_16x16x32_bf16 v[116:119], v[184:187], v[200:203], v[116:119]
	v_mfma_f32_16x16x32_bf16 v[112:115], v[192:195], v[200:203], v[112:115]
	v_mfma_f32_16x16x32_bf16 v[100:103], v[184:187], v[212:215], v[100:103]
	v_mfma_f32_16x16x32_bf16 v[96:99], v[192:195], v[212:215], v[96:99]
	v_mfma_f32_16x16x32_bf16 v[84:87], v[184:187], v[220:223], v[84:87]
	v_mfma_f32_16x16x32_bf16 v[80:83], v[192:195], v[220:223], v[80:83]
	v_mfma_f32_16x16x32_bf16 v[68:71], v[184:187], v[228:231], v[68:71]
	v_mfma_f32_16x16x32_bf16 v[64:67], v[192:195], v[228:231], v[64:67]
	v_mfma_f32_16x16x32_bf16 v[116:119], v[188:191], v[208:211], v[116:119]
	v_mfma_f32_16x16x32_bf16 v[112:115], v[196:199], v[208:211], v[112:115]
	v_mfma_f32_16x16x32_bf16 v[100:103], v[188:191], v[216:219], v[100:103]
	v_mfma_f32_16x16x32_bf16 v[96:99], v[196:199], v[216:219], v[96:99]
	v_mfma_f32_16x16x32_bf16 v[84:87], v[188:191], v[224:227], v[84:87]
	v_mfma_f32_16x16x32_bf16 v[80:83], v[196:199], v[224:227], v[80:83]
	v_mfma_f32_16x16x32_bf16 v[68:71], v[188:191], v[232:235], v[68:71]
	v_mfma_f32_16x16x32_bf16 v[64:67], v[196:199], v[232:235], v[64:67]
	s_barrier
	s_add_i32 s65, s58, s48
	v_lshl_add_u64 v[204:205], s[40:41], 0, v[138:139]
	s_mov_b32 m0, s65
	ds_read_b128 v[200:203], v174 offset:16384
	ds_read_b128 v[208:211], v174 offset:17408
	ds_read_b128 v[212:215], v174 offset:18432
	ds_read_b128 v[216:219], v174 offset:19456
	ds_read_b128 v[220:223], v174 offset:20480
	ds_read_b128 v[224:227], v174 offset:21504
	ds_read_b128 v[228:231], v174 offset:22528
	ds_read_b128 v[232:235], v174 offset:23552
	global_load_lds_dwordx4 v[204:205], off
	s_add_i32 m0, s65, 0x2000
	s_add_u32 s66, s40, 0x40000
	v_lshl_add_u64 v[206:207], s[40:41], 0, v[142:143]
	s_addc_u32 s67, s41, 0
	s_add_i32 s65, s59, s48
	global_load_lds_dwordx4 v[206:207], off
	v_lshl_add_u64 v[236:237], s[66:67], 0, v[138:139]
	s_mov_b32 m0, s65
	s_nop 0
	global_load_lds_dwordx4 v[236:237], off
	v_lshl_add_u64 v[236:237], s[66:67], 0, v[142:143]
	s_add_i32 m0, s65, 0x2000
	s_nop 0
	global_load_lds_dwordx4 v[236:237], off
	v_lshl_add_u64 v[236:237], s[42:43], 0, v[136:137]
	s_mov_b32 m0, s49
	s_nop 0
	global_load_lds_dwordx4 v[236:237], off
	v_lshl_add_u64 v[236:237], s[42:43], 0, v[140:141]
	s_mov_b32 m0, s50
	s_nop 0
	global_load_lds_dwordx4 v[236:237], off
	s_waitcnt vmcnt(8)
	s_waitcnt lgkmcnt(0)
	s_barrier
; #define PG8_STAGE(bufoff, gbase, voff) do { _Pragma("unroll") for (int _i = 0; _i < 2; ++_i) \
;         __builtin_amdgcn_global_load_lds((const unsigned*)((const char*)(gbase) + (voff)[_i]), (PG8_LAS unsigned*)(lds + (bufoff) + ldsw + _i * 8192), 16, 0, 0); } while (0)
; #define PG8_LDA(dst, b, h) do { _Pragma("unroll") for (int m = 0; m < 4; ++m) _Pragma("unroll") for (int k = 0; k < 2; ++k) dst[m][k] = *(const PG8_LAS bf16x8*)(lds + PG8_SA(b, h) + aoff + m * 2048 + k * 1024); } while (0)
; #define PG8_LDB(dst, b, h) do { _Pragma("unroll") for (int n = 0; n < 2; ++n) _Pragma("unroll") for (int k = 0; k < 2; ++k) dst[n][k] = *(const PG8_LAS bf16x8*)(lds + PG8_SB(b, h) + boff + n * 2048 + k * 1024); } while (0)
; #define PG8_MMA(ai, bj, At, Bt) do { __builtin_amdgcn_s_setprio(1); _Pragma("unroll") for (int m = 0; m < 4; ++m) _Pragma("unroll") for (int n = 0; n < 2; ++n) _Pragma("unroll") for (int k = 0; k < 2; ++k) \
;         acc[ai][bj][m][n] = __builtin_amdgcn_mfma_f32_16x16x32_bf16(Bt[n][k], At[m][k], acc[ai][bj][m][n], 0, 0, 0); __builtin_amdgcn_s_setprio(0); } while (0)
; #define PG8_WAIT_V(n) asm volatile("s_waitcnt vmcnt(" #n ")" ::: "memory")
; #define PG8_WAIT_L(n) asm volatile("s_waitcnt lgkmcnt(" #n ")" ::: "memory")
; #define PG8_BAR __builtin_amdgcn_s_barrier()
; #define PG8_SCHED __builtin_amdgcn_sched_barrier(0)
; template <class Epi, class Sched, bool ALIGN_EPI = false, bool SP2 = false>
; __device__ __forceinline__ void gemm_phase(PG8_LAS unsigned char* lds, const Gemm g, const Sched& S, const Epi& E) {
;     ...
;             PG8_WAIT_V(8); PG8_WAIT_L(0); PG8_BAR; PG8_MMA(1, 0, At, B0); PG8_MMA(1, 1, At, B1); PG8_BAR; PG8_SCHED;
;             PG8_LDB(B0, 1, 0); PG8_LDB(B1, 1, 1); PG8_SCHED; PG8_LDA(At, 1, 0); PG8_STAGE(PG8_SA(0, 1), a2 + hstepA, voffA);
;             PG8_WAIT_V(8); PG8_WAIT_L(0); PG8_BAR; PG8_MMA(0, 0, At, B0); PG8_MMA(0, 1, At, B1); PG8_BAR; PG8_SCHED;
	s_waitcnt lgkmcnt(0)
	v_mfma_f32_16x16x32_bf16 v[60:63], v[132:135], v[200:203], v[60:63]
	v_mfma_f32_16x16x32_bf16 v[56:59], v[176:179], v[200:203], v[56:59]
	v_mfma_f32_16x16x32_bf16 v[44:47], v[132:135], v[212:215], v[44:47]
	v_mfma_f32_16x16x32_bf16 v[40:43], v[176:179], v[212:215], v[40:43]
	v_mfma_f32_16x16x32_bf16 v[28:31], v[132:135], v[220:223], v[28:31]
	v_mfma_f32_16x16x32_bf16 v[24:27], v[176:179], v[220:223], v[24:27]
	v_mfma_f32_16x16x32_bf16 v[12:15], v[132:135], v[228:231], v[12:15]
	v_mfma_f32_16x16x32_bf16 v[8:11], v[176:179], v[228:231], v[8:11]
	v_mfma_f32_16x16x32_bf16 v[60:63], v[158:161], v[208:211], v[60:63]
	v_mfma_f32_16x16x32_bf16 v[56:59], v[180:183], v[208:211], v[56:59]
	v_mfma_f32_16x16x32_bf16 v[44:47], v[158:161], v[216:219], v[44:47]
	v_mfma_f32_16x16x32_bf16 v[40:43], v[180:183], v[216:219], v[40:43]
	v_mfma_f32_16x16x32_bf16 v[28:31], v[158:161], v[224:227], v[28:31]
	v_mfma_f32_16x16x32_bf16 v[24:27], v[180:183], v[224:227], v[24:27]
	v_mfma_f32_16x16x32_bf16 v[12:15], v[158:161], v[232:235], v[12:15]
	v_mfma_f32_16x16x32_bf16 v[8:11], v[180:183], v[232:235], v[8:11]
	v_mfma_f32_16x16x32_bf16 v[52:55], v[184:187], v[200:203], v[52:55]
	v_mfma_f32_16x16x32_bf16 v[48:51], v[192:195], v[200:203], v[48:51]
	v_mfma_f32_16x16x32_bf16 v[36:39], v[184:187], v[212:215], v[36:39]
	v_mfma_f32_16x16x32_bf16 v[32:35], v[192:195], v[212:215], v[32:35]
	v_mfma_f32_16x16x32_bf16 v[20:23], v[184:187], v[220:223], v[20:23]
	v_mfma_f32_16x16x32_bf16 v[16:19], v[192:195], v[220:223], v[16:19]
	v_mfma_f32_16x16x32_bf16 v[4:7], v[184:187], v[228:231], v[4:7]
	v_mfma_f32_16x16x32_bf16 v[0:3], v[192:195], v[228:231], v[0:3]
	v_mfma_f32_16x16x32_bf16 v[52:55], v[188:191], v[208:211], v[52:55]
	v_mfma_f32_16x16x32_bf16 v[48:51], v[196:199], v[208:211], v[48:51]
	v_mfma_f32_16x16x32_bf16 v[36:39], v[188:191], v[216:219], v[36:39]
	v_mfma_f32_16x16x32_bf16 v[32:35], v[196:199], v[216:219], v[32:35]
	v_mfma_f32_16x16x32_bf16 v[20:23], v[188:191], v[224:227], v[20:23]
	v_mfma_f32_16x16x32_bf16 v[16:19], v[196:199], v[224:227], v[16:19]
	v_mfma_f32_16x16x32_bf16 v[4:7], v[188:191], v[232:235], v[4:7]
	v_mfma_f32_16x16x32_bf16 v[0:3], v[196:199], v[232:235], v[0:3]
	s_barrier
	s_add_i32 s65, 0, 0x18000
	v_add_u32_e32 v144, s65, v163
	s_add_i32 s66, 0, 0x1c000
	ds_read_b128 v[132:135], v144
	ds_read_b128 v[158:161], v144 offset:1024
	ds_read_b128 v[176:179], v144 offset:2048
	ds_read_b128 v[180:183], v144 offset:3072
	v_add_u32_e32 v144, s66, v163
	ds_read_b128 v[184:187], v144
	ds_read_b128 v[188:191], v144 offset:1024
	ds_read_b128 v[192:195], v144 offset:2048
	ds_read_b128 v[196:199], v144 offset:3072
	s_add_u32 s42, s42, 0x40000
	s_addc_u32 s43, s43, 0
	s_mov_b32 m0, s51
	v_lshl_add_u64 v[236:237], s[42:43], 0, v[136:137]
	ds_read_b128 v[200:203], v174 offset:32768
	ds_read_b128 v[208:211], v174 offset:33792
	ds_read_b128 v[212:215], v174 offset:34816
	ds_read_b128 v[216:219], v174 offset:35840
	ds_read_b128 v[220:223], v174 offset:36864
	ds_read_b128 v[224:227], v174 offset:37888
	ds_read_b128 v[228:231], v174 offset:38912
	ds_read_b128 v[232:235], v174 offset:39936
	global_load_lds_dwordx4 v[236:237], off
	v_lshl_add_u64 v[236:237], s[42:43], 0, v[140:141]
	s_mov_b32 m0, s52
	s_nop 0
	global_load_lds_dwordx4 v[236:237], off
	s_waitcnt vmcnt(8)
	s_waitcnt lgkmcnt(0)
	s_barrier
	s_waitcnt lgkmcnt(0)
	v_mfma_f32_16x16x32_bf16 v[124:127], v[132:135], v[200:203], v[124:127]
	v_mfma_f32_16x16x32_bf16 v[120:123], v[176:179], v[200:203], v[120:123]
	v_mfma_f32_16x16x32_bf16 v[108:111], v[132:135], v[212:215], v[108:111]
	v_mfma_f32_16x16x32_bf16 v[104:107], v[176:179], v[212:215], v[104:107]
	v_mfma_f32_16x16x32_bf16 v[92:95], v[132:135], v[220:223], v[92:95]
	v_mfma_f32_16x16x32_bf16 v[88:91], v[176:179], v[220:223], v[88:91]
	v_mfma_f32_16x16x32_bf16 v[76:79], v[132:135], v[228:231], v[76:79]
	v_mfma_f32_16x16x32_bf16 v[72:75], v[176:179], v[228:231], v[72:75]
	v_mfma_f32_16x16x32_bf16 v[124:127], v[158:161], v[208:211], v[124:127]
	v_mfma_f32_16x16x32_bf16 v[120:123], v[180:183], v[208:211], v[120:123]
	v_mfma_f32_16x16x32_bf16 v[108:111], v[158:161], v[216:219], v[108:111]
	v_mfma_f32_16x16x32_bf16 v[104:107], v[180:183], v[216:219], v[104:107]
	v_mfma_f32_16x16x32_bf16 v[92:95], v[158:161], v[224:227], v[92:95]
	v_mfma_f32_16x16x32_bf16 v[88:91], v[180:183], v[224:227], v[88:91]
	v_mfma_f32_16x16x32_bf16 v[76:79], v[158:161], v[232:235], v[76:79]
	v_mfma_f32_16x16x32_bf16 v[72:75], v[180:183], v[232:235], v[72:75]
	v_mfma_f32_16x16x32_bf16 v[116:119], v[184:187], v[200:203], v[116:119]
	v_mfma_f32_16x16x32_bf16 v[112:115], v[192:195], v[200:203], v[112:115]
	v_mfma_f32_16x16x32_bf16 v[100:103], v[184:187], v[212:215], v[100:103]
	v_mfma_f32_16x16x32_bf16 v[96:99], v[192:195], v[212:215], v[96:99]
	v_mfma_f32_16x16x32_bf16 v[84:87], v[184:187], v[220:223], v[84:87]
	v_mfma_f32_16x16x32_bf16 v[80:83], v[192:195], v[220:223], v[80:83]
	v_mfma_f32_16x16x32_bf16 v[68:71], v[184:187], v[228:231], v[68:71]
	v_mfma_f32_16x16x32_bf16 v[64:67], v[192:195], v[228:231], v[64:67]
	v_mfma_f32_16x16x32_bf16 v[116:119], v[188:191], v[208:211], v[116:119]
	v_mfma_f32_16x16x32_bf16 v[112:115], v[196:199], v[208:211], v[112:115]
	v_mfma_f32_16x16x32_bf16 v[100:103], v[188:191], v[216:219], v[100:103]
	v_mfma_f32_16x16x32_bf16 v[96:99], v[196:199], v[216:219], v[96:99]
	v_mfma_f32_16x16x32_bf16 v[84:87], v[188:191], v[224:227], v[84:87]
	v_mfma_f32_16x16x32_bf16 v[80:83], v[196:199], v[224:227], v[80:83]
	v_mfma_f32_16x16x32_bf16 v[68:71], v[188:191], v[232:235], v[68:71]
	v_mfma_f32_16x16x32_bf16 v[64:67], v[196:199], v[232:235], v[64:67]
	s_barrier
; #define PG8_STAGE(bufoff, gbase, voff) do { _Pragma("unroll") for (int _i = 0; _i < 2; ++_i) \
;         __builtin_amdgcn_global_load_lds((const unsigned*)((const char*)(gbase) + (voff)[_i]), (PG8_LAS unsigned*)(lds + (bufoff) + ldsw + _i * 8192), 16, 0, 0); } while (0)
; #define PG8_LDA(dst, b, h) do { _Pragma("unroll") for (int m = 0; m < 4; ++m) _Pragma("unroll") for (int k = 0; k < 2; ++k) dst[m][k] = *(const PG8_LAS bf16x8*)(lds + PG8_SA(b, h) + aoff + m * 2048 + k * 1024); } while (0)
; #define PG8_MMA(ai, bj, At, Bt) do { __builtin_amdgcn_s_setprio(1); _Pragma("unroll") for (int m = 0; m < 4; ++m) _Pragma("unroll") for (int n = 0; n < 2; ++n) _Pragma("unroll") for (int k = 0; k < 2; ++k) \
;         acc[ai][bj][m][n] = __builtin_amdgcn_mfma_f32_16x16x32_bf16(Bt[n][k], At[m][k], acc[ai][bj][m][n], 0, 0, 0); __builtin_amdgcn_s_setprio(0); } while (0)
; #define PG8_WAIT_V(n) asm volatile("s_waitcnt vmcnt(" #n ")" ::: "memory")
; #define PG8_WAIT_L(n) asm volatile("s_waitcnt lgkmcnt(" #n ")" ::: "memory")
; #define PG8_BAR __builtin_amdgcn_s_barrier()
; #define PG8_SCHED __builtin_amdgcn_sched_barrier(0)
; template <class Epi, class Sched, bool ALIGN_EPI = false, bool SP2 = false>
; __device__ __forceinline__ void gemm_phase(PG8_LAS unsigned char* lds, const Gemm g, const Sched& S, const Epi& E) {
;     ...
;             PG8_LDA(At, 1, 1); PG8_STAGE(PG8_SB(1, 0), b3, voffB); PG8_STAGE(PG8_SB(1, 1), b3 + hstepB, voffB); PG8_STAGE(PG8_SA(1, 0), a3, voffA);
;             PG8_WAIT_V(8); PG8_WAIT_L(0); PG8_BAR; PG8_MMA(1, 0, At, B0); PG8_MMA(1, 1, At, B1); PG8_BAR; PG8_SCHED;
	s_add_i32 s42, s65, s48
	v_lshl_add_u64 v[204:205], v[204:205], 0, s[14:15]
	s_mov_b32 m0, s42
	ds_read_b128 v[200:203], v174 offset:49152
	ds_read_b128 v[208:211], v174 offset:50176
	ds_read_b128 v[212:215], v174 offset:51200
	ds_read_b128 v[216:219], v174 offset:52224
	ds_read_b128 v[220:223], v174 offset:53248
	ds_read_b128 v[224:227], v174 offset:54272
	ds_read_b128 v[228:231], v174 offset:55296
	ds_read_b128 v[232:235], v174 offset:56320
	global_load_lds_dwordx4 v[204:205], off
	s_add_i32 m0, s42, 0x2000
	s_add_u32 s40, s40, 0x40080
	v_lshl_add_u64 v[204:205], v[206:207], 0, s[14:15]
	s_addc_u32 s41, s41, 0
	s_add_i32 s42, s66, s48
	global_load_lds_dwordx4 v[204:205], off
	v_lshl_add_u64 v[204:205], s[40:41], 0, v[138:139]
	s_mov_b32 m0, s42
	s_nop 0
	global_load_lds_dwordx4 v[204:205], off
	v_lshl_add_u64 v[204:205], s[40:41], 0, v[142:143]
	s_add_i32 m0, s42, 0x2000
	s_nop 0
	global_load_lds_dwordx4 v[204:205], off
	v_lshl_add_u64 v[204:205], s[38:39], 0, v[136:137]
	s_mov_b32 m0, s53
	s_nop 0
	global_load_lds_dwordx4 v[204:205], off
	v_lshl_add_u64 v[204:205], s[38:39], 0, v[140:141]
	s_mov_b32 m0, s54
	s_nop 0
	global_load_lds_dwordx4 v[204:205], off
	s_waitcnt vmcnt(8)
	s_waitcnt lgkmcnt(0)
	s_barrier
	s_waitcnt lgkmcnt(0)
	v_mfma_f32_16x16x32_bf16 v[60:63], v[132:135], v[200:203], v[60:63]
	v_mfma_f32_16x16x32_bf16 v[56:59], v[176:179], v[200:203], v[56:59]
	v_mfma_f32_16x16x32_bf16 v[44:47], v[132:135], v[212:215], v[44:47]
	v_mfma_f32_16x16x32_bf16 v[40:43], v[176:179], v[212:215], v[40:43]
	v_mfma_f32_16x16x32_bf16 v[28:31], v[132:135], v[220:223], v[28:31]
	v_mfma_f32_16x16x32_bf16 v[24:27], v[176:179], v[220:223], v[24:27]
	v_mfma_f32_16x16x32_bf16 v[12:15], v[132:135], v[228:231], v[12:15]
	v_mfma_f32_16x16x32_bf16 v[8:11], v[176:179], v[228:231], v[8:11]
	v_mfma_f32_16x16x32_bf16 v[60:63], v[158:161], v[208:211], v[60:63]
	v_mfma_f32_16x16x32_bf16 v[56:59], v[180:183], v[208:211], v[56:59]
	v_mfma_f32_16x16x32_bf16 v[44:47], v[158:161], v[216:219], v[44:47]
	v_mfma_f32_16x16x32_bf16 v[40:43], v[180:183], v[216:219], v[40:43]
	v_mfma_f32_16x16x32_bf16 v[28:31], v[158:161], v[224:227], v[28:31]
	v_mfma_f32_16x16x32_bf16 v[24:27], v[180:183], v[224:227], v[24:27]
	v_mfma_f32_16x16x32_bf16 v[12:15], v[158:161], v[232:235], v[12:15]
	v_mfma_f32_16x16x32_bf16 v[8:11], v[180:183], v[232:235], v[8:11]
	v_mfma_f32_16x16x32_bf16 v[52:55], v[184:187], v[200:203], v[52:55]
	v_mfma_f32_16x16x32_bf16 v[48:51], v[192:195], v[200:203], v[48:51]
	v_mfma_f32_16x16x32_bf16 v[36:39], v[184:187], v[212:215], v[36:39]
	v_mfma_f32_16x16x32_bf16 v[32:35], v[192:195], v[212:215], v[32:35]
	v_mfma_f32_16x16x32_bf16 v[20:23], v[184:187], v[220:223], v[20:23]
	v_mfma_f32_16x16x32_bf16 v[16:19], v[192:195], v[220:223], v[16:19]
	v_mfma_f32_16x16x32_bf16 v[4:7], v[184:187], v[228:231], v[4:7]
	v_mfma_f32_16x16x32_bf16 v[0:3], v[192:195], v[228:231], v[0:3]
	v_mfma_f32_16x16x32_bf16 v[52:55], v[188:191], v[208:211], v[52:55]
	v_mfma_f32_16x16x32_bf16 v[48:51], v[196:199], v[208:211], v[48:51]
	v_mfma_f32_16x16x32_bf16 v[36:39], v[188:191], v[216:219], v[36:39]
	v_mfma_f32_16x16x32_bf16 v[32:35], v[196:199], v[216:219], v[32:35]
	v_mfma_f32_16x16x32_bf16 v[20:23], v[188:191], v[224:227], v[20:23]
	v_mfma_f32_16x16x32_bf16 v[16:19], v[196:199], v[224:227], v[16:19]
	v_mfma_f32_16x16x32_bf16 v[4:7], v[188:191], v[232:235], v[4:7]
	v_mfma_f32_16x16x32_bf16 v[0:3], v[196:199], v[232:235], v[0:3]
	s_barrier
	s_add_i32 s64, s64, 2
	s_add_u32 s34, s34, 0x100
	s_addc_u32 s35, s35, 0
	s_cmp_gt_u32 s64, 13
	s_cbranch_scc0 .LBB0_129
	s_and_b64 vcc, exec, s[16:17]
	s_cbranch_vccz .LBB0_134
	s_barrier
	s_cmp_gt_i32 s30, 3
	s_mov_b64 s[28:29], -1
	s_cbranch_scc1 .LBB0_135

; __device__ __forceinline__ void attn_phase(unsigned char* lds, const bf16_t* Q, const bf16_t* Kb, const bf16_t* Vb, bf16_t* O, const float* sink, int G, int blk) {
;     int tid_l = threadIdx.x; asm volatile("" : "+v"(tid_l)); const int tid = tid_l, lane = tid & 63, wid = __builtin_amdgcn_readfirstlane(tid >> 6), r32 = lane & 31, hi = lane >> 5;
;     bf16_t* Ks = (bf16_t*)lds; bf16_t* Vt = (bf16_t*)(lds + 384 * 72 * 2);
;     for (int unit = blk; unit < 1024; unit += G) {
;         const int b = unit >> 9, kvh = (unit >> 7) & 3, qb = unit & 127, start = qb * 128;
;         asm volatile("s_waitcnt lgkmcnt(0)\n\ts_barrier" ::: "memory");
;         for (int idx = tid; idx < 384 * 8; idx += 512) {
;             const int key = idx >> 3, ch = idx & 7, kpos = start - 128 + key;
;             if (kpos >= 0 && kpos < SEQ) {
;                 const size_t gofs = ((size_t)(b * SEQ + kpos)) * 256 + kvh * 64 + ch * 8;
;                 const u32x4 kv = *(const u32x4*)(Kb + gofs); *(u32x4*)(Ks + key * 72 + ch * 8) = kv;
;                 const u32x4 vv = *(const u32x4*)(Vb + gofs);
; #pragma unroll
;                 for (int jj = 0; jj < 4; ++jj) { const unsigned w = vv[jj]; Vt[(ch * 8 + 2 * jj) * 392 + key] = (bf16_t)(w & 0xffffu); Vt[(ch * 8 + 2 * jj + 1) * 392 + key] = (bf16_t)(w >> 16); }
;             }
;         }
;         __syncthreads();
;         const int g = wid >> 1, half = wid & 1, head = kvh * 4 + g;
;         const float sk = sink[head] * LOG2E;
;         for (int sb = 0; sb < 2; ++sb) {
;             const int r0 = 64 * half + 32 * sb; const size_t tok = (size_t)b * SEQ + start + r0 + r32;
;             bf16x8 qf[4];
; #pragma unroll
;             for (int ks = 0; ks < 4; ++ks) qf[ks] = *(const bf16x8*)(Q + tok * 1024 + head * 64 + 16 * ks + 8 * hi);
;             float m = sk, l = 1.f; f32x16 o0 = {}, o1 = {};
;             const int base_pos = start - 128 + r0;
;             const int jlo = base_pos < 0 ? ((-base_pos + 31) >> 5) : 0, jhi = (SEQ - base_pos) >= 288 ? 9 : ((SEQ - base_pos) >> 5);
;             bf16x8 kc[4];
; #pragma unroll
;             for (int ks = 0; ks < 4; ++ks) kc[ks] = *(const bf16x8*)(Ks + (r0 + 32 * jlo + r32) * 72 + 16 * ks + 8 * hi);
;             for (int j = jlo; j < jhi; ++j) {
;                 const int key0 = r0 + 32 * j;
;                 bf16x8 kn[4];
.LBB0_241:
	v_writelane_b32 v255, s0, 2
	s_nop 1
	v_writelane_b32 v255, s1, 3
	s_or_b64 exec, exec, s[4:5]
	s_setprio 0
	v_readlane_b32 s4, v255, 2
	s_mov_b32 s94, s2
	s_mov_b32 s95, s74
	v_readlane_b32 s5, v255, 3
	v_mov_b32_e32 v107, v254
	s_waitcnt lgkmcnt(0)
	s_barrier
	s_cmpk_gt_i32 s94, 0x3ff
	v_readfirstlane_b32 s3, v107
	s_cbranch_scc1 .LBB0_261
	s_load_dwordx2 s[6:7], s[4:5], 0x90
	s_load_dwordx2 s[80:81], s[4:5], 0x18
	v_bfe_u32 v4, v107, 5, 1
	v_mov_b32_e32 v103, 0
	v_lshlrev_b32_e32 v0, 4, v4
	s_waitcnt lgkmcnt(0)
	s_add_u32 s82, s6, 0x13800000
	s_addc_u32 s83, s7, 0
	v_mov_b32_e32 v1, v103
	s_add_u32 s84, s6, 0x14800000
	v_lshlrev_b32_e32 v102, 3, v4
	v_lshl_add_u64 v[2:3], s[6:7], 0, v[0:1]
	s_mov_b64 s[8:9], 0xf800000
	s_addc_u32 s85, s7, 0
	v_lshl_add_u64 v[104:105], v[2:3], 0, s[8:9]
	v_add_u32_e32 v106, 0, v0
	v_lshlrev_b32_e32 v2, 2, v4
	v_lshl_add_u64 v[0:1], s[6:7], 0, v[102:103]
	s_mov_b64 s[6:7], 0x15800000
	v_and_b32_e32 v100, 31, v107
	s_ashr_i32 s96, s3, 7
	s_and_b32 s97, s3, 64
	v_lshl_add_u64 v[108:109], v[0:1], 0, s[6:7]
	v_or_b32_e32 v0, 1, v2
	s_lshl_b32 s3, s3, 1
	v_cmp_lt_u32_e64 s[8:9], v0, v100
	v_or_b32_e32 v0, 2, v2
	s_and_b32 s3, s3, 0x80
	v_cmp_lt_u32_e64 s[10:11], v0, v100
	v_cmp_gt_u32_e64 s[42:43], v0, v100
	s_movk_i32 s70, 0x310
	v_mov_b32_e32 v0, s3
	v_mad_u32_u24 v0, v100, s70, v0
	v_or_b32_e32 v0, v0, v102
	v_add_u32_e32 v118, 0, v0
	v_mbcnt_lo_u32_b32 v0, -1, 0
	v_mbcnt_hi_u32_b32 v119, -1, v0
	s_movk_i32 s4, 0xc00
	v_or_b32_e32 v1, 3, v2
	v_or_b32_e32 v3, 8, v2
	v_or_b32_e32 v4, 9, v2
	v_or_b32_e32 v5, 10, v2
	v_or_b32_e32 v6, 11, v2
	v_or_b32_e32 v7, 16, v2
	v_or_b32_e32 v8, 17, v2
	v_or_b32_e32 v9, 18, v2
	v_or_b32_e32 v10, 19, v2
	v_or_b32_e32 v11, 24, v2
	v_or_b32_e32 v12, 25, v2
	v_or_b32_e32 v13, 26, v2
	v_or_b32_e32 v14, 27, v2
	v_and_b32_e32 v0, 64, v119
	s_mov_b64 s[0:1], s[90:91]
	v_cmp_gt_i32_e64 s[4:5], s4, v107
	v_cmp_lt_u32_e64 s[6:7], v2, v100
	v_cmp_lt_u32_e64 s[12:13], v1, v100
	v_cmp_lt_u32_e64 s[14:15], v3, v100
	v_cmp_lt_u32_e64 s[16:17], v4, v100
	v_cmp_lt_u32_e64 s[18:19], v5, v100
	v_cmp_lt_u32_e64 s[20:21], v6, v100
	v_cmp_lt_u32_e64 s[22:23], v7, v100
	v_cmp_lt_u32_e64 s[24:25], v8, v100
	v_cmp_lt_u32_e64 s[26:27], v9, v100
	v_cmp_lt_u32_e64 s[28:29], v10, v100
	v_cmp_lt_u32_e64 s[30:31], v11, v100
	v_cmp_lt_u32_e64 s[34:35], v12, v100
	v_cmp_lt_u32_e64 s[36:37], v13, v100
	v_cmp_lt_u32_e64 s[38:39], v14, v100
	v_cmp_gt_u32_e64 s[40:41], v2, v100
	v_cmp_gt_u32_e64 s[44:45], v1, v100
	v_cmp_gt_u32_e64 s[46:47], v3, v100
	v_cmp_gt_u32_e64 s[48:49], v4, v100
	v_cmp_gt_u32_e64 s[50:51], v5, v100
	v_cmp_gt_u32_e64 s[52:53], v6, v100
	v_cmp_gt_u32_e64 s[54:55], v7, v100
	v_cmp_gt_u32_e64 s[56:57], v8, v100
	v_cmp_gt_u32_e64 s[58:59], v9, v100
	v_cmp_gt_u32_e64 s[60:61], v10, v100
	v_cmp_gt_u32_e64 s[62:63], v11, v100
	v_cmp_gt_u32_e64 s[64:65], v12, v100
	v_cmp_gt_u32_e64 s[66:67], v13, v100
	v_cmp_gt_u32_e64 s[68:69], v14, v100
	v_or_b32_e32 v116, s97, v100
	v_lshlrev_b32_e32 v117, 3, v107
	s_movk_i32 s3, 0x90
	v_xor_b32_e32 v120, 32, v119
	v_add_u32_e32 v121, 64, v0
	v_mov_b32_e32 v122, 0xff800000
	s_branch .LBB0_244

; #define GEMM_PHASE(EPI, Aptr, LDA, Bptr, LDB, NN, KK, Eobj) GEMM_PHASE_H(EPI, Aptr, LDA, 0, Bptr, LDB, NN, KK, Eobj)
; #define KPTR() KP kp = (KP)__builtin_amdgcn_kernarg_segment_ptr(); int G = gridDim.x, blk = blockIdx.x; asm volatile("" : "+s"(kp), "+s"(G), "+s"(blk)); unsigned char* ws = kp->ws; (void)ws
;     __host__ __device__ bool next(int i, Unit& u) const {
;         const long L = (long)i * G + c; if (L >= nwg) return false;
;         int wgid = (int)L; { const int q = nwg / NXCD, r = nwg % NXCD, xcd = wgid % NXCD, off = wgid / NXCD; wgid = (xcd < r ? xcd * (q + 1) : r * (q + 1) + (xcd - r) * q) + off; }
;         const int nig = WGM * nN, gid = wgid / nig, fm = gid * WGM, gsz = (nM - fm) < WGM ? (nM - fm) : WGM;
;         u.pm = fm + ((wgid % nig) % gsz); u.pn = (wgid % nig) / gsz; return true;
; template <int L> __device__ __forceinline__ void layer_fwd(unsigned char* lds, const XcdBarrier& bar) {
;     ...
;             { KPTR(); bf16_t* LOA = (bf16_t*)kp->out; using ER_ = EpiRes<false, L == 0>; ER_ E{kp->x, (const bf16_t*)(ws + WS_XBX), LOA, (bf16_t*)(ws + WS_XBX), LOA, (f32x2*)(ws + WS_ST1), nullptr, nullptr, nullptr}; GEMM_PHASE(ER_, ws + WS_O, D, ws + WS_WOUT, D, D, D, E); }
.Lprio_out0:
	s_mov_b32 s25, s2
	s_mov_b32 s48, s74
	s_mov_b64 s[4:5], s[0:1]
	s_waitcnt lgkmcnt(0)
	s_barrier
	s_load_dwordx2 s[12:13], s[4:5], 0x0
	v_mov_b32_e32 v8, v254
	s_cmpk_lt_i32 s25, 0x200
	s_cselect_b64 s[6:7], -1, 0
	s_cmpk_gt_i32 s25, 0x1ff
	v_readfirstlane_b32 s3, v8
	s_cbranch_scc1 .LBB0_319
	s_ashr_i32 s8, s25, 31
	s_lshr_b32 s8, s8, 29
	s_add_i32 s14, s25, s8
	s_and_b32 s8, s14, -8
	s_sub_i32 s10, s25, s8
	s_cmp_gt_i32 s10, -1
	s_cbranch_scc0 .LBB0_316
	s_lshl_b32 s11, s10, 6
	s_ashr_i32 s8, s14, 3
	s_cbranch_execz .LBB0_317
	s_branch .LBB0_318

; #define PG8_STAGE(bufoff, gbase, voff) do { _Pragma("unroll") for (int _i = 0; _i < 2; ++_i) \
;         __builtin_amdgcn_global_load_lds((const unsigned*)((const char*)(gbase) + (voff)[_i]), (PG8_LAS unsigned*)(lds + (bufoff) + ldsw + _i * 8192), 16, 0, 0); } while (0)
; #define PG8_LDA(dst, b, h) do { _Pragma("unroll") for (int m = 0; m < 4; ++m) _Pragma("unroll") for (int k = 0; k < 2; ++k) dst[m][k] = *(const PG8_LAS bf16x8*)(lds + PG8_SA(b, h) + aoff + m * 2048 + k * 1024); } while (0)
; #define PG8_LDB(dst, b, h) do { _Pragma("unroll") for (int n = 0; n < 2; ++n) _Pragma("unroll") for (int k = 0; k < 2; ++k) dst[n][k] = *(const PG8_LAS bf16x8*)(lds + PG8_SB(b, h) + boff + n * 2048 + k * 1024); } while (0)
; #define PG8_MMA(ai, bj, At, Bt) do { __builtin_amdgcn_s_setprio(1); _Pragma("unroll") for (int m = 0; m < 4; ++m) _Pragma("unroll") for (int n = 0; n < 2; ++n) _Pragma("unroll") for (int k = 0; k < 2; ++k) \
;         acc[ai][bj][m][n] = __builtin_amdgcn_mfma_f32_16x16x32_bf16(Bt[n][k], At[m][k], acc[ai][bj][m][n], 0, 0, 0); __builtin_amdgcn_s_setprio(0); } while (0)
; #define PG8_WAIT_V(n) asm volatile("s_waitcnt vmcnt(" #n ")" ::: "memory")
; #define PG8_WAIT_L(n) asm volatile("s_waitcnt lgkmcnt(" #n ")" ::: "memory")
; #define PG8_BAR __builtin_amdgcn_s_barrier()
; #define PG8_SCHED __builtin_amdgcn_sched_barrier(0)
; template <class Epi, class Sched, bool ALIGN_EPI = false, bool SP2 = false>
; __device__ __forceinline__ void gemm_phase(PG8_LAS unsigned char* lds, const Gemm g, const Sched& S, const Epi& E) {
;     ...
;             const bool last = (t == nt - 2);
;             const char* a1 = cA + PG8_AK(t + 1);
;             const char* a2 = last ? nA : cA + PG8_AK(t + 2); const char* b2 = last ? nB : cB + (size_t)(t + 2) * kstep;
;             const char* a3 = last ? nA + PG8_AK(1) : cA + PG8_AK(t + 3); const char* b3 = b2 + kstep;
;             if (last && has_next) S.a_ready(nxt);
;             if constexpr (SP2) {
;             PG8_LDB(B0, 0, 0); PG8_LDB(B1, 0, 1); PG8_SCHED; PG8_LDA(At, 0, 0); PG8_STAGE(PG8_SA(1, 1), a1 + hstepA, voffA);
;             PG8_WAIT_V(8); PG8_WAIT_L(0); PG8_BAR; PG8_MMA(0, 0, At, B0); PG8_MMA(0, 1, At, B1); PG8_BAR; PG8_SCHED;
;             PG8_LDA(At, 0, 1); PG8_STAGE(PG8_SB(0, 0), b2, voffB); PG8_STAGE(PG8_SB(0, 1), b2 + hstepB, voffB); PG8_STAGE(PG8_SA(0, 0), a2, voffA);
.LBB0_332:
	ds_read_b128 v[180:183], v147
	ds_read_b128 v[184:187], v147 offset:1024
	ds_read_b128 v[188:191], v147 offset:2048
	ds_read_b128 v[192:195], v147 offset:3072
	ds_read_b128 v[196:199], v149
	ds_read_b128 v[200:203], v149 offset:1024
	ds_read_b128 v[208:211], v149 offset:2048
	ds_read_b128 v[212:215], v149 offset:3072
	s_add_u32 s42, s38, s40
	s_addc_u32 s43, s39, s41
	s_add_u32 s46, s42, 0x100
	s_addc_u32 s47, s43, 0
	s_add_u32 s44, s79, s40
	s_addc_u32 s45, s80, s41
	s_add_u32 s42, s42, 0x180
	s_addc_u32 s43, s43, 0
	s_cmpk_eq_i32 s40, 0x700
	s_cselect_b32 s43, s78, s43
	s_cselect_b32 s42, s69, s42
	s_cselect_b32 s45, s27, s45
	s_cselect_b32 s44, s37, s44
	s_cselect_b32 s47, s3, s47
	s_cselect_b32 s46, s29, s46
	v_lshl_add_u64 v[204:205], v[178:179], 0, s[40:41]
	s_add_i32 m0, s54, 0xc000
	ds_read_b128 v[216:219], v143
	ds_read_b128 v[220:223], v143 offset:1024
	ds_read_b128 v[224:227], v143 offset:2048
	ds_read_b128 v[228:231], v143 offset:3072
	ds_read_b128 v[232:235], v143 offset:4096
	ds_read_b128 v[236:239], v143 offset:5120
	ds_read_b128 v[240:243], v143 offset:6144
	ds_read_b128 v[244:247], v143 offset:7168
	global_load_lds_dwordx4 v[204:205], off
	v_lshl_add_u64 v[204:205], v[176:177], 0, s[40:41]
	s_add_i32 m0, s54, 0xe000
	s_nop 0
	global_load_lds_dwordx4 v[204:205], off
	s_waitcnt vmcnt(8)
	s_waitcnt lgkmcnt(0)
	s_barrier
	s_waitcnt lgkmcnt(0)
	v_mfma_f32_16x16x32_bf16 v[124:127], v[180:183], v[216:219], v[124:127]
	v_mfma_f32_16x16x32_bf16 v[120:123], v[188:191], v[216:219], v[120:123]
	v_mfma_f32_16x16x32_bf16 v[116:119], v[180:183], v[224:227], v[116:119]
	v_mfma_f32_16x16x32_bf16 v[112:115], v[188:191], v[224:227], v[112:115]
	v_mfma_f32_16x16x32_bf16 v[108:111], v[180:183], v[232:235], v[108:111]
	v_mfma_f32_16x16x32_bf16 v[104:107], v[188:191], v[232:235], v[104:107]
	v_mfma_f32_16x16x32_bf16 v[100:103], v[180:183], v[240:243], v[100:103]
	v_mfma_f32_16x16x32_bf16 v[96:99], v[188:191], v[240:243], v[96:99]
	v_mfma_f32_16x16x32_bf16 v[124:127], v[184:187], v[220:223], v[124:127]
	v_mfma_f32_16x16x32_bf16 v[120:123], v[192:195], v[220:223], v[120:123]
	v_mfma_f32_16x16x32_bf16 v[116:119], v[184:187], v[228:231], v[116:119]
	v_mfma_f32_16x16x32_bf16 v[112:115], v[192:195], v[228:231], v[112:115]
	v_mfma_f32_16x16x32_bf16 v[108:111], v[184:187], v[236:239], v[108:111]
	v_mfma_f32_16x16x32_bf16 v[104:107], v[192:195], v[236:239], v[104:107]
	v_mfma_f32_16x16x32_bf16 v[100:103], v[184:187], v[244:247], v[100:103]
	v_mfma_f32_16x16x32_bf16 v[96:99], v[192:195], v[244:247], v[96:99]
	v_mfma_f32_16x16x32_bf16 v[64:67], v[196:199], v[216:219], v[64:67]
	v_mfma_f32_16x16x32_bf16 v[56:59], v[208:211], v[216:219], v[56:59]
	v_mfma_f32_16x16x32_bf16 v[52:55], v[196:199], v[224:227], v[52:55]
	v_mfma_f32_16x16x32_bf16 v[48:51], v[208:211], v[224:227], v[48:51]
	v_mfma_f32_16x16x32_bf16 v[44:47], v[196:199], v[232:235], v[44:47]
	v_mfma_f32_16x16x32_bf16 v[40:43], v[208:211], v[232:235], v[40:43]
	v_mfma_f32_16x16x32_bf16 v[36:39], v[196:199], v[240:243], v[36:39]
	v_mfma_f32_16x16x32_bf16 v[32:35], v[208:211], v[240:243], v[32:35]
	v_mfma_f32_16x16x32_bf16 v[64:67], v[200:203], v[220:223], v[64:67]
	v_mfma_f32_16x16x32_bf16 v[56:59], v[212:215], v[220:223], v[56:59]
	v_mfma_f32_16x16x32_bf16 v[52:55], v[200:203], v[228:231], v[52:55]
	v_mfma_f32_16x16x32_bf16 v[48:51], v[212:215], v[228:231], v[48:51]
	v_mfma_f32_16x16x32_bf16 v[44:47], v[200:203], v[236:239], v[44:47]
	v_mfma_f32_16x16x32_bf16 v[40:43], v[212:215], v[236:239], v[40:43]
	v_mfma_f32_16x16x32_bf16 v[36:39], v[200:203], v[244:247], v[36:39]
	v_mfma_f32_16x16x32_bf16 v[32:35], v[212:215], v[244:247], v[32:35]
	s_barrier
	s_add_i32 s70, s66, s53
	v_lshl_add_u64 v[204:205], s[44:45], 0, v[130:131]
	s_mov_b32 m0, s70
	ds_read_b128 v[216:219], v143 offset:16384
	ds_read_b128 v[220:223], v143 offset:17408
	ds_read_b128 v[224:227], v143 offset:18432
	ds_read_b128 v[228:231], v143 offset:19456
	ds_read_b128 v[232:235], v143 offset:20480
	ds_read_b128 v[236:239], v143 offset:21504
	ds_read_b128 v[240:243], v143 offset:22528
	ds_read_b128 v[244:247], v143 offset:23552
	global_load_lds_dwordx4 v[204:205], off
	s_add_i32 m0, s70, 0x2000
	s_add_u32 s70, s44, 0x40000
	v_lshl_add_u64 v[206:207], s[44:45], 0, v[134:135]
	s_addc_u32 s71, s45, 0
	s_add_i32 s82, s67, s53
	global_load_lds_dwordx4 v[206:207], off
	v_lshl_add_u64 v[248:249], s[70:71], 0, v[130:131]
	s_mov_b32 m0, s82
	s_nop 0
	global_load_lds_dwordx4 v[248:249], off
	v_lshl_add_u64 v[248:249], s[70:71], 0, v[134:135]
	s_add_i32 m0, s82, 0x2000
	s_nop 0
	global_load_lds_dwordx4 v[248:249], off
	v_lshl_add_u64 v[248:249], s[46:47], 0, v[128:129]
	s_mov_b32 m0, s54
	s_nop 0
	global_load_lds_dwordx4 v[248:249], off
	v_lshl_add_u64 v[248:249], s[46:47], 0, v[132:133]
	s_mov_b32 m0, s55
	s_nop 0
	global_load_lds_dwordx4 v[248:249], off
	s_waitcnt vmcnt(8)
	s_waitcnt lgkmcnt(0)
	s_barrier
; #define PG8_STAGE(bufoff, gbase, voff) do { _Pragma("unroll") for (int _i = 0; _i < 2; ++_i) \
;         __builtin_amdgcn_global_load_lds((const unsigned*)((const char*)(gbase) + (voff)[_i]), (PG8_LAS unsigned*)(lds + (bufoff) + ldsw + _i * 8192), 16, 0, 0); } while (0)
; #define PG8_LDA(dst, b, h) do { _Pragma("unroll") for (int m = 0; m < 4; ++m) _Pragma("unroll") for (int k = 0; k < 2; ++k) dst[m][k] = *(const PG8_LAS bf16x8*)(lds + PG8_SA(b, h) + aoff + m * 2048 + k * 1024); } while (0)
; #define PG8_LDB(dst, b, h) do { _Pragma("unroll") for (int n = 0; n < 2; ++n) _Pragma("unroll") for (int k = 0; k < 2; ++k) dst[n][k] = *(const PG8_LAS bf16x8*)(lds + PG8_SB(b, h) + boff + n * 2048 + k * 1024); } while (0)
; #define PG8_MMA(ai, bj, At, Bt) do { __builtin_amdgcn_s_setprio(1); _Pragma("unroll") for (int m = 0; m < 4; ++m) _Pragma("unroll") for (int n = 0; n < 2; ++n) _Pragma("unroll") for (int k = 0; k < 2; ++k) \
;         acc[ai][bj][m][n] = __builtin_amdgcn_mfma_f32_16x16x32_bf16(Bt[n][k], At[m][k], acc[ai][bj][m][n], 0, 0, 0); __builtin_amdgcn_s_setprio(0); } while (0)
; #define PG8_WAIT_V(n) asm volatile("s_waitcnt vmcnt(" #n ")" ::: "memory")
; #define PG8_WAIT_L(n) asm volatile("s_waitcnt lgkmcnt(" #n ")" ::: "memory")
; #define PG8_BAR __builtin_amdgcn_s_barrier()
; #define PG8_SCHED __builtin_amdgcn_sched_barrier(0)
; template <class Epi, class Sched, bool ALIGN_EPI = false, bool SP2 = false>
; __device__ __forceinline__ void gemm_phase(PG8_LAS unsigned char* lds, const Gemm g, const Sched& S, const Epi& E) {
;     ...
;             PG8_WAIT_V(8); PG8_WAIT_L(0); PG8_BAR; PG8_MMA(1, 0, At, B0); PG8_MMA(1, 1, At, B1); PG8_BAR; PG8_SCHED;
;             PG8_LDB(B0, 1, 0); PG8_LDB(B1, 1, 1); PG8_SCHED; PG8_LDA(At, 1, 0); PG8_STAGE(PG8_SA(0, 1), a2 + hstepA, voffA);
;             PG8_WAIT_V(8); PG8_WAIT_L(0); PG8_BAR; PG8_MMA(0, 0, At, B0); PG8_MMA(0, 1, At, B1); PG8_BAR; PG8_SCHED;
	s_waitcnt lgkmcnt(0)
	v_mfma_f32_16x16x32_bf16 v[92:95], v[180:183], v[216:219], v[92:95]
	v_mfma_f32_16x16x32_bf16 v[88:91], v[188:191], v[216:219], v[88:91]
	v_mfma_f32_16x16x32_bf16 v[84:87], v[180:183], v[224:227], v[84:87]
	v_mfma_f32_16x16x32_bf16 v[80:83], v[188:191], v[224:227], v[80:83]
	v_mfma_f32_16x16x32_bf16 v[76:79], v[180:183], v[232:235], v[76:79]
	v_mfma_f32_16x16x32_bf16 v[72:75], v[188:191], v[232:235], v[72:75]
	v_mfma_f32_16x16x32_bf16 v[68:71], v[180:183], v[240:243], v[68:71]
	v_mfma_f32_16x16x32_bf16 v[60:63], v[188:191], v[240:243], v[60:63]
	v_mfma_f32_16x16x32_bf16 v[92:95], v[184:187], v[220:223], v[92:95]
	v_mfma_f32_16x16x32_bf16 v[88:91], v[192:195], v[220:223], v[88:91]
	v_mfma_f32_16x16x32_bf16 v[84:87], v[184:187], v[228:231], v[84:87]
	v_mfma_f32_16x16x32_bf16 v[80:83], v[192:195], v[228:231], v[80:83]
	v_mfma_f32_16x16x32_bf16 v[76:79], v[184:187], v[236:239], v[76:79]
	v_mfma_f32_16x16x32_bf16 v[72:75], v[192:195], v[236:239], v[72:75]
	v_mfma_f32_16x16x32_bf16 v[68:71], v[184:187], v[244:247], v[68:71]
	v_mfma_f32_16x16x32_bf16 v[60:63], v[192:195], v[244:247], v[60:63]
	v_mfma_f32_16x16x32_bf16 v[28:31], v[196:199], v[216:219], v[28:31]
	v_mfma_f32_16x16x32_bf16 v[24:27], v[208:211], v[216:219], v[24:27]
	v_mfma_f32_16x16x32_bf16 v[20:23], v[196:199], v[224:227], v[20:23]
	v_mfma_f32_16x16x32_bf16 v[16:19], v[208:211], v[224:227], v[16:19]
	v_mfma_f32_16x16x32_bf16 v[12:15], v[196:199], v[232:235], v[12:15]
	v_mfma_f32_16x16x32_bf16 v[8:11], v[208:211], v[232:235], v[8:11]
	v_mfma_f32_16x16x32_bf16 v[4:7], v[196:199], v[240:243], v[4:7]
	v_mfma_f32_16x16x32_bf16 v[0:3], v[208:211], v[240:243], v[0:3]
	v_mfma_f32_16x16x32_bf16 v[28:31], v[200:203], v[220:223], v[28:31]
	v_mfma_f32_16x16x32_bf16 v[24:27], v[212:215], v[220:223], v[24:27]
	v_mfma_f32_16x16x32_bf16 v[20:23], v[200:203], v[228:231], v[20:23]
	v_mfma_f32_16x16x32_bf16 v[16:19], v[212:215], v[228:231], v[16:19]
	v_mfma_f32_16x16x32_bf16 v[12:15], v[200:203], v[236:239], v[12:15]
	v_mfma_f32_16x16x32_bf16 v[8:11], v[212:215], v[236:239], v[8:11]
	v_mfma_f32_16x16x32_bf16 v[4:7], v[200:203], v[244:247], v[4:7]
	v_mfma_f32_16x16x32_bf16 v[0:3], v[212:215], v[244:247], v[0:3]
	s_barrier
	s_add_i32 s70, 0, 0x18000
	v_add_u32_e32 v137, s70, v141
	s_add_i32 s71, 0, 0x1c000
	ds_read_b128 v[180:183], v137
	ds_read_b128 v[184:187], v137 offset:1024
	ds_read_b128 v[188:191], v137 offset:2048
	ds_read_b128 v[192:195], v137 offset:3072
	v_add_u32_e32 v137, s71, v141
	ds_read_b128 v[196:199], v137
	ds_read_b128 v[200:203], v137 offset:1024
	ds_read_b128 v[208:211], v137 offset:2048
	ds_read_b128 v[212:215], v137 offset:3072
	s_add_u32 s46, s46, 0x40000
	s_addc_u32 s47, s47, 0
	s_mov_b32 m0, s56
	v_lshl_add_u64 v[248:249], s[46:47], 0, v[128:129]
	ds_read_b128 v[216:219], v143 offset:32768
	ds_read_b128 v[220:223], v143 offset:33792
	ds_read_b128 v[224:227], v143 offset:34816
	ds_read_b128 v[228:231], v143 offset:35840
	ds_read_b128 v[232:235], v143 offset:36864
	ds_read_b128 v[236:239], v143 offset:37888
	ds_read_b128 v[240:243], v143 offset:38912
	ds_read_b128 v[244:247], v143 offset:39936
	global_load_lds_dwordx4 v[248:249], off
	v_lshl_add_u64 v[248:249], s[46:47], 0, v[132:133]
	s_mov_b32 m0, s57
	s_nop 0
	global_load_lds_dwordx4 v[248:249], off
	s_waitcnt vmcnt(8)
	s_waitcnt lgkmcnt(0)
	s_barrier
	s_waitcnt lgkmcnt(0)
	v_mfma_f32_16x16x32_bf16 v[124:127], v[180:183], v[216:219], v[124:127]
	v_mfma_f32_16x16x32_bf16 v[120:123], v[188:191], v[216:219], v[120:123]
	v_mfma_f32_16x16x32_bf16 v[116:119], v[180:183], v[224:227], v[116:119]
	v_mfma_f32_16x16x32_bf16 v[112:115], v[188:191], v[224:227], v[112:115]
	v_mfma_f32_16x16x32_bf16 v[108:111], v[180:183], v[232:235], v[108:111]
	v_mfma_f32_16x16x32_bf16 v[104:107], v[188:191], v[232:235], v[104:107]
	v_mfma_f32_16x16x32_bf16 v[100:103], v[180:183], v[240:243], v[100:103]
	v_mfma_f32_16x16x32_bf16 v[96:99], v[188:191], v[240:243], v[96:99]
	v_mfma_f32_16x16x32_bf16 v[124:127], v[184:187], v[220:223], v[124:127]
	v_mfma_f32_16x16x32_bf16 v[120:123], v[192:195], v[220:223], v[120:123]
	v_mfma_f32_16x16x32_bf16 v[116:119], v[184:187], v[228:231], v[116:119]
	v_mfma_f32_16x16x32_bf16 v[112:115], v[192:195], v[228:231], v[112:115]
	v_mfma_f32_16x16x32_bf16 v[108:111], v[184:187], v[236:239], v[108:111]
	v_mfma_f32_16x16x32_bf16 v[104:107], v[192:195], v[236:239], v[104:107]
	v_mfma_f32_16x16x32_bf16 v[100:103], v[184:187], v[244:247], v[100:103]
	v_mfma_f32_16x16x32_bf16 v[96:99], v[192:195], v[244:247], v[96:99]
	v_mfma_f32_16x16x32_bf16 v[64:67], v[196:199], v[216:219], v[64:67]
	v_mfma_f32_16x16x32_bf16 v[56:59], v[208:211], v[216:219], v[56:59]
	v_mfma_f32_16x16x32_bf16 v[52:55], v[196:199], v[224:227], v[52:55]
	v_mfma_f32_16x16x32_bf16 v[48:51], v[208:211], v[224:227], v[48:51]
	v_mfma_f32_16x16x32_bf16 v[44:47], v[196:199], v[232:235], v[44:47]
	v_mfma_f32_16x16x32_bf16 v[40:43], v[208:211], v[232:235], v[40:43]
	v_mfma_f32_16x16x32_bf16 v[36:39], v[196:199], v[240:243], v[36:39]
	v_mfma_f32_16x16x32_bf16 v[32:35], v[208:211], v[240:243], v[32:35]
	v_mfma_f32_16x16x32_bf16 v[64:67], v[200:203], v[220:223], v[64:67]
	v_mfma_f32_16x16x32_bf16 v[56:59], v[212:215], v[220:223], v[56:59]
	v_mfma_f32_16x16x32_bf16 v[52:55], v[200:203], v[228:231], v[52:55]
	v_mfma_f32_16x16x32_bf16 v[48:51], v[212:215], v[228:231], v[48:51]
	v_mfma_f32_16x16x32_bf16 v[44:47], v[200:203], v[236:239], v[44:47]
	v_mfma_f32_16x16x32_bf16 v[40:43], v[212:215], v[236:239], v[40:43]
	v_mfma_f32_16x16x32_bf16 v[36:39], v[200:203], v[244:247], v[36:39]
	v_mfma_f32_16x16x32_bf16 v[32:35], v[212:215], v[244:247], v[32:35]
	s_barrier
; #define PG8_STAGE(bufoff, gbase, voff) do { _Pragma("unroll") for (int _i = 0; _i < 2; ++_i) \
;         __builtin_amdgcn_global_load_lds((const unsigned*)((const char*)(gbase) + (voff)[_i]), (PG8_LAS unsigned*)(lds + (bufoff) + ldsw + _i * 8192), 16, 0, 0); } while (0)
; #define PG8_LDA(dst, b, h) do { _Pragma("unroll") for (int m = 0; m < 4; ++m) _Pragma("unroll") for (int k = 0; k < 2; ++k) dst[m][k] = *(const PG8_LAS bf16x8*)(lds + PG8_SA(b, h) + aoff + m * 2048 + k * 1024); } while (0)
; #define PG8_MMA(ai, bj, At, Bt) do { __builtin_amdgcn_s_setprio(1); _Pragma("unroll") for (int m = 0; m < 4; ++m) _Pragma("unroll") for (int n = 0; n < 2; ++n) _Pragma("unroll") for (int k = 0; k < 2; ++k) \
;         acc[ai][bj][m][n] = __builtin_amdgcn_mfma_f32_16x16x32_bf16(Bt[n][k], At[m][k], acc[ai][bj][m][n], 0, 0, 0); __builtin_amdgcn_s_setprio(0); } while (0)
; #define PG8_WAIT_V(n) asm volatile("s_waitcnt vmcnt(" #n ")" ::: "memory")
; #define PG8_WAIT_L(n) asm volatile("s_waitcnt lgkmcnt(" #n ")" ::: "memory")
; #define PG8_BAR __builtin_amdgcn_s_barrier()
; #define PG8_SCHED __builtin_amdgcn_sched_barrier(0)
; template <class Epi, class Sched, bool ALIGN_EPI = false, bool SP2 = false>
; __device__ __forceinline__ void gemm_phase(PG8_LAS unsigned char* lds, const Gemm g, const Sched& S, const Epi& E) {
;     ...
;             PG8_LDA(At, 1, 1); PG8_STAGE(PG8_SB(1, 0), b3, voffB); PG8_STAGE(PG8_SB(1, 1), b3 + hstepB, voffB); PG8_STAGE(PG8_SA(1, 0), a3, voffA);
;             PG8_WAIT_V(8); PG8_WAIT_L(0); PG8_BAR; PG8_MMA(1, 0, At, B0); PG8_MMA(1, 1, At, B1); PG8_BAR; PG8_SCHED;
;     ...
;         if constexpr (ALIGN_EPI) { if (wr == 0) PG8_BAR; }
	s_add_i32 s46, s70, s53
	v_lshl_add_u64 v[204:205], v[204:205], 0, s[20:21]
	s_mov_b32 m0, s46
	ds_read_b128 v[216:219], v143 offset:49152
	ds_read_b128 v[220:223], v143 offset:50176
	ds_read_b128 v[224:227], v143 offset:51200
	ds_read_b128 v[228:231], v143 offset:52224
	ds_read_b128 v[232:235], v143 offset:53248
	ds_read_b128 v[236:239], v143 offset:54272
	ds_read_b128 v[240:243], v143 offset:55296
	ds_read_b128 v[244:247], v143 offset:56320
	global_load_lds_dwordx4 v[204:205], off
	s_add_i32 m0, s46, 0x2000
	s_add_u32 s44, s44, 0x40080
	v_lshl_add_u64 v[204:205], v[206:207], 0, s[20:21]
	s_addc_u32 s45, s45, 0
	s_add_i32 s46, s71, s53
	global_load_lds_dwordx4 v[204:205], off
	v_lshl_add_u64 v[204:205], s[44:45], 0, v[130:131]
	s_mov_b32 m0, s46
	s_nop 0
	global_load_lds_dwordx4 v[204:205], off
	v_lshl_add_u64 v[204:205], s[44:45], 0, v[134:135]
	s_add_i32 m0, s46, 0x2000
	s_nop 0
	global_load_lds_dwordx4 v[204:205], off
	v_lshl_add_u64 v[204:205], s[42:43], 0, v[128:129]
	s_mov_b32 m0, s62
	s_nop 0
	global_load_lds_dwordx4 v[204:205], off
	v_lshl_add_u64 v[204:205], s[42:43], 0, v[132:133]
	s_mov_b32 m0, s63
	s_nop 0
	global_load_lds_dwordx4 v[204:205], off
	s_waitcnt vmcnt(8)
	s_waitcnt lgkmcnt(0)
	s_barrier
	s_waitcnt lgkmcnt(0)
	v_mfma_f32_16x16x32_bf16 v[92:95], v[180:183], v[216:219], v[92:95]
	v_mfma_f32_16x16x32_bf16 v[88:91], v[188:191], v[216:219], v[88:91]
	v_mfma_f32_16x16x32_bf16 v[84:87], v[180:183], v[224:227], v[84:87]
	v_mfma_f32_16x16x32_bf16 v[80:83], v[188:191], v[224:227], v[80:83]
	v_mfma_f32_16x16x32_bf16 v[76:79], v[180:183], v[232:235], v[76:79]
	v_mfma_f32_16x16x32_bf16 v[72:75], v[188:191], v[232:235], v[72:75]
	v_mfma_f32_16x16x32_bf16 v[68:71], v[180:183], v[240:243], v[68:71]
	v_mfma_f32_16x16x32_bf16 v[60:63], v[188:191], v[240:243], v[60:63]
	v_mfma_f32_16x16x32_bf16 v[92:95], v[184:187], v[220:223], v[92:95]
	v_mfma_f32_16x16x32_bf16 v[88:91], v[192:195], v[220:223], v[88:91]
	v_mfma_f32_16x16x32_bf16 v[84:87], v[184:187], v[228:231], v[84:87]
	v_mfma_f32_16x16x32_bf16 v[80:83], v[192:195], v[228:231], v[80:83]
	v_mfma_f32_16x16x32_bf16 v[76:79], v[184:187], v[236:239], v[76:79]
	v_mfma_f32_16x16x32_bf16 v[72:75], v[192:195], v[236:239], v[72:75]
	v_mfma_f32_16x16x32_bf16 v[68:71], v[184:187], v[244:247], v[68:71]
	v_mfma_f32_16x16x32_bf16 v[60:63], v[192:195], v[244:247], v[60:63]
	v_mfma_f32_16x16x32_bf16 v[28:31], v[196:199], v[216:219], v[28:31]
	v_mfma_f32_16x16x32_bf16 v[24:27], v[208:211], v[216:219], v[24:27]
	v_mfma_f32_16x16x32_bf16 v[20:23], v[196:199], v[224:227], v[20:23]
	v_mfma_f32_16x16x32_bf16 v[16:19], v[208:211], v[224:227], v[16:19]
	v_mfma_f32_16x16x32_bf16 v[12:15], v[196:199], v[232:235], v[12:15]
	v_mfma_f32_16x16x32_bf16 v[8:11], v[208:211], v[232:235], v[8:11]
	v_mfma_f32_16x16x32_bf16 v[4:7], v[196:199], v[240:243], v[4:7]
	v_mfma_f32_16x16x32_bf16 v[0:3], v[208:211], v[240:243], v[0:3]
	v_mfma_f32_16x16x32_bf16 v[28:31], v[200:203], v[220:223], v[28:31]
	v_mfma_f32_16x16x32_bf16 v[24:27], v[212:215], v[220:223], v[24:27]
	v_mfma_f32_16x16x32_bf16 v[20:23], v[200:203], v[228:231], v[20:23]
	v_mfma_f32_16x16x32_bf16 v[16:19], v[212:215], v[228:231], v[16:19]
	v_mfma_f32_16x16x32_bf16 v[12:15], v[200:203], v[236:239], v[12:15]
	v_mfma_f32_16x16x32_bf16 v[8:11], v[212:215], v[236:239], v[8:11]
	v_mfma_f32_16x16x32_bf16 v[4:7], v[200:203], v[244:247], v[4:7]
	v_mfma_f32_16x16x32_bf16 v[0:3], v[212:215], v[244:247], v[0:3]
	s_barrier
	s_add_i32 s81, s81, 2
	s_add_u32 s40, s40, 0x100
	s_addc_u32 s41, s41, 0
	s_cmp_gt_u32 s81, 13
	s_cbranch_scc0 .LBB0_332
	s_and_b64 vcc, exec, s[22:23]
	s_cbranch_vccz .LBB0_335
	s_barrier

; #define PG8_STAGE(bufoff, gbase, voff) do { _Pragma("unroll") for (int _i = 0; _i < 2; ++_i) \
;         __builtin_amdgcn_global_load_lds((const unsigned*)((const char*)(gbase) + (voff)[_i]), (PG8_LAS unsigned*)(lds + (bufoff) + ldsw + _i * 8192), 16, 0, 0); } while (0)
; #define PG8_WAIT_V(n) asm volatile("s_waitcnt vmcnt(" #n ")" ::: "memory")
; #define PG8_BAR __builtin_amdgcn_s_barrier()
; template <class Epi, class Sched, bool ALIGN_EPI = false, bool SP2 = false>
; __device__ __forceinline__ void gemm_phase(PG8_LAS unsigned char* lds, const Gemm g, const Sched& S, const Epi& E) {
;     ...
;     const int tid = tid_l, wid = __builtin_amdgcn_readfirstlane(tid >> 6), lane = tid & 63, wr = wid >> 2, wc = wid & 3, fr = lane & 15, fq = lane >> 4;
;     const int K = g.K, nt = K / BK;
;     unsigned voffA[2], voffB[2];
; #pragma unroll
;     for (int i = 0; i < 2; ++i) { int R, C; stage_rc(tid * 16 + i * 8192, R, C); const int Rb = Epi::PERM ? ((R & ~31) + perm32(R & 31)) : R;
;         voffA[i] = (unsigned)(R * g.lda + C) * 2u; voffB[i] = (unsigned)(Rb * g.ldb + C) * 2u; }
;     const size_t kstep = (size_t)(BK * 2);
;     ...
;     const size_t hstepA = (size_t)HALF * g.lda * 2, hstepB = (size_t)HALF * g.ldb * 2;
;     const size_t tstepA = 2 * hstepA, tstepB = 2 * hstepB;
;     const unsigned ldsw = (unsigned)wid * 1024u;
;     const int aoff = lds_byte(wr * 64 + fr, fq * 8), boff = lds_byte(wc * 32 + fr, fq * 8);
;     ...
;     Unit cur, nxt; int ui = 0;
;     if (!S.next(0, cur)) return;
;     f32x4 acc[2][2][4][2];
; #pragma unroll
;     for (int a = 0; a < 2; ++a)
; #pragma unroll
;         for (int b = 0; b < 2; ++b)
; #pragma unroll
;             for (int m = 0; m < 4; ++m)
; #pragma unroll
;                 for (int n = 0; n < 2; ++n) acc[a][b][m][n] = (f32x4){0.f, 0.f, 0.f, 0.f};
;     bf16x8 At[4][2], B0[2][2], B1[2][2];
;     const char* cA = (const char*)g.A + (size_t)cur.pm * tstepA; const char* cB = (const char*)g.Bt + (size_t)cur.pn * tstepB;
;     S.a_ready(cur);
;     if constexpr (SP2) {
;         PG8_STAGE(PG8_SB(0, 0), cB, voffB); PG8_STAGE(PG8_SB(0, 1), cB + hstepB, voffB); PG8_STAGE(PG8_SA(0, 0), cA, voffA); PG8_STAGE(PG8_SA(0, 1), cA + hstepA, voffA);
;         if (wr == 1) PG8_BAR;
;         PG8_WAIT_V(2); PG8_BAR;
.Lprio_ffn1_0:
	s_mov_b64 s[4:5], s[0:1]
	s_mov_b32 s21, s2
	s_mov_b32 s44, s74
	v_mov_b32_e32 v8, v254
	s_waitcnt lgkmcnt(0)
	s_barrier
	s_cmpk_gt_i32 s21, 0xaff
	v_readfirstlane_b32 s3, v8
	s_cbranch_scc1 .LBB0_423
	v_lshlrev_b32_e32 v0, 4, v8
	v_add_u32_e32 v1, 0x2000, v0
	v_ashrrev_i32_e32 v2, 31, v1
	v_lshrrev_b32_e32 v2, 22, v2
	v_add_u32_e32 v2, v1, v2
	v_ashrrev_i32_e32 v9, 10, v2
	v_mul_i32_i24_e32 v2, 0x400, v9
	v_sub_u32_e32 v1, v1, v2
	v_lshrrev_b32_e32 v2, 4, v1
	v_bitop3_b32 v1, v2, v1, 32 bitop3:0x6c
	v_ashrrev_i32_e32 v2, 31, v1
	v_lshrrev_b32_e32 v2, 26, v2
	v_add_u32_e32 v2, v1, v2
	v_lshlrev_b32_e32 v3, 3, v9
	v_ashrrev_i32_e32 v10, 6, v2
	v_and_b32_e32 v3, -16, v3
	v_add_u32_e32 v3, v10, v3
	v_and_b32_e32 v4, 3, v10
	s_mov_b32 s6, 0x1fffe0
	v_lshrrev_b32_e32 v5, 2, v3
	v_lshlrev_b32_e32 v6, 1, v3
	v_and_b32_e32 v2, 0xc0, v2
	v_and_or_b32 v4, v3, s6, v4
	v_and_b32_e32 v5, 4, v5
	v_and_b32_e32 v6, 24, v6
	v_sub_u32_e32 v1, v1, v2
	v_mov_b32_e32 v2, 1
	v_or3_b32 v4, v4, v5, v6
	v_lshlrev_b32_e32 v5, 5, v9
	v_ashrrev_i16_sdwa v1, v2, sext(v1) dst_sel:DWORD dst_unused:UNUSED_PAD src0_sel:DWORD src1_sel:BYTE_0
	v_and_b32_e32 v5, 32, v5
	v_bfe_i32 v11, v1, 0, 16
	v_add_lshl_u32 v1, v5, v11, 1
	v_lshl_add_u32 v144, v4, 11, v1
	v_lshl_add_u32 v146, v3, 11, v1
	v_bfe_i32 v1, v8, 27, 1
	v_lshrrev_b32_e32 v1, 22, v1
	v_add_u32_e32 v1, v0, v1
	s_load_dwordx2 s[4:5], s[4:5], 0x90
	v_and_b32_e32 v1, 0xfffffc00, v1
	v_sub_u32_e32 v0, v0, v1
	v_lshrrev_b32_e32 v1, 4, v0
	v_ashrrev_i32_e32 v3, 31, v8
	v_bitop3_b32 v0, v1, v0, 32 bitop3:0x6c
	v_lshrrev_b32_e32 v3, 26, v3
	v_ashrrev_i32_e32 v1, 31, v0
	v_add_u32_e32 v3, v8, v3
	s_waitcnt lgkmcnt(0)
	s_add_u32 s45, s4, 0x2800000
	v_lshrrev_b32_e32 v1, 26, v1
	v_ashrrev_i32_e32 v13, 6, v3
	s_addc_u32 s46, s5, 0
	v_add_u32_e32 v1, v0, v1
	v_lshlrev_b32_e32 v3, 3, v13
	s_add_u32 s47, s4, 0xc00000
	v_ashrrev_i32_e32 v12, 6, v1
	v_and_b32_e32 v3, -16, v3
	s_addc_u32 s48, s5, 0
	v_add_u32_e32 v3, v12, v3
	v_and_b32_e32 v4, 3, v12
	s_ashr_i32 s50, s21, 31
	v_and_or_b32 v4, v3, s6, v4
	s_lshr_b32 s6, s50, 29
	s_add_i32 s6, s21, s6
	s_ashr_i32 s16, s3, 6
	s_ashr_i32 s7, s6, 3
	s_and_b32 s6, s6, -8
	s_ashr_i32 s19, s3, 8
	s_lshl_b32 s49, s16, 10
	s_sub_i32 s6, s21, s6
	s_cmp_lt_i32 s6, 0
	s_movk_i32 s51, 0x161
	s_cselect_b32 s8, s51, 0x160
	s_mul_i32 s6, s8, s6
	s_add_i32 s6, s6, s7
	s_mul_hi_i32 s7, s6, 0x2e8ba2e9
	s_lshr_b32 s8, s7, 31
	s_ashr_i32 s7, s7, 5
	s_add_i32 s7, s7, s8
	s_lshl_b32 s8, s7, 3
	s_mulk_i32 s7, 0xb0
	s_sub_i32 s6, s6, s7
	s_bfe_u32 s7, s6, 0x3001c
	s_add_i32 s7, s6, s7
	s_sext_i32_i16 s9, s7
	s_and_b32 s7, s7, 0xfff8
	s_sub_i32 s6, s6, s7
	s_sext_i32_i16 s6, s6
	v_lshrrev_b32_e32 v5, 2, v3
	v_lshlrev_b32_e32 v6, 1, v3
	v_and_b32_e32 v1, 0xc0, v1
	s_lshr_b32 s18, s9, 3
	s_add_i32 s30, s8, s6
	v_and_b32_e32 v5, 4, v5
	v_and_b32_e32 v6, 24, v6
	v_sub_u32_e32 v0, v0, v1
	s_ashr_i32 s31, s30, 31
	s_bfe_i64 s[8:9], s[18:19], 0x100000
	v_or3_b32 v4, v4, v5, v6
	v_lshlrev_b32_e32 v5, 5, v13
	v_ashrrev_i16_sdwa v0, v2, sext(v0) dst_sel:DWORD dst_unused:UNUSED_PAD src0_sel:DWORD src1_sel:BYTE_0
	s_lshl_b64 s[6:7], s[30:31], 19
	s_lshl_b64 s[8:9], s[8:9], 19
	v_and_b32_e32 v5, 32, v5
	v_bfe_i32 v14, v0, 0, 16
	s_add_u32 s36, s47, s8
	v_add_lshl_u32 v0, v5, v14, 1
	s_addc_u32 s37, s48, s9
	s_add_i32 s31, s49, 0
	v_lshl_add_u32 v148, v4, 11, v0
	s_add_i32 m0, s31, 0x10000
	v_lshl_add_u32 v150, v3, 11, v0
	global_load_lds_dwordx4 v148, s[36:37]
	s_add_i32 m0, s31, 0x12000
	s_add_u32 s8, s36, 0x40000
	global_load_lds_dwordx4 v144, s[36:37]
	s_addc_u32 s9, s37, 0
	s_add_i32 m0, s31, 0x14000
	v_mov_b32_e32 v149, 0
	global_load_lds_dwordx4 v148, s[8:9]
	s_add_i32 m0, s31, 0x16000
	s_add_u32 s34, s45, s6
	s_addc_u32 s35, s46, s7
	s_add_i32 s52, s31, 0x2000
	global_load_lds_dwordx4 v144, s[8:9]
	s_mov_b32 m0, s31
	s_add_u32 s6, s34, 0x40000
	global_load_lds_dwordx4 v150, s[34:35]
	s_mov_b32 m0, s52
	s_addc_u32 s7, s35, 0
	s_add_i32 s53, s31, 0x4000
	global_load_lds_dwordx4 v146, s[34:35]
	s_mov_b32 m0, s53
	s_add_i32 s54, s31, 0x6000
	global_load_lds_dwordx4 v150, s[6:7]
	s_mov_b32 m0, s54
	v_mov_b32_e32 v145, v149
	global_load_lds_dwordx4 v146, s[6:7]
	v_mov_b32_e32 v151, v149
	v_mov_b32_e32 v147, v149
	s_cmp_eq_u32 s19, 1
	s_mov_b32 s55, 0
	v_lshl_add_u64 v[6:7], s[36:37], 0, v[148:149]
	v_lshl_add_u64 v[4:5], s[36:37], 0, v[144:145]
	v_lshl_add_u64 v[0:1], s[34:35], 0, v[150:151]
	s_cselect_b64 s[6:7], -1, 0
	s_cmp_lg_u32 s19, 1
	v_lshl_add_u64 v[2:3], s[34:35], 0, v[146:147]
	s_cbranch_scc1 .LBB0_410
	s_barrier

; #define PG8_STAGE(bufoff, gbase, voff) do { _Pragma("unroll") for (int _i = 0; _i < 2; ++_i) \
;         __builtin_amdgcn_global_load_lds((const unsigned*)((const char*)(gbase) + (voff)[_i]), (PG8_LAS unsigned*)(lds + (bufoff) + ldsw + _i * 8192), 16, 0, 0); } while (0)
; #define PG8_LDA(dst, b, h) do { _Pragma("unroll") for (int m = 0; m < 4; ++m) _Pragma("unroll") for (int k = 0; k < 2; ++k) dst[m][k] = *(const PG8_LAS bf16x8*)(lds + PG8_SA(b, h) + aoff + m * 2048 + k * 1024); } while (0)
; #define PG8_LDB(dst, b, h) do { _Pragma("unroll") for (int n = 0; n < 2; ++n) _Pragma("unroll") for (int k = 0; k < 2; ++k) dst[n][k] = *(const PG8_LAS bf16x8*)(lds + PG8_SB(b, h) + boff + n * 2048 + k * 1024); } while (0)
; #define PG8_MMA(ai, bj, At, Bt) do { __builtin_amdgcn_s_setprio(1); _Pragma("unroll") for (int m = 0; m < 4; ++m) _Pragma("unroll") for (int n = 0; n < 2; ++n) _Pragma("unroll") for (int k = 0; k < 2; ++k) \
;         acc[ai][bj][m][n] = __builtin_amdgcn_mfma_f32_16x16x32_bf16(Bt[n][k], At[m][k], acc[ai][bj][m][n], 0, 0, 0); __builtin_amdgcn_s_setprio(0); } while (0)
; #define PG8_WAIT_V(n) asm volatile("s_waitcnt vmcnt(" #n ")" ::: "memory")
; #define PG8_WAIT_L(n) asm volatile("s_waitcnt lgkmcnt(" #n ")" ::: "memory")
; #define PG8_BAR __builtin_amdgcn_s_barrier()
; #define PG8_SCHED __builtin_amdgcn_sched_barrier(0)
; template <class Epi, class Sched, bool ALIGN_EPI = false, bool SP2 = false>
; __device__ __forceinline__ void gemm_phase(PG8_LAS unsigned char* lds, const Gemm g, const Sched& S, const Epi& E) {
;     ...
;             const bool last = (t == nt - 2);
;             const char* a1 = cA + PG8_AK(t + 1);
;             const char* a2 = last ? nA : cA + PG8_AK(t + 2); const char* b2 = last ? nB : cB + (size_t)(t + 2) * kstep;
;             const char* a3 = last ? nA + PG8_AK(1) : cA + PG8_AK(t + 3); const char* b3 = b2 + kstep;
;             if (last && has_next) S.a_ready(nxt);
;             if constexpr (SP2) {
;             PG8_LDB(B0, 0, 0); PG8_LDB(B1, 0, 1); PG8_SCHED; PG8_LDA(At, 0, 0); PG8_STAGE(PG8_SA(1, 1), a1 + hstepA, voffA);
;             PG8_WAIT_V(8); PG8_WAIT_L(0); PG8_BAR; PG8_MMA(0, 0, At, B0); PG8_MMA(0, 1, At, B1); PG8_BAR; PG8_SCHED;
;             PG8_LDA(At, 0, 1); PG8_STAGE(PG8_SB(0, 0), b2, voffB); PG8_STAGE(PG8_SB(0, 1), b2 + hstepB, voffB); PG8_STAGE(PG8_SA(0, 0), a2, voffA);
.LBB0_416:
	ds_read_b128 v[132:135], v171
	ds_read_b128 v[136:139], v171 offset:1024
	ds_read_b128 v[140:143], v171 offset:2048
	ds_read_b128 v[178:181], v171 offset:3072
	ds_read_b128 v[182:185], v173
	ds_read_b128 v[186:189], v173 offset:1024
	ds_read_b128 v[190:193], v173 offset:2048
	ds_read_b128 v[194:197], v173 offset:3072
	s_add_u32 s38, s34, s36
	s_addc_u32 s39, s35, s37
	s_add_u32 s42, s38, 0x100
	s_addc_u32 s43, s39, 0
	s_add_u32 s40, s66, s36
	s_addc_u32 s41, s67, s37
	s_add_u32 s38, s38, 0x180
	s_addc_u32 s39, s39, 0
	s_cmpk_eq_i32 s36, 0x700
	s_cselect_b32 s39, s65, s39
	s_cselect_b32 s38, s64, s38
	s_cselect_b32 s41, s23, s41
	s_cselect_b32 s40, s63, s40
	s_cselect_b32 s43, s3, s43
	s_cselect_b32 s42, s25, s42
	v_lshl_add_u64 v[206:207], v[130:131], 0, s[36:37]
	s_add_i32 m0, s31, 0xc000
	ds_read_b128 v[198:201], v175
	ds_read_b128 v[202:205], v175 offset:1024
	ds_read_b128 v[208:211], v175 offset:2048
	ds_read_b128 v[212:215], v175 offset:3072
	ds_read_b128 v[216:219], v175 offset:4096
	ds_read_b128 v[220:223], v175 offset:5120
	ds_read_b128 v[224:227], v175 offset:6144
	ds_read_b128 v[228:231], v175 offset:7168
	global_load_lds_dwordx4 v[206:207], off
	v_lshl_add_u64 v[206:207], v[128:129], 0, s[36:37]
	s_add_i32 m0, s31, 0xe000
	s_nop 0
	global_load_lds_dwordx4 v[206:207], off
	s_waitcnt vmcnt(8)
	s_waitcnt lgkmcnt(0)
	s_barrier
	s_waitcnt lgkmcnt(0)
	v_mfma_f32_16x16x32_bf16 v[124:127], v[132:135], v[198:201], v[124:127]
	v_mfma_f32_16x16x32_bf16 v[120:123], v[140:143], v[198:201], v[120:123]
	v_mfma_f32_16x16x32_bf16 v[116:119], v[132:135], v[208:211], v[116:119]
	v_mfma_f32_16x16x32_bf16 v[112:115], v[140:143], v[208:211], v[112:115]
	v_mfma_f32_16x16x32_bf16 v[108:111], v[132:135], v[216:219], v[108:111]
	v_mfma_f32_16x16x32_bf16 v[104:107], v[140:143], v[216:219], v[104:107]
	v_mfma_f32_16x16x32_bf16 v[100:103], v[132:135], v[224:227], v[100:103]
	v_mfma_f32_16x16x32_bf16 v[96:99], v[140:143], v[224:227], v[96:99]
	v_mfma_f32_16x16x32_bf16 v[124:127], v[136:139], v[202:205], v[124:127]
	v_mfma_f32_16x16x32_bf16 v[120:123], v[178:181], v[202:205], v[120:123]
	v_mfma_f32_16x16x32_bf16 v[116:119], v[136:139], v[212:215], v[116:119]
	v_mfma_f32_16x16x32_bf16 v[112:115], v[178:181], v[212:215], v[112:115]
	v_mfma_f32_16x16x32_bf16 v[108:111], v[136:139], v[220:223], v[108:111]
	v_mfma_f32_16x16x32_bf16 v[104:107], v[178:181], v[220:223], v[104:107]
	v_mfma_f32_16x16x32_bf16 v[100:103], v[136:139], v[228:231], v[100:103]
	v_mfma_f32_16x16x32_bf16 v[96:99], v[178:181], v[228:231], v[96:99]
	v_mfma_f32_16x16x32_bf16 v[64:67], v[182:185], v[198:201], v[64:67]
	v_mfma_f32_16x16x32_bf16 v[56:59], v[190:193], v[198:201], v[56:59]
	v_mfma_f32_16x16x32_bf16 v[52:55], v[182:185], v[208:211], v[52:55]
	v_mfma_f32_16x16x32_bf16 v[48:51], v[190:193], v[208:211], v[48:51]
	v_mfma_f32_16x16x32_bf16 v[44:47], v[182:185], v[216:219], v[44:47]
	v_mfma_f32_16x16x32_bf16 v[40:43], v[190:193], v[216:219], v[40:43]
	v_mfma_f32_16x16x32_bf16 v[36:39], v[182:185], v[224:227], v[36:39]
	v_mfma_f32_16x16x32_bf16 v[32:35], v[190:193], v[224:227], v[32:35]
	v_mfma_f32_16x16x32_bf16 v[64:67], v[186:189], v[202:205], v[64:67]
	v_mfma_f32_16x16x32_bf16 v[56:59], v[194:197], v[202:205], v[56:59]
	v_mfma_f32_16x16x32_bf16 v[52:55], v[186:189], v[212:215], v[52:55]
	v_mfma_f32_16x16x32_bf16 v[48:51], v[194:197], v[212:215], v[48:51]
	v_mfma_f32_16x16x32_bf16 v[44:47], v[186:189], v[220:223], v[44:47]
	v_mfma_f32_16x16x32_bf16 v[40:43], v[194:197], v[220:223], v[40:43]
	v_mfma_f32_16x16x32_bf16 v[36:39], v[186:189], v[228:231], v[36:39]
	v_mfma_f32_16x16x32_bf16 v[32:35], v[194:197], v[228:231], v[32:35]
	s_barrier
	s_add_i32 s69, s59, s49
	v_lshl_add_u64 v[206:207], s[40:41], 0, v[148:149]
	s_mov_b32 m0, s69
	ds_read_b128 v[198:201], v175 offset:16384
	ds_read_b128 v[202:205], v175 offset:17408
	ds_read_b128 v[208:211], v175 offset:18432
	ds_read_b128 v[212:215], v175 offset:19456
	ds_read_b128 v[216:219], v175 offset:20480
	ds_read_b128 v[220:223], v175 offset:21504
	ds_read_b128 v[224:227], v175 offset:22528
	ds_read_b128 v[228:231], v175 offset:23552
	global_load_lds_dwordx4 v[206:207], off
	s_add_i32 m0, s69, 0x2000
	s_add_u32 s70, s40, 0x40000
	v_lshl_add_u64 v[232:233], s[40:41], 0, v[144:145]
	s_addc_u32 s71, s41, 0
	s_add_i32 s69, s60, s49
	global_load_lds_dwordx4 v[232:233], off
	v_lshl_add_u64 v[234:235], s[70:71], 0, v[148:149]
	s_mov_b32 m0, s69
	s_nop 0
	global_load_lds_dwordx4 v[234:235], off
	v_lshl_add_u64 v[234:235], s[70:71], 0, v[144:145]
	s_add_i32 m0, s69, 0x2000
	s_nop 0
	global_load_lds_dwordx4 v[234:235], off
	v_lshl_add_u64 v[234:235], s[42:43], 0, v[150:151]
	s_mov_b32 m0, s31
	s_nop 0
	global_load_lds_dwordx4 v[234:235], off
	v_lshl_add_u64 v[234:235], s[42:43], 0, v[146:147]
	s_mov_b32 m0, s52
	s_nop 0
	global_load_lds_dwordx4 v[234:235], off
	s_waitcnt vmcnt(8)
	s_waitcnt lgkmcnt(0)
	s_barrier
; #define PG8_STAGE(bufoff, gbase, voff) do { _Pragma("unroll") for (int _i = 0; _i < 2; ++_i) \
;         __builtin_amdgcn_global_load_lds((const unsigned*)((const char*)(gbase) + (voff)[_i]), (PG8_LAS unsigned*)(lds + (bufoff) + ldsw + _i * 8192), 16, 0, 0); } while (0)
; #define PG8_LDA(dst, b, h) do { _Pragma("unroll") for (int m = 0; m < 4; ++m) _Pragma("unroll") for (int k = 0; k < 2; ++k) dst[m][k] = *(const PG8_LAS bf16x8*)(lds + PG8_SA(b, h) + aoff + m * 2048 + k * 1024); } while (0)
; #define PG8_LDB(dst, b, h) do { _Pragma("unroll") for (int n = 0; n < 2; ++n) _Pragma("unroll") for (int k = 0; k < 2; ++k) dst[n][k] = *(const PG8_LAS bf16x8*)(lds + PG8_SB(b, h) + boff + n * 2048 + k * 1024); } while (0)
; #define PG8_MMA(ai, bj, At, Bt) do { __builtin_amdgcn_s_setprio(1); _Pragma("unroll") for (int m = 0; m < 4; ++m) _Pragma("unroll") for (int n = 0; n < 2; ++n) _Pragma("unroll") for (int k = 0; k < 2; ++k) \
;         acc[ai][bj][m][n] = __builtin_amdgcn_mfma_f32_16x16x32_bf16(Bt[n][k], At[m][k], acc[ai][bj][m][n], 0, 0, 0); __builtin_amdgcn_s_setprio(0); } while (0)
; #define PG8_WAIT_V(n) asm volatile("s_waitcnt vmcnt(" #n ")" ::: "memory")
; #define PG8_WAIT_L(n) asm volatile("s_waitcnt lgkmcnt(" #n ")" ::: "memory")
; #define PG8_BAR __builtin_amdgcn_s_barrier()
; #define PG8_SCHED __builtin_amdgcn_sched_barrier(0)
; template <class Epi, class Sched, bool ALIGN_EPI = false, bool SP2 = false>
; __device__ __forceinline__ void gemm_phase(PG8_LAS unsigned char* lds, const Gemm g, const Sched& S, const Epi& E) {
;     ...
;             PG8_WAIT_V(8); PG8_WAIT_L(0); PG8_BAR; PG8_MMA(1, 0, At, B0); PG8_MMA(1, 1, At, B1); PG8_BAR; PG8_SCHED;
;             PG8_LDB(B0, 1, 0); PG8_LDB(B1, 1, 1); PG8_SCHED; PG8_LDA(At, 1, 0); PG8_STAGE(PG8_SA(0, 1), a2 + hstepA, voffA);
;             PG8_WAIT_V(8); PG8_WAIT_L(0); PG8_BAR; PG8_MMA(0, 0, At, B0); PG8_MMA(0, 1, At, B1); PG8_BAR; PG8_SCHED;
	s_waitcnt lgkmcnt(0)
	v_mfma_f32_16x16x32_bf16 v[92:95], v[132:135], v[198:201], v[92:95]
	v_mfma_f32_16x16x32_bf16 v[88:91], v[140:143], v[198:201], v[88:91]
	v_mfma_f32_16x16x32_bf16 v[84:87], v[132:135], v[208:211], v[84:87]
	v_mfma_f32_16x16x32_bf16 v[80:83], v[140:143], v[208:211], v[80:83]
	v_mfma_f32_16x16x32_bf16 v[76:79], v[132:135], v[216:219], v[76:79]
	v_mfma_f32_16x16x32_bf16 v[72:75], v[140:143], v[216:219], v[72:75]
	v_mfma_f32_16x16x32_bf16 v[68:71], v[132:135], v[224:227], v[68:71]
	v_mfma_f32_16x16x32_bf16 v[60:63], v[140:143], v[224:227], v[60:63]
	v_mfma_f32_16x16x32_bf16 v[92:95], v[136:139], v[202:205], v[92:95]
	v_mfma_f32_16x16x32_bf16 v[88:91], v[178:181], v[202:205], v[88:91]
	v_mfma_f32_16x16x32_bf16 v[84:87], v[136:139], v[212:215], v[84:87]
	v_mfma_f32_16x16x32_bf16 v[80:83], v[178:181], v[212:215], v[80:83]
	v_mfma_f32_16x16x32_bf16 v[76:79], v[136:139], v[220:223], v[76:79]
	v_mfma_f32_16x16x32_bf16 v[72:75], v[178:181], v[220:223], v[72:75]
	v_mfma_f32_16x16x32_bf16 v[68:71], v[136:139], v[228:231], v[68:71]
	v_mfma_f32_16x16x32_bf16 v[60:63], v[178:181], v[228:231], v[60:63]
	v_mfma_f32_16x16x32_bf16 v[28:31], v[182:185], v[198:201], v[28:31]
	v_mfma_f32_16x16x32_bf16 v[24:27], v[190:193], v[198:201], v[24:27]
	v_mfma_f32_16x16x32_bf16 v[20:23], v[182:185], v[208:211], v[20:23]
	v_mfma_f32_16x16x32_bf16 v[16:19], v[190:193], v[208:211], v[16:19]
	v_mfma_f32_16x16x32_bf16 v[12:15], v[182:185], v[216:219], v[12:15]
	v_mfma_f32_16x16x32_bf16 v[8:11], v[190:193], v[216:219], v[8:11]
	v_mfma_f32_16x16x32_bf16 v[4:7], v[182:185], v[224:227], v[4:7]
	v_mfma_f32_16x16x32_bf16 v[0:3], v[190:193], v[224:227], v[0:3]
	v_mfma_f32_16x16x32_bf16 v[28:31], v[186:189], v[202:205], v[28:31]
	v_mfma_f32_16x16x32_bf16 v[24:27], v[194:197], v[202:205], v[24:27]
	v_mfma_f32_16x16x32_bf16 v[20:23], v[186:189], v[212:215], v[20:23]
	v_mfma_f32_16x16x32_bf16 v[16:19], v[194:197], v[212:215], v[16:19]
	v_mfma_f32_16x16x32_bf16 v[12:15], v[186:189], v[220:223], v[12:15]
	v_mfma_f32_16x16x32_bf16 v[8:11], v[194:197], v[220:223], v[8:11]
	v_mfma_f32_16x16x32_bf16 v[4:7], v[186:189], v[228:231], v[4:7]
	v_mfma_f32_16x16x32_bf16 v[0:3], v[194:197], v[228:231], v[0:3]
	s_barrier
	s_add_i32 s69, 0, 0x18000
	v_add_u32_e32 v160, s69, v163
	s_add_i32 s70, 0, 0x1c000
	ds_read_b128 v[132:135], v160
	ds_read_b128 v[136:139], v160 offset:1024
	ds_read_b128 v[140:143], v160 offset:2048
	ds_read_b128 v[178:181], v160 offset:3072
	v_add_u32_e32 v160, s70, v163
	ds_read_b128 v[182:185], v160
	ds_read_b128 v[186:189], v160 offset:1024
	ds_read_b128 v[190:193], v160 offset:2048
	ds_read_b128 v[194:197], v160 offset:3072
	s_add_u32 s42, s42, 0x40000
	s_addc_u32 s43, s43, 0
	s_mov_b32 m0, s53
	v_lshl_add_u64 v[234:235], s[42:43], 0, v[150:151]
	ds_read_b128 v[198:201], v175 offset:32768
	ds_read_b128 v[202:205], v175 offset:33792
	ds_read_b128 v[208:211], v175 offset:34816
	ds_read_b128 v[212:215], v175 offset:35840
	ds_read_b128 v[216:219], v175 offset:36864
	ds_read_b128 v[220:223], v175 offset:37888
	ds_read_b128 v[224:227], v175 offset:38912
	ds_read_b128 v[228:231], v175 offset:39936
	global_load_lds_dwordx4 v[234:235], off
	v_lshl_add_u64 v[234:235], s[42:43], 0, v[146:147]
	s_mov_b32 m0, s54
	s_nop 0
	global_load_lds_dwordx4 v[234:235], off
	s_waitcnt vmcnt(8)
	s_waitcnt lgkmcnt(0)
	s_barrier
	s_waitcnt lgkmcnt(0)
	v_mfma_f32_16x16x32_bf16 v[124:127], v[132:135], v[198:201], v[124:127]
	v_mfma_f32_16x16x32_bf16 v[120:123], v[140:143], v[198:201], v[120:123]
	v_mfma_f32_16x16x32_bf16 v[116:119], v[132:135], v[208:211], v[116:119]
	v_mfma_f32_16x16x32_bf16 v[112:115], v[140:143], v[208:211], v[112:115]
	v_mfma_f32_16x16x32_bf16 v[108:111], v[132:135], v[216:219], v[108:111]
	v_mfma_f32_16x16x32_bf16 v[104:107], v[140:143], v[216:219], v[104:107]
	v_mfma_f32_16x16x32_bf16 v[100:103], v[132:135], v[224:227], v[100:103]
	v_mfma_f32_16x16x32_bf16 v[96:99], v[140:143], v[224:227], v[96:99]
	v_mfma_f32_16x16x32_bf16 v[124:127], v[136:139], v[202:205], v[124:127]
	v_mfma_f32_16x16x32_bf16 v[120:123], v[178:181], v[202:205], v[120:123]
	v_mfma_f32_16x16x32_bf16 v[116:119], v[136:139], v[212:215], v[116:119]
	v_mfma_f32_16x16x32_bf16 v[112:115], v[178:181], v[212:215], v[112:115]
	v_mfma_f32_16x16x32_bf16 v[108:111], v[136:139], v[220:223], v[108:111]
	v_mfma_f32_16x16x32_bf16 v[104:107], v[178:181], v[220:223], v[104:107]
	v_mfma_f32_16x16x32_bf16 v[100:103], v[136:139], v[228:231], v[100:103]
	v_mfma_f32_16x16x32_bf16 v[96:99], v[178:181], v[228:231], v[96:99]
	v_mfma_f32_16x16x32_bf16 v[64:67], v[182:185], v[198:201], v[64:67]
	v_mfma_f32_16x16x32_bf16 v[56:59], v[190:193], v[198:201], v[56:59]
	v_mfma_f32_16x16x32_bf16 v[52:55], v[182:185], v[208:211], v[52:55]
	v_mfma_f32_16x16x32_bf16 v[48:51], v[190:193], v[208:211], v[48:51]
	v_mfma_f32_16x16x32_bf16 v[44:47], v[182:185], v[216:219], v[44:47]
	v_mfma_f32_16x16x32_bf16 v[40:43], v[190:193], v[216:219], v[40:43]
	v_mfma_f32_16x16x32_bf16 v[36:39], v[182:185], v[224:227], v[36:39]
	v_mfma_f32_16x16x32_bf16 v[32:35], v[190:193], v[224:227], v[32:35]
	v_mfma_f32_16x16x32_bf16 v[64:67], v[186:189], v[202:205], v[64:67]
	v_mfma_f32_16x16x32_bf16 v[56:59], v[194:197], v[202:205], v[56:59]
	v_mfma_f32_16x16x32_bf16 v[52:55], v[186:189], v[212:215], v[52:55]
	v_mfma_f32_16x16x32_bf16 v[48:51], v[194:197], v[212:215], v[48:51]
	v_mfma_f32_16x16x32_bf16 v[44:47], v[186:189], v[220:223], v[44:47]
	v_mfma_f32_16x16x32_bf16 v[40:43], v[194:197], v[220:223], v[40:43]
	v_mfma_f32_16x16x32_bf16 v[36:39], v[186:189], v[228:231], v[36:39]
	v_mfma_f32_16x16x32_bf16 v[32:35], v[194:197], v[228:231], v[32:35]
	s_barrier
; #define PG8_STAGE(bufoff, gbase, voff) do { _Pragma("unroll") for (int _i = 0; _i < 2; ++_i) \
;         __builtin_amdgcn_global_load_lds((const unsigned*)((const char*)(gbase) + (voff)[_i]), (PG8_LAS unsigned*)(lds + (bufoff) + ldsw + _i * 8192), 16, 0, 0); } while (0)
; #define PG8_LDA(dst, b, h) do { _Pragma("unroll") for (int m = 0; m < 4; ++m) _Pragma("unroll") for (int k = 0; k < 2; ++k) dst[m][k] = *(const PG8_LAS bf16x8*)(lds + PG8_SA(b, h) + aoff + m * 2048 + k * 1024); } while (0)
; #define PG8_MMA(ai, bj, At, Bt) do { __builtin_amdgcn_s_setprio(1); _Pragma("unroll") for (int m = 0; m < 4; ++m) _Pragma("unroll") for (int n = 0; n < 2; ++n) _Pragma("unroll") for (int k = 0; k < 2; ++k) \
;         acc[ai][bj][m][n] = __builtin_amdgcn_mfma_f32_16x16x32_bf16(Bt[n][k], At[m][k], acc[ai][bj][m][n], 0, 0, 0); __builtin_amdgcn_s_setprio(0); } while (0)
; #define PG8_WAIT_V(n) asm volatile("s_waitcnt vmcnt(" #n ")" ::: "memory")
; #define PG8_WAIT_L(n) asm volatile("s_waitcnt lgkmcnt(" #n ")" ::: "memory")
; #define PG8_BAR __builtin_amdgcn_s_barrier()
; #define PG8_SCHED __builtin_amdgcn_sched_barrier(0)
; template <class Epi, class Sched, bool ALIGN_EPI = false, bool SP2 = false>
; __device__ __forceinline__ void gemm_phase(PG8_LAS unsigned char* lds, const Gemm g, const Sched& S, const Epi& E) {
;     ...
;             PG8_LDA(At, 1, 1); PG8_STAGE(PG8_SB(1, 0), b3, voffB); PG8_STAGE(PG8_SB(1, 1), b3 + hstepB, voffB); PG8_STAGE(PG8_SA(1, 0), a3, voffA);
;             PG8_WAIT_V(8); PG8_WAIT_L(0); PG8_BAR; PG8_MMA(1, 0, At, B0); PG8_MMA(1, 1, At, B1); PG8_BAR; PG8_SCHED;
;     ...
;         if constexpr (ALIGN_EPI) { if (wr == 0) PG8_BAR; }
	s_add_i32 s42, s69, s49
	v_lshl_add_u64 v[206:207], v[206:207], 0, s[16:17]
	s_mov_b32 m0, s42
	ds_read_b128 v[198:201], v175 offset:49152
	ds_read_b128 v[202:205], v175 offset:50176
	ds_read_b128 v[208:211], v175 offset:51200
	ds_read_b128 v[212:215], v175 offset:52224
	ds_read_b128 v[216:219], v175 offset:53248
	ds_read_b128 v[220:223], v175 offset:54272
	ds_read_b128 v[224:227], v175 offset:55296
	ds_read_b128 v[228:231], v175 offset:56320
	global_load_lds_dwordx4 v[206:207], off
	s_add_i32 m0, s42, 0x2000
	s_add_u32 s40, s40, 0x40080
	v_lshl_add_u64 v[206:207], v[232:233], 0, s[16:17]
	s_addc_u32 s41, s41, 0
	s_add_i32 s42, s70, s49
	global_load_lds_dwordx4 v[206:207], off
	v_lshl_add_u64 v[206:207], s[40:41], 0, v[148:149]
	s_mov_b32 m0, s42
	s_nop 0
	global_load_lds_dwordx4 v[206:207], off
	v_lshl_add_u64 v[206:207], s[40:41], 0, v[144:145]
	s_add_i32 m0, s42, 0x2000
	s_nop 0
	global_load_lds_dwordx4 v[206:207], off
	v_lshl_add_u64 v[206:207], s[38:39], 0, v[150:151]
	s_mov_b32 m0, s56
	s_nop 0
	global_load_lds_dwordx4 v[206:207], off
	v_lshl_add_u64 v[206:207], s[38:39], 0, v[146:147]
	s_mov_b32 m0, s57
	s_nop 0
	global_load_lds_dwordx4 v[206:207], off
	s_waitcnt vmcnt(8)
	s_waitcnt lgkmcnt(0)
	s_barrier
	s_waitcnt lgkmcnt(0)
	v_mfma_f32_16x16x32_bf16 v[92:95], v[132:135], v[198:201], v[92:95]
	v_mfma_f32_16x16x32_bf16 v[88:91], v[140:143], v[198:201], v[88:91]
	v_mfma_f32_16x16x32_bf16 v[84:87], v[132:135], v[208:211], v[84:87]
	v_mfma_f32_16x16x32_bf16 v[80:83], v[140:143], v[208:211], v[80:83]
	v_mfma_f32_16x16x32_bf16 v[76:79], v[132:135], v[216:219], v[76:79]
	v_mfma_f32_16x16x32_bf16 v[72:75], v[140:143], v[216:219], v[72:75]
	v_mfma_f32_16x16x32_bf16 v[68:71], v[132:135], v[224:227], v[68:71]
	v_mfma_f32_16x16x32_bf16 v[60:63], v[140:143], v[224:227], v[60:63]
	v_mfma_f32_16x16x32_bf16 v[92:95], v[136:139], v[202:205], v[92:95]
	v_mfma_f32_16x16x32_bf16 v[88:91], v[178:181], v[202:205], v[88:91]
	v_mfma_f32_16x16x32_bf16 v[84:87], v[136:139], v[212:215], v[84:87]
	v_mfma_f32_16x16x32_bf16 v[80:83], v[178:181], v[212:215], v[80:83]
	v_mfma_f32_16x16x32_bf16 v[76:79], v[136:139], v[220:223], v[76:79]
	v_mfma_f32_16x16x32_bf16 v[72:75], v[178:181], v[220:223], v[72:75]
	v_mfma_f32_16x16x32_bf16 v[68:71], v[136:139], v[228:231], v[68:71]
	v_mfma_f32_16x16x32_bf16 v[60:63], v[178:181], v[228:231], v[60:63]
	v_mfma_f32_16x16x32_bf16 v[28:31], v[182:185], v[198:201], v[28:31]
	v_mfma_f32_16x16x32_bf16 v[24:27], v[190:193], v[198:201], v[24:27]
	v_mfma_f32_16x16x32_bf16 v[20:23], v[182:185], v[208:211], v[20:23]
	v_mfma_f32_16x16x32_bf16 v[16:19], v[190:193], v[208:211], v[16:19]
	v_mfma_f32_16x16x32_bf16 v[12:15], v[182:185], v[216:219], v[12:15]
	v_mfma_f32_16x16x32_bf16 v[8:11], v[190:193], v[216:219], v[8:11]
	v_mfma_f32_16x16x32_bf16 v[4:7], v[182:185], v[224:227], v[4:7]
	v_mfma_f32_16x16x32_bf16 v[0:3], v[190:193], v[224:227], v[0:3]
	v_mfma_f32_16x16x32_bf16 v[28:31], v[186:189], v[202:205], v[28:31]
	v_mfma_f32_16x16x32_bf16 v[24:27], v[194:197], v[202:205], v[24:27]
	v_mfma_f32_16x16x32_bf16 v[20:23], v[186:189], v[212:215], v[20:23]
	v_mfma_f32_16x16x32_bf16 v[16:19], v[194:197], v[212:215], v[16:19]
	v_mfma_f32_16x16x32_bf16 v[12:15], v[186:189], v[220:223], v[12:15]
	v_mfma_f32_16x16x32_bf16 v[8:11], v[194:197], v[220:223], v[8:11]
	v_mfma_f32_16x16x32_bf16 v[4:7], v[186:189], v[228:231], v[4:7]
	v_mfma_f32_16x16x32_bf16 v[0:3], v[194:197], v[228:231], v[0:3]
	s_barrier
	s_add_i32 s68, s68, 2
	s_add_u32 s36, s36, 0x100
	s_addc_u32 s37, s37, 0
	s_cmp_gt_u32 s68, 13
	s_cbranch_scc0 .LBB0_416
	s_and_b64 vcc, exec, s[18:19]
	s_cbranch_vccz .LBB0_419
	s_barrier

; #define PG8_STAGE(bufoff, gbase, voff) do { _Pragma("unroll") for (int _i = 0; _i < 2; ++_i) \
;         __builtin_amdgcn_global_load_lds((const unsigned*)((const char*)(gbase) + (voff)[_i]), (PG8_LAS unsigned*)(lds + (bufoff) + ldsw + _i * 8192), 16, 0, 0); } while (0)
; #define PG8_LDA(dst, b, h) do { _Pragma("unroll") for (int m = 0; m < 4; ++m) _Pragma("unroll") for (int k = 0; k < 2; ++k) dst[m][k] = *(const PG8_LAS bf16x8*)(lds + PG8_SA(b, h) + aoff + m * 2048 + k * 1024); } while (0)
; #define PG8_LDB(dst, b, h) do { _Pragma("unroll") for (int n = 0; n < 2; ++n) _Pragma("unroll") for (int k = 0; k < 2; ++k) dst[n][k] = *(const PG8_LAS bf16x8*)(lds + PG8_SB(b, h) + boff + n * 2048 + k * 1024); } while (0)
; #define PG8_MMA(ai, bj, At, Bt) do { __builtin_amdgcn_s_setprio(1); _Pragma("unroll") for (int m = 0; m < 4; ++m) _Pragma("unroll") for (int n = 0; n < 2; ++n) _Pragma("unroll") for (int k = 0; k < 2; ++k) \
;         acc[ai][bj][m][n] = __builtin_amdgcn_mfma_f32_16x16x32_bf16(Bt[n][k], At[m][k], acc[ai][bj][m][n], 0, 0, 0); __builtin_amdgcn_s_setprio(0); } while (0)
; template <class Epi, class Sched, bool ALIGN_EPI = false, bool SP2 = false>
; __device__ __forceinline__ void gemm_phase(PG8_LAS unsigned char* lds, const Gemm g, const Sched& S, const Epi& E) {
;     ...
;         const bool has_next = S.next(ui + 1, nxt);
;         const char* nA = has_next ? (const char*)g.A + (size_t)nxt.pm * tstepA : cA; const char* nB = has_next ? (const char*)g.Bt + (size_t)nxt.pn * tstepB : cB;
;         for (int t = 0; t < nt; t += 2) {
;             const bool last = (t == nt - 2);
;             const char* a1 = cA + PG8_AK(t + 1);
;             const char* a2 = last ? nA : cA + PG8_AK(t + 2); const char* b2 = last ? nB : cB + (size_t)(t + 2) * kstep;
;             const char* a3 = last ? nA + PG8_AK(1) : cA + PG8_AK(t + 3); const char* b3 = b2 + kstep;
;             if (last && has_next) S.a_ready(nxt);
;             if constexpr (SP2) {
;             PG8_LDB(B0, 0, 0); PG8_LDB(B1, 0, 1); PG8_SCHED; PG8_LDA(At, 0, 0); PG8_STAGE(PG8_SA(1, 1), a1 + hstepA, voffA);
;             PG8_WAIT_V(8); PG8_WAIT_L(0); PG8_BAR; PG8_MMA(0, 0, At, B0); PG8_MMA(0, 1, At, B1); PG8_BAR; PG8_SCHED;
;             PG8_LDA(At, 0, 1); PG8_STAGE(PG8_SB(0, 0), b2, voffB); PG8_STAGE(PG8_SB(0, 1), b2 + hstepB, voffB); PG8_STAGE(PG8_SA(0, 0), a2, voffA);
.LBB0_439:
	ds_read_b128 v[0:3], v145
	ds_read_b128 v[4:7], v145 offset:1024
	ds_read_b128 v[8:11], v145 offset:2048
	ds_read_b128 v[12:15], v145 offset:3072
	ds_read_b128 v[16:19], v146
	ds_read_b128 v[20:23], v146 offset:1024
	ds_read_b128 v[24:27], v146 offset:2048
	ds_read_b128 v[28:31], v146 offset:3072
	s_ashr_i32 s31, s30, 31
	s_lshl_b64 s[34:35], s[30:31], 17
	s_add_u32 s34, s49, s34
	s_addc_u32 s35, s50, s35
	s_and_b64 s[36:37], s[4:5], exec
	s_cselect_b32 s47, s35, s41
	s_cselect_b32 s46, s34, s40
	s_ashr_i32 s29, s28, 31
	s_lshl_b64 s[36:37], s[28:29], 17
	s_add_u32 s36, s51, s36
	s_addc_u32 s37, s52, s37
	s_and_b64 s[44:45], s[4:5], exec
	s_cselect_b32 s45, s37, s43
	s_cselect_b32 s44, s36, s42
	s_add_u32 s66, s40, 0x10080
	s_addc_u32 s67, s41, 0
	s_add_i32 s78, s3, 0xc000
	v_lshl_add_u64 v[64:65], s[66:67], 0, v[128:129]
	s_mov_b32 m0, s78
	s_add_i32 s29, s3, 0xe000
	ds_read_b128 v[32:35], v147
	ds_read_b128 v[36:39], v147 offset:1024
	ds_read_b128 v[40:43], v147 offset:2048
	ds_read_b128 v[44:47], v147 offset:3072
	ds_read_b128 v[48:51], v147 offset:4096
	ds_read_b128 v[52:55], v147 offset:5120
	ds_read_b128 v[56:59], v147 offset:6144
	ds_read_b128 v[60:63], v147 offset:7168
	global_load_lds_dwordx4 v[64:65], off
	v_lshl_add_u64 v[64:65], s[66:67], 0, v[132:133]
	s_mov_b32 m0, s29
	s_nop 0
	global_load_lds_dwordx4 v[64:65], off
	s_waitcnt vmcnt(8)
	s_waitcnt lgkmcnt(0)
	s_barrier
	s_waitcnt lgkmcnt(0)
	v_mfma_f32_16x16x32_bf16 v[64:67], v[0:3], v[32:35], 0
	v_mfma_f32_16x16x32_bf16 v[68:71], v[8:11], v[32:35], 0
	v_mfma_f32_16x16x32_bf16 v[72:75], v[0:3], v[40:43], 0
	v_mfma_f32_16x16x32_bf16 v[76:79], v[8:11], v[40:43], 0
	v_mfma_f32_16x16x32_bf16 v[80:83], v[0:3], v[48:51], 0
	v_mfma_f32_16x16x32_bf16 v[84:87], v[8:11], v[48:51], 0
	v_mfma_f32_16x16x32_bf16 v[88:91], v[0:3], v[56:59], 0
	v_mfma_f32_16x16x32_bf16 v[92:95], v[8:11], v[56:59], 0
	v_mfma_f32_16x16x32_bf16 v[64:67], v[4:7], v[36:39], v[64:67]
	v_mfma_f32_16x16x32_bf16 v[68:71], v[12:15], v[36:39], v[68:71]
	v_mfma_f32_16x16x32_bf16 v[72:75], v[4:7], v[44:47], v[72:75]
	v_mfma_f32_16x16x32_bf16 v[76:79], v[12:15], v[44:47], v[76:79]
	v_mfma_f32_16x16x32_bf16 v[80:83], v[4:7], v[52:55], v[80:83]
	v_mfma_f32_16x16x32_bf16 v[84:87], v[12:15], v[52:55], v[84:87]
	v_mfma_f32_16x16x32_bf16 v[88:91], v[4:7], v[60:63], v[88:91]
	v_mfma_f32_16x16x32_bf16 v[92:95], v[12:15], v[60:63], v[92:95]
	v_mfma_f32_16x16x32_bf16 v[96:99], v[16:19], v[32:35], 0
	v_mfma_f32_16x16x32_bf16 v[32:35], v[24:27], v[32:35], 0
	v_mfma_f32_16x16x32_bf16 v[96:99], v[20:23], v[36:39], v[96:99]
	v_mfma_f32_16x16x32_bf16 v[32:35], v[28:31], v[36:39], v[32:35]
	v_mfma_f32_16x16x32_bf16 v[36:39], v[16:19], v[40:43], 0
	v_mfma_f32_16x16x32_bf16 v[40:43], v[24:27], v[40:43], 0
	v_mfma_f32_16x16x32_bf16 v[36:39], v[20:23], v[44:47], v[36:39]
	v_mfma_f32_16x16x32_bf16 v[40:43], v[28:31], v[44:47], v[40:43]
	v_mfma_f32_16x16x32_bf16 v[44:47], v[16:19], v[48:51], 0
	v_mfma_f32_16x16x32_bf16 v[48:51], v[24:27], v[48:51], 0
	v_mfma_f32_16x16x32_bf16 v[44:47], v[20:23], v[52:55], v[44:47]
	v_mfma_f32_16x16x32_bf16 v[48:51], v[28:31], v[52:55], v[48:51]
	v_mfma_f32_16x16x32_bf16 v[52:55], v[16:19], v[56:59], 0
	v_mfma_f32_16x16x32_bf16 v[56:59], v[24:27], v[56:59], 0
	v_mfma_f32_16x16x32_bf16 v[52:55], v[20:23], v[60:63], v[52:55]
	v_mfma_f32_16x16x32_bf16 v[56:59], v[28:31], v[60:63], v[56:59]
	s_barrier
	s_add_i32 s68, s59, s53
	v_lshl_add_u64 v[140:141], s[42:43], 0, v[130:131]
	s_add_i32 s31, s68, 0x2000
	v_lshl_add_u64 v[148:149], v[140:141], 0, s[16:17]
	s_mov_b32 m0, s68
	v_lshl_add_u64 v[204:205], s[42:43], 0, v[134:135]
	s_add_u32 s70, s42, 0x10100
	ds_read_b128 v[60:63], v147 offset:16384
	ds_read_b128 v[100:103], v147 offset:17408
	ds_read_b128 v[104:107], v147 offset:18432
	ds_read_b128 v[108:111], v147 offset:19456
	ds_read_b128 v[112:115], v147 offset:20480
	ds_read_b128 v[116:119], v147 offset:21504
	ds_read_b128 v[120:123], v147 offset:22528
	ds_read_b128 v[124:127], v147 offset:23552
	global_load_lds_dwordx4 v[148:149], off
	v_lshl_add_u64 v[148:149], v[204:205], 0, s[16:17]
	s_mov_b32 m0, s31
	s_addc_u32 s71, s43, 0
	s_add_i32 s66, s60, s53
	global_load_lds_dwordx4 v[148:149], off
	v_lshl_add_u64 v[148:149], s[70:71], 0, v[130:131]
	s_mov_b32 m0, s66
	s_add_i32 s67, s66, 0x2000
	global_load_lds_dwordx4 v[148:149], off
	v_lshl_add_u64 v[148:149], s[70:71], 0, v[134:135]
	s_mov_b32 m0, s67
	v_lshl_add_u64 v[206:207], s[40:41], 0, v[128:129]
	global_load_lds_dwordx4 v[148:149], off
	v_lshl_add_u64 v[148:149], v[206:207], 0, s[16:17]
	s_mov_b32 m0, s3
	v_lshl_add_u64 v[216:217], s[40:41], 0, v[132:133]
	global_load_lds_dwordx4 v[148:149], off
	v_lshl_add_u64 v[148:149], v[216:217], 0, s[16:17]
	s_mov_b32 m0, s39
	s_nop 0
	global_load_lds_dwordx4 v[148:149], off
	s_waitcnt vmcnt(8)
	s_waitcnt lgkmcnt(0)
	s_barrier
; #define PG8_STAGE(bufoff, gbase, voff) do { _Pragma("unroll") for (int _i = 0; _i < 2; ++_i) \
;         __builtin_amdgcn_global_load_lds((const unsigned*)((const char*)(gbase) + (voff)[_i]), (PG8_LAS unsigned*)(lds + (bufoff) + ldsw + _i * 8192), 16, 0, 0); } while (0)
; #define PG8_LDA(dst, b, h) do { _Pragma("unroll") for (int m = 0; m < 4; ++m) _Pragma("unroll") for (int k = 0; k < 2; ++k) dst[m][k] = *(const PG8_LAS bf16x8*)(lds + PG8_SA(b, h) + aoff + m * 2048 + k * 1024); } while (0)
; #define PG8_LDB(dst, b, h) do { _Pragma("unroll") for (int n = 0; n < 2; ++n) _Pragma("unroll") for (int k = 0; k < 2; ++k) dst[n][k] = *(const PG8_LAS bf16x8*)(lds + PG8_SB(b, h) + boff + n * 2048 + k * 1024); } while (0)
; #define PG8_MMA(ai, bj, At, Bt) do { __builtin_amdgcn_s_setprio(1); _Pragma("unroll") for (int m = 0; m < 4; ++m) _Pragma("unroll") for (int n = 0; n < 2; ++n) _Pragma("unroll") for (int k = 0; k < 2; ++k) \
;         acc[ai][bj][m][n] = __builtin_amdgcn_mfma_f32_16x16x32_bf16(Bt[n][k], At[m][k], acc[ai][bj][m][n], 0, 0, 0); __builtin_amdgcn_s_setprio(0); } while (0)
; #define PG8_WAIT_V(n) asm volatile("s_waitcnt vmcnt(" #n ")" ::: "memory")
; #define PG8_WAIT_L(n) asm volatile("s_waitcnt lgkmcnt(" #n ")" ::: "memory")
; #define PG8_BAR __builtin_amdgcn_s_barrier()
; #define PG8_SCHED __builtin_amdgcn_sched_barrier(0)
; template <class Epi, class Sched, bool ALIGN_EPI = false, bool SP2 = false>
; __device__ __forceinline__ void gemm_phase(PG8_LAS unsigned char* lds, const Gemm g, const Sched& S, const Epi& E) {
;     ...
;             PG8_WAIT_V(8); PG8_WAIT_L(0); PG8_BAR; PG8_MMA(1, 0, At, B0); PG8_MMA(1, 1, At, B1); PG8_BAR; PG8_SCHED;
;             PG8_LDB(B0, 1, 0); PG8_LDB(B1, 1, 1); PG8_SCHED; PG8_LDA(At, 1, 0); PG8_STAGE(PG8_SA(0, 1), a2 + hstepA, voffA);
;             PG8_WAIT_V(8); PG8_WAIT_L(0); PG8_BAR; PG8_MMA(0, 0, At, B0); PG8_MMA(0, 1, At, B1); PG8_BAR; PG8_SCHED;
	s_waitcnt lgkmcnt(0)
	v_mfma_f32_16x16x32_bf16 v[148:151], v[0:3], v[60:63], 0
	v_mfma_f32_16x16x32_bf16 v[156:159], v[0:3], v[104:107], 0
	v_mfma_f32_16x16x32_bf16 v[164:167], v[0:3], v[112:115], 0
	v_mfma_f32_16x16x32_bf16 v[0:3], v[0:3], v[120:123], 0
	v_mfma_f32_16x16x32_bf16 v[148:151], v[4:7], v[100:103], v[148:151]
	v_mfma_f32_16x16x32_bf16 v[156:159], v[4:7], v[108:111], v[156:159]
	v_mfma_f32_16x16x32_bf16 v[164:167], v[4:7], v[116:119], v[164:167]
	v_mfma_f32_16x16x32_bf16 v[0:3], v[4:7], v[124:127], v[0:3]
	v_mfma_f32_16x16x32_bf16 v[4:7], v[8:11], v[120:123], 0
	v_mfma_f32_16x16x32_bf16 v[152:155], v[8:11], v[60:63], 0
	v_mfma_f32_16x16x32_bf16 v[160:163], v[8:11], v[104:107], 0
	v_mfma_f32_16x16x32_bf16 v[168:171], v[8:11], v[112:115], 0
	v_mfma_f32_16x16x32_bf16 v[4:7], v[12:15], v[124:127], v[4:7]
	v_mfma_f32_16x16x32_bf16 v[152:155], v[12:15], v[100:103], v[152:155]
	v_mfma_f32_16x16x32_bf16 v[160:163], v[12:15], v[108:111], v[160:163]
	v_mfma_f32_16x16x32_bf16 v[168:171], v[12:15], v[116:119], v[168:171]
	v_mfma_f32_16x16x32_bf16 v[8:11], v[16:19], v[60:63], 0
	v_mfma_f32_16x16x32_bf16 v[12:15], v[24:27], v[60:63], 0
	v_mfma_f32_16x16x32_bf16 v[8:11], v[20:23], v[100:103], v[8:11]
	v_mfma_f32_16x16x32_bf16 v[12:15], v[28:31], v[100:103], v[12:15]
	v_mfma_f32_16x16x32_bf16 v[60:63], v[16:19], v[104:107], 0
	v_mfma_f32_16x16x32_bf16 v[100:103], v[24:27], v[104:107], 0
	v_mfma_f32_16x16x32_bf16 v[104:107], v[16:19], v[112:115], 0
	v_mfma_f32_16x16x32_bf16 v[16:19], v[16:19], v[120:123], 0
	v_mfma_f32_16x16x32_bf16 v[60:63], v[20:23], v[108:111], v[60:63]
	v_mfma_f32_16x16x32_bf16 v[100:103], v[28:31], v[108:111], v[100:103]
	v_mfma_f32_16x16x32_bf16 v[104:107], v[20:23], v[116:119], v[104:107]
	v_mfma_f32_16x16x32_bf16 v[108:111], v[24:27], v[112:115], 0
	v_mfma_f32_16x16x32_bf16 v[16:19], v[20:23], v[124:127], v[16:19]
	v_mfma_f32_16x16x32_bf16 v[20:23], v[24:27], v[120:123], 0
	v_mfma_f32_16x16x32_bf16 v[108:111], v[28:31], v[116:119], v[108:111]
	v_mfma_f32_16x16x32_bf16 v[20:23], v[28:31], v[124:127], v[20:23]
	s_barrier
	s_add_i32 s79, 0, 0x18000
	s_add_i32 s80, 0, 0x1c000
	v_add_u32_e32 v228, s79, v143
	v_add_u32_e32 v236, s80, v143
	ds_read_b128 v[24:27], v228
	ds_read_b128 v[28:31], v228 offset:1024
	ds_read_b128 v[112:115], v228 offset:2048
	ds_read_b128 v[116:119], v228 offset:3072
	ds_read_b128 v[120:123], v236
	ds_read_b128 v[124:127], v236 offset:1024
	ds_read_b128 v[172:175], v236 offset:2048
	ds_read_b128 v[176:179], v236 offset:3072
	s_add_u32 s70, s40, 0x10100
	s_addc_u32 s71, s41, 0
	s_mov_b32 m0, s54
	v_lshl_add_u64 v[218:219], s[70:71], 0, v[128:129]
	ds_read_b128 v[180:183], v147 offset:32768
	ds_read_b128 v[184:187], v147 offset:33792
	ds_read_b128 v[188:191], v147 offset:34816
	ds_read_b128 v[192:195], v147 offset:35840
	ds_read_b128 v[196:199], v147 offset:36864
	ds_read_b128 v[200:203], v147 offset:37888
	ds_read_b128 v[208:211], v147 offset:38912
	ds_read_b128 v[212:215], v147 offset:39936
	global_load_lds_dwordx4 v[218:219], off
	v_lshl_add_u64 v[218:219], s[70:71], 0, v[132:133]
	s_mov_b32 m0, s55
	s_nop 0
	global_load_lds_dwordx4 v[218:219], off
	s_waitcnt vmcnt(8)
	s_waitcnt lgkmcnt(0)
	s_barrier
	s_waitcnt lgkmcnt(0)
	v_mfma_f32_16x16x32_bf16 v[64:67], v[24:27], v[180:183], v[64:67]
	v_mfma_f32_16x16x32_bf16 v[68:71], v[112:115], v[180:183], v[68:71]
	v_mfma_f32_16x16x32_bf16 v[72:75], v[24:27], v[188:191], v[72:75]
	v_mfma_f32_16x16x32_bf16 v[76:79], v[112:115], v[188:191], v[76:79]
	v_mfma_f32_16x16x32_bf16 v[80:83], v[24:27], v[196:199], v[80:83]
	v_mfma_f32_16x16x32_bf16 v[84:87], v[112:115], v[196:199], v[84:87]
	v_mfma_f32_16x16x32_bf16 v[88:91], v[24:27], v[208:211], v[88:91]
	v_mfma_f32_16x16x32_bf16 v[92:95], v[112:115], v[208:211], v[92:95]
	v_mfma_f32_16x16x32_bf16 v[64:67], v[28:31], v[184:187], v[64:67]
	v_mfma_f32_16x16x32_bf16 v[68:71], v[116:119], v[184:187], v[68:71]
	v_mfma_f32_16x16x32_bf16 v[72:75], v[28:31], v[192:195], v[72:75]
	v_mfma_f32_16x16x32_bf16 v[76:79], v[116:119], v[192:195], v[76:79]
	v_mfma_f32_16x16x32_bf16 v[80:83], v[28:31], v[200:203], v[80:83]
	v_mfma_f32_16x16x32_bf16 v[84:87], v[116:119], v[200:203], v[84:87]
	v_mfma_f32_16x16x32_bf16 v[88:91], v[28:31], v[212:215], v[88:91]
	v_mfma_f32_16x16x32_bf16 v[92:95], v[116:119], v[212:215], v[92:95]
	v_mfma_f32_16x16x32_bf16 v[96:99], v[120:123], v[180:183], v[96:99]
	v_mfma_f32_16x16x32_bf16 v[32:35], v[172:175], v[180:183], v[32:35]
	v_mfma_f32_16x16x32_bf16 v[36:39], v[120:123], v[188:191], v[36:39]
	v_mfma_f32_16x16x32_bf16 v[40:43], v[172:175], v[188:191], v[40:43]
	v_mfma_f32_16x16x32_bf16 v[44:47], v[120:123], v[196:199], v[44:47]
	v_mfma_f32_16x16x32_bf16 v[48:51], v[172:175], v[196:199], v[48:51]
	v_mfma_f32_16x16x32_bf16 v[52:55], v[120:123], v[208:211], v[52:55]
	v_mfma_f32_16x16x32_bf16 v[56:59], v[172:175], v[208:211], v[56:59]
	v_mfma_f32_16x16x32_bf16 v[96:99], v[124:127], v[184:187], v[96:99]
	v_mfma_f32_16x16x32_bf16 v[32:35], v[176:179], v[184:187], v[32:35]
	v_mfma_f32_16x16x32_bf16 v[36:39], v[124:127], v[192:195], v[36:39]
	v_mfma_f32_16x16x32_bf16 v[40:43], v[176:179], v[192:195], v[40:43]
	v_mfma_f32_16x16x32_bf16 v[44:47], v[124:127], v[200:203], v[44:47]
	v_mfma_f32_16x16x32_bf16 v[48:51], v[176:179], v[200:203], v[48:51]
	v_mfma_f32_16x16x32_bf16 v[52:55], v[124:127], v[212:215], v[52:55]
	v_mfma_f32_16x16x32_bf16 v[56:59], v[176:179], v[212:215], v[56:59]
	s_barrier
; #define PG8_STAGE(bufoff, gbase, voff) do { _Pragma("unroll") for (int _i = 0; _i < 2; ++_i) \
;         __builtin_amdgcn_global_load_lds((const unsigned*)((const char*)(gbase) + (voff)[_i]), (PG8_LAS unsigned*)(lds + (bufoff) + ldsw + _i * 8192), 16, 0, 0); } while (0)
; #define PG8_LDA(dst, b, h) do { _Pragma("unroll") for (int m = 0; m < 4; ++m) _Pragma("unroll") for (int k = 0; k < 2; ++k) dst[m][k] = *(const PG8_LAS bf16x8*)(lds + PG8_SA(b, h) + aoff + m * 2048 + k * 1024); } while (0)
; #define PG8_LDB(dst, b, h) do { _Pragma("unroll") for (int n = 0; n < 2; ++n) _Pragma("unroll") for (int k = 0; k < 2; ++k) dst[n][k] = *(const PG8_LAS bf16x8*)(lds + PG8_SB(b, h) + boff + n * 2048 + k * 1024); } while (0)
; #define PG8_MMA(ai, bj, At, Bt) do { __builtin_amdgcn_s_setprio(1); _Pragma("unroll") for (int m = 0; m < 4; ++m) _Pragma("unroll") for (int n = 0; n < 2; ++n) _Pragma("unroll") for (int k = 0; k < 2; ++k) \
;         acc[ai][bj][m][n] = __builtin_amdgcn_mfma_f32_16x16x32_bf16(Bt[n][k], At[m][k], acc[ai][bj][m][n], 0, 0, 0); __builtin_amdgcn_s_setprio(0); } while (0)
; #define PG8_WAIT_V(n) asm volatile("s_waitcnt vmcnt(" #n ")" ::: "memory")
; template <class Epi, class Sched, bool ALIGN_EPI = false, bool SP2 = false>
; __device__ __forceinline__ void gemm_phase(PG8_LAS unsigned char* lds, const Gemm g, const Sched& S, const Epi& E) {
;     ...
;             PG8_LDB(B0, 0, 0); PG8_LDB(B1, 0, 1); PG8_SCHED; PG8_LDA(At, 0, 0); PG8_STAGE(PG8_SA(1, 1), a1 + hstepA, voffA);
;             PG8_WAIT_V(8); PG8_WAIT_L(0); PG8_BAR; PG8_MMA(0, 0, At, B0); PG8_MMA(0, 1, At, B1); PG8_BAR; PG8_SCHED;
;             PG8_LDA(At, 0, 1); PG8_STAGE(PG8_SB(0, 0), b2, voffB); PG8_STAGE(PG8_SB(0, 1), b2 + hstepB, voffB); PG8_STAGE(PG8_SA(0, 0), a2, voffA);
;             PG8_WAIT_V(8); PG8_WAIT_L(0); PG8_BAR; PG8_MMA(1, 0, At, B0); PG8_MMA(1, 1, At, B1); PG8_BAR; PG8_SCHED;
;             PG8_LDB(B0, 1, 0); PG8_LDB(B1, 1, 1); PG8_SCHED; PG8_LDA(At, 1, 0); PG8_STAGE(PG8_SA(0, 1), a2 + hstepA, voffA);
;             PG8_WAIT_V(8); PG8_WAIT_L(0); PG8_BAR; PG8_MMA(0, 0, At, B0); PG8_MMA(0, 1, At, B1); PG8_BAR; PG8_SCHED;
;             PG8_LDA(At, 1, 1); PG8_STAGE(PG8_SB(1, 0), b3, voffB); PG8_STAGE(PG8_SB(1, 1), b3 + hstepB, voffB); PG8_STAGE(PG8_SA(1, 0), a3, voffA);
;             PG8_WAIT_V(8); PG8_WAIT_L(0); PG8_BAR; PG8_MMA(1, 0, At, B0); PG8_MMA(1, 1, At, B1); PG8_BAR; PG8_SCHED;
	s_add_i32 s79, s79, s53
	s_add_i32 s69, s79, 0x2000
	v_lshl_add_u64 v[140:141], v[140:141], 0, s[18:19]
	s_mov_b32 m0, s79
	s_add_u32 s70, s42, 0x10180
	ds_read_b128 v[180:183], v147 offset:49152
	ds_read_b128 v[184:187], v147 offset:50176
	ds_read_b128 v[188:191], v147 offset:51200
	ds_read_b128 v[192:195], v147 offset:52224
	ds_read_b128 v[196:199], v147 offset:53248
	ds_read_b128 v[200:203], v147 offset:54272
	ds_read_b128 v[208:211], v147 offset:55296
	ds_read_b128 v[212:215], v147 offset:56320
	global_load_lds_dwordx4 v[140:141], off
	v_lshl_add_u64 v[140:141], v[204:205], 0, s[18:19]
	s_mov_b32 m0, s69
	s_addc_u32 s71, s43, 0
	s_add_i32 s42, s80, s53
	global_load_lds_dwordx4 v[140:141], off
	v_lshl_add_u64 v[140:141], s[70:71], 0, v[130:131]
	s_mov_b32 m0, s42
	s_add_i32 s43, s42, 0x2000
	global_load_lds_dwordx4 v[140:141], off
	v_lshl_add_u64 v[140:141], s[70:71], 0, v[134:135]
	s_mov_b32 m0, s43
	s_nop 0
	global_load_lds_dwordx4 v[140:141], off
	v_lshl_add_u64 v[140:141], v[206:207], 0, s[18:19]
	s_mov_b32 m0, s56
	s_nop 0
	global_load_lds_dwordx4 v[140:141], off
	v_lshl_add_u64 v[140:141], v[216:217], 0, s[18:19]
	s_mov_b32 m0, s57
	s_nop 0
	global_load_lds_dwordx4 v[140:141], off
	s_waitcnt vmcnt(8)
	s_waitcnt lgkmcnt(0)
	s_barrier
	s_waitcnt lgkmcnt(0)
	v_mfma_f32_16x16x32_bf16 v[0:3], v[24:27], v[208:211], v[0:3]
	v_mfma_f32_16x16x32_bf16 v[4:7], v[112:115], v[208:211], v[4:7]
	v_mfma_f32_16x16x32_bf16 v[148:151], v[24:27], v[180:183], v[148:151]
	v_mfma_f32_16x16x32_bf16 v[152:155], v[112:115], v[180:183], v[152:155]
	v_mfma_f32_16x16x32_bf16 v[156:159], v[24:27], v[188:191], v[156:159]
	v_mfma_f32_16x16x32_bf16 v[160:163], v[112:115], v[188:191], v[160:163]
	v_mfma_f32_16x16x32_bf16 v[164:167], v[24:27], v[196:199], v[164:167]
	v_mfma_f32_16x16x32_bf16 v[168:171], v[112:115], v[196:199], v[168:171]
	v_mfma_f32_16x16x32_bf16 v[0:3], v[28:31], v[212:215], v[0:3]
	v_mfma_f32_16x16x32_bf16 v[4:7], v[116:119], v[212:215], v[4:7]
	v_mfma_f32_16x16x32_bf16 v[148:151], v[28:31], v[184:187], v[148:151]
	v_mfma_f32_16x16x32_bf16 v[152:155], v[116:119], v[184:187], v[152:155]
	v_mfma_f32_16x16x32_bf16 v[156:159], v[28:31], v[192:195], v[156:159]
	v_mfma_f32_16x16x32_bf16 v[160:163], v[116:119], v[192:195], v[160:163]
	v_mfma_f32_16x16x32_bf16 v[164:167], v[28:31], v[200:203], v[164:167]
	v_mfma_f32_16x16x32_bf16 v[168:171], v[116:119], v[200:203], v[168:171]
	v_mfma_f32_16x16x32_bf16 v[8:11], v[120:123], v[180:183], v[8:11]
	v_mfma_f32_16x16x32_bf16 v[12:15], v[172:175], v[180:183], v[12:15]
	v_mfma_f32_16x16x32_bf16 v[24:27], v[120:123], v[188:191], v[60:63]
	v_mfma_f32_16x16x32_bf16 v[28:31], v[172:175], v[188:191], v[100:103]
	v_mfma_f32_16x16x32_bf16 v[60:63], v[120:123], v[196:199], v[104:107]
	v_mfma_f32_16x16x32_bf16 v[100:103], v[172:175], v[196:199], v[108:111]
	v_mfma_f32_16x16x32_bf16 v[16:19], v[120:123], v[208:211], v[16:19]
	v_mfma_f32_16x16x32_bf16 v[20:23], v[172:175], v[208:211], v[20:23]
	v_mfma_f32_16x16x32_bf16 v[8:11], v[124:127], v[184:187], v[8:11]
	v_mfma_f32_16x16x32_bf16 v[12:15], v[176:179], v[184:187], v[12:15]
	v_mfma_f32_16x16x32_bf16 v[24:27], v[124:127], v[192:195], v[24:27]
	v_mfma_f32_16x16x32_bf16 v[28:31], v[176:179], v[192:195], v[28:31]
	v_mfma_f32_16x16x32_bf16 v[60:63], v[124:127], v[200:203], v[60:63]
	v_mfma_f32_16x16x32_bf16 v[100:103], v[176:179], v[200:203], v[100:103]
	v_mfma_f32_16x16x32_bf16 v[16:19], v[124:127], v[212:215], v[16:19]
	v_mfma_f32_16x16x32_bf16 v[20:23], v[176:179], v[212:215], v[20:23]
	s_barrier
	ds_read_b128 v[104:107], v145
	ds_read_b128 v[108:111], v145 offset:1024
	ds_read_b128 v[112:115], v145 offset:2048
	ds_read_b128 v[116:119], v145 offset:3072
	ds_read_b128 v[120:123], v146
	ds_read_b128 v[124:127], v146 offset:1024
	ds_read_b128 v[172:175], v146 offset:2048
	ds_read_b128 v[176:179], v146 offset:3072
	s_add_u32 s40, s40, 0x10180
	s_addc_u32 s41, s41, 0
	s_mov_b32 m0, s78
	v_lshl_add_u64 v[140:141], s[40:41], 0, v[128:129]
	ds_read_b128 v[180:183], v147
	ds_read_b128 v[184:187], v147 offset:1024
	ds_read_b128 v[188:191], v147 offset:2048
	ds_read_b128 v[192:195], v147 offset:3072
	ds_read_b128 v[196:199], v147 offset:4096
	ds_read_b128 v[200:203], v147 offset:5120
	ds_read_b128 v[208:211], v147 offset:6144
	ds_read_b128 v[212:215], v147 offset:7168
	global_load_lds_dwordx4 v[140:141], off
	v_lshl_add_u64 v[140:141], s[40:41], 0, v[132:133]
	s_mov_b32 m0, s29
	s_nop 0
	global_load_lds_dwordx4 v[140:141], off
	s_waitcnt vmcnt(8)
	s_waitcnt lgkmcnt(0)
	s_barrier
; #define PG8_STAGE(bufoff, gbase, voff) do { _Pragma("unroll") for (int _i = 0; _i < 2; ++_i) \
;         __builtin_amdgcn_global_load_lds((const unsigned*)((const char*)(gbase) + (voff)[_i]), (PG8_LAS unsigned*)(lds + (bufoff) + ldsw + _i * 8192), 16, 0, 0); } while (0)
; #define PG8_LDA(dst, b, h) do { _Pragma("unroll") for (int m = 0; m < 4; ++m) _Pragma("unroll") for (int k = 0; k < 2; ++k) dst[m][k] = *(const PG8_LAS bf16x8*)(lds + PG8_SA(b, h) + aoff + m * 2048 + k * 1024); } while (0)
; #define PG8_LDB(dst, b, h) do { _Pragma("unroll") for (int n = 0; n < 2; ++n) _Pragma("unroll") for (int k = 0; k < 2; ++k) dst[n][k] = *(const PG8_LAS bf16x8*)(lds + PG8_SB(b, h) + boff + n * 2048 + k * 1024); } while (0)
; #define PG8_MMA(ai, bj, At, Bt) do { __builtin_amdgcn_s_setprio(1); _Pragma("unroll") for (int m = 0; m < 4; ++m) _Pragma("unroll") for (int n = 0; n < 2; ++n) _Pragma("unroll") for (int k = 0; k < 2; ++k) \
;         acc[ai][bj][m][n] = __builtin_amdgcn_mfma_f32_16x16x32_bf16(Bt[n][k], At[m][k], acc[ai][bj][m][n], 0, 0, 0); __builtin_amdgcn_s_setprio(0); } while (0)
; #define PG8_WAIT_V(n) asm volatile("s_waitcnt vmcnt(" #n ")" ::: "memory")
; #define PG8_WAIT_L(n) asm volatile("s_waitcnt lgkmcnt(" #n ")" ::: "memory")
; #define PG8_BAR __builtin_amdgcn_s_barrier()
; #define PG8_SCHED __builtin_amdgcn_sched_barrier(0)
; template <class Epi, class Sched, bool ALIGN_EPI = false, bool SP2 = false>
; __device__ __forceinline__ void gemm_phase(PG8_LAS unsigned char* lds, const Gemm g, const Sched& S, const Epi& E) {
;     ...
;             PG8_WAIT_V(8); PG8_WAIT_L(0); PG8_BAR; PG8_MMA(0, 0, At, B0); PG8_MMA(0, 1, At, B1); PG8_BAR; PG8_SCHED;
;             PG8_LDA(At, 0, 1); PG8_STAGE(PG8_SB(0, 0), b2, voffB); PG8_STAGE(PG8_SB(0, 1), b2 + hstepB, voffB); PG8_STAGE(PG8_SA(0, 0), a2, voffA);
;             PG8_WAIT_V(8); PG8_WAIT_L(0); PG8_BAR; PG8_MMA(1, 0, At, B0); PG8_MMA(1, 1, At, B1); PG8_BAR; PG8_SCHED;
;             PG8_LDB(B0, 1, 0); PG8_LDB(B1, 1, 1); PG8_SCHED; PG8_LDA(At, 1, 0); PG8_STAGE(PG8_SA(0, 1), a2 + hstepA, voffA);
;             PG8_WAIT_V(8); PG8_WAIT_L(0); PG8_BAR; PG8_MMA(0, 0, At, B0); PG8_MMA(0, 1, At, B1); PG8_BAR; PG8_SCHED;
	s_waitcnt lgkmcnt(0)
	v_mfma_f32_16x16x32_bf16 v[88:91], v[104:107], v[208:211], v[88:91]
	v_mfma_f32_16x16x32_bf16 v[64:67], v[104:107], v[180:183], v[64:67]
	v_mfma_f32_16x16x32_bf16 v[68:71], v[112:115], v[180:183], v[68:71]
	v_mfma_f32_16x16x32_bf16 v[72:75], v[104:107], v[188:191], v[72:75]
	v_mfma_f32_16x16x32_bf16 v[76:79], v[112:115], v[188:191], v[76:79]
	v_mfma_f32_16x16x32_bf16 v[80:83], v[104:107], v[196:199], v[80:83]
	v_mfma_f32_16x16x32_bf16 v[84:87], v[112:115], v[196:199], v[84:87]
	v_mfma_f32_16x16x32_bf16 v[216:219], v[108:111], v[212:215], v[88:91]
	v_mfma_f32_16x16x32_bf16 v[88:91], v[112:115], v[208:211], v[92:95]
	v_mfma_f32_16x16x32_bf16 v[64:67], v[108:111], v[184:187], v[64:67]
	v_mfma_f32_16x16x32_bf16 v[68:71], v[116:119], v[184:187], v[68:71]
	v_mfma_f32_16x16x32_bf16 v[72:75], v[108:111], v[192:195], v[72:75]
	v_mfma_f32_16x16x32_bf16 v[76:79], v[116:119], v[192:195], v[76:79]
	v_mfma_f32_16x16x32_bf16 v[80:83], v[108:111], v[200:203], v[80:83]
	v_mfma_f32_16x16x32_bf16 v[84:87], v[116:119], v[200:203], v[84:87]
	v_mfma_f32_16x16x32_bf16 v[92:95], v[116:119], v[212:215], v[88:91]
	v_mfma_f32_16x16x32_bf16 v[48:51], v[172:175], v[196:199], v[48:51]
	v_mfma_f32_16x16x32_bf16 v[88:91], v[120:123], v[180:183], v[96:99]
	v_mfma_f32_16x16x32_bf16 v[32:35], v[172:175], v[180:183], v[32:35]
	v_mfma_f32_16x16x32_bf16 v[36:39], v[120:123], v[188:191], v[36:39]
	v_mfma_f32_16x16x32_bf16 v[40:43], v[172:175], v[188:191], v[40:43]
	v_mfma_f32_16x16x32_bf16 v[44:47], v[120:123], v[196:199], v[44:47]
	v_mfma_f32_16x16x32_bf16 v[180:183], v[176:179], v[200:203], v[48:51]
	v_mfma_f32_16x16x32_bf16 v[48:51], v[120:123], v[208:211], v[52:55]
	v_mfma_f32_16x16x32_bf16 v[32:35], v[176:179], v[184:187], v[32:35]
	v_mfma_f32_16x16x32_bf16 v[36:39], v[124:127], v[192:195], v[36:39]
	v_mfma_f32_16x16x32_bf16 v[40:43], v[176:179], v[192:195], v[40:43]
	v_mfma_f32_16x16x32_bf16 v[44:47], v[124:127], v[200:203], v[44:47]
	v_mfma_f32_16x16x32_bf16 v[52:55], v[124:127], v[212:215], v[48:51]
	v_mfma_f32_16x16x32_bf16 v[48:51], v[172:175], v[208:211], v[56:59]
	v_mfma_f32_16x16x32_bf16 v[220:223], v[124:127], v[184:187], v[88:91]
	v_mfma_f32_16x16x32_bf16 v[184:187], v[176:179], v[212:215], v[48:51]
	s_barrier
	s_mov_b32 m0, s68
	v_lshl_add_u64 v[140:141], s[44:45], 0, v[130:131]
	s_add_u32 s40, s44, 0x10000
	s_nop 0
	ds_read_b128 v[48:51], v147 offset:16384
	ds_read_b128 v[56:59], v147 offset:17408
	ds_read_b128 v[88:91], v147 offset:18432
	ds_read_b128 v[96:99], v147 offset:19456
	ds_read_b128 v[188:191], v147 offset:20480
	ds_read_b128 v[192:195], v147 offset:21504
	ds_read_b128 v[196:199], v147 offset:22528
	ds_read_b128 v[200:203], v147 offset:23552
	global_load_lds_dwordx4 v[140:141], off
	v_lshl_add_u64 v[252:253], s[44:45], 0, v[134:135]
	s_mov_b32 m0, s31
	s_addc_u32 s41, s45, 0
	global_load_lds_dwordx4 v[252:253], off
	v_lshl_add_u64 v[204:205], s[40:41], 0, v[130:131]
	s_mov_b32 m0, s66
	v_lshl_add_u64 v[136:137], s[46:47], 0, v[128:129]
	global_load_lds_dwordx4 v[204:205], off
	v_lshl_add_u64 v[204:205], s[40:41], 0, v[134:135]
	s_mov_b32 m0, s67
	v_lshl_add_u64 v[138:139], s[46:47], 0, v[132:133]
	global_load_lds_dwordx4 v[204:205], off
	s_mov_b32 m0, s3
	s_nop 0
	global_load_lds_dwordx4 v[136:137], off
	s_mov_b32 m0, s39
	s_nop 0
	global_load_lds_dwordx4 v[138:139], off
	s_waitcnt vmcnt(8)
	s_waitcnt lgkmcnt(0)
	s_barrier
	s_waitcnt lgkmcnt(0)
	v_mfma_f32_16x16x32_bf16 v[0:3], v[104:107], v[196:199], v[0:3]
	v_mfma_f32_16x16x32_bf16 v[4:7], v[112:115], v[196:199], v[4:7]
	v_mfma_f32_16x16x32_bf16 v[148:151], v[104:107], v[48:51], v[148:151]
	v_mfma_f32_16x16x32_bf16 v[152:155], v[112:115], v[48:51], v[152:155]
	v_mfma_f32_16x16x32_bf16 v[156:159], v[104:107], v[88:91], v[156:159]
	v_mfma_f32_16x16x32_bf16 v[160:163], v[112:115], v[88:91], v[160:163]
	v_mfma_f32_16x16x32_bf16 v[164:167], v[104:107], v[188:191], v[164:167]
	v_mfma_f32_16x16x32_bf16 v[168:171], v[112:115], v[188:191], v[168:171]
	v_mfma_f32_16x16x32_bf16 v[0:3], v[108:111], v[200:203], v[0:3]
	v_mfma_f32_16x16x32_bf16 v[4:7], v[116:119], v[200:203], v[4:7]
	v_mfma_f32_16x16x32_bf16 v[148:151], v[108:111], v[56:59], v[148:151]
	v_mfma_f32_16x16x32_bf16 v[152:155], v[116:119], v[56:59], v[152:155]
	v_mfma_f32_16x16x32_bf16 v[156:159], v[108:111], v[96:99], v[156:159]
	v_mfma_f32_16x16x32_bf16 v[160:163], v[116:119], v[96:99], v[160:163]
	v_mfma_f32_16x16x32_bf16 v[164:167], v[108:111], v[192:195], v[164:167]
	v_mfma_f32_16x16x32_bf16 v[168:171], v[116:119], v[192:195], v[168:171]
	v_mfma_f32_16x16x32_bf16 v[12:15], v[172:175], v[48:51], v[12:15]
	v_mfma_f32_16x16x32_bf16 v[208:211], v[176:179], v[56:59], v[12:15]
	v_mfma_f32_16x16x32_bf16 v[12:15], v[120:123], v[88:91], v[24:27]
	v_mfma_f32_16x16x32_bf16 v[24:27], v[124:127], v[96:99], v[12:15]
	v_mfma_f32_16x16x32_bf16 v[12:15], v[172:175], v[88:91], v[28:31]
	v_mfma_f32_16x16x32_bf16 v[212:215], v[176:179], v[96:99], v[12:15]
	v_mfma_f32_16x16x32_bf16 v[12:15], v[120:123], v[188:191], v[60:63]
	v_mfma_f32_16x16x32_bf16 v[224:227], v[124:127], v[192:195], v[12:15]
	v_mfma_f32_16x16x32_bf16 v[12:15], v[172:175], v[188:191], v[100:103]
	v_mfma_f32_16x16x32_bf16 v[8:11], v[120:123], v[48:51], v[8:11]
	v_mfma_f32_16x16x32_bf16 v[188:191], v[176:179], v[192:195], v[12:15]
	v_mfma_f32_16x16x32_bf16 v[12:15], v[120:123], v[196:199], v[16:19]
	v_mfma_f32_16x16x32_bf16 v[8:11], v[124:127], v[56:59], v[8:11]
	v_mfma_f32_16x16x32_bf16 v[192:195], v[124:127], v[200:203], v[12:15]
	v_mfma_f32_16x16x32_bf16 v[12:15], v[172:175], v[196:199], v[20:23]
	v_mfma_f32_16x16x32_bf16 v[172:175], v[176:179], v[200:203], v[12:15]
	s_barrier
; #define PG8_STAGE(bufoff, gbase, voff) do { _Pragma("unroll") for (int _i = 0; _i < 2; ++_i) \
;         __builtin_amdgcn_global_load_lds((const unsigned*)((const char*)(gbase) + (voff)[_i]), (PG8_LAS unsigned*)(lds + (bufoff) + ldsw + _i * 8192), 16, 0, 0); } while (0)
; #define PG8_LDA(dst, b, h) do { _Pragma("unroll") for (int m = 0; m < 4; ++m) _Pragma("unroll") for (int k = 0; k < 2; ++k) dst[m][k] = *(const PG8_LAS bf16x8*)(lds + PG8_SA(b, h) + aoff + m * 2048 + k * 1024); } while (0)
; #define PG8_LDB(dst, b, h) do { _Pragma("unroll") for (int n = 0; n < 2; ++n) _Pragma("unroll") for (int k = 0; k < 2; ++k) dst[n][k] = *(const PG8_LAS bf16x8*)(lds + PG8_SB(b, h) + boff + n * 2048 + k * 1024); } while (0)
; #define PG8_MMA(ai, bj, At, Bt) do { __builtin_amdgcn_s_setprio(1); _Pragma("unroll") for (int m = 0; m < 4; ++m) _Pragma("unroll") for (int n = 0; n < 2; ++n) _Pragma("unroll") for (int k = 0; k < 2; ++k) \
;         acc[ai][bj][m][n] = __builtin_amdgcn_mfma_f32_16x16x32_bf16(Bt[n][k], At[m][k], acc[ai][bj][m][n], 0, 0, 0); __builtin_amdgcn_s_setprio(0); } while (0)
; #define PG8_WAIT_V(n) asm volatile("s_waitcnt vmcnt(" #n ")" ::: "memory")
; #define PG8_WAIT_L(n) asm volatile("s_waitcnt lgkmcnt(" #n ")" ::: "memory")
; #define PG8_BAR __builtin_amdgcn_s_barrier()
; #define PG8_SCHED __builtin_amdgcn_sched_barrier(0)
; template <class Epi, class Sched, bool ALIGN_EPI = false, bool SP2 = false>
; __device__ __forceinline__ void gemm_phase(PG8_LAS unsigned char* lds, const Gemm g, const Sched& S, const Epi& E) {
;     ...
;             PG8_LDB(B0, 1, 0); PG8_LDB(B1, 1, 1); PG8_SCHED; PG8_LDA(At, 1, 0); PG8_STAGE(PG8_SA(0, 1), a2 + hstepA, voffA);
;             PG8_WAIT_V(8); PG8_WAIT_L(0); PG8_BAR; PG8_MMA(0, 0, At, B0); PG8_MMA(0, 1, At, B1); PG8_BAR; PG8_SCHED;
;             PG8_LDA(At, 1, 1); PG8_STAGE(PG8_SB(1, 0), b3, voffB); PG8_STAGE(PG8_SB(1, 1), b3 + hstepB, voffB); PG8_STAGE(PG8_SA(1, 0), a3, voffA);
;             PG8_WAIT_V(8); PG8_WAIT_L(0); PG8_BAR; PG8_MMA(1, 0, At, B0); PG8_MMA(1, 1, At, B1); PG8_BAR; PG8_SCHED;
	s_nop 4
	ds_read_b128 v[12:15], v228
	ds_read_b128 v[16:19], v228 offset:1024
	ds_read_b128 v[176:179], v228 offset:2048
	ds_read_b128 v[196:199], v228 offset:3072
	ds_read_b128 v[200:203], v236
	ds_read_b128 v[228:231], v236 offset:1024
	ds_read_b128 v[232:235], v236 offset:2048
	ds_read_b128 v[236:239], v236 offset:3072
	s_add_u32 s40, s46, 0x10000
	s_addc_u32 s41, s47, 0
	s_mov_b32 m0, s54
	v_lshl_add_u64 v[48:49], s[40:41], 0, v[128:129]
	ds_read_b128 v[20:23], v147 offset:32768
	ds_read_b128 v[28:31], v147 offset:33792
	ds_read_b128 v[60:63], v147 offset:34816
	ds_read_b128 v[100:103], v147 offset:35840
	ds_read_b128 v[240:243], v147 offset:36864
	ds_read_b128 v[244:247], v147 offset:37888
	ds_read_b128 v[248:251], v147 offset:38912
	ds_read_b128 v[204:207], v147 offset:39936
	global_load_lds_dwordx4 v[48:49], off
	v_lshl_add_u64 v[48:49], s[40:41], 0, v[132:133]
	s_mov_b32 m0, s55
	s_nop 0
	global_load_lds_dwordx4 v[48:49], off
	s_waitcnt vmcnt(8)
	s_waitcnt lgkmcnt(0)
	s_barrier
	s_waitcnt lgkmcnt(0)
	v_mfma_f32_16x16x32_bf16 v[48:51], v[12:15], v[20:23], v[64:67]
	v_mfma_f32_16x16x32_bf16 v[120:123], v[16:19], v[28:31], v[48:51]
	v_mfma_f32_16x16x32_bf16 v[48:51], v[176:179], v[20:23], v[68:71]
	v_mfma_f32_16x16x32_bf16 v[112:115], v[196:199], v[28:31], v[48:51]
	v_mfma_f32_16x16x32_bf16 v[48:51], v[12:15], v[60:63], v[72:75]
	v_mfma_f32_16x16x32_bf16 v[104:107], v[16:19], v[100:103], v[48:51]
	v_mfma_f32_16x16x32_bf16 v[48:51], v[176:179], v[60:63], v[76:79]
	v_mfma_f32_16x16x32_bf16 v[96:99], v[196:199], v[100:103], v[48:51]
	v_mfma_f32_16x16x32_bf16 v[48:51], v[12:15], v[240:243], v[80:83]
	v_mfma_f32_16x16x32_bf16 v[88:91], v[16:19], v[244:247], v[48:51]
	v_mfma_f32_16x16x32_bf16 v[48:51], v[176:179], v[240:243], v[84:87]
	v_mfma_f32_16x16x32_bf16 v[80:83], v[196:199], v[244:247], v[48:51]
	v_mfma_f32_16x16x32_bf16 v[48:51], v[12:15], v[248:251], v[216:219]
	v_mfma_f32_16x16x32_bf16 v[56:59], v[16:19], v[204:207], v[48:51]
	v_mfma_f32_16x16x32_bf16 v[48:51], v[176:179], v[248:251], v[92:95]
	v_mfma_f32_16x16x32_bf16 v[48:51], v[196:199], v[204:207], v[48:51]
	v_mfma_f32_16x16x32_bf16 v[64:67], v[200:203], v[20:23], v[220:223]
	v_mfma_f32_16x16x32_bf16 v[20:23], v[232:235], v[20:23], v[32:35]
	v_mfma_f32_16x16x32_bf16 v[116:119], v[236:239], v[28:31], v[20:23]
	v_mfma_f32_16x16x32_bf16 v[20:23], v[200:203], v[60:63], v[36:39]
	v_mfma_f32_16x16x32_bf16 v[108:111], v[228:231], v[100:103], v[20:23]
	v_mfma_f32_16x16x32_bf16 v[20:23], v[232:235], v[60:63], v[40:43]
	v_mfma_f32_16x16x32_bf16 v[100:103], v[236:239], v[100:103], v[20:23]
	v_mfma_f32_16x16x32_bf16 v[20:23], v[200:203], v[240:243], v[44:47]
	v_mfma_f32_16x16x32_bf16 v[92:95], v[228:231], v[244:247], v[20:23]
	v_mfma_f32_16x16x32_bf16 v[20:23], v[232:235], v[240:243], v[180:183]
	v_mfma_f32_16x16x32_bf16 v[84:87], v[236:239], v[244:247], v[20:23]
	v_mfma_f32_16x16x32_bf16 v[20:23], v[200:203], v[248:251], v[52:55]
	v_mfma_f32_16x16x32_bf16 v[60:63], v[228:231], v[204:207], v[20:23]
	v_mfma_f32_16x16x32_bf16 v[20:23], v[232:235], v[248:251], v[184:187]
	v_mfma_f32_16x16x32_bf16 v[124:127], v[228:231], v[28:31], v[64:67]
	v_mfma_f32_16x16x32_bf16 v[52:55], v[236:239], v[204:207], v[20:23]
	s_barrier
	s_mov_b32 m0, s79
	s_nop 2
	v_lshl_add_u64 v[20:21], v[140:141], 0, s[10:11]
	s_add_u32 s40, s44, 0x10080
	ds_read_b128 v[32:35], v147 offset:49152
	ds_read_b128 v[40:43], v147 offset:50176
	ds_read_b128 v[180:183], v147 offset:51200
	ds_read_b128 v[184:187], v147 offset:52224
	ds_read_b128 v[204:207], v147 offset:53248
	ds_read_b128 v[216:219], v147 offset:54272
	ds_read_b128 v[220:223], v147 offset:55296
	ds_read_b128 v[240:243], v147 offset:56320
	global_load_lds_dwordx4 v[20:21], off
	v_lshl_add_u64 v[20:21], v[252:253], 0, s[10:11]
	s_mov_b32 m0, s69
	s_addc_u32 s41, s45, 0
	global_load_lds_dwordx4 v[20:21], off
	v_lshl_add_u64 v[20:21], s[40:41], 0, v[130:131]
	s_mov_b32 m0, s42
	s_nop 0
	global_load_lds_dwordx4 v[20:21], off
	v_lshl_add_u64 v[20:21], s[40:41], 0, v[134:135]
	s_mov_b32 m0, s43
	s_nop 0
	global_load_lds_dwordx4 v[20:21], off
	v_lshl_add_u64 v[20:21], v[136:137], 0, s[10:11]
	s_mov_b32 m0, s56
	s_nop 0
	global_load_lds_dwordx4 v[20:21], off
	v_lshl_add_u64 v[20:21], v[138:139], 0, s[10:11]
	s_mov_b32 m0, s57
	s_nop 0
	global_load_lds_dwordx4 v[20:21], off
	s_waitcnt vmcnt(8)
	s_waitcnt lgkmcnt(0)
	s_barrier
	s_waitcnt lgkmcnt(0)
	v_mfma_f32_16x16x32_bf16 v[20:23], v[12:15], v[32:35], v[148:151]
	v_mfma_f32_16x16x32_bf16 v[76:79], v[16:19], v[40:43], v[20:23]
	v_mfma_f32_16x16x32_bf16 v[20:23], v[176:179], v[32:35], v[152:155]
	v_mfma_f32_16x16x32_bf16 v[68:71], v[196:199], v[40:43], v[20:23]
	v_mfma_f32_16x16x32_bf16 v[20:23], v[12:15], v[180:183], v[156:159]
	v_mfma_f32_16x16x32_bf16 v[44:47], v[16:19], v[184:187], v[20:23]
	v_mfma_f32_16x16x32_bf16 v[20:23], v[176:179], v[180:183], v[160:163]
	v_mfma_f32_16x16x32_bf16 v[36:39], v[196:199], v[184:187], v[20:23]
	v_mfma_f32_16x16x32_bf16 v[20:23], v[12:15], v[204:207], v[164:167]
	v_mfma_f32_16x16x32_bf16 v[0:3], v[12:15], v[220:223], v[0:3]
	v_mfma_f32_16x16x32_bf16 v[28:31], v[16:19], v[216:219], v[20:23]
	v_mfma_f32_16x16x32_bf16 v[20:23], v[176:179], v[204:207], v[168:171]
	v_mfma_f32_16x16x32_bf16 v[12:15], v[16:19], v[240:243], v[0:3]
	v_mfma_f32_16x16x32_bf16 v[0:3], v[176:179], v[220:223], v[4:7]
	v_mfma_f32_16x16x32_bf16 v[20:23], v[196:199], v[216:219], v[20:23]
	v_mfma_f32_16x16x32_bf16 v[4:7], v[196:199], v[240:243], v[0:3]
	v_mfma_f32_16x16x32_bf16 v[0:3], v[200:203], v[32:35], v[8:11]
	v_mfma_f32_16x16x32_bf16 v[72:75], v[228:231], v[40:43], v[0:3]
	v_mfma_f32_16x16x32_bf16 v[0:3], v[232:235], v[32:35], v[208:211]
	v_mfma_f32_16x16x32_bf16 v[64:67], v[236:239], v[40:43], v[0:3]
	v_mfma_f32_16x16x32_bf16 v[0:3], v[200:203], v[180:183], v[24:27]
	v_mfma_f32_16x16x32_bf16 v[40:43], v[228:231], v[184:187], v[0:3]
	v_mfma_f32_16x16x32_bf16 v[0:3], v[232:235], v[180:183], v[212:215]
	v_mfma_f32_16x16x32_bf16 v[32:35], v[236:239], v[184:187], v[0:3]
	v_mfma_f32_16x16x32_bf16 v[0:3], v[200:203], v[204:207], v[224:227]
	v_mfma_f32_16x16x32_bf16 v[24:27], v[228:231], v[216:219], v[0:3]
	v_mfma_f32_16x16x32_bf16 v[0:3], v[232:235], v[204:207], v[188:191]
	v_mfma_f32_16x16x32_bf16 v[16:19], v[236:239], v[216:219], v[0:3]
	v_mfma_f32_16x16x32_bf16 v[0:3], v[200:203], v[220:223], v[192:195]
	v_mfma_f32_16x16x32_bf16 v[8:11], v[228:231], v[240:243], v[0:3]
	v_mfma_f32_16x16x32_bf16 v[0:3], v[232:235], v[220:223], v[172:175]
	v_mfma_f32_16x16x32_bf16 v[0:3], v[236:239], v[240:243], v[0:3]
	s_barrier
	s_andn2_b64 vcc, exec, s[12:13]
	s_cbranch_vccnz .LBB0_441
	s_barrier

;     __host__ __device__ bool next(int i, Unit& u) const {
;         const long L = (long)i * G + c; if (L >= nwg) return false;
;         int wgid = (int)L; { const int q = nwg / NXCD, r = nwg % NXCD, xcd = wgid % NXCD, off = wgid / NXCD; wgid = (xcd < r ? xcd * (q + 1) : r * (q + 1) + (xcd - r) * q) + off; }
;         const int nig = WGM * nN, gid = wgid / nig, fm = gid * WGM, gsz = (nM - fm) < WGM ? (nM - fm) : WGM;
;         u.pm = fm + ((wgid % nig) % gsz); u.pn = (wgid % nig) / gsz; return true;
; template <class Epi, class Sched, bool ALIGN_EPI = false, bool SP2 = false>
; __device__ __forceinline__ void gemm_phase(PG8_LAS unsigned char* lds, const Gemm g, const Sched& S, const Epi& E) {
;     ...
;     Unit cur, nxt; int ui = 0;
;     if (!S.next(0, cur)) return;
.Lprio_ffn2_0:
	s_mov_b32 s31, s2
	s_mov_b32 s35, s74
	s_mov_b64 s[4:5], s[0:1]
	s_waitcnt lgkmcnt(0)
	s_barrier
	v_mov_b32_e32 v8, v254
	s_cmpk_lt_i32 s31, 0x200
	s_cselect_b64 s[6:7], -1, 0
	s_cmpk_gt_i32 s31, 0x1ff
	v_readfirstlane_b32 s3, v8
	s_cbranch_scc1 .LBB0_503
	s_ashr_i32 s8, s31, 31
	s_lshr_b32 s8, s8, 29
	s_add_i32 s12, s31, s8
	s_and_b32 s8, s12, -8
	s_sub_i32 s10, s31, s8
	s_cmp_gt_i32 s10, -1
	s_cbranch_scc0 .LBB0_500
	s_lshl_b32 s11, s10, 6
	s_ashr_i32 s8, s12, 3
	s_cbranch_execz .LBB0_501
	s_branch .LBB0_502

; #define PG8_STAGE(bufoff, gbase, voff) do { _Pragma("unroll") for (int _i = 0; _i < 2; ++_i) \
;         __builtin_amdgcn_global_load_lds((const unsigned*)((const char*)(gbase) + (voff)[_i]), (PG8_LAS unsigned*)(lds + (bufoff) + ldsw + _i * 8192), 16, 0, 0); } while (0)
; #define PG8_LDA(dst, b, h) do { _Pragma("unroll") for (int m = 0; m < 4; ++m) _Pragma("unroll") for (int k = 0; k < 2; ++k) dst[m][k] = *(const PG8_LAS bf16x8*)(lds + PG8_SA(b, h) + aoff + m * 2048 + k * 1024); } while (0)
; #define PG8_LDB(dst, b, h) do { _Pragma("unroll") for (int n = 0; n < 2; ++n) _Pragma("unroll") for (int k = 0; k < 2; ++k) dst[n][k] = *(const PG8_LAS bf16x8*)(lds + PG8_SB(b, h) + boff + n * 2048 + k * 1024); } while (0)
; #define PG8_MMA(ai, bj, At, Bt) do { __builtin_amdgcn_s_setprio(1); _Pragma("unroll") for (int m = 0; m < 4; ++m) _Pragma("unroll") for (int n = 0; n < 2; ++n) _Pragma("unroll") for (int k = 0; k < 2; ++k) \
;         acc[ai][bj][m][n] = __builtin_amdgcn_mfma_f32_16x16x32_bf16(Bt[n][k], At[m][k], acc[ai][bj][m][n], 0, 0, 0); __builtin_amdgcn_s_setprio(0); } while (0)
; #define PG8_WAIT_V(n) asm volatile("s_waitcnt vmcnt(" #n ")" ::: "memory")
; #define PG8_WAIT_L(n) asm volatile("s_waitcnt lgkmcnt(" #n ")" ::: "memory")
; #define PG8_BAR __builtin_amdgcn_s_barrier()
; #define PG8_SCHED __builtin_amdgcn_sched_barrier(0)
; template <class Epi, class Sched, bool ALIGN_EPI = false, bool SP2 = false>
; __device__ __forceinline__ void gemm_phase(PG8_LAS unsigned char* lds, const Gemm g, const Sched& S, const Epi& E) {
;     ...
;             const bool last = (t == nt - 2);
;             const char* a1 = cA + PG8_AK(t + 1);
;             const char* a2 = last ? nA : cA + PG8_AK(t + 2); const char* b2 = last ? nB : cB + (size_t)(t + 2) * kstep;
;             const char* a3 = last ? nA + PG8_AK(1) : cA + PG8_AK(t + 3); const char* b3 = b2 + kstep;
;             if (last && has_next) S.a_ready(nxt);
;             if constexpr (SP2) {
;             PG8_LDB(B0, 0, 0); PG8_LDB(B1, 0, 1); PG8_SCHED; PG8_LDA(At, 0, 0); PG8_STAGE(PG8_SA(1, 1), a1 + hstepA, voffA);
;             PG8_WAIT_V(8); PG8_WAIT_L(0); PG8_BAR; PG8_MMA(0, 0, At, B0); PG8_MMA(0, 1, At, B1); PG8_BAR; PG8_SCHED;
;             PG8_LDA(At, 0, 1); PG8_STAGE(PG8_SB(0, 0), b2, voffB); PG8_STAGE(PG8_SB(0, 1), b2 + hstepB, voffB); PG8_STAGE(PG8_SA(0, 0), a2, voffA);
.LBB0_520:
	ds_read_b128 v[124:127], v210
	ds_read_b128 v[128:131], v210 offset:1024
	ds_read_b128 v[132:135], v210 offset:2048
	ds_read_b128 v[144:147], v210 offset:3072
	ds_read_b128 v[148:151], v211
	ds_read_b128 v[170:173], v211 offset:1024
	ds_read_b128 v[174:177], v211 offset:2048
	ds_read_b128 v[178:181], v211 offset:3072
	s_add_u32 s42, s38, s40
	s_addc_u32 s43, s39, s41
	s_add_u32 s46, s42, 0x100
	s_addc_u32 s47, s43, 0
	s_add_u32 s44, s79, s40
	s_addc_u32 s45, s83, s41
	s_add_u32 s42, s42, 0x180
	s_addc_u32 s43, s43, 0
	s_cmpk_eq_i32 s40, 0x1500
	s_cselect_b32 s43, s78, s43
	s_cselect_b32 s42, s3, s42
	s_cselect_b32 s45, s37, s45
	s_cselect_b32 s44, s36, s44
	s_cselect_b32 s47, s9, s47
	s_cselect_b32 s46, s8, s46
	v_lshl_add_u64 v[206:207], v[122:123], 0, s[40:41]
	s_add_i32 m0, s53, 0xc000
	ds_read_b128 v[212:215], v191
	ds_read_b128 v[216:219], v191 offset:1024
	ds_read_b128 v[220:223], v191 offset:2048
	ds_read_b128 v[224:227], v191 offset:3072
	ds_read_b128 v[228:231], v191 offset:4096
	ds_read_b128 v[232:235], v191 offset:5120
	ds_read_b128 v[236:239], v191 offset:6144
	ds_read_b128 v[240:243], v191 offset:7168
	global_load_lds_dwordx4 v[206:207], off
	v_lshl_add_u64 v[206:207], v[120:121], 0, s[40:41]
	s_add_i32 m0, s53, 0xe000
	s_nop 0
	global_load_lds_dwordx4 v[206:207], off
	s_waitcnt vmcnt(8)
	s_waitcnt lgkmcnt(0)
	s_barrier
	s_waitcnt lgkmcnt(0)
	v_mfma_f32_16x16x32_bf16 v[140:143], v[124:127], v[212:215], v[140:143]
	v_mfma_f32_16x16x32_bf16 v[136:139], v[132:135], v[212:215], v[136:139]
	v_mfma_f32_16x16x32_bf16 v[116:119], v[124:127], v[220:223], v[116:119]
	v_mfma_f32_16x16x32_bf16 v[112:115], v[132:135], v[220:223], v[112:115]
	v_mfma_f32_16x16x32_bf16 v[108:111], v[124:127], v[228:231], v[108:111]
	v_mfma_f32_16x16x32_bf16 v[104:107], v[132:135], v[228:231], v[104:107]
	v_mfma_f32_16x16x32_bf16 v[100:103], v[124:127], v[236:239], v[100:103]
	v_mfma_f32_16x16x32_bf16 v[96:99], v[132:135], v[236:239], v[96:99]
	v_mfma_f32_16x16x32_bf16 v[140:143], v[128:131], v[216:219], v[140:143]
	v_mfma_f32_16x16x32_bf16 v[136:139], v[144:147], v[216:219], v[136:139]
	v_mfma_f32_16x16x32_bf16 v[116:119], v[128:131], v[224:227], v[116:119]
	v_mfma_f32_16x16x32_bf16 v[112:115], v[144:147], v[224:227], v[112:115]
	v_mfma_f32_16x16x32_bf16 v[108:111], v[128:131], v[232:235], v[108:111]
	v_mfma_f32_16x16x32_bf16 v[104:107], v[144:147], v[232:235], v[104:107]
	v_mfma_f32_16x16x32_bf16 v[100:103], v[128:131], v[240:243], v[100:103]
	v_mfma_f32_16x16x32_bf16 v[96:99], v[144:147], v[240:243], v[96:99]
	v_mfma_f32_16x16x32_bf16 v[60:63], v[148:151], v[212:215], v[60:63]
	v_mfma_f32_16x16x32_bf16 v[56:59], v[174:177], v[212:215], v[56:59]
	v_mfma_f32_16x16x32_bf16 v[52:55], v[148:151], v[220:223], v[52:55]
	v_mfma_f32_16x16x32_bf16 v[48:51], v[174:177], v[220:223], v[48:51]
	v_mfma_f32_16x16x32_bf16 v[44:47], v[148:151], v[228:231], v[44:47]
	v_mfma_f32_16x16x32_bf16 v[40:43], v[174:177], v[228:231], v[40:43]
	v_mfma_f32_16x16x32_bf16 v[36:39], v[148:151], v[236:239], v[36:39]
	v_mfma_f32_16x16x32_bf16 v[32:35], v[174:177], v[236:239], v[32:35]
	v_mfma_f32_16x16x32_bf16 v[60:63], v[170:173], v[216:219], v[60:63]
	v_mfma_f32_16x16x32_bf16 v[56:59], v[178:181], v[216:219], v[56:59]
	v_mfma_f32_16x16x32_bf16 v[52:55], v[170:173], v[224:227], v[52:55]
	v_mfma_f32_16x16x32_bf16 v[48:51], v[178:181], v[224:227], v[48:51]
	v_mfma_f32_16x16x32_bf16 v[44:47], v[170:173], v[232:235], v[44:47]
	v_mfma_f32_16x16x32_bf16 v[40:43], v[178:181], v[232:235], v[40:43]
	v_mfma_f32_16x16x32_bf16 v[36:39], v[170:173], v[240:243], v[36:39]
	v_mfma_f32_16x16x32_bf16 v[32:35], v[178:181], v[240:243], v[32:35]
	s_barrier
	s_add_i32 s70, s67, s52
	v_lshl_add_u64 v[206:207], s[44:45], 0, v[154:155]
	s_mov_b32 m0, s70
	ds_read_b128 v[212:215], v191 offset:16384
	ds_read_b128 v[216:219], v191 offset:17408
	ds_read_b128 v[220:223], v191 offset:18432
	ds_read_b128 v[224:227], v191 offset:19456
	ds_read_b128 v[228:231], v191 offset:20480
	ds_read_b128 v[232:235], v191 offset:21504
	ds_read_b128 v[236:239], v191 offset:22528
	ds_read_b128 v[240:243], v191 offset:23552
	global_load_lds_dwordx4 v[206:207], off
	s_add_i32 m0, s70, 0x2000
	s_add_u32 s70, s44, 0xb0000
	v_lshl_add_u64 v[244:245], s[44:45], 0, v[158:159]
	s_addc_u32 s71, s45, 0
	s_add_i32 s85, s68, s52
	global_load_lds_dwordx4 v[244:245], off
	v_lshl_add_u64 v[246:247], s[70:71], 0, v[154:155]
	s_mov_b32 m0, s85
	s_nop 0
	global_load_lds_dwordx4 v[246:247], off
	v_lshl_add_u64 v[246:247], s[70:71], 0, v[158:159]
	s_add_i32 m0, s85, 0x2000
	s_nop 0
	global_load_lds_dwordx4 v[246:247], off
	v_lshl_add_u64 v[246:247], s[46:47], 0, v[152:153]
	s_mov_b32 m0, s53
	s_nop 0
	global_load_lds_dwordx4 v[246:247], off
	v_lshl_add_u64 v[246:247], s[46:47], 0, v[156:157]
	s_mov_b32 m0, s54
	s_nop 0
	global_load_lds_dwordx4 v[246:247], off
	s_waitcnt vmcnt(8)
	s_waitcnt lgkmcnt(0)
	s_barrier
; #define PG8_STAGE(bufoff, gbase, voff) do { _Pragma("unroll") for (int _i = 0; _i < 2; ++_i) \
;         __builtin_amdgcn_global_load_lds((const unsigned*)((const char*)(gbase) + (voff)[_i]), (PG8_LAS unsigned*)(lds + (bufoff) + ldsw + _i * 8192), 16, 0, 0); } while (0)
; #define PG8_LDA(dst, b, h) do { _Pragma("unroll") for (int m = 0; m < 4; ++m) _Pragma("unroll") for (int k = 0; k < 2; ++k) dst[m][k] = *(const PG8_LAS bf16x8*)(lds + PG8_SA(b, h) + aoff + m * 2048 + k * 1024); } while (0)
; #define PG8_LDB(dst, b, h) do { _Pragma("unroll") for (int n = 0; n < 2; ++n) _Pragma("unroll") for (int k = 0; k < 2; ++k) dst[n][k] = *(const PG8_LAS bf16x8*)(lds + PG8_SB(b, h) + boff + n * 2048 + k * 1024); } while (0)
; #define PG8_MMA(ai, bj, At, Bt) do { __builtin_amdgcn_s_setprio(1); _Pragma("unroll") for (int m = 0; m < 4; ++m) _Pragma("unroll") for (int n = 0; n < 2; ++n) _Pragma("unroll") for (int k = 0; k < 2; ++k) \
;         acc[ai][bj][m][n] = __builtin_amdgcn_mfma_f32_16x16x32_bf16(Bt[n][k], At[m][k], acc[ai][bj][m][n], 0, 0, 0); __builtin_amdgcn_s_setprio(0); } while (0)
; #define PG8_WAIT_V(n) asm volatile("s_waitcnt vmcnt(" #n ")" ::: "memory")
; #define PG8_WAIT_L(n) asm volatile("s_waitcnt lgkmcnt(" #n ")" ::: "memory")
; #define PG8_BAR __builtin_amdgcn_s_barrier()
; #define PG8_SCHED __builtin_amdgcn_sched_barrier(0)
; template <class Epi, class Sched, bool ALIGN_EPI = false, bool SP2 = false>
; __device__ __forceinline__ void gemm_phase(PG8_LAS unsigned char* lds, const Gemm g, const Sched& S, const Epi& E) {
;     ...
;             PG8_WAIT_V(8); PG8_WAIT_L(0); PG8_BAR; PG8_MMA(1, 0, At, B0); PG8_MMA(1, 1, At, B1); PG8_BAR; PG8_SCHED;
;             PG8_LDB(B0, 1, 0); PG8_LDB(B1, 1, 1); PG8_SCHED; PG8_LDA(At, 1, 0); PG8_STAGE(PG8_SA(0, 1), a2 + hstepA, voffA);
;             PG8_WAIT_V(8); PG8_WAIT_L(0); PG8_BAR; PG8_MMA(0, 0, At, B0); PG8_MMA(0, 1, At, B1); PG8_BAR; PG8_SCHED;
	s_waitcnt lgkmcnt(0)
	v_mfma_f32_16x16x32_bf16 v[92:95], v[124:127], v[212:215], v[92:95]
	v_mfma_f32_16x16x32_bf16 v[88:91], v[132:135], v[212:215], v[88:91]
	v_mfma_f32_16x16x32_bf16 v[84:87], v[124:127], v[220:223], v[84:87]
	v_mfma_f32_16x16x32_bf16 v[80:83], v[132:135], v[220:223], v[80:83]
	v_mfma_f32_16x16x32_bf16 v[76:79], v[124:127], v[228:231], v[76:79]
	v_mfma_f32_16x16x32_bf16 v[72:75], v[132:135], v[228:231], v[72:75]
	v_mfma_f32_16x16x32_bf16 v[68:71], v[124:127], v[236:239], v[68:71]
	v_mfma_f32_16x16x32_bf16 v[64:67], v[132:135], v[236:239], v[64:67]
	v_mfma_f32_16x16x32_bf16 v[92:95], v[128:131], v[216:219], v[92:95]
	v_mfma_f32_16x16x32_bf16 v[88:91], v[144:147], v[216:219], v[88:91]
	v_mfma_f32_16x16x32_bf16 v[84:87], v[128:131], v[224:227], v[84:87]
	v_mfma_f32_16x16x32_bf16 v[80:83], v[144:147], v[224:227], v[80:83]
	v_mfma_f32_16x16x32_bf16 v[76:79], v[128:131], v[232:235], v[76:79]
	v_mfma_f32_16x16x32_bf16 v[72:75], v[144:147], v[232:235], v[72:75]
	v_mfma_f32_16x16x32_bf16 v[68:71], v[128:131], v[240:243], v[68:71]
	v_mfma_f32_16x16x32_bf16 v[64:67], v[144:147], v[240:243], v[64:67]
	v_mfma_f32_16x16x32_bf16 v[28:31], v[148:151], v[212:215], v[28:31]
	v_mfma_f32_16x16x32_bf16 v[24:27], v[174:177], v[212:215], v[24:27]
	v_mfma_f32_16x16x32_bf16 v[20:23], v[148:151], v[220:223], v[20:23]
	v_mfma_f32_16x16x32_bf16 v[16:19], v[174:177], v[220:223], v[16:19]
	v_mfma_f32_16x16x32_bf16 v[12:15], v[148:151], v[228:231], v[12:15]
	v_mfma_f32_16x16x32_bf16 v[8:11], v[174:177], v[228:231], v[8:11]
	v_mfma_f32_16x16x32_bf16 v[4:7], v[148:151], v[236:239], v[4:7]
	v_mfma_f32_16x16x32_bf16 v[0:3], v[174:177], v[236:239], v[0:3]
	v_mfma_f32_16x16x32_bf16 v[28:31], v[170:173], v[216:219], v[28:31]
	v_mfma_f32_16x16x32_bf16 v[24:27], v[178:181], v[216:219], v[24:27]
	v_mfma_f32_16x16x32_bf16 v[20:23], v[170:173], v[224:227], v[20:23]
	v_mfma_f32_16x16x32_bf16 v[16:19], v[178:181], v[224:227], v[16:19]
	v_mfma_f32_16x16x32_bf16 v[12:15], v[170:173], v[232:235], v[12:15]
	v_mfma_f32_16x16x32_bf16 v[8:11], v[178:181], v[232:235], v[8:11]
	v_mfma_f32_16x16x32_bf16 v[4:7], v[170:173], v[240:243], v[4:7]
	v_mfma_f32_16x16x32_bf16 v[0:3], v[178:181], v[240:243], v[0:3]
	s_barrier
	s_add_i32 s70, 0, 0x18000
	s_add_i32 s71, 0, 0x1c000
	v_add_u32_e32 v144, s70, v185
	v_add_u32_e32 v161, s71, v185
	ds_read_b128 v[124:127], v144
	ds_read_b128 v[128:131], v144 offset:1024
	ds_read_b128 v[132:135], v144 offset:2048
	ds_read_b128 v[144:147], v144 offset:3072
	ds_read_b128 v[148:151], v161
	ds_read_b128 v[170:173], v161 offset:1024
	ds_read_b128 v[174:177], v161 offset:2048
	ds_read_b128 v[178:181], v161 offset:3072
	s_add_u32 s46, s46, 0xb0000
	s_addc_u32 s47, s47, 0
	s_mov_b32 m0, s55
	v_lshl_add_u64 v[246:247], s[46:47], 0, v[152:153]
	ds_read_b128 v[212:215], v191 offset:32768
	ds_read_b128 v[216:219], v191 offset:33792
	ds_read_b128 v[220:223], v191 offset:34816
	ds_read_b128 v[224:227], v191 offset:35840
	ds_read_b128 v[228:231], v191 offset:36864
	ds_read_b128 v[232:235], v191 offset:37888
	ds_read_b128 v[236:239], v191 offset:38912
	ds_read_b128 v[240:243], v191 offset:39936
	global_load_lds_dwordx4 v[246:247], off
	v_lshl_add_u64 v[246:247], s[46:47], 0, v[156:157]
	s_mov_b32 m0, s56
	s_nop 0
	global_load_lds_dwordx4 v[246:247], off
	s_waitcnt vmcnt(8)
	s_waitcnt lgkmcnt(0)
	s_barrier
	s_waitcnt lgkmcnt(0)
	v_mfma_f32_16x16x32_bf16 v[140:143], v[124:127], v[212:215], v[140:143]
	v_mfma_f32_16x16x32_bf16 v[136:139], v[132:135], v[212:215], v[136:139]
	v_mfma_f32_16x16x32_bf16 v[116:119], v[124:127], v[220:223], v[116:119]
	v_mfma_f32_16x16x32_bf16 v[112:115], v[132:135], v[220:223], v[112:115]
	v_mfma_f32_16x16x32_bf16 v[108:111], v[124:127], v[228:231], v[108:111]
	v_mfma_f32_16x16x32_bf16 v[104:107], v[132:135], v[228:231], v[104:107]
	v_mfma_f32_16x16x32_bf16 v[100:103], v[124:127], v[236:239], v[100:103]
	v_mfma_f32_16x16x32_bf16 v[96:99], v[132:135], v[236:239], v[96:99]
	v_mfma_f32_16x16x32_bf16 v[140:143], v[128:131], v[216:219], v[140:143]
	v_mfma_f32_16x16x32_bf16 v[136:139], v[144:147], v[216:219], v[136:139]
	v_mfma_f32_16x16x32_bf16 v[116:119], v[128:131], v[224:227], v[116:119]
	v_mfma_f32_16x16x32_bf16 v[112:115], v[144:147], v[224:227], v[112:115]
	v_mfma_f32_16x16x32_bf16 v[108:111], v[128:131], v[232:235], v[108:111]
	v_mfma_f32_16x16x32_bf16 v[104:107], v[144:147], v[232:235], v[104:107]
	v_mfma_f32_16x16x32_bf16 v[100:103], v[128:131], v[240:243], v[100:103]
	v_mfma_f32_16x16x32_bf16 v[96:99], v[144:147], v[240:243], v[96:99]
	v_mfma_f32_16x16x32_bf16 v[60:63], v[148:151], v[212:215], v[60:63]
	v_mfma_f32_16x16x32_bf16 v[56:59], v[174:177], v[212:215], v[56:59]
	v_mfma_f32_16x16x32_bf16 v[52:55], v[148:151], v[220:223], v[52:55]
	v_mfma_f32_16x16x32_bf16 v[48:51], v[174:177], v[220:223], v[48:51]
	v_mfma_f32_16x16x32_bf16 v[44:47], v[148:151], v[228:231], v[44:47]
	v_mfma_f32_16x16x32_bf16 v[40:43], v[174:177], v[228:231], v[40:43]
	v_mfma_f32_16x16x32_bf16 v[36:39], v[148:151], v[236:239], v[36:39]
	v_mfma_f32_16x16x32_bf16 v[32:35], v[174:177], v[236:239], v[32:35]
	v_mfma_f32_16x16x32_bf16 v[60:63], v[170:173], v[216:219], v[60:63]
	v_mfma_f32_16x16x32_bf16 v[56:59], v[178:181], v[216:219], v[56:59]
	v_mfma_f32_16x16x32_bf16 v[52:55], v[170:173], v[224:227], v[52:55]
	v_mfma_f32_16x16x32_bf16 v[48:51], v[178:181], v[224:227], v[48:51]
	v_mfma_f32_16x16x32_bf16 v[44:47], v[170:173], v[232:235], v[44:47]
	v_mfma_f32_16x16x32_bf16 v[40:43], v[178:181], v[232:235], v[40:43]
	v_mfma_f32_16x16x32_bf16 v[36:39], v[170:173], v[240:243], v[36:39]
	v_mfma_f32_16x16x32_bf16 v[32:35], v[178:181], v[240:243], v[32:35]
	s_barrier
; #define PG8_STAGE(bufoff, gbase, voff) do { _Pragma("unroll") for (int _i = 0; _i < 2; ++_i) \
;         __builtin_amdgcn_global_load_lds((const unsigned*)((const char*)(gbase) + (voff)[_i]), (PG8_LAS unsigned*)(lds + (bufoff) + ldsw + _i * 8192), 16, 0, 0); } while (0)
; #define PG8_LDA(dst, b, h) do { _Pragma("unroll") for (int m = 0; m < 4; ++m) _Pragma("unroll") for (int k = 0; k < 2; ++k) dst[m][k] = *(const PG8_LAS bf16x8*)(lds + PG8_SA(b, h) + aoff + m * 2048 + k * 1024); } while (0)
; #define PG8_MMA(ai, bj, At, Bt) do { __builtin_amdgcn_s_setprio(1); _Pragma("unroll") for (int m = 0; m < 4; ++m) _Pragma("unroll") for (int n = 0; n < 2; ++n) _Pragma("unroll") for (int k = 0; k < 2; ++k) \
;         acc[ai][bj][m][n] = __builtin_amdgcn_mfma_f32_16x16x32_bf16(Bt[n][k], At[m][k], acc[ai][bj][m][n], 0, 0, 0); __builtin_amdgcn_s_setprio(0); } while (0)
; #define PG8_WAIT_V(n) asm volatile("s_waitcnt vmcnt(" #n ")" ::: "memory")
; #define PG8_WAIT_L(n) asm volatile("s_waitcnt lgkmcnt(" #n ")" ::: "memory")
; #define PG8_BAR __builtin_amdgcn_s_barrier()
; #define PG8_SCHED __builtin_amdgcn_sched_barrier(0)
; template <class Epi, class Sched, bool ALIGN_EPI = false, bool SP2 = false>
; __device__ __forceinline__ void gemm_phase(PG8_LAS unsigned char* lds, const Gemm g, const Sched& S, const Epi& E) {
;     ...
;             PG8_LDA(At, 1, 1); PG8_STAGE(PG8_SB(1, 0), b3, voffB); PG8_STAGE(PG8_SB(1, 1), b3 + hstepB, voffB); PG8_STAGE(PG8_SA(1, 0), a3, voffA);
;             PG8_WAIT_V(8); PG8_WAIT_L(0); PG8_BAR; PG8_MMA(1, 0, At, B0); PG8_MMA(1, 1, At, B1); PG8_BAR; PG8_SCHED;
;     ...
;         if constexpr (ALIGN_EPI) { if (wr == 0) PG8_BAR; }
	s_add_i32 s46, s70, s52
	v_lshl_add_u64 v[206:207], v[206:207], 0, s[26:27]
	s_mov_b32 m0, s46
	ds_read_b128 v[212:215], v191 offset:49152
	ds_read_b128 v[216:219], v191 offset:50176
	ds_read_b128 v[220:223], v191 offset:51200
	ds_read_b128 v[224:227], v191 offset:52224
	ds_read_b128 v[228:231], v191 offset:53248
	ds_read_b128 v[232:235], v191 offset:54272
	ds_read_b128 v[236:239], v191 offset:55296
	ds_read_b128 v[240:243], v191 offset:56320
	global_load_lds_dwordx4 v[206:207], off
	s_add_i32 m0, s46, 0x2000
	s_add_u32 s44, s44, 0xb0080
	v_lshl_add_u64 v[206:207], v[244:245], 0, s[26:27]
	s_addc_u32 s45, s45, 0
	s_add_i32 s46, s71, s52
	global_load_lds_dwordx4 v[206:207], off
	v_lshl_add_u64 v[206:207], s[44:45], 0, v[154:155]
	s_mov_b32 m0, s46
	s_nop 0
	global_load_lds_dwordx4 v[206:207], off
	v_lshl_add_u64 v[206:207], s[44:45], 0, v[158:159]
	s_add_i32 m0, s46, 0x2000
	s_nop 0
	global_load_lds_dwordx4 v[206:207], off
	v_lshl_add_u64 v[206:207], s[42:43], 0, v[152:153]
	s_mov_b32 m0, s63
	s_nop 0
	global_load_lds_dwordx4 v[206:207], off
	v_lshl_add_u64 v[206:207], s[42:43], 0, v[156:157]
	s_mov_b32 m0, s64
	s_nop 0
	global_load_lds_dwordx4 v[206:207], off
	s_waitcnt vmcnt(8)
	s_waitcnt lgkmcnt(0)
	s_barrier
	s_waitcnt lgkmcnt(0)
	v_mfma_f32_16x16x32_bf16 v[92:95], v[124:127], v[212:215], v[92:95]
	v_mfma_f32_16x16x32_bf16 v[88:91], v[132:135], v[212:215], v[88:91]
	v_mfma_f32_16x16x32_bf16 v[84:87], v[124:127], v[220:223], v[84:87]
	v_mfma_f32_16x16x32_bf16 v[80:83], v[132:135], v[220:223], v[80:83]
	v_mfma_f32_16x16x32_bf16 v[76:79], v[124:127], v[228:231], v[76:79]
	v_mfma_f32_16x16x32_bf16 v[72:75], v[132:135], v[228:231], v[72:75]
	v_mfma_f32_16x16x32_bf16 v[68:71], v[124:127], v[236:239], v[68:71]
	v_mfma_f32_16x16x32_bf16 v[64:67], v[132:135], v[236:239], v[64:67]
	v_mfma_f32_16x16x32_bf16 v[92:95], v[128:131], v[216:219], v[92:95]
	v_mfma_f32_16x16x32_bf16 v[88:91], v[144:147], v[216:219], v[88:91]
	v_mfma_f32_16x16x32_bf16 v[84:87], v[128:131], v[224:227], v[84:87]
	v_mfma_f32_16x16x32_bf16 v[80:83], v[144:147], v[224:227], v[80:83]
	v_mfma_f32_16x16x32_bf16 v[76:79], v[128:131], v[232:235], v[76:79]
	v_mfma_f32_16x16x32_bf16 v[72:75], v[144:147], v[232:235], v[72:75]
	v_mfma_f32_16x16x32_bf16 v[68:71], v[128:131], v[240:243], v[68:71]
	v_mfma_f32_16x16x32_bf16 v[64:67], v[144:147], v[240:243], v[64:67]
	v_mfma_f32_16x16x32_bf16 v[28:31], v[148:151], v[212:215], v[28:31]
	v_mfma_f32_16x16x32_bf16 v[24:27], v[174:177], v[212:215], v[24:27]
	v_mfma_f32_16x16x32_bf16 v[20:23], v[148:151], v[220:223], v[20:23]
	v_mfma_f32_16x16x32_bf16 v[16:19], v[174:177], v[220:223], v[16:19]
	v_mfma_f32_16x16x32_bf16 v[12:15], v[148:151], v[228:231], v[12:15]
	v_mfma_f32_16x16x32_bf16 v[8:11], v[174:177], v[228:231], v[8:11]
	v_mfma_f32_16x16x32_bf16 v[4:7], v[148:151], v[236:239], v[4:7]
	v_mfma_f32_16x16x32_bf16 v[0:3], v[174:177], v[236:239], v[0:3]
	v_mfma_f32_16x16x32_bf16 v[28:31], v[170:173], v[216:219], v[28:31]
	v_mfma_f32_16x16x32_bf16 v[24:27], v[178:181], v[216:219], v[24:27]
	v_mfma_f32_16x16x32_bf16 v[20:23], v[170:173], v[224:227], v[20:23]
	v_mfma_f32_16x16x32_bf16 v[16:19], v[178:181], v[224:227], v[16:19]
	v_mfma_f32_16x16x32_bf16 v[12:15], v[170:173], v[232:235], v[12:15]
	v_mfma_f32_16x16x32_bf16 v[8:11], v[178:181], v[232:235], v[8:11]
	v_mfma_f32_16x16x32_bf16 v[4:7], v[170:173], v[240:243], v[4:7]
	v_mfma_f32_16x16x32_bf16 v[0:3], v[178:181], v[240:243], v[0:3]
	s_barrier
	s_add_i32 s84, s84, 2
	s_add_u32 s40, s40, 0x100
	s_addc_u32 s41, s41, 0
	s_cmp_gt_u32 s84, 41
	s_cbranch_scc0 .LBB0_520
	s_and_b64 vcc, exec, s[28:29]
	s_cbranch_vccz .LBB0_523
	s_barrier

;     __host__ __device__ bool next(int i, Unit& u) const {
;         const long L = (long)i * G + c; if (L >= nwg) return false;
;         int wgid = (int)L; { const int q = nwg / NXCD, r = nwg % NXCD, xcd = wgid % NXCD, off = wgid / NXCD; wgid = (xcd < r ? xcd * (q + 1) : r * (q + 1) + (xcd - r) * q) + off; }
;         const int nig = WGM * nN, gid = wgid / nig, fm = gid * WGM, gsz = (nM - fm) < WGM ? (nM - fm) : WGM;
;         u.pm = fm + ((wgid % nig) % gsz); u.pn = (wgid % nig) / gsz; return true;
; template <class Epi, class Sched, bool ALIGN_EPI = false, bool SP2 = false>
; __device__ __forceinline__ void gemm_phase(PG8_LAS unsigned char* lds, const Gemm g, const Sched& S, const Epi& E) {
;     ...
;     Unit cur, nxt; int ui = 0;
;     if (!S.next(0, cur)) return;
.Lprio_gate0:
	s_mov_b32 s27, s74
	s_mov_b64 s[4:5], s[0:1]
	s_mov_b32 s50, s2
	v_mov_b32_e32 v9, v254
	s_waitcnt lgkmcnt(0)
	s_barrier
	s_cmpk_gt_i32 s50, 0x1ff
	v_readfirstlane_b32 s3, v9
	s_cbranch_scc1 .LBB0_619
	s_ashr_i32 s51, s50, 31
	s_lshr_b32 s6, s51, 29
	s_add_i32 s14, s50, s6
	s_and_b32 s6, s14, -8
	s_sub_i32 s13, s50, s6
	s_cmp_gt_i32 s13, -1
	s_cbranch_scc0 .LBB0_598
	s_lshl_b32 s12, s13, 6
	s_load_dwordx4 s[8:11], s[4:5], 0x88
	s_ashr_i32 s6, s14, 3
	s_cbranch_execz .LBB0_599
	s_branch .LBB0_600

; #define PG8_STAGE(bufoff, gbase, voff) do { _Pragma("unroll") for (int _i = 0; _i < 2; ++_i) \
;         __builtin_amdgcn_global_load_lds((const unsigned*)((const char*)(gbase) + (voff)[_i]), (PG8_LAS unsigned*)(lds + (bufoff) + ldsw + _i * 8192), 16, 0, 0); } while (0)
; #define PG8_LDA(dst, b, h) do { _Pragma("unroll") for (int m = 0; m < 4; ++m) _Pragma("unroll") for (int k = 0; k < 2; ++k) dst[m][k] = *(const PG8_LAS bf16x8*)(lds + PG8_SA(b, h) + aoff + m * 2048 + k * 1024); } while (0)
; #define PG8_LDB(dst, b, h) do { _Pragma("unroll") for (int n = 0; n < 2; ++n) _Pragma("unroll") for (int k = 0; k < 2; ++k) dst[n][k] = *(const PG8_LAS bf16x8*)(lds + PG8_SB(b, h) + boff + n * 2048 + k * 1024); } while (0)
; #define PG8_MMA(ai, bj, At, Bt) do { __builtin_amdgcn_s_setprio(1); _Pragma("unroll") for (int m = 0; m < 4; ++m) _Pragma("unroll") for (int n = 0; n < 2; ++n) _Pragma("unroll") for (int k = 0; k < 2; ++k) \
;         acc[ai][bj][m][n] = __builtin_amdgcn_mfma_f32_16x16x32_bf16(Bt[n][k], At[m][k], acc[ai][bj][m][n], 0, 0, 0); __builtin_amdgcn_s_setprio(0); } while (0)
; #define PG8_WAIT_V(n) asm volatile("s_waitcnt vmcnt(" #n ")" ::: "memory")
; #define PG8_WAIT_L(n) asm volatile("s_waitcnt lgkmcnt(" #n ")" ::: "memory")
; #define PG8_BAR __builtin_amdgcn_s_barrier()
; #define PG8_SCHED __builtin_amdgcn_sched_barrier(0)
; template <class Epi, class Sched, bool ALIGN_EPI = false, bool SP2 = false>
; __device__ __forceinline__ void gemm_phase(PG8_LAS unsigned char* lds, const Gemm g, const Sched& S, const Epi& E) {
;     ...
;             const bool last = (t == nt - 2);
;             const char* a1 = cA + PG8_AK(t + 1);
;             const char* a2 = last ? nA : cA + PG8_AK(t + 2); const char* b2 = last ? nB : cB + (size_t)(t + 2) * kstep;
;             const char* a3 = last ? nA + PG8_AK(1) : cA + PG8_AK(t + 3); const char* b3 = b2 + kstep;
;             if (last && has_next) S.a_ready(nxt);
;             if constexpr (SP2) {
;             PG8_LDB(B0, 0, 0); PG8_LDB(B1, 0, 1); PG8_SCHED; PG8_LDA(At, 0, 0); PG8_STAGE(PG8_SA(1, 1), a1 + hstepA, voffA);
;             PG8_WAIT_V(8); PG8_WAIT_L(0); PG8_BAR; PG8_MMA(0, 0, At, B0); PG8_MMA(0, 1, At, B1); PG8_BAR; PG8_SCHED;
;             PG8_LDA(At, 0, 1); PG8_STAGE(PG8_SB(0, 0), b2, voffB); PG8_STAGE(PG8_SB(0, 1), b2 + hstepB, voffB); PG8_STAGE(PG8_SA(0, 0), a2, voffA);
.LBB0_612:
	ds_read_b128 v[100:103], v226
	ds_read_b128 v[104:107], v226 offset:1024
	ds_read_b128 v[108:111], v226 offset:2048
	ds_read_b128 v[120:123], v226 offset:3072
	ds_read_b128 v[124:127], v227
	ds_read_b128 v[128:131], v227 offset:1024
	ds_read_b128 v[132:135], v227 offset:2048
	ds_read_b128 v[160:163], v227 offset:3072
	s_add_u32 s44, s40, s42
	s_addc_u32 s45, s41, s43
	s_add_u32 s48, s44, 0x100
	s_addc_u32 s49, s45, 0
	s_add_u32 s46, s83, s42
	s_addc_u32 s47, s84, s43
	s_add_u32 s44, s44, 0x180
	s_addc_u32 s45, s45, 0
	s_cmpk_eq_i32 s42, 0x700
	s_cselect_b32 s45, s82, s45
	s_cselect_b32 s44, s79, s44
	s_cselect_b32 s47, s29, s47
	s_cselect_b32 s46, s78, s46
	s_cselect_b32 s49, s3, s49
	s_cselect_b32 s48, s31, s48
	v_lshl_add_u64 v[236:237], v[98:99], 0, s[42:43]
	s_add_i32 m0, s57, 0xc000
	ds_read_b128 v[164:167], v209
	ds_read_b128 v[168:171], v209 offset:1024
	ds_read_b128 v[192:195], v209 offset:2048
	ds_read_b128 v[196:199], v209 offset:3072
	ds_read_b128 v[200:203], v209 offset:4096
	ds_read_b128 v[204:207], v209 offset:5120
	ds_read_b128 v[228:231], v209 offset:6144
	ds_read_b128 v[232:235], v209 offset:7168
	global_load_lds_dwordx4 v[236:237], off
	v_lshl_add_u64 v[236:237], v[96:97], 0, s[42:43]
	s_add_i32 m0, s57, 0xe000
	s_nop 0
	global_load_lds_dwordx4 v[236:237], off
	s_waitcnt vmcnt(8)
	s_waitcnt lgkmcnt(0)
	s_barrier
	s_waitcnt lgkmcnt(0)
	v_mfma_f32_16x16x32_bf16 v[156:159], v[100:103], v[164:167], v[156:159]
	v_mfma_f32_16x16x32_bf16 v[152:155], v[108:111], v[164:167], v[152:155]
	v_mfma_f32_16x16x32_bf16 v[148:151], v[100:103], v[192:195], v[148:151]
	v_mfma_f32_16x16x32_bf16 v[144:147], v[108:111], v[192:195], v[144:147]
	v_mfma_f32_16x16x32_bf16 v[140:143], v[100:103], v[200:203], v[140:143]
	v_mfma_f32_16x16x32_bf16 v[136:139], v[108:111], v[200:203], v[136:139]
	v_mfma_f32_16x16x32_bf16 v[116:119], v[100:103], v[228:231], v[116:119]
	v_mfma_f32_16x16x32_bf16 v[112:115], v[108:111], v[228:231], v[112:115]
	v_mfma_f32_16x16x32_bf16 v[156:159], v[104:107], v[168:171], v[156:159]
	v_mfma_f32_16x16x32_bf16 v[152:155], v[120:123], v[168:171], v[152:155]
	v_mfma_f32_16x16x32_bf16 v[148:151], v[104:107], v[196:199], v[148:151]
	v_mfma_f32_16x16x32_bf16 v[144:147], v[120:123], v[196:199], v[144:147]
	v_mfma_f32_16x16x32_bf16 v[140:143], v[104:107], v[204:207], v[140:143]
	v_mfma_f32_16x16x32_bf16 v[136:139], v[120:123], v[204:207], v[136:139]
	v_mfma_f32_16x16x32_bf16 v[116:119], v[104:107], v[232:235], v[116:119]
	v_mfma_f32_16x16x32_bf16 v[112:115], v[120:123], v[232:235], v[112:115]
	v_mfma_f32_16x16x32_bf16 v[60:63], v[124:127], v[164:167], v[60:63]
	v_mfma_f32_16x16x32_bf16 v[56:59], v[132:135], v[164:167], v[56:59]
	v_mfma_f32_16x16x32_bf16 v[52:55], v[124:127], v[192:195], v[52:55]
	v_mfma_f32_16x16x32_bf16 v[48:51], v[132:135], v[192:195], v[48:51]
	v_mfma_f32_16x16x32_bf16 v[44:47], v[124:127], v[200:203], v[44:47]
	v_mfma_f32_16x16x32_bf16 v[40:43], v[132:135], v[200:203], v[40:43]
	v_mfma_f32_16x16x32_bf16 v[36:39], v[124:127], v[228:231], v[36:39]
	v_mfma_f32_16x16x32_bf16 v[32:35], v[132:135], v[228:231], v[32:35]
	v_mfma_f32_16x16x32_bf16 v[60:63], v[128:131], v[168:171], v[60:63]
	v_mfma_f32_16x16x32_bf16 v[56:59], v[160:163], v[168:171], v[56:59]
	v_mfma_f32_16x16x32_bf16 v[52:55], v[128:131], v[196:199], v[52:55]
	v_mfma_f32_16x16x32_bf16 v[48:51], v[160:163], v[196:199], v[48:51]
	v_mfma_f32_16x16x32_bf16 v[44:47], v[128:131], v[204:207], v[44:47]
	v_mfma_f32_16x16x32_bf16 v[40:43], v[160:163], v[204:207], v[40:43]
	v_mfma_f32_16x16x32_bf16 v[36:39], v[128:131], v[232:235], v[36:39]
	v_mfma_f32_16x16x32_bf16 v[32:35], v[160:163], v[232:235], v[32:35]
	s_barrier
	s_add_i32 s70, s69, s56
	v_lshl_add_u64 v[236:237], s[46:47], 0, v[174:175]
	s_mov_b32 m0, s70
	ds_read_b128 v[164:167], v209 offset:16384
	ds_read_b128 v[168:171], v209 offset:17408
	ds_read_b128 v[192:195], v209 offset:18432
	ds_read_b128 v[196:199], v209 offset:19456
	ds_read_b128 v[200:203], v209 offset:20480
	ds_read_b128 v[204:207], v209 offset:21504
	ds_read_b128 v[228:231], v209 offset:22528
	ds_read_b128 v[232:235], v209 offset:23552
	global_load_lds_dwordx4 v[236:237], off
	s_add_i32 m0, s70, 0x2000
	s_add_u32 s70, s46, 0x40000
	v_lshl_add_u64 v[238:239], s[46:47], 0, v[178:179]
	s_addc_u32 s71, s47, 0
	s_add_i32 s86, s80, s56
	global_load_lds_dwordx4 v[238:239], off
	v_lshl_add_u64 v[240:241], s[70:71], 0, v[174:175]
	s_mov_b32 m0, s86
	s_nop 0
	global_load_lds_dwordx4 v[240:241], off
	v_lshl_add_u64 v[240:241], s[70:71], 0, v[178:179]
	s_add_i32 m0, s86, 0x2000
	s_nop 0
	global_load_lds_dwordx4 v[240:241], off
	v_lshl_add_u64 v[240:241], s[48:49], 0, v[172:173]
	s_mov_b32 m0, s57
	s_nop 0
	global_load_lds_dwordx4 v[240:241], off
	v_lshl_add_u64 v[240:241], s[48:49], 0, v[176:177]
	s_mov_b32 m0, s58
	s_nop 0
	global_load_lds_dwordx4 v[240:241], off
	s_waitcnt vmcnt(8)
	s_waitcnt lgkmcnt(0)
	s_barrier
; #define PG8_STAGE(bufoff, gbase, voff) do { _Pragma("unroll") for (int _i = 0; _i < 2; ++_i) \
;         __builtin_amdgcn_global_load_lds((const unsigned*)((const char*)(gbase) + (voff)[_i]), (PG8_LAS unsigned*)(lds + (bufoff) + ldsw + _i * 8192), 16, 0, 0); } while (0)
; #define PG8_LDA(dst, b, h) do { _Pragma("unroll") for (int m = 0; m < 4; ++m) _Pragma("unroll") for (int k = 0; k < 2; ++k) dst[m][k] = *(const PG8_LAS bf16x8*)(lds + PG8_SA(b, h) + aoff + m * 2048 + k * 1024); } while (0)
; #define PG8_LDB(dst, b, h) do { _Pragma("unroll") for (int n = 0; n < 2; ++n) _Pragma("unroll") for (int k = 0; k < 2; ++k) dst[n][k] = *(const PG8_LAS bf16x8*)(lds + PG8_SB(b, h) + boff + n * 2048 + k * 1024); } while (0)
; #define PG8_MMA(ai, bj, At, Bt) do { __builtin_amdgcn_s_setprio(1); _Pragma("unroll") for (int m = 0; m < 4; ++m) _Pragma("unroll") for (int n = 0; n < 2; ++n) _Pragma("unroll") for (int k = 0; k < 2; ++k) \
;         acc[ai][bj][m][n] = __builtin_amdgcn_mfma_f32_16x16x32_bf16(Bt[n][k], At[m][k], acc[ai][bj][m][n], 0, 0, 0); __builtin_amdgcn_s_setprio(0); } while (0)
; #define PG8_WAIT_V(n) asm volatile("s_waitcnt vmcnt(" #n ")" ::: "memory")
; #define PG8_WAIT_L(n) asm volatile("s_waitcnt lgkmcnt(" #n ")" ::: "memory")
; #define PG8_BAR __builtin_amdgcn_s_barrier()
; #define PG8_SCHED __builtin_amdgcn_sched_barrier(0)
; template <class Epi, class Sched, bool ALIGN_EPI = false, bool SP2 = false>
; __device__ __forceinline__ void gemm_phase(PG8_LAS unsigned char* lds, const Gemm g, const Sched& S, const Epi& E) {
;     ...
;             PG8_WAIT_V(8); PG8_WAIT_L(0); PG8_BAR; PG8_MMA(1, 0, At, B0); PG8_MMA(1, 1, At, B1); PG8_BAR; PG8_SCHED;
;             PG8_LDB(B0, 1, 0); PG8_LDB(B1, 1, 1); PG8_SCHED; PG8_LDA(At, 1, 0); PG8_STAGE(PG8_SA(0, 1), a2 + hstepA, voffA);
;             PG8_WAIT_V(8); PG8_WAIT_L(0); PG8_BAR; PG8_MMA(0, 0, At, B0); PG8_MMA(0, 1, At, B1); PG8_BAR; PG8_SCHED;
	s_waitcnt lgkmcnt(0)
	v_mfma_f32_16x16x32_bf16 v[92:95], v[100:103], v[164:167], v[92:95]
	v_mfma_f32_16x16x32_bf16 v[88:91], v[108:111], v[164:167], v[88:91]
	v_mfma_f32_16x16x32_bf16 v[84:87], v[100:103], v[192:195], v[84:87]
	v_mfma_f32_16x16x32_bf16 v[80:83], v[108:111], v[192:195], v[80:83]
	v_mfma_f32_16x16x32_bf16 v[76:79], v[100:103], v[200:203], v[76:79]
	v_mfma_f32_16x16x32_bf16 v[72:75], v[108:111], v[200:203], v[72:75]
	v_mfma_f32_16x16x32_bf16 v[68:71], v[100:103], v[228:231], v[68:71]
	v_mfma_f32_16x16x32_bf16 v[64:67], v[108:111], v[228:231], v[64:67]
	v_mfma_f32_16x16x32_bf16 v[92:95], v[104:107], v[168:171], v[92:95]
	v_mfma_f32_16x16x32_bf16 v[88:91], v[120:123], v[168:171], v[88:91]
	v_mfma_f32_16x16x32_bf16 v[84:87], v[104:107], v[196:199], v[84:87]
	v_mfma_f32_16x16x32_bf16 v[80:83], v[120:123], v[196:199], v[80:83]
	v_mfma_f32_16x16x32_bf16 v[76:79], v[104:107], v[204:207], v[76:79]
	v_mfma_f32_16x16x32_bf16 v[72:75], v[120:123], v[204:207], v[72:75]
	v_mfma_f32_16x16x32_bf16 v[68:71], v[104:107], v[232:235], v[68:71]
	v_mfma_f32_16x16x32_bf16 v[64:67], v[120:123], v[232:235], v[64:67]
	v_mfma_f32_16x16x32_bf16 v[28:31], v[124:127], v[164:167], v[28:31]
	v_mfma_f32_16x16x32_bf16 v[24:27], v[132:135], v[164:167], v[24:27]
	v_mfma_f32_16x16x32_bf16 v[20:23], v[124:127], v[192:195], v[20:23]
	v_mfma_f32_16x16x32_bf16 v[16:19], v[132:135], v[192:195], v[16:19]
	v_mfma_f32_16x16x32_bf16 v[12:15], v[124:127], v[200:203], v[12:15]
	v_mfma_f32_16x16x32_bf16 v[8:11], v[132:135], v[200:203], v[8:11]
	v_mfma_f32_16x16x32_bf16 v[4:7], v[124:127], v[228:231], v[4:7]
	v_mfma_f32_16x16x32_bf16 v[0:3], v[132:135], v[228:231], v[0:3]
	v_mfma_f32_16x16x32_bf16 v[28:31], v[128:131], v[168:171], v[28:31]
	v_mfma_f32_16x16x32_bf16 v[24:27], v[160:163], v[168:171], v[24:27]
	v_mfma_f32_16x16x32_bf16 v[20:23], v[128:131], v[196:199], v[20:23]
	v_mfma_f32_16x16x32_bf16 v[16:19], v[160:163], v[196:199], v[16:19]
	v_mfma_f32_16x16x32_bf16 v[12:15], v[128:131], v[204:207], v[12:15]
	v_mfma_f32_16x16x32_bf16 v[8:11], v[160:163], v[204:207], v[8:11]
	v_mfma_f32_16x16x32_bf16 v[4:7], v[128:131], v[232:235], v[4:7]
	v_mfma_f32_16x16x32_bf16 v[0:3], v[160:163], v[232:235], v[0:3]
	s_barrier
	s_add_i32 s70, 0, 0x18000
	s_add_i32 s71, 0, 0x1c000
	v_add_u32_e32 v120, s70, v189
	v_add_u32_e32 v160, s71, v189
	ds_read_b128 v[100:103], v120
	ds_read_b128 v[104:107], v120 offset:1024
	ds_read_b128 v[108:111], v120 offset:2048
	ds_read_b128 v[120:123], v120 offset:3072
	ds_read_b128 v[124:127], v160
	ds_read_b128 v[128:131], v160 offset:1024
	ds_read_b128 v[132:135], v160 offset:2048
	ds_read_b128 v[160:163], v160 offset:3072
	s_add_u32 s48, s48, 0x40000
	s_addc_u32 s49, s49, 0
	s_mov_b32 m0, s59
	v_lshl_add_u64 v[240:241], s[48:49], 0, v[172:173]
	ds_read_b128 v[164:167], v209 offset:32768
	ds_read_b128 v[168:171], v209 offset:33792
	ds_read_b128 v[192:195], v209 offset:34816
	ds_read_b128 v[196:199], v209 offset:35840
	ds_read_b128 v[200:203], v209 offset:36864
	ds_read_b128 v[204:207], v209 offset:37888
	ds_read_b128 v[228:231], v209 offset:38912
	ds_read_b128 v[232:235], v209 offset:39936
	global_load_lds_dwordx4 v[240:241], off
	v_lshl_add_u64 v[240:241], s[48:49], 0, v[176:177]
	s_mov_b32 m0, s60
	s_nop 0
	global_load_lds_dwordx4 v[240:241], off
	s_waitcnt vmcnt(8)
	s_waitcnt lgkmcnt(0)
	s_barrier
	s_waitcnt lgkmcnt(0)
	v_mfma_f32_16x16x32_bf16 v[156:159], v[100:103], v[164:167], v[156:159]
	v_mfma_f32_16x16x32_bf16 v[152:155], v[108:111], v[164:167], v[152:155]
	v_mfma_f32_16x16x32_bf16 v[148:151], v[100:103], v[192:195], v[148:151]
	v_mfma_f32_16x16x32_bf16 v[144:147], v[108:111], v[192:195], v[144:147]
	v_mfma_f32_16x16x32_bf16 v[140:143], v[100:103], v[200:203], v[140:143]
	v_mfma_f32_16x16x32_bf16 v[136:139], v[108:111], v[200:203], v[136:139]
	v_mfma_f32_16x16x32_bf16 v[116:119], v[100:103], v[228:231], v[116:119]
	v_mfma_f32_16x16x32_bf16 v[112:115], v[108:111], v[228:231], v[112:115]
	v_mfma_f32_16x16x32_bf16 v[156:159], v[104:107], v[168:171], v[156:159]
	v_mfma_f32_16x16x32_bf16 v[152:155], v[120:123], v[168:171], v[152:155]
	v_mfma_f32_16x16x32_bf16 v[148:151], v[104:107], v[196:199], v[148:151]
	v_mfma_f32_16x16x32_bf16 v[144:147], v[120:123], v[196:199], v[144:147]
	v_mfma_f32_16x16x32_bf16 v[140:143], v[104:107], v[204:207], v[140:143]
	v_mfma_f32_16x16x32_bf16 v[136:139], v[120:123], v[204:207], v[136:139]
	v_mfma_f32_16x16x32_bf16 v[116:119], v[104:107], v[232:235], v[116:119]
	v_mfma_f32_16x16x32_bf16 v[112:115], v[120:123], v[232:235], v[112:115]
	v_mfma_f32_16x16x32_bf16 v[60:63], v[124:127], v[164:167], v[60:63]
	v_mfma_f32_16x16x32_bf16 v[56:59], v[132:135], v[164:167], v[56:59]
	v_mfma_f32_16x16x32_bf16 v[52:55], v[124:127], v[192:195], v[52:55]
	v_mfma_f32_16x16x32_bf16 v[48:51], v[132:135], v[192:195], v[48:51]
	v_mfma_f32_16x16x32_bf16 v[44:47], v[124:127], v[200:203], v[44:47]
	v_mfma_f32_16x16x32_bf16 v[40:43], v[132:135], v[200:203], v[40:43]
	v_mfma_f32_16x16x32_bf16 v[36:39], v[124:127], v[228:231], v[36:39]
	v_mfma_f32_16x16x32_bf16 v[32:35], v[132:135], v[228:231], v[32:35]
	v_mfma_f32_16x16x32_bf16 v[60:63], v[128:131], v[168:171], v[60:63]
	v_mfma_f32_16x16x32_bf16 v[56:59], v[160:163], v[168:171], v[56:59]
	v_mfma_f32_16x16x32_bf16 v[52:55], v[128:131], v[196:199], v[52:55]
	v_mfma_f32_16x16x32_bf16 v[48:51], v[160:163], v[196:199], v[48:51]
	v_mfma_f32_16x16x32_bf16 v[44:47], v[128:131], v[204:207], v[44:47]
	v_mfma_f32_16x16x32_bf16 v[40:43], v[160:163], v[204:207], v[40:43]
	v_mfma_f32_16x16x32_bf16 v[36:39], v[128:131], v[232:235], v[36:39]
	v_mfma_f32_16x16x32_bf16 v[32:35], v[160:163], v[232:235], v[32:35]
	s_barrier
; #define PG8_STAGE(bufoff, gbase, voff) do { _Pragma("unroll") for (int _i = 0; _i < 2; ++_i) \
;         __builtin_amdgcn_global_load_lds((const unsigned*)((const char*)(gbase) + (voff)[_i]), (PG8_LAS unsigned*)(lds + (bufoff) + ldsw + _i * 8192), 16, 0, 0); } while (0)
; #define PG8_LDA(dst, b, h) do { _Pragma("unroll") for (int m = 0; m < 4; ++m) _Pragma("unroll") for (int k = 0; k < 2; ++k) dst[m][k] = *(const PG8_LAS bf16x8*)(lds + PG8_SA(b, h) + aoff + m * 2048 + k * 1024); } while (0)
; #define PG8_MMA(ai, bj, At, Bt) do { __builtin_amdgcn_s_setprio(1); _Pragma("unroll") for (int m = 0; m < 4; ++m) _Pragma("unroll") for (int n = 0; n < 2; ++n) _Pragma("unroll") for (int k = 0; k < 2; ++k) \
;         acc[ai][bj][m][n] = __builtin_amdgcn_mfma_f32_16x16x32_bf16(Bt[n][k], At[m][k], acc[ai][bj][m][n], 0, 0, 0); __builtin_amdgcn_s_setprio(0); } while (0)
; #define PG8_WAIT_V(n) asm volatile("s_waitcnt vmcnt(" #n ")" ::: "memory")
; #define PG8_WAIT_L(n) asm volatile("s_waitcnt lgkmcnt(" #n ")" ::: "memory")
; #define PG8_BAR __builtin_amdgcn_s_barrier()
; #define PG8_SCHED __builtin_amdgcn_sched_barrier(0)
; template <class Epi, class Sched, bool ALIGN_EPI = false, bool SP2 = false>
; __device__ __forceinline__ void gemm_phase(PG8_LAS unsigned char* lds, const Gemm g, const Sched& S, const Epi& E) {
;     ...
;             PG8_LDA(At, 1, 1); PG8_STAGE(PG8_SB(1, 0), b3, voffB); PG8_STAGE(PG8_SB(1, 1), b3 + hstepB, voffB); PG8_STAGE(PG8_SA(1, 0), a3, voffA);
;             PG8_WAIT_V(8); PG8_WAIT_L(0); PG8_BAR; PG8_MMA(1, 0, At, B0); PG8_MMA(1, 1, At, B1); PG8_BAR; PG8_SCHED;
;     ...
;         if constexpr (ALIGN_EPI) { if (wr == 0) PG8_BAR; }
	s_add_i32 s48, s70, s56
	v_lshl_add_u64 v[236:237], v[236:237], 0, s[10:11]
	s_mov_b32 m0, s48
	ds_read_b128 v[164:167], v209 offset:49152
	ds_read_b128 v[168:171], v209 offset:50176
	ds_read_b128 v[192:195], v209 offset:51200
	ds_read_b128 v[196:199], v209 offset:52224
	ds_read_b128 v[200:203], v209 offset:53248
	ds_read_b128 v[204:207], v209 offset:54272
	ds_read_b128 v[228:231], v209 offset:55296
	ds_read_b128 v[232:235], v209 offset:56320
	global_load_lds_dwordx4 v[236:237], off
	s_add_i32 m0, s48, 0x2000
	s_add_u32 s46, s46, 0x40080
	v_lshl_add_u64 v[236:237], v[238:239], 0, s[10:11]
	s_addc_u32 s47, s47, 0
	s_add_i32 s48, s71, s56
	global_load_lds_dwordx4 v[236:237], off
	v_lshl_add_u64 v[236:237], s[46:47], 0, v[174:175]
	s_mov_b32 m0, s48
	s_nop 0
	global_load_lds_dwordx4 v[236:237], off
	v_lshl_add_u64 v[236:237], s[46:47], 0, v[178:179]
	s_add_i32 m0, s48, 0x2000
	s_nop 0
	global_load_lds_dwordx4 v[236:237], off
	v_lshl_add_u64 v[236:237], s[44:45], 0, v[172:173]
	s_mov_b32 m0, s66
	s_nop 0
	global_load_lds_dwordx4 v[236:237], off
	v_lshl_add_u64 v[236:237], s[44:45], 0, v[176:177]
	s_mov_b32 m0, s67
	s_nop 0
	global_load_lds_dwordx4 v[236:237], off
	s_waitcnt vmcnt(8)
	s_waitcnt lgkmcnt(0)
	s_barrier
	s_waitcnt lgkmcnt(0)
	v_mfma_f32_16x16x32_bf16 v[92:95], v[100:103], v[164:167], v[92:95]
	v_mfma_f32_16x16x32_bf16 v[88:91], v[108:111], v[164:167], v[88:91]
	v_mfma_f32_16x16x32_bf16 v[84:87], v[100:103], v[192:195], v[84:87]
	v_mfma_f32_16x16x32_bf16 v[80:83], v[108:111], v[192:195], v[80:83]
	v_mfma_f32_16x16x32_bf16 v[76:79], v[100:103], v[200:203], v[76:79]
	v_mfma_f32_16x16x32_bf16 v[72:75], v[108:111], v[200:203], v[72:75]
	v_mfma_f32_16x16x32_bf16 v[68:71], v[100:103], v[228:231], v[68:71]
	v_mfma_f32_16x16x32_bf16 v[64:67], v[108:111], v[228:231], v[64:67]
	v_mfma_f32_16x16x32_bf16 v[92:95], v[104:107], v[168:171], v[92:95]
	v_mfma_f32_16x16x32_bf16 v[88:91], v[120:123], v[168:171], v[88:91]
	v_mfma_f32_16x16x32_bf16 v[84:87], v[104:107], v[196:199], v[84:87]
	v_mfma_f32_16x16x32_bf16 v[80:83], v[120:123], v[196:199], v[80:83]
	v_mfma_f32_16x16x32_bf16 v[76:79], v[104:107], v[204:207], v[76:79]
	v_mfma_f32_16x16x32_bf16 v[72:75], v[120:123], v[204:207], v[72:75]
	v_mfma_f32_16x16x32_bf16 v[68:71], v[104:107], v[232:235], v[68:71]
	v_mfma_f32_16x16x32_bf16 v[64:67], v[120:123], v[232:235], v[64:67]
	v_mfma_f32_16x16x32_bf16 v[28:31], v[124:127], v[164:167], v[28:31]
	v_mfma_f32_16x16x32_bf16 v[24:27], v[132:135], v[164:167], v[24:27]
	v_mfma_f32_16x16x32_bf16 v[20:23], v[124:127], v[192:195], v[20:23]
	v_mfma_f32_16x16x32_bf16 v[16:19], v[132:135], v[192:195], v[16:19]
	v_mfma_f32_16x16x32_bf16 v[12:15], v[124:127], v[200:203], v[12:15]
	v_mfma_f32_16x16x32_bf16 v[8:11], v[132:135], v[200:203], v[8:11]
	v_mfma_f32_16x16x32_bf16 v[4:7], v[124:127], v[228:231], v[4:7]
	v_mfma_f32_16x16x32_bf16 v[0:3], v[132:135], v[228:231], v[0:3]
	v_mfma_f32_16x16x32_bf16 v[28:31], v[128:131], v[168:171], v[28:31]
	v_mfma_f32_16x16x32_bf16 v[24:27], v[160:163], v[168:171], v[24:27]
	v_mfma_f32_16x16x32_bf16 v[20:23], v[128:131], v[196:199], v[20:23]
	v_mfma_f32_16x16x32_bf16 v[16:19], v[160:163], v[196:199], v[16:19]
	v_mfma_f32_16x16x32_bf16 v[12:15], v[128:131], v[204:207], v[12:15]
	v_mfma_f32_16x16x32_bf16 v[8:11], v[160:163], v[204:207], v[8:11]
	v_mfma_f32_16x16x32_bf16 v[4:7], v[128:131], v[232:235], v[4:7]
	v_mfma_f32_16x16x32_bf16 v[0:3], v[160:163], v[232:235], v[0:3]
	s_barrier
	s_add_i32 s85, s85, 2
	s_add_u32 s42, s42, 0x100
	s_addc_u32 s43, s43, 0
	s_cmp_gt_u32 s85, 13
	s_cbranch_scc0 .LBB0_612
	s_and_b64 vcc, exec, s[24:25]
	s_cbranch_vccz .LBB0_615
	s_barrier

; __device__ __forceinline__ void wconv_phase(KP Pk, int L, unsigned char* lds, int G, int blk) {
;     ...
;     int tid_l = threadIdx.x; asm volatile("" : "+v"(tid_l)); const int tid = tid_l, lane = tid & 63, wid = __builtin_amdgcn_readfirstlane(tid >> 6), j = L >> 1; const bool att = (L & 1) == 0;
;     float* scr = (float*)(lds + wid * 16384);
;     unsigned char* ws = P.ws;
;     bf16_t *WIN = (bf16_t*)(ws + WS_WIN), *WOUT = (bf16_t*)(ws + WS_WOUT), *W1 = (bf16_t*)(ws + WS_W1), *W2 = (bf16_t*)(ws + WS_W2), *WG = (bf16_t*)(ws + WS_WG), *WP = (bf16_t*)(ws + WS_WP);
;     float* vecp = (float*)(ws + WS_VECP);
;     const int nin = att ? NQKV / 32 : HIN / 32;
;     const int I0 = nin * 16, I1 = I0 + 32 * 16, I2 = I1 + 176 * 16, I3 = I2 + 32 * 44, I4 = I3 + 32 * 16, I5 = I4 + 32 * 4;
;     for (int it = wid * G + blk; it < I5; it += 8 * G) {
.LBB0_671:
	s_or_b64 exec, exec, s[4:5]
	s_setprio 0
	s_mov_b64 s[10:11], s[0:1]
	s_mov_b32 s8, s2
	s_mov_b32 s6, s74
	s_waitcnt lgkmcnt(0)
	v_mov_b32_e32 v0, v254
	s_barrier
	s_load_dwordx2 s[12:13], s[10:11], 0x90
	v_readfirstlane_b32 s3, v0
	s_ashr_i32 s3, s3, 6
	s_mul_i32 s4, s3, s6
	s_add_i32 s7, s4, s8
	s_cmpk_gt_i32 s7, 0x1eff
	s_cbranch_scc1 .LBB0_710
	s_waitcnt lgkmcnt(0)
	s_add_u32 s9, s12, 0x1fd00000
	v_lshlrev_b32_e32 v3, 3, v0
	s_addc_u32 s24, s13, 0
	s_lshl_b32 s3, s3, 14
	v_and_b32_e32 v4, 56, v3
	v_bfe_u32 v3, v0, 3, 3
	s_add_i32 s4, s3, 0
	v_mul_u32_u24_e32 v5, 0x84, v4
	v_lshlrev_b32_e32 v6, 2, v3
	v_add3_u32 v86, s4, v5, v6
	v_lshlrev_b32_e32 v4, 1, v4
	v_mov_b32_e32 v5, 0
	v_bfe_u32 v2, v0, 5, 1
	v_lshl_add_u64 v[6:7], s[12:13], 0, v[4:5]
	s_mov_b64 s[4:5], 0x1f00000
	v_and_b32_e32 v4, 1, v0
	v_and_b32_e32 v12, 63, v0
	v_and_b32_e32 v1, 31, v0
	v_lshl_add_u64 v[8:9], v[6:7], 0, s[4:5]
	s_mov_b64 s[4:5], 0x1d00000
	s_mov_b64 s[16:17], 0x1700000
	v_cmp_eq_u32_e32 vcc, 1, v4
	v_mul_u32_u24_e32 v4, 0x84, v2
	v_lshl_add_u64 v[10:11], v[6:7], 0, s[4:5]
	v_cmp_gt_u32_e64 s[4:5], 32, v12
	v_lshl_add_u64 v[12:13], v[6:7], 0, s[16:17]
	v_mov_b32_e32 v14, 0xb00
	s_mov_b64 s[16:17], 0xc00000
	v_or_b32_e32 v4, s3, v4
	v_lshlrev_b32_e32 v18, 2, v1
	v_cndmask_b32_e32 v90, 0, v14, vcc
	v_lshl_add_u64 v[14:15], v[6:7], 0, s[16:17]
	s_mov_b64 s[16:17], 0xa00000
	v_add3_u32 v91, v4, v18, 0
	s_lshl_b32 s3, s7, 3
	s_add_i32 s34, s7, 0xfffff400
	v_mbcnt_lo_u32_b32 v4, -1, 0
	s_mov_b32 s15, 0
	v_or_b32_e32 v87, 8, v3
	v_or_b32_e32 v88, 16, v3
	v_or_b32_e32 v89, 24, v3
	v_lshl_add_u64 v[16:17], v[6:7], 0, s[16:17]
	s_lshl_b32 s25, s6, 3
	s_add_i32 s26, s3, 0xffff0c00
	s_lshl_b32 s27, s6, 6
	v_or_b32_e32 v92, 14, v2
	s_lshl_b32 s28, s7, 6
	s_lshl_b32 s29, s6, 9
	v_or_b32_e32 v93, 12, v2
	v_or_b32_e32 v94, 10, v2
	v_or_b32_e32 v95, 8, v2
	v_or_b32_e32 v96, 6, v2
	v_or_b32_e32 v97, 4, v2
	v_or_b32_e32 v98, 2, v2
	v_or_b32_e32 v99, 0xffffc700, v1
	s_lshl_b32 s30, s7, 1
	s_lshl_b32 s31, s6, 4
	s_lshl_b32 s35, s34, 1
	v_or_b32_e32 v100, 0xffffec00, v1
	s_mov_b64 s[16:17], 0x10000
	s_movk_i32 s36, 0x5800
	s_mov_b64 s[18:19], 0x1600000
	s_mov_b64 s[20:21], 0x58000
	s_movk_i32 s37, 0x5000
	v_mov_b32_e32 v101, 0x400000
	v_mbcnt_hi_u32_b32 v102, -1, v4
	v_mov_b64_e32 v[18:19], 0x1600000
	s_mov_b32 s38, s7
	s_branch .LBB0_674

; __device__ __forceinline__ void vec_finalize(unsigned char* ws, int G, int blk) {
;     const float* vecp = (const float*)(ws + WS_VECP); float* vec = (float*)(ws + WS_VEC);
;     for (int i = blk * 512 + threadIdx.x; i < 13312; i += G * 512) { float a = 0.f;
; #pragma unroll
;         for (int kb = 0; kb < 16; ++kb) a += vecp[(size_t)kb * 13312 + i];
;         vec[i] = a; }
.Lprio_hin1:
	s_mov_b64 s[4:5], s[0:1]
	s_mov_b32 s42, s2
	s_mov_b32 s43, s74
	s_waitcnt lgkmcnt(0)
	s_barrier
	s_load_dwordx2 s[10:11], s[4:5], 0x90
	v_lshl_add_u32 v0, s42, 9, v254
	s_movk_i32 s3, 0x3400
	v_cmp_gt_i32_e32 vcc, s3, v0
	s_and_saveexec_b64 s[4:5], vcc
	s_cbranch_execz .LBB0_771
	s_lshl_b32 s6, s43, 9
	v_ashrrev_i32_e32 v1, 31, v0
	s_waitcnt lgkmcnt(0)
	v_lshl_add_u64 v[2:3], v[0:1], 2, s[10:11]
	s_mov_b64 s[8:9], 0x1fdc3000
	s_ashr_i32 s7, s6, 31
	v_lshl_add_u64 v[2:3], v[2:3], 0, s[8:9]
	s_lshl_b64 s[8:9], s[6:7], 2
	s_mov_b64 s[12:13], 0
	s_movk_i32 s3, 0x33ff

; #define PG8_STAGE(bufoff, gbase, voff) do { _Pragma("unroll") for (int _i = 0; _i < 2; ++_i) \
;         __builtin_amdgcn_global_load_lds((const unsigned*)((const char*)(gbase) + (voff)[_i]), (PG8_LAS unsigned*)(lds + (bufoff) + ldsw + _i * 8192), 16, 0, 0); } while (0)
; #define PG8_LDA(dst, b, h) do { _Pragma("unroll") for (int m = 0; m < 4; ++m) _Pragma("unroll") for (int k = 0; k < 2; ++k) dst[m][k] = *(const PG8_LAS bf16x8*)(lds + PG8_SA(b, h) + aoff + m * 2048 + k * 1024); } while (0)
; #define PG8_LDB(dst, b, h) do { _Pragma("unroll") for (int n = 0; n < 2; ++n) _Pragma("unroll") for (int k = 0; k < 2; ++k) dst[n][k] = *(const PG8_LAS bf16x8*)(lds + PG8_SB(b, h) + boff + n * 2048 + k * 1024); } while (0)
; #define PG8_MMA(ai, bj, At, Bt) do { __builtin_amdgcn_s_setprio(1); _Pragma("unroll") for (int m = 0; m < 4; ++m) _Pragma("unroll") for (int n = 0; n < 2; ++n) _Pragma("unroll") for (int k = 0; k < 2; ++k) \
;         acc[ai][bj][m][n] = __builtin_amdgcn_mfma_f32_16x16x32_bf16(Bt[n][k], At[m][k], acc[ai][bj][m][n], 0, 0, 0); __builtin_amdgcn_s_setprio(0); } while (0)
; #define PG8_WAIT_V(n) asm volatile("s_waitcnt vmcnt(" #n ")" ::: "memory")
; #define PG8_WAIT_L(n) asm volatile("s_waitcnt lgkmcnt(" #n ")" ::: "memory")
; #define PG8_BAR __builtin_amdgcn_s_barrier()
; #define PG8_SCHED __builtin_amdgcn_sched_barrier(0)
; template <class Epi, class Sched, bool ALIGN_EPI = false, bool SP2 = false>
; __device__ __forceinline__ void gemm_phase(PG8_LAS unsigned char* lds, const Gemm g, const Sched& S, const Epi& E) {
;     ...
;             const bool last = (t == nt - 2);
;             const char* a1 = cA + PG8_AK(t + 1);
;             const char* a2 = last ? nA : cA + PG8_AK(t + 2); const char* b2 = last ? nB : cB + (size_t)(t + 2) * kstep;
;             const char* a3 = last ? nA + PG8_AK(1) : cA + PG8_AK(t + 3); const char* b3 = b2 + kstep;
;             if (last && has_next) S.a_ready(nxt);
;             if constexpr (SP2) {
;             PG8_LDB(B0, 0, 0); PG8_LDB(B1, 0, 1); PG8_SCHED; PG8_LDA(At, 0, 0); PG8_STAGE(PG8_SA(1, 1), a1 + hstepA, voffA);
;             PG8_WAIT_V(8); PG8_WAIT_L(0); PG8_BAR; PG8_MMA(0, 0, At, B0); PG8_MMA(0, 1, At, B1); PG8_BAR; PG8_SCHED;
;             PG8_LDA(At, 0, 1); PG8_STAGE(PG8_SB(0, 0), b2, voffB); PG8_STAGE(PG8_SB(0, 1), b2 + hstepB, voffB); PG8_STAGE(PG8_SA(0, 0), a2, voffA);
.LBB0_782:
	ds_read_b128 v[100:103], v167
	ds_read_b128 v[154:157], v167 offset:1024
	ds_read_b128 v[158:161], v167 offset:2048
	ds_read_b128 v[170:173], v167 offset:3072
	ds_read_b128 v[174:177], v168
	ds_read_b128 v[178:181], v168 offset:1024
	ds_read_b128 v[182:185], v168 offset:2048
	ds_read_b128 v[186:189], v168 offset:3072
	s_add_u32 s36, s6, s34
	s_addc_u32 s37, s7, s35
	s_add_u32 s40, s36, 0x100
	s_addc_u32 s41, s37, 0
	s_add_u32 s38, s62, s34
	s_addc_u32 s39, s63, s35
	s_add_u32 s36, s36, 0x180
	s_addc_u32 s37, s37, 0
	s_cmpk_eq_i32 s34, 0x700
	s_cselect_b32 s37, s61, s37
	s_cselect_b32 s36, s31, s36
	s_cselect_b32 s39, s23, s39
	s_cselect_b32 s38, s25, s38
	s_cselect_b32 s41, s3, s41
	s_cselect_b32 s40, s9, s40
	v_lshl_add_u64 v[162:163], v[98:99], 0, s[34:35]
	s_add_i32 m0, s47, 0xc000
	ds_read_b128 v[190:193], v169
	ds_read_b128 v[194:197], v169 offset:1024
	ds_read_b128 v[198:201], v169 offset:2048
	ds_read_b128 v[202:205], v169 offset:3072
	ds_read_b128 v[206:209], v169 offset:4096
	ds_read_b128 v[210:213], v169 offset:5120
	ds_read_b128 v[214:217], v169 offset:6144
	ds_read_b128 v[218:221], v169 offset:7168
	global_load_lds_dwordx4 v[162:163], off
	v_lshl_add_u64 v[162:163], v[96:97], 0, s[34:35]
	s_add_i32 m0, s47, 0xe000
	s_nop 0
	global_load_lds_dwordx4 v[162:163], off
	s_waitcnt vmcnt(8)
	s_waitcnt lgkmcnt(0)
	s_barrier
	s_waitcnt lgkmcnt(0)
	v_mfma_f32_16x16x32_bf16 v[132:135], v[100:103], v[190:193], v[132:135]
	v_mfma_f32_16x16x32_bf16 v[128:131], v[158:161], v[190:193], v[128:131]
	v_mfma_f32_16x16x32_bf16 v[124:127], v[100:103], v[198:201], v[124:127]
	v_mfma_f32_16x16x32_bf16 v[120:123], v[158:161], v[198:201], v[120:123]
	v_mfma_f32_16x16x32_bf16 v[116:119], v[100:103], v[206:209], v[116:119]
	v_mfma_f32_16x16x32_bf16 v[112:115], v[158:161], v[206:209], v[112:115]
	v_mfma_f32_16x16x32_bf16 v[108:111], v[100:103], v[214:217], v[108:111]
	v_mfma_f32_16x16x32_bf16 v[104:107], v[158:161], v[214:217], v[104:107]
	v_mfma_f32_16x16x32_bf16 v[132:135], v[154:157], v[194:197], v[132:135]
	v_mfma_f32_16x16x32_bf16 v[128:131], v[170:173], v[194:197], v[128:131]
	v_mfma_f32_16x16x32_bf16 v[124:127], v[154:157], v[202:205], v[124:127]
	v_mfma_f32_16x16x32_bf16 v[120:123], v[170:173], v[202:205], v[120:123]
	v_mfma_f32_16x16x32_bf16 v[116:119], v[154:157], v[210:213], v[116:119]
	v_mfma_f32_16x16x32_bf16 v[112:115], v[170:173], v[210:213], v[112:115]
	v_mfma_f32_16x16x32_bf16 v[108:111], v[154:157], v[218:221], v[108:111]
	v_mfma_f32_16x16x32_bf16 v[104:107], v[170:173], v[218:221], v[104:107]
	v_mfma_f32_16x16x32_bf16 v[60:63], v[174:177], v[190:193], v[60:63]
	v_mfma_f32_16x16x32_bf16 v[56:59], v[182:185], v[190:193], v[56:59]
	v_mfma_f32_16x16x32_bf16 v[52:55], v[174:177], v[198:201], v[52:55]
	v_mfma_f32_16x16x32_bf16 v[48:51], v[182:185], v[198:201], v[48:51]
	v_mfma_f32_16x16x32_bf16 v[44:47], v[174:177], v[206:209], v[44:47]
	v_mfma_f32_16x16x32_bf16 v[40:43], v[182:185], v[206:209], v[40:43]
	v_mfma_f32_16x16x32_bf16 v[36:39], v[174:177], v[214:217], v[36:39]
	v_mfma_f32_16x16x32_bf16 v[32:35], v[182:185], v[214:217], v[32:35]
	v_mfma_f32_16x16x32_bf16 v[60:63], v[178:181], v[194:197], v[60:63]
	v_mfma_f32_16x16x32_bf16 v[56:59], v[186:189], v[194:197], v[56:59]
	v_mfma_f32_16x16x32_bf16 v[52:55], v[178:181], v[202:205], v[52:55]
	v_mfma_f32_16x16x32_bf16 v[48:51], v[186:189], v[202:205], v[48:51]
	v_mfma_f32_16x16x32_bf16 v[44:47], v[178:181], v[210:213], v[44:47]
	v_mfma_f32_16x16x32_bf16 v[40:43], v[186:189], v[210:213], v[40:43]
	v_mfma_f32_16x16x32_bf16 v[36:39], v[178:181], v[218:221], v[36:39]
	v_mfma_f32_16x16x32_bf16 v[32:35], v[186:189], v[218:221], v[32:35]
	s_barrier
	s_add_i32 s65, s58, s46
	v_lshl_add_u64 v[162:163], s[38:39], 0, v[138:139]
	s_mov_b32 m0, s65
	ds_read_b128 v[190:193], v169 offset:16384
	ds_read_b128 v[194:197], v169 offset:17408
	ds_read_b128 v[198:201], v169 offset:18432
	ds_read_b128 v[202:205], v169 offset:19456
	ds_read_b128 v[206:209], v169 offset:20480
	ds_read_b128 v[210:213], v169 offset:21504
	ds_read_b128 v[214:217], v169 offset:22528
	ds_read_b128 v[218:221], v169 offset:23552
	global_load_lds_dwordx4 v[162:163], off
	s_add_i32 m0, s65, 0x2000
	s_add_u32 s66, s38, 0x40000
	v_lshl_add_u64 v[222:223], s[38:39], 0, v[142:143]
	s_addc_u32 s67, s39, 0
	s_add_i32 s65, s59, s46
	global_load_lds_dwordx4 v[222:223], off
	v_lshl_add_u64 v[224:225], s[66:67], 0, v[138:139]
	s_mov_b32 m0, s65
	s_nop 0
	global_load_lds_dwordx4 v[224:225], off
	v_lshl_add_u64 v[224:225], s[66:67], 0, v[142:143]
	s_add_i32 m0, s65, 0x2000
	s_nop 0
	global_load_lds_dwordx4 v[224:225], off
	v_lshl_add_u64 v[224:225], s[40:41], 0, v[136:137]
	s_mov_b32 m0, s47
	s_nop 0
	global_load_lds_dwordx4 v[224:225], off
	v_lshl_add_u64 v[224:225], s[40:41], 0, v[140:141]
	s_mov_b32 m0, s48
	s_nop 0
	global_load_lds_dwordx4 v[224:225], off
	s_waitcnt vmcnt(8)
	s_waitcnt lgkmcnt(0)
	s_barrier
; #define PG8_STAGE(bufoff, gbase, voff) do { _Pragma("unroll") for (int _i = 0; _i < 2; ++_i) \
;         __builtin_amdgcn_global_load_lds((const unsigned*)((const char*)(gbase) + (voff)[_i]), (PG8_LAS unsigned*)(lds + (bufoff) + ldsw + _i * 8192), 16, 0, 0); } while (0)
; #define PG8_LDA(dst, b, h) do { _Pragma("unroll") for (int m = 0; m < 4; ++m) _Pragma("unroll") for (int k = 0; k < 2; ++k) dst[m][k] = *(const PG8_LAS bf16x8*)(lds + PG8_SA(b, h) + aoff + m * 2048 + k * 1024); } while (0)
; #define PG8_LDB(dst, b, h) do { _Pragma("unroll") for (int n = 0; n < 2; ++n) _Pragma("unroll") for (int k = 0; k < 2; ++k) dst[n][k] = *(const PG8_LAS bf16x8*)(lds + PG8_SB(b, h) + boff + n * 2048 + k * 1024); } while (0)
; #define PG8_MMA(ai, bj, At, Bt) do { __builtin_amdgcn_s_setprio(1); _Pragma("unroll") for (int m = 0; m < 4; ++m) _Pragma("unroll") for (int n = 0; n < 2; ++n) _Pragma("unroll") for (int k = 0; k < 2; ++k) \
;         acc[ai][bj][m][n] = __builtin_amdgcn_mfma_f32_16x16x32_bf16(Bt[n][k], At[m][k], acc[ai][bj][m][n], 0, 0, 0); __builtin_amdgcn_s_setprio(0); } while (0)
; #define PG8_WAIT_V(n) asm volatile("s_waitcnt vmcnt(" #n ")" ::: "memory")
; #define PG8_WAIT_L(n) asm volatile("s_waitcnt lgkmcnt(" #n ")" ::: "memory")
; #define PG8_BAR __builtin_amdgcn_s_barrier()
; #define PG8_SCHED __builtin_amdgcn_sched_barrier(0)
; template <class Epi, class Sched, bool ALIGN_EPI = false, bool SP2 = false>
; __device__ __forceinline__ void gemm_phase(PG8_LAS unsigned char* lds, const Gemm g, const Sched& S, const Epi& E) {
;     ...
;             PG8_WAIT_V(8); PG8_WAIT_L(0); PG8_BAR; PG8_MMA(1, 0, At, B0); PG8_MMA(1, 1, At, B1); PG8_BAR; PG8_SCHED;
;             PG8_LDB(B0, 1, 0); PG8_LDB(B1, 1, 1); PG8_SCHED; PG8_LDA(At, 1, 0); PG8_STAGE(PG8_SA(0, 1), a2 + hstepA, voffA);
;             PG8_WAIT_V(8); PG8_WAIT_L(0); PG8_BAR; PG8_MMA(0, 0, At, B0); PG8_MMA(0, 1, At, B1); PG8_BAR; PG8_SCHED;
	s_waitcnt lgkmcnt(0)
	v_mfma_f32_16x16x32_bf16 v[92:95], v[100:103], v[190:193], v[92:95]
	v_mfma_f32_16x16x32_bf16 v[88:91], v[158:161], v[190:193], v[88:91]
	v_mfma_f32_16x16x32_bf16 v[84:87], v[100:103], v[198:201], v[84:87]
	v_mfma_f32_16x16x32_bf16 v[80:83], v[158:161], v[198:201], v[80:83]
	v_mfma_f32_16x16x32_bf16 v[76:79], v[100:103], v[206:209], v[76:79]
	v_mfma_f32_16x16x32_bf16 v[72:75], v[158:161], v[206:209], v[72:75]
	v_mfma_f32_16x16x32_bf16 v[68:71], v[100:103], v[214:217], v[68:71]
	v_mfma_f32_16x16x32_bf16 v[64:67], v[158:161], v[214:217], v[64:67]
	v_mfma_f32_16x16x32_bf16 v[92:95], v[154:157], v[194:197], v[92:95]
	v_mfma_f32_16x16x32_bf16 v[88:91], v[170:173], v[194:197], v[88:91]
	v_mfma_f32_16x16x32_bf16 v[84:87], v[154:157], v[202:205], v[84:87]
	v_mfma_f32_16x16x32_bf16 v[80:83], v[170:173], v[202:205], v[80:83]
	v_mfma_f32_16x16x32_bf16 v[76:79], v[154:157], v[210:213], v[76:79]
	v_mfma_f32_16x16x32_bf16 v[72:75], v[170:173], v[210:213], v[72:75]
	v_mfma_f32_16x16x32_bf16 v[68:71], v[154:157], v[218:221], v[68:71]
	v_mfma_f32_16x16x32_bf16 v[64:67], v[170:173], v[218:221], v[64:67]
	v_mfma_f32_16x16x32_bf16 v[28:31], v[174:177], v[190:193], v[28:31]
	v_mfma_f32_16x16x32_bf16 v[24:27], v[182:185], v[190:193], v[24:27]
	v_mfma_f32_16x16x32_bf16 v[20:23], v[174:177], v[198:201], v[20:23]
	v_mfma_f32_16x16x32_bf16 v[16:19], v[182:185], v[198:201], v[16:19]
	v_mfma_f32_16x16x32_bf16 v[12:15], v[174:177], v[206:209], v[12:15]
	v_mfma_f32_16x16x32_bf16 v[8:11], v[182:185], v[206:209], v[8:11]
	v_mfma_f32_16x16x32_bf16 v[4:7], v[174:177], v[214:217], v[4:7]
	v_mfma_f32_16x16x32_bf16 v[0:3], v[182:185], v[214:217], v[0:3]
	v_mfma_f32_16x16x32_bf16 v[28:31], v[178:181], v[194:197], v[28:31]
	v_mfma_f32_16x16x32_bf16 v[24:27], v[186:189], v[194:197], v[24:27]
	v_mfma_f32_16x16x32_bf16 v[20:23], v[178:181], v[202:205], v[20:23]
	v_mfma_f32_16x16x32_bf16 v[16:19], v[186:189], v[202:205], v[16:19]
	v_mfma_f32_16x16x32_bf16 v[12:15], v[178:181], v[210:213], v[12:15]
	v_mfma_f32_16x16x32_bf16 v[8:11], v[186:189], v[210:213], v[8:11]
	v_mfma_f32_16x16x32_bf16 v[4:7], v[178:181], v[218:221], v[4:7]
	v_mfma_f32_16x16x32_bf16 v[0:3], v[186:189], v[218:221], v[0:3]
	s_barrier
	s_add_i32 s65, 0, 0x18000
	s_add_i32 s66, 0, 0x1c000
	v_add_u32_e32 v170, s65, v165
	v_add_u32_e32 v186, s66, v165
	ds_read_b128 v[100:103], v170
	ds_read_b128 v[154:157], v170 offset:1024
	ds_read_b128 v[158:161], v170 offset:2048
	ds_read_b128 v[170:173], v170 offset:3072
	ds_read_b128 v[174:177], v186
	ds_read_b128 v[178:181], v186 offset:1024
	ds_read_b128 v[182:185], v186 offset:2048
	ds_read_b128 v[186:189], v186 offset:3072
	s_add_u32 s40, s40, 0x40000
	s_addc_u32 s41, s41, 0
	s_mov_b32 m0, s49
	v_lshl_add_u64 v[224:225], s[40:41], 0, v[136:137]
	ds_read_b128 v[190:193], v169 offset:32768
	ds_read_b128 v[194:197], v169 offset:33792
	ds_read_b128 v[198:201], v169 offset:34816
	ds_read_b128 v[202:205], v169 offset:35840
	ds_read_b128 v[206:209], v169 offset:36864
	ds_read_b128 v[210:213], v169 offset:37888
	ds_read_b128 v[214:217], v169 offset:38912
	ds_read_b128 v[218:221], v169 offset:39936
	global_load_lds_dwordx4 v[224:225], off
	v_lshl_add_u64 v[224:225], s[40:41], 0, v[140:141]
	s_mov_b32 m0, s50
	s_nop 0
	global_load_lds_dwordx4 v[224:225], off
	s_waitcnt vmcnt(8)
	s_waitcnt lgkmcnt(0)
	s_barrier
	s_waitcnt lgkmcnt(0)
	v_mfma_f32_16x16x32_bf16 v[132:135], v[100:103], v[190:193], v[132:135]
	v_mfma_f32_16x16x32_bf16 v[128:131], v[158:161], v[190:193], v[128:131]
	v_mfma_f32_16x16x32_bf16 v[124:127], v[100:103], v[198:201], v[124:127]
	v_mfma_f32_16x16x32_bf16 v[120:123], v[158:161], v[198:201], v[120:123]
	v_mfma_f32_16x16x32_bf16 v[116:119], v[100:103], v[206:209], v[116:119]
	v_mfma_f32_16x16x32_bf16 v[112:115], v[158:161], v[206:209], v[112:115]
	v_mfma_f32_16x16x32_bf16 v[108:111], v[100:103], v[214:217], v[108:111]
	v_mfma_f32_16x16x32_bf16 v[104:107], v[158:161], v[214:217], v[104:107]
	v_mfma_f32_16x16x32_bf16 v[132:135], v[154:157], v[194:197], v[132:135]
	v_mfma_f32_16x16x32_bf16 v[128:131], v[170:173], v[194:197], v[128:131]
	v_mfma_f32_16x16x32_bf16 v[124:127], v[154:157], v[202:205], v[124:127]
	v_mfma_f32_16x16x32_bf16 v[120:123], v[170:173], v[202:205], v[120:123]
	v_mfma_f32_16x16x32_bf16 v[116:119], v[154:157], v[210:213], v[116:119]
	v_mfma_f32_16x16x32_bf16 v[112:115], v[170:173], v[210:213], v[112:115]
	v_mfma_f32_16x16x32_bf16 v[108:111], v[154:157], v[218:221], v[108:111]
	v_mfma_f32_16x16x32_bf16 v[104:107], v[170:173], v[218:221], v[104:107]
	v_mfma_f32_16x16x32_bf16 v[60:63], v[174:177], v[190:193], v[60:63]
	v_mfma_f32_16x16x32_bf16 v[56:59], v[182:185], v[190:193], v[56:59]
	v_mfma_f32_16x16x32_bf16 v[52:55], v[174:177], v[198:201], v[52:55]
	v_mfma_f32_16x16x32_bf16 v[48:51], v[182:185], v[198:201], v[48:51]
	v_mfma_f32_16x16x32_bf16 v[44:47], v[174:177], v[206:209], v[44:47]
	v_mfma_f32_16x16x32_bf16 v[40:43], v[182:185], v[206:209], v[40:43]
	v_mfma_f32_16x16x32_bf16 v[36:39], v[174:177], v[214:217], v[36:39]
	v_mfma_f32_16x16x32_bf16 v[32:35], v[182:185], v[214:217], v[32:35]
	v_mfma_f32_16x16x32_bf16 v[60:63], v[178:181], v[194:197], v[60:63]
	v_mfma_f32_16x16x32_bf16 v[56:59], v[186:189], v[194:197], v[56:59]
	v_mfma_f32_16x16x32_bf16 v[52:55], v[178:181], v[202:205], v[52:55]
	v_mfma_f32_16x16x32_bf16 v[48:51], v[186:189], v[202:205], v[48:51]
	v_mfma_f32_16x16x32_bf16 v[44:47], v[178:181], v[210:213], v[44:47]
	v_mfma_f32_16x16x32_bf16 v[40:43], v[186:189], v[210:213], v[40:43]
	v_mfma_f32_16x16x32_bf16 v[36:39], v[178:181], v[218:221], v[36:39]
	v_mfma_f32_16x16x32_bf16 v[32:35], v[186:189], v[218:221], v[32:35]
	s_barrier
; #define PG8_STAGE(bufoff, gbase, voff) do { _Pragma("unroll") for (int _i = 0; _i < 2; ++_i) \
;         __builtin_amdgcn_global_load_lds((const unsigned*)((const char*)(gbase) + (voff)[_i]), (PG8_LAS unsigned*)(lds + (bufoff) + ldsw + _i * 8192), 16, 0, 0); } while (0)
; #define PG8_LDA(dst, b, h) do { _Pragma("unroll") for (int m = 0; m < 4; ++m) _Pragma("unroll") for (int k = 0; k < 2; ++k) dst[m][k] = *(const PG8_LAS bf16x8*)(lds + PG8_SA(b, h) + aoff + m * 2048 + k * 1024); } while (0)
; #define PG8_MMA(ai, bj, At, Bt) do { __builtin_amdgcn_s_setprio(1); _Pragma("unroll") for (int m = 0; m < 4; ++m) _Pragma("unroll") for (int n = 0; n < 2; ++n) _Pragma("unroll") for (int k = 0; k < 2; ++k) \
;         acc[ai][bj][m][n] = __builtin_amdgcn_mfma_f32_16x16x32_bf16(Bt[n][k], At[m][k], acc[ai][bj][m][n], 0, 0, 0); __builtin_amdgcn_s_setprio(0); } while (0)
; #define PG8_WAIT_V(n) asm volatile("s_waitcnt vmcnt(" #n ")" ::: "memory")
; #define PG8_WAIT_L(n) asm volatile("s_waitcnt lgkmcnt(" #n ")" ::: "memory")
; #define PG8_BAR __builtin_amdgcn_s_barrier()
; #define PG8_SCHED __builtin_amdgcn_sched_barrier(0)
; template <class Epi, class Sched, bool ALIGN_EPI = false, bool SP2 = false>
; __device__ __forceinline__ void gemm_phase(PG8_LAS unsigned char* lds, const Gemm g, const Sched& S, const Epi& E) {
;     ...
;             PG8_LDA(At, 1, 1); PG8_STAGE(PG8_SB(1, 0), b3, voffB); PG8_STAGE(PG8_SB(1, 1), b3 + hstepB, voffB); PG8_STAGE(PG8_SA(1, 0), a3, voffA);
;             PG8_WAIT_V(8); PG8_WAIT_L(0); PG8_BAR; PG8_MMA(1, 0, At, B0); PG8_MMA(1, 1, At, B1); PG8_BAR; PG8_SCHED;
;     ...
;         if constexpr (ALIGN_EPI) { if (wr == 0) PG8_BAR; }
	s_add_i32 s40, s65, s46
	v_lshl_add_u64 v[162:163], v[162:163], 0, s[18:19]
	s_mov_b32 m0, s40
	ds_read_b128 v[190:193], v169 offset:49152
	ds_read_b128 v[194:197], v169 offset:50176
	ds_read_b128 v[198:201], v169 offset:51200
	ds_read_b128 v[202:205], v169 offset:52224
	ds_read_b128 v[206:209], v169 offset:53248
	ds_read_b128 v[210:213], v169 offset:54272
	ds_read_b128 v[214:217], v169 offset:55296
	ds_read_b128 v[218:221], v169 offset:56320
	global_load_lds_dwordx4 v[162:163], off
	s_add_i32 m0, s40, 0x2000
	s_add_u32 s38, s38, 0x40080
	v_lshl_add_u64 v[162:163], v[222:223], 0, s[18:19]
	s_addc_u32 s39, s39, 0
	s_add_i32 s40, s66, s46
	global_load_lds_dwordx4 v[162:163], off
	v_lshl_add_u64 v[162:163], s[38:39], 0, v[138:139]
	s_mov_b32 m0, s40
	s_nop 0
	global_load_lds_dwordx4 v[162:163], off
	v_lshl_add_u64 v[162:163], s[38:39], 0, v[142:143]
	s_add_i32 m0, s40, 0x2000
	s_nop 0
	global_load_lds_dwordx4 v[162:163], off
	v_lshl_add_u64 v[162:163], s[36:37], 0, v[136:137]
	s_mov_b32 m0, s53
	s_nop 0
	global_load_lds_dwordx4 v[162:163], off
	v_lshl_add_u64 v[162:163], s[36:37], 0, v[140:141]
	s_mov_b32 m0, s54
	s_nop 0
	global_load_lds_dwordx4 v[162:163], off
	s_waitcnt vmcnt(8)
	s_waitcnt lgkmcnt(0)
	s_barrier
	s_waitcnt lgkmcnt(0)
	v_mfma_f32_16x16x32_bf16 v[92:95], v[100:103], v[190:193], v[92:95]
	v_mfma_f32_16x16x32_bf16 v[88:91], v[158:161], v[190:193], v[88:91]
	v_mfma_f32_16x16x32_bf16 v[84:87], v[100:103], v[198:201], v[84:87]
	v_mfma_f32_16x16x32_bf16 v[80:83], v[158:161], v[198:201], v[80:83]
	v_mfma_f32_16x16x32_bf16 v[76:79], v[100:103], v[206:209], v[76:79]
	v_mfma_f32_16x16x32_bf16 v[72:75], v[158:161], v[206:209], v[72:75]
	v_mfma_f32_16x16x32_bf16 v[68:71], v[100:103], v[214:217], v[68:71]
	v_mfma_f32_16x16x32_bf16 v[64:67], v[158:161], v[214:217], v[64:67]
	v_mfma_f32_16x16x32_bf16 v[92:95], v[154:157], v[194:197], v[92:95]
	v_mfma_f32_16x16x32_bf16 v[88:91], v[170:173], v[194:197], v[88:91]
	v_mfma_f32_16x16x32_bf16 v[84:87], v[154:157], v[202:205], v[84:87]
	v_mfma_f32_16x16x32_bf16 v[80:83], v[170:173], v[202:205], v[80:83]
	v_mfma_f32_16x16x32_bf16 v[76:79], v[154:157], v[210:213], v[76:79]
	v_mfma_f32_16x16x32_bf16 v[72:75], v[170:173], v[210:213], v[72:75]
	v_mfma_f32_16x16x32_bf16 v[68:71], v[154:157], v[218:221], v[68:71]
	v_mfma_f32_16x16x32_bf16 v[64:67], v[170:173], v[218:221], v[64:67]
	v_mfma_f32_16x16x32_bf16 v[28:31], v[174:177], v[190:193], v[28:31]
	v_mfma_f32_16x16x32_bf16 v[24:27], v[182:185], v[190:193], v[24:27]
	v_mfma_f32_16x16x32_bf16 v[20:23], v[174:177], v[198:201], v[20:23]
	v_mfma_f32_16x16x32_bf16 v[16:19], v[182:185], v[198:201], v[16:19]
	v_mfma_f32_16x16x32_bf16 v[12:15], v[174:177], v[206:209], v[12:15]
	v_mfma_f32_16x16x32_bf16 v[8:11], v[182:185], v[206:209], v[8:11]
	v_mfma_f32_16x16x32_bf16 v[4:7], v[174:177], v[214:217], v[4:7]
	v_mfma_f32_16x16x32_bf16 v[0:3], v[182:185], v[214:217], v[0:3]
	v_mfma_f32_16x16x32_bf16 v[28:31], v[178:181], v[194:197], v[28:31]
	v_mfma_f32_16x16x32_bf16 v[24:27], v[186:189], v[194:197], v[24:27]
	v_mfma_f32_16x16x32_bf16 v[20:23], v[178:181], v[202:205], v[20:23]
	v_mfma_f32_16x16x32_bf16 v[16:19], v[186:189], v[202:205], v[16:19]
	v_mfma_f32_16x16x32_bf16 v[12:15], v[178:181], v[210:213], v[12:15]
	v_mfma_f32_16x16x32_bf16 v[8:11], v[186:189], v[210:213], v[8:11]
	v_mfma_f32_16x16x32_bf16 v[4:7], v[178:181], v[218:221], v[4:7]
	v_mfma_f32_16x16x32_bf16 v[0:3], v[186:189], v[218:221], v[0:3]
	s_barrier
	s_add_i32 s64, s64, 2
	s_add_u32 s34, s34, 0x100
	s_addc_u32 s35, s35, 0
	s_cmp_gt_u32 s64, 13
	s_cbranch_scc0 .LBB0_782
	s_and_b64 vcc, exec, s[20:21]
	s_cbranch_vccz .LBB0_785
	s_barrier

; __device__ __forceinline__ void h1_phase(unsigned char* lds, unsigned char* ws, bf16_t* SF, int G, int blk) {
;     int tid_l = threadIdx.x; asm volatile("" : "+v"(tid_l)); const int tid = tid_l, lane = tid & 63, wid = __builtin_amdgcn_readfirstlane(tid >> 6), r = lane & 15, kq = lane >> 4;
;     const bf16_t* Z = (const bf16_t*)(ws + WS_Z); bf16_t* VT = (bf16_t*)(lds + L_VT);
;     for (int unit = blk; unit < 2048; unit += G) {
;         const int b = unit >> 10, c = (unit >> 3) & 127, h = unit & 7, chain = b * 8 + h;
;         const bf16_t* zrow = Z + ((size_t)h * M + (size_t)b * SEQ + c * 128 + 16 * wid + r) * 128;
.LBB0_941:
	s_or_b64 exec, exec, s[4:5]
	s_setprio 0
	s_mov_b64 s[4:5], s[0:1]
	s_mov_b32 s20, s2
	s_mov_b32 s21, s74
	s_waitcnt lgkmcnt(0)
	v_mov_b32_e32 v0, v254
	s_barrier
	s_cmpk_gt_i32 s20, 0x7ff
	v_readfirstlane_b32 s3, v0
	s_cbranch_scc1 .LBB0_988
	s_load_dwordx4 s[8:11], s[4:5], 0x88
	v_and_b32_e32 v1, 15, v0
	v_lshrrev_b32_e32 v0, 1, v0
	v_and_b32_e32 v0, 24, v0
	v_lshlrev_b32_e32 v2, 1, v1
	s_waitcnt lgkmcnt(0)
	s_add_u32 s22, s8, 0x4000000
	s_addc_u32 s23, s9, 0
	s_add_u32 s6, s10, 0x6800000
	s_addc_u32 s7, s11, 0
	s_ashr_i32 s3, s3, 2
	s_and_b32 s3, s3, -16
	s_lshl_b32 s8, s3, 1
	s_add_i32 s8, s8, 0
	s_ashr_i32 s9, s3, 31
	s_add_u32 s24, s10, 0x1fa00000
	s_addc_u32 s25, s11, 0
	v_or_b32_e32 v32, s3, v1
	s_add_u32 s26, s10, 0x1a800000
	v_mul_u32_u24_e32 v1, 0x88, v0
	s_addc_u32 s27, s11, 0
	v_lshlrev_b32_e32 v1, 1, v1
	s_add_i32 s8, s8, 0x13000
	v_mov_b32_e32 v35, 0
	v_add3_u32 v81, v1, s8, v2
	s_mov_b64 s[4:5], 0x4000000
	v_mov_b32_e32 v33, s9
	v_add3_u32 v80, s8, v2, v1
	v_add_u32_e32 v82, 0x220, v81
	v_add_u32_e32 v83, 0x440, v81
	v_add_u32_e32 v84, 0x660, v81
	v_add_u32_e32 v85, 0x2200, v81
	v_add_u32_e32 v86, 0x2420, v81
	v_add_u32_e32 v87, 0x2640, v81
	v_add_u32_e32 v88, 0x2860, v81
	v_add_u32_e32 v89, 0x4400, v81
	v_add_u32_e32 v90, 0x4620, v81
	v_add_u32_e32 v91, 0x4840, v81
	v_add_u32_e32 v92, 0x4a60, v81
	v_add_u32_e32 v93, 0x6600, v81
	v_add_u32_e32 v94, 0x6820, v81
	v_add_u32_e32 v95, 0x6a40, v81
	v_add_u32_e32 v96, 0x6c60, v81
	v_lshlrev_b32_e32 v36, 1, v0
	v_mov_b32_e32 v37, v35
	s_mov_b64 s[8:9], 0xc000000
	s_brev_b32 s28, 48
	s_brev_b32 s29, 32
	s_movk_i32 s30, 0x110
	s_mov_b64 s[10:11], 0x8000000
	s_brev_b32 s31, 16
	s_mov_b64 s[12:13], 0x100000
	s_mov_b32 s34, 0x100000
	s_add_i32 s35, 0, 0x13000
	s_branch .LBB0_944

; __device__ __forceinline__ void h2_phase(unsigned char* ws, bf16_t* SF, int G, int blk) {
;     int tid_l = threadIdx.x; asm volatile("" : "+v"(tid_l));
;     const size_t gt = (size_t)blk * 512 + tid_l, GT = (size_t)G * 512;
;     for (size_t w = gt; w < (size_t)32 * 4096; w += GT) {
;         const int ch32 = (int)(w >> 12), dir = ch32 >> 4, chain = ch32 & 15, e4 = (int)(w & 4095);
;         bf16_t* base = (dir ? (bf16_t*)(ws + WS_SB) : SF) + (size_t)chain * 128 * 16384 + (size_t)e4 * 4;
;         const float* dbase = (const float*)(ws + WS_DEC) + ((size_t)(dir * 16 + chain) * 128) * 128 + ((e4 * 4) & 127);
;         f32x4 S = {0.f, 0.f, 0.f, 0.f};
.LBB0_1040:
	s_or_b64 exec, exec, s[4:5]
	s_setprio 0
	s_mov_b64 s[6:7], s[0:1]
	s_mov_b32 s4, s2
	s_mov_b32 s10, s74
	s_waitcnt lgkmcnt(0)
	s_barrier
	v_mov_b32_e32 v0, v254
	s_ashr_i32 s5, s4, 31
	s_lshl_b64 s[4:5], s[4:5], 9
	v_ashrrev_i32_e32 v1, 31, v0
	v_lshl_add_u64 v[0:1], s[4:5], 0, v[0:1]
	s_mov_b64 s[4:5], 0x20000
	v_cmp_gt_u64_e32 vcc, s[4:5], v[0:1]
	s_and_saveexec_b64 s[4:5], vcc
	s_cbranch_execz .LBB0_1045
	s_load_dwordx4 s[12:15], s[6:7], 0x88
	s_mov_b64 s[6:7], 0
	s_mov_b64 s[8:9], 0x10000
	v_mov_b32_e32 v3, 0
	s_waitcnt lgkmcnt(0)
	s_add_u32 s3, s12, 0x4000000
	s_addc_u32 s16, s13, 0
	s_ashr_i32 s11, s10, 31
	s_lshl_b64 s[10:11], s[10:11], 9
	s_add_u32 s17, s14, 0x1a800000
	s_addc_u32 s18, s15, 0
	s_add_u32 s12, s14, 0x1fa00000
	s_addc_u32 s13, s15, 0
	v_mov_b32_e32 v26, s18
	v_mov_b32_e32 v27, s16
	v_mov_b32_e32 v28, s17
	v_mov_b32_e32 v29, s3
	s_mov_b64 s[14:15], 0x1ffff

; template <bool STORE> __device__ __forceinline__ void h3_phase(unsigned char* lds, unsigned char* ws, const bf16_t* SF, const float* norm_g, int G, int blk) {
;     int tid_l = threadIdx.x; asm volatile("" : "+v"(tid_l)); const int tid = tid_l, lane = tid & 63, wid = __builtin_amdgcn_readfirstlane(tid >> 6), r = lane & 15, kq = lane >> 4;
;     bf16_t* Z = (bf16_t*)(ws + WS_Z); bf16_t* VT = (bf16_t*)(lds + L_VT); float* STGF = (float*)(lds + L_KO) + wid * 16 * 132;
;     for (int unit = blk; unit < 2048; unit += G) {
;         const int b = unit >> 10, c = (unit >> 3) & 127, h = unit & 7, chain = b * 8 + h;
;         const size_t tok0 = (size_t)b * SEQ + c * 128 + 16 * wid;
;         const bf16_t* zrow = Z + ((size_t)h * M + tok0 + r) * 128;
.LBB0_1097:
	s_or_b64 exec, exec, s[4:5]
	s_setprio 0
	s_mov_b64 s[4:5], s[0:1]
	s_mov_b32 s16, s2
	s_mov_b32 s17, s74
	s_waitcnt lgkmcnt(0)
	v_mov_b32_e32 v0, v254
	s_barrier
	s_cmpk_gt_i32 s16, 0x7ff
	v_readfirstlane_b32 s3, v0
	s_cbranch_scc1 .LBB0_1120
	s_load_dwordx4 s[12:15], s[4:5], 0x88
	s_load_dwordx2 s[6:7], s[4:5], 0x38
	v_and_b32_e32 v112, 15, v0
	v_bfe_u32 v114, v0, 4, 2
	v_lshlrev_b32_e32 v0, 3, v0
	s_waitcnt lgkmcnt(0)
	s_add_u32 s18, s12, 0x4000000
	s_addc_u32 s19, s13, 0
	s_add_u32 s10, s14, 0x6800000
	s_addc_u32 s11, s15, 0
	s_ashr_i32 s3, s3, 2
	s_and_b32 s20, s3, -16
	s_mul_i32 s3, s20, 0x210
	s_lshl_b32 s5, s20, 1
	v_and_b32_e32 v0, 0x78, v0
	s_mov_b32 s4, 0
	s_add_i32 s3, s3, 0
	v_mov_b32_e32 v117, 0
	s_add_i32 s5, s5, 0
	v_lshlrev_b32_e32 v116, 2, v0
	v_mul_u32_u24_e32 v5, 0x440, v114
	s_ashr_i32 s21, s20, 31
	s_add_i32 s5, s5, 0x13000
	v_lshlrev_b32_e32 v1, 1, v112
	v_add_u32_e32 v4, s3, v116
	v_lshl_add_u64 v[118:119], s[6:7], 0, v[116:117]
	v_lshlrev_b32_e32 v116, 1, v0
	v_mul_u32_u24_e32 v0, 0x210, v114
	v_lshlrev_b32_e32 v5, 1, v5
	v_or_b32_e32 v122, 4, v114
	s_mov_b32 s6, s4
	s_mov_b32 s7, s4
	v_lshlrev_b32_e32 v2, 3, v114
	s_add_u32 s22, s14, 0x1a800000
	v_lshl_add_u32 v3, v112, 2, s3
	v_add3_u32 v113, s5, v1, v5
	v_add3_u32 v115, s5, v5, v1
	v_mul_u32_u24_e32 v1, 0x840, v114
	v_mul_u32_u24_e32 v5, 0x210, v122
	s_mov_b32 s5, s4
	v_mov_b64_e32 v[186:187], s[6:7]
	v_add_u32_e32 v145, v4, v0
	v_mbcnt_lo_u32_b32 v0, -1, 0
	s_mov_b64 s[8:9], 0x4000000
	s_addc_u32 s23, s15, 0
	v_lshl_add_u64 v[120:121], s[10:11], 0, v[116:117]
	s_movk_i32 s24, 0x440
	v_add_u32_e32 v123, 0x220, v113
	v_add_u32_e32 v125, 0x440, v113
	v_add_u32_e32 v127, 0x660, v113
	v_add_u32_e32 v130, 0x2200, v113
	v_add_u32_e32 v131, 0x2420, v113
	v_add_u32_e32 v132, 0x2640, v113
	v_add_u32_e32 v133, 0x2860, v113
	v_add_u32_e32 v134, 0x4400, v113
	v_add_u32_e32 v135, 0x4620, v113
	v_add_u32_e32 v136, 0x4840, v113
	v_add_u32_e32 v137, 0x4a60, v113
	v_add_u32_e32 v138, 0x6600, v113
	v_add_u32_e32 v139, 0x6820, v113
	v_add_u32_e32 v140, 0x6a40, v113
	v_add_u32_e32 v141, 0x6c60, v113
	v_or_b32_e32 v124, 8, v114
	v_or_b32_e32 v126, 12, v114
	v_lshlrev_b32_e32 v128, 1, v2
	v_mov_b32_e32 v129, v117
	s_mov_b64 s[12:13], 0xc000000
	s_brev_b32 s25, 48
	s_brev_b32 s26, 32
	s_movk_i32 s27, 0x110
	v_mov_b64_e32 v[184:185], s[4:5]
	s_mov_b64 s[14:15], 0x8000000
	s_brev_b32 s28, 16
	v_mov_b32_e32 v142, 0x3727c5ac
	s_mov_b32 s29, 0xf800000
	v_mov_b32_e32 v143, 0x260
	v_add_u32_e32 v144, v3, v1
	s_brev_b32 s30, 8
	v_add_u32_e32 v146, v4, v5
	v_mbcnt_hi_u32_b32 v147, -1, v0
	s_branch .LBB0_1100

;     __host__ __device__ bool next(int i, Unit& u) const {
;         const long L = (long)i * G + c; if (L >= nwg) return false;
;         int wgid = (int)L; { const int q = nwg / NXCD, r = nwg % NXCD, xcd = wgid % NXCD, off = wgid / NXCD; wgid = (xcd < r ? xcd * (q + 1) : r * (q + 1) + (xcd - r) * q) + off; }
;         const int nig = WGM * nN, gid = wgid / nig, fm = gid * WGM, gsz = (nM - fm) < WGM ? (nM - fm) : WGM;
;         u.pm = fm + ((wgid % nig) % gsz); u.pn = (wgid % nig) / gsz; return true;
; template <class Epi, class Sched, bool ALIGN_EPI = false, bool SP2 = false>
; __device__ __forceinline__ void gemm_phase(PG8_LAS unsigned char* lds, const Gemm g, const Sched& S, const Epi& E) {
;     ...
;     Unit cur, nxt; int ui = 0;
;     if (!S.next(0, cur)) return;
.Lprio_out1:
	s_mov_b64 s[4:5], s[0:1]
	s_mov_b32 s23, s2
	s_mov_b32 s44, s74
	s_waitcnt lgkmcnt(0)
	s_barrier
	v_mov_b32_e32 v8, v254
	s_cmpk_lt_i32 s23, 0x200
	s_cselect_b64 s[6:7], -1, 0
	s_cmpk_gt_i32 s23, 0x1ff
	v_readfirstlane_b32 s3, v8
	s_cbranch_scc1 .LBB0_1178
	s_ashr_i32 s8, s23, 31
	s_lshr_b32 s8, s8, 29
	s_add_i32 s12, s23, s8
	s_and_b32 s8, s12, -8
	s_sub_i32 s10, s23, s8
	s_cmp_gt_i32 s10, -1
	s_cbranch_scc0 .LBB0_1175
	s_lshl_b32 s11, s10, 6
	s_ashr_i32 s8, s12, 3
	s_cbranch_execz .LBB0_1176
	s_branch .LBB0_1177

; #define PG8_STAGE(bufoff, gbase, voff) do { _Pragma("unroll") for (int _i = 0; _i < 2; ++_i) \
;         __builtin_amdgcn_global_load_lds((const unsigned*)((const char*)(gbase) + (voff)[_i]), (PG8_LAS unsigned*)(lds + (bufoff) + ldsw + _i * 8192), 16, 0, 0); } while (0)
; #define PG8_LDA(dst, b, h) do { _Pragma("unroll") for (int m = 0; m < 4; ++m) _Pragma("unroll") for (int k = 0; k < 2; ++k) dst[m][k] = *(const PG8_LAS bf16x8*)(lds + PG8_SA(b, h) + aoff + m * 2048 + k * 1024); } while (0)
; #define PG8_LDB(dst, b, h) do { _Pragma("unroll") for (int n = 0; n < 2; ++n) _Pragma("unroll") for (int k = 0; k < 2; ++k) dst[n][k] = *(const PG8_LAS bf16x8*)(lds + PG8_SB(b, h) + boff + n * 2048 + k * 1024); } while (0)
; #define PG8_MMA(ai, bj, At, Bt) do { __builtin_amdgcn_s_setprio(1); _Pragma("unroll") for (int m = 0; m < 4; ++m) _Pragma("unroll") for (int n = 0; n < 2; ++n) _Pragma("unroll") for (int k = 0; k < 2; ++k) \
;         acc[ai][bj][m][n] = __builtin_amdgcn_mfma_f32_16x16x32_bf16(Bt[n][k], At[m][k], acc[ai][bj][m][n], 0, 0, 0); __builtin_amdgcn_s_setprio(0); } while (0)
; #define PG8_WAIT_V(n) asm volatile("s_waitcnt vmcnt(" #n ")" ::: "memory")
; #define PG8_WAIT_L(n) asm volatile("s_waitcnt lgkmcnt(" #n ")" ::: "memory")
; #define PG8_BAR __builtin_amdgcn_s_barrier()
; #define PG8_SCHED __builtin_amdgcn_sched_barrier(0)
; template <class Epi, class Sched, bool ALIGN_EPI = false, bool SP2 = false>
; __device__ __forceinline__ void gemm_phase(PG8_LAS unsigned char* lds, const Gemm g, const Sched& S, const Epi& E) {
;     ...
;             const bool last = (t == nt - 2);
;             const char* a1 = cA + PG8_AK(t + 1);
;             const char* a2 = last ? nA : cA + PG8_AK(t + 2); const char* b2 = last ? nB : cB + (size_t)(t + 2) * kstep;
;             const char* a3 = last ? nA + PG8_AK(1) : cA + PG8_AK(t + 3); const char* b3 = b2 + kstep;
;             if (last && has_next) S.a_ready(nxt);
;             if constexpr (SP2) {
;             PG8_LDB(B0, 0, 0); PG8_LDB(B1, 0, 1); PG8_SCHED; PG8_LDA(At, 0, 0); PG8_STAGE(PG8_SA(1, 1), a1 + hstepA, voffA);
;             PG8_WAIT_V(8); PG8_WAIT_L(0); PG8_BAR; PG8_MMA(0, 0, At, B0); PG8_MMA(0, 1, At, B1); PG8_BAR; PG8_SCHED;
;             PG8_LDA(At, 0, 1); PG8_STAGE(PG8_SB(0, 0), b2, voffB); PG8_STAGE(PG8_SB(0, 1), b2 + hstepB, voffB); PG8_STAGE(PG8_SA(0, 0), a2, voffA);
.LBB0_1191:
	ds_read_b128 v[128:131], v191
	ds_read_b128 v[132:135], v191 offset:1024
	ds_read_b128 v[136:139], v191 offset:2048
	ds_read_b128 v[140:143], v191 offset:3072
	ds_read_b128 v[162:165], v192
	ds_read_b128 v[166:169], v192 offset:1024
	ds_read_b128 v[194:197], v192 offset:2048
	ds_read_b128 v[198:201], v192 offset:3072
	s_add_u32 s38, s36, 0x800000
	s_addc_u32 s39, s37, 0
	s_cmp_eq_u32 s67, 12
	s_cselect_b32 s43, s3, s39
	s_cselect_b32 s42, s27, s38
	s_cselect_b32 s41, s25, s66
	s_cselect_b32 s40, s35, s65
	v_lshl_add_u64 v[170:171], s[36:37], 0, v[156:157]
	s_add_i32 m0, s50, 0xc000
	ds_read_b128 v[202:205], v174
	ds_read_b128 v[206:209], v174 offset:1024
	ds_read_b128 v[210:213], v174 offset:2048
	ds_read_b128 v[214:217], v174 offset:3072
	ds_read_b128 v[218:221], v174 offset:4096
	ds_read_b128 v[222:225], v174 offset:5120
	ds_read_b128 v[226:229], v174 offset:6144
	ds_read_b128 v[230:233], v174 offset:7168
	global_load_lds_dwordx4 v[170:171], off
	v_lshl_add_u64 v[170:171], s[36:37], 0, v[154:155]
	s_add_i32 m0, s50, 0xe000
	s_nop 0
	global_load_lds_dwordx4 v[170:171], off
	s_waitcnt vmcnt(8)
	s_waitcnt lgkmcnt(0)
	s_barrier
	s_waitcnt lgkmcnt(0)
	v_mfma_f32_16x16x32_bf16 v[124:127], v[128:131], v[202:205], v[124:127]
	v_mfma_f32_16x16x32_bf16 v[120:123], v[136:139], v[202:205], v[120:123]
	v_mfma_f32_16x16x32_bf16 v[116:119], v[128:131], v[210:213], v[116:119]
	v_mfma_f32_16x16x32_bf16 v[112:115], v[136:139], v[210:213], v[112:115]
	v_mfma_f32_16x16x32_bf16 v[108:111], v[128:131], v[218:221], v[108:111]
	v_mfma_f32_16x16x32_bf16 v[104:107], v[136:139], v[218:221], v[104:107]
	v_mfma_f32_16x16x32_bf16 v[100:103], v[128:131], v[226:229], v[100:103]
	v_mfma_f32_16x16x32_bf16 v[96:99], v[136:139], v[226:229], v[96:99]
	v_mfma_f32_16x16x32_bf16 v[124:127], v[132:135], v[206:209], v[124:127]
	v_mfma_f32_16x16x32_bf16 v[120:123], v[140:143], v[206:209], v[120:123]
	v_mfma_f32_16x16x32_bf16 v[116:119], v[132:135], v[214:217], v[116:119]
	v_mfma_f32_16x16x32_bf16 v[112:115], v[140:143], v[214:217], v[112:115]
	v_mfma_f32_16x16x32_bf16 v[108:111], v[132:135], v[222:225], v[108:111]
	v_mfma_f32_16x16x32_bf16 v[104:107], v[140:143], v[222:225], v[104:107]
	v_mfma_f32_16x16x32_bf16 v[100:103], v[132:135], v[230:233], v[100:103]
	v_mfma_f32_16x16x32_bf16 v[96:99], v[140:143], v[230:233], v[96:99]
	v_mfma_f32_16x16x32_bf16 v[60:63], v[162:165], v[202:205], v[60:63]
	v_mfma_f32_16x16x32_bf16 v[56:59], v[194:197], v[202:205], v[56:59]
	v_mfma_f32_16x16x32_bf16 v[52:55], v[162:165], v[210:213], v[52:55]
	v_mfma_f32_16x16x32_bf16 v[48:51], v[194:197], v[210:213], v[48:51]
	v_mfma_f32_16x16x32_bf16 v[44:47], v[162:165], v[218:221], v[44:47]
	v_mfma_f32_16x16x32_bf16 v[40:43], v[194:197], v[218:221], v[40:43]
	v_mfma_f32_16x16x32_bf16 v[36:39], v[162:165], v[226:229], v[36:39]
	v_mfma_f32_16x16x32_bf16 v[32:35], v[194:197], v[226:229], v[32:35]
	v_mfma_f32_16x16x32_bf16 v[60:63], v[166:169], v[206:209], v[60:63]
	v_mfma_f32_16x16x32_bf16 v[56:59], v[198:201], v[206:209], v[56:59]
	v_mfma_f32_16x16x32_bf16 v[52:55], v[166:169], v[214:217], v[52:55]
	v_mfma_f32_16x16x32_bf16 v[48:51], v[198:201], v[214:217], v[48:51]
	v_mfma_f32_16x16x32_bf16 v[44:47], v[166:169], v[222:225], v[44:47]
	v_mfma_f32_16x16x32_bf16 v[40:43], v[198:201], v[222:225], v[40:43]
	v_mfma_f32_16x16x32_bf16 v[36:39], v[166:169], v[230:233], v[36:39]
	v_mfma_f32_16x16x32_bf16 v[32:35], v[198:201], v[230:233], v[32:35]
	s_barrier
	s_add_i32 s36, s62, s49
	v_lshl_add_u64 v[170:171], s[40:41], 0, v[146:147]
	s_mov_b32 m0, s36
	ds_read_b128 v[202:205], v174 offset:16384
	ds_read_b128 v[206:209], v174 offset:17408
	ds_read_b128 v[210:213], v174 offset:18432
	ds_read_b128 v[214:217], v174 offset:19456
	ds_read_b128 v[218:221], v174 offset:20480
	ds_read_b128 v[222:225], v174 offset:21504
	ds_read_b128 v[226:229], v174 offset:22528
	ds_read_b128 v[230:233], v174 offset:23552
	global_load_lds_dwordx4 v[170:171], off
	s_add_i32 m0, s36, 0x2000
	s_add_u32 s36, s40, 0x40000
	v_lshl_add_u64 v[234:235], s[40:41], 0, v[150:151]
	s_addc_u32 s37, s41, 0
	s_add_i32 s68, s63, s49
	global_load_lds_dwordx4 v[234:235], off
	v_lshl_add_u64 v[236:237], s[36:37], 0, v[146:147]
	s_mov_b32 m0, s68
	v_lshl_add_u64 v[238:239], s[42:43], 0, v[148:149]
	global_load_lds_dwordx4 v[236:237], off
	v_lshl_add_u64 v[236:237], s[36:37], 0, v[150:151]
	s_add_i32 m0, s68, 0x2000
	s_nop 0
	global_load_lds_dwordx4 v[236:237], off
	v_lshl_add_u64 v[236:237], s[42:43], 0, v[144:145]
	s_mov_b32 m0, s50
	s_nop 0
	global_load_lds_dwordx4 v[236:237], off
	s_mov_b32 m0, s51
	s_nop 0
	global_load_lds_dwordx4 v[238:239], off
	s_waitcnt vmcnt(8)
	s_waitcnt lgkmcnt(0)
	s_barrier
; #define PG8_STAGE(bufoff, gbase, voff) do { _Pragma("unroll") for (int _i = 0; _i < 2; ++_i) \
;         __builtin_amdgcn_global_load_lds((const unsigned*)((const char*)(gbase) + (voff)[_i]), (PG8_LAS unsigned*)(lds + (bufoff) + ldsw + _i * 8192), 16, 0, 0); } while (0)
; #define PG8_LDA(dst, b, h) do { _Pragma("unroll") for (int m = 0; m < 4; ++m) _Pragma("unroll") for (int k = 0; k < 2; ++k) dst[m][k] = *(const PG8_LAS bf16x8*)(lds + PG8_SA(b, h) + aoff + m * 2048 + k * 1024); } while (0)
; #define PG8_LDB(dst, b, h) do { _Pragma("unroll") for (int n = 0; n < 2; ++n) _Pragma("unroll") for (int k = 0; k < 2; ++k) dst[n][k] = *(const PG8_LAS bf16x8*)(lds + PG8_SB(b, h) + boff + n * 2048 + k * 1024); } while (0)
; #define PG8_MMA(ai, bj, At, Bt) do { __builtin_amdgcn_s_setprio(1); _Pragma("unroll") for (int m = 0; m < 4; ++m) _Pragma("unroll") for (int n = 0; n < 2; ++n) _Pragma("unroll") for (int k = 0; k < 2; ++k) \
;         acc[ai][bj][m][n] = __builtin_amdgcn_mfma_f32_16x16x32_bf16(Bt[n][k], At[m][k], acc[ai][bj][m][n], 0, 0, 0); __builtin_amdgcn_s_setprio(0); } while (0)
; #define PG8_WAIT_V(n) asm volatile("s_waitcnt vmcnt(" #n ")" ::: "memory")
; #define PG8_WAIT_L(n) asm volatile("s_waitcnt lgkmcnt(" #n ")" ::: "memory")
; #define PG8_BAR __builtin_amdgcn_s_barrier()
; #define PG8_SCHED __builtin_amdgcn_sched_barrier(0)
; template <class Epi, class Sched, bool ALIGN_EPI = false, bool SP2 = false>
; __device__ __forceinline__ void gemm_phase(PG8_LAS unsigned char* lds, const Gemm g, const Sched& S, const Epi& E) {
;     ...
;             PG8_WAIT_V(8); PG8_WAIT_L(0); PG8_BAR; PG8_MMA(1, 0, At, B0); PG8_MMA(1, 1, At, B1); PG8_BAR; PG8_SCHED;
;             PG8_LDB(B0, 1, 0); PG8_LDB(B1, 1, 1); PG8_SCHED; PG8_LDA(At, 1, 0); PG8_STAGE(PG8_SA(0, 1), a2 + hstepA, voffA);
;             PG8_WAIT_V(8); PG8_WAIT_L(0); PG8_BAR; PG8_MMA(0, 0, At, B0); PG8_MMA(0, 1, At, B1); PG8_BAR; PG8_SCHED;
	s_waitcnt lgkmcnt(0)
	v_mfma_f32_16x16x32_bf16 v[92:95], v[128:131], v[202:205], v[92:95]
	v_mfma_f32_16x16x32_bf16 v[88:91], v[136:139], v[202:205], v[88:91]
	v_mfma_f32_16x16x32_bf16 v[84:87], v[128:131], v[210:213], v[84:87]
	v_mfma_f32_16x16x32_bf16 v[80:83], v[136:139], v[210:213], v[80:83]
	v_mfma_f32_16x16x32_bf16 v[76:79], v[128:131], v[218:221], v[76:79]
	v_mfma_f32_16x16x32_bf16 v[72:75], v[136:139], v[218:221], v[72:75]
	v_mfma_f32_16x16x32_bf16 v[68:71], v[128:131], v[226:229], v[68:71]
	v_mfma_f32_16x16x32_bf16 v[64:67], v[136:139], v[226:229], v[64:67]
	v_mfma_f32_16x16x32_bf16 v[92:95], v[132:135], v[206:209], v[92:95]
	v_mfma_f32_16x16x32_bf16 v[88:91], v[140:143], v[206:209], v[88:91]
	v_mfma_f32_16x16x32_bf16 v[84:87], v[132:135], v[214:217], v[84:87]
	v_mfma_f32_16x16x32_bf16 v[80:83], v[140:143], v[214:217], v[80:83]
	v_mfma_f32_16x16x32_bf16 v[76:79], v[132:135], v[222:225], v[76:79]
	v_mfma_f32_16x16x32_bf16 v[72:75], v[140:143], v[222:225], v[72:75]
	v_mfma_f32_16x16x32_bf16 v[68:71], v[132:135], v[230:233], v[68:71]
	v_mfma_f32_16x16x32_bf16 v[64:67], v[140:143], v[230:233], v[64:67]
	v_mfma_f32_16x16x32_bf16 v[28:31], v[162:165], v[202:205], v[28:31]
	v_mfma_f32_16x16x32_bf16 v[24:27], v[194:197], v[202:205], v[24:27]
	v_mfma_f32_16x16x32_bf16 v[20:23], v[162:165], v[210:213], v[20:23]
	v_mfma_f32_16x16x32_bf16 v[16:19], v[194:197], v[210:213], v[16:19]
	v_mfma_f32_16x16x32_bf16 v[12:15], v[162:165], v[218:221], v[12:15]
	v_mfma_f32_16x16x32_bf16 v[8:11], v[194:197], v[218:221], v[8:11]
	v_mfma_f32_16x16x32_bf16 v[4:7], v[162:165], v[226:229], v[4:7]
	v_mfma_f32_16x16x32_bf16 v[0:3], v[194:197], v[226:229], v[0:3]
	v_mfma_f32_16x16x32_bf16 v[28:31], v[166:169], v[206:209], v[28:31]
	v_mfma_f32_16x16x32_bf16 v[24:27], v[198:201], v[206:209], v[24:27]
	v_mfma_f32_16x16x32_bf16 v[20:23], v[166:169], v[214:217], v[20:23]
	v_mfma_f32_16x16x32_bf16 v[16:19], v[198:201], v[214:217], v[16:19]
	v_mfma_f32_16x16x32_bf16 v[12:15], v[166:169], v[222:225], v[12:15]
	v_mfma_f32_16x16x32_bf16 v[8:11], v[198:201], v[222:225], v[8:11]
	v_mfma_f32_16x16x32_bf16 v[4:7], v[166:169], v[230:233], v[4:7]
	v_mfma_f32_16x16x32_bf16 v[0:3], v[198:201], v[230:233], v[0:3]
	s_barrier
	s_add_i32 s68, 0, 0x18000
	s_add_i32 s69, 0, 0x1c000
	v_add_u32_e32 v140, s68, v173
	v_add_u32_e32 v153, s69, v173
	ds_read_b128 v[128:131], v140
	ds_read_b128 v[132:135], v140 offset:1024
	ds_read_b128 v[136:139], v140 offset:2048
	ds_read_b128 v[140:143], v140 offset:3072
	ds_read_b128 v[162:165], v153
	ds_read_b128 v[166:169], v153 offset:1024
	ds_read_b128 v[194:197], v153 offset:2048
	ds_read_b128 v[198:201], v153 offset:3072
	s_add_u32 s36, s42, 0x8000
	s_addc_u32 s37, s43, 0
	s_mov_b32 m0, s52
	v_lshl_add_u64 v[240:241], s[36:37], 0, v[144:145]
	ds_read_b128 v[202:205], v174 offset:32768
	ds_read_b128 v[206:209], v174 offset:33792
	ds_read_b128 v[210:213], v174 offset:34816
	ds_read_b128 v[214:217], v174 offset:35840
	ds_read_b128 v[218:221], v174 offset:36864
	ds_read_b128 v[222:225], v174 offset:37888
	ds_read_b128 v[226:229], v174 offset:38912
	ds_read_b128 v[230:233], v174 offset:39936
	global_load_lds_dwordx4 v[240:241], off
	v_lshl_add_u64 v[240:241], s[36:37], 0, v[148:149]
	s_mov_b32 m0, s53
	s_nop 0
	global_load_lds_dwordx4 v[240:241], off
	s_waitcnt vmcnt(8)
	s_waitcnt lgkmcnt(0)
	s_barrier
	s_waitcnt lgkmcnt(0)
	v_mfma_f32_16x16x32_bf16 v[124:127], v[128:131], v[202:205], v[124:127]
	v_mfma_f32_16x16x32_bf16 v[120:123], v[136:139], v[202:205], v[120:123]
	v_mfma_f32_16x16x32_bf16 v[116:119], v[128:131], v[210:213], v[116:119]
	v_mfma_f32_16x16x32_bf16 v[112:115], v[136:139], v[210:213], v[112:115]
	v_mfma_f32_16x16x32_bf16 v[108:111], v[128:131], v[218:221], v[108:111]
	v_mfma_f32_16x16x32_bf16 v[104:107], v[136:139], v[218:221], v[104:107]
	v_mfma_f32_16x16x32_bf16 v[100:103], v[128:131], v[226:229], v[100:103]
	v_mfma_f32_16x16x32_bf16 v[96:99], v[136:139], v[226:229], v[96:99]
	v_mfma_f32_16x16x32_bf16 v[124:127], v[132:135], v[206:209], v[124:127]
	v_mfma_f32_16x16x32_bf16 v[120:123], v[140:143], v[206:209], v[120:123]
	v_mfma_f32_16x16x32_bf16 v[116:119], v[132:135], v[214:217], v[116:119]
	v_mfma_f32_16x16x32_bf16 v[112:115], v[140:143], v[214:217], v[112:115]
	v_mfma_f32_16x16x32_bf16 v[108:111], v[132:135], v[222:225], v[108:111]
	v_mfma_f32_16x16x32_bf16 v[104:107], v[140:143], v[222:225], v[104:107]
	v_mfma_f32_16x16x32_bf16 v[100:103], v[132:135], v[230:233], v[100:103]
	v_mfma_f32_16x16x32_bf16 v[96:99], v[140:143], v[230:233], v[96:99]
	v_mfma_f32_16x16x32_bf16 v[60:63], v[162:165], v[202:205], v[60:63]
	v_mfma_f32_16x16x32_bf16 v[56:59], v[194:197], v[202:205], v[56:59]
	v_mfma_f32_16x16x32_bf16 v[52:55], v[162:165], v[210:213], v[52:55]
	v_mfma_f32_16x16x32_bf16 v[48:51], v[194:197], v[210:213], v[48:51]
	v_mfma_f32_16x16x32_bf16 v[44:47], v[162:165], v[218:221], v[44:47]
	v_mfma_f32_16x16x32_bf16 v[40:43], v[194:197], v[218:221], v[40:43]
	v_mfma_f32_16x16x32_bf16 v[36:39], v[162:165], v[226:229], v[36:39]
	v_mfma_f32_16x16x32_bf16 v[32:35], v[194:197], v[226:229], v[32:35]
	v_mfma_f32_16x16x32_bf16 v[60:63], v[166:169], v[206:209], v[60:63]
	v_mfma_f32_16x16x32_bf16 v[56:59], v[198:201], v[206:209], v[56:59]
	v_mfma_f32_16x16x32_bf16 v[52:55], v[166:169], v[214:217], v[52:55]
	v_mfma_f32_16x16x32_bf16 v[48:51], v[198:201], v[214:217], v[48:51]
	v_mfma_f32_16x16x32_bf16 v[44:47], v[166:169], v[222:225], v[44:47]
	v_mfma_f32_16x16x32_bf16 v[40:43], v[198:201], v[222:225], v[40:43]
	v_mfma_f32_16x16x32_bf16 v[36:39], v[166:169], v[230:233], v[36:39]
	v_mfma_f32_16x16x32_bf16 v[32:35], v[198:201], v[230:233], v[32:35]
	s_barrier
; #define PG8_STAGE(bufoff, gbase, voff) do { _Pragma("unroll") for (int _i = 0; _i < 2; ++_i) \
;         __builtin_amdgcn_global_load_lds((const unsigned*)((const char*)(gbase) + (voff)[_i]), (PG8_LAS unsigned*)(lds + (bufoff) + ldsw + _i * 8192), 16, 0, 0); } while (0)
; #define PG8_LDA(dst, b, h) do { _Pragma("unroll") for (int m = 0; m < 4; ++m) _Pragma("unroll") for (int k = 0; k < 2; ++k) dst[m][k] = *(const PG8_LAS bf16x8*)(lds + PG8_SA(b, h) + aoff + m * 2048 + k * 1024); } while (0)
; #define PG8_MMA(ai, bj, At, Bt) do { __builtin_amdgcn_s_setprio(1); _Pragma("unroll") for (int m = 0; m < 4; ++m) _Pragma("unroll") for (int n = 0; n < 2; ++n) _Pragma("unroll") for (int k = 0; k < 2; ++k) \
;         acc[ai][bj][m][n] = __builtin_amdgcn_mfma_f32_16x16x32_bf16(Bt[n][k], At[m][k], acc[ai][bj][m][n], 0, 0, 0); __builtin_amdgcn_s_setprio(0); } while (0)
; #define PG8_WAIT_V(n) asm volatile("s_waitcnt vmcnt(" #n ")" ::: "memory")
; #define PG8_WAIT_L(n) asm volatile("s_waitcnt lgkmcnt(" #n ")" ::: "memory")
; #define PG8_BAR __builtin_amdgcn_s_barrier()
; #define PG8_SCHED __builtin_amdgcn_sched_barrier(0)
; template <class Epi, class Sched, bool ALIGN_EPI = false, bool SP2 = false>
; __device__ __forceinline__ void gemm_phase(PG8_LAS unsigned char* lds, const Gemm g, const Sched& S, const Epi& E) {
;     ...
;         for (int t = 0; t < nt; t += 2) {
;     ...
;             PG8_LDA(At, 1, 1); PG8_STAGE(PG8_SB(1, 0), b3, voffB); PG8_STAGE(PG8_SB(1, 1), b3 + hstepB, voffB); PG8_STAGE(PG8_SA(1, 0), a3, voffA);
;             PG8_WAIT_V(8); PG8_WAIT_L(0); PG8_BAR; PG8_MMA(1, 0, At, B0); PG8_MMA(1, 1, At, B1); PG8_BAR; PG8_SCHED;
	s_add_i32 s36, s68, s49
	v_lshl_add_u64 v[170:171], v[170:171], 0, s[18:19]
	s_mov_b32 m0, s36
	ds_read_b128 v[202:205], v174 offset:49152
	ds_read_b128 v[206:209], v174 offset:50176
	ds_read_b128 v[210:213], v174 offset:51200
	ds_read_b128 v[214:217], v174 offset:52224
	ds_read_b128 v[218:221], v174 offset:53248
	ds_read_b128 v[222:225], v174 offset:54272
	ds_read_b128 v[226:229], v174 offset:55296
	ds_read_b128 v[230:233], v174 offset:56320
	global_load_lds_dwordx4 v[170:171], off
	s_add_i32 m0, s36, 0x2000
	s_add_u32 s36, s40, 0x40080
	v_lshl_add_u64 v[170:171], v[234:235], 0, s[18:19]
	s_addc_u32 s37, s41, 0
	s_add_i32 s40, s69, s49
	global_load_lds_dwordx4 v[170:171], off
	v_lshl_add_u64 v[170:171], s[36:37], 0, v[146:147]
	s_mov_b32 m0, s40
	s_nop 0
	global_load_lds_dwordx4 v[170:171], off
	v_lshl_add_u64 v[170:171], s[36:37], 0, v[150:151]
	s_add_i32 m0, s40, 0x2000
	s_nop 0
	global_load_lds_dwordx4 v[170:171], off
	v_lshl_add_u64 v[170:171], v[236:237], 0, s[18:19]
	s_mov_b32 m0, s58
	s_nop 0
	global_load_lds_dwordx4 v[170:171], off
	v_lshl_add_u64 v[170:171], v[238:239], 0, s[18:19]
	s_mov_b32 m0, s59
	s_nop 0
	global_load_lds_dwordx4 v[170:171], off
	s_waitcnt vmcnt(8)
	s_waitcnt lgkmcnt(0)
	s_barrier
	s_waitcnt lgkmcnt(0)
	v_mfma_f32_16x16x32_bf16 v[92:95], v[128:131], v[202:205], v[92:95]
	v_mfma_f32_16x16x32_bf16 v[88:91], v[136:139], v[202:205], v[88:91]
	v_mfma_f32_16x16x32_bf16 v[84:87], v[128:131], v[210:213], v[84:87]
	v_mfma_f32_16x16x32_bf16 v[80:83], v[136:139], v[210:213], v[80:83]
	v_mfma_f32_16x16x32_bf16 v[76:79], v[128:131], v[218:221], v[76:79]
	v_mfma_f32_16x16x32_bf16 v[72:75], v[136:139], v[218:221], v[72:75]
	v_mfma_f32_16x16x32_bf16 v[68:71], v[128:131], v[226:229], v[68:71]
	v_mfma_f32_16x16x32_bf16 v[64:67], v[136:139], v[226:229], v[64:67]
	v_mfma_f32_16x16x32_bf16 v[92:95], v[132:135], v[206:209], v[92:95]
	v_mfma_f32_16x16x32_bf16 v[88:91], v[140:143], v[206:209], v[88:91]
	v_mfma_f32_16x16x32_bf16 v[84:87], v[132:135], v[214:217], v[84:87]
	v_mfma_f32_16x16x32_bf16 v[80:83], v[140:143], v[214:217], v[80:83]
	v_mfma_f32_16x16x32_bf16 v[76:79], v[132:135], v[222:225], v[76:79]
	v_mfma_f32_16x16x32_bf16 v[72:75], v[140:143], v[222:225], v[72:75]
	v_mfma_f32_16x16x32_bf16 v[68:71], v[132:135], v[230:233], v[68:71]
	v_mfma_f32_16x16x32_bf16 v[64:67], v[140:143], v[230:233], v[64:67]
	v_mfma_f32_16x16x32_bf16 v[28:31], v[162:165], v[202:205], v[28:31]
	v_mfma_f32_16x16x32_bf16 v[24:27], v[194:197], v[202:205], v[24:27]
	v_mfma_f32_16x16x32_bf16 v[20:23], v[162:165], v[210:213], v[20:23]
	v_mfma_f32_16x16x32_bf16 v[16:19], v[194:197], v[210:213], v[16:19]
	v_mfma_f32_16x16x32_bf16 v[12:15], v[162:165], v[218:221], v[12:15]
	v_mfma_f32_16x16x32_bf16 v[8:11], v[194:197], v[218:221], v[8:11]
	v_mfma_f32_16x16x32_bf16 v[4:7], v[162:165], v[226:229], v[4:7]
	v_mfma_f32_16x16x32_bf16 v[0:3], v[194:197], v[226:229], v[0:3]
	v_mfma_f32_16x16x32_bf16 v[28:31], v[166:169], v[206:209], v[28:31]
	v_mfma_f32_16x16x32_bf16 v[24:27], v[198:201], v[206:209], v[24:27]
	v_mfma_f32_16x16x32_bf16 v[20:23], v[166:169], v[214:217], v[20:23]
	v_mfma_f32_16x16x32_bf16 v[16:19], v[198:201], v[214:217], v[16:19]
	v_mfma_f32_16x16x32_bf16 v[12:15], v[166:169], v[222:225], v[12:15]
	v_mfma_f32_16x16x32_bf16 v[8:11], v[198:201], v[222:225], v[8:11]
	v_mfma_f32_16x16x32_bf16 v[4:7], v[166:169], v[230:233], v[4:7]
	v_mfma_f32_16x16x32_bf16 v[0:3], v[198:201], v[230:233], v[0:3]
	s_barrier
	s_add_i32 s67, s67, 2
	s_add_u32 s65, s65, 0x100
	s_addc_u32 s66, s66, 0
	s_cmp_gt_u32 s67, 13
	s_mov_b64 s[36:37], s[38:39]
	s_cbranch_scc0 .LBB0_1191
	s_and_b64 vcc, exec, s[20:21]
	s_cbranch_vccz .LBB0_1194
	s_barrier

; #define PG8_STAGE(bufoff, gbase, voff) do { _Pragma("unroll") for (int _i = 0; _i < 2; ++_i) \
;         __builtin_amdgcn_global_load_lds((const unsigned*)((const char*)(gbase) + (voff)[_i]), (PG8_LAS unsigned*)(lds + (bufoff) + ldsw + _i * 8192), 16, 0, 0); } while (0)
; #define PG8_WAIT_V(n) asm volatile("s_waitcnt vmcnt(" #n ")" ::: "memory")
; #define PG8_BAR __builtin_amdgcn_s_barrier()
; template <class Epi, class Sched, bool ALIGN_EPI = false, bool SP2 = false>
; __device__ __forceinline__ void gemm_phase(PG8_LAS unsigned char* lds, const Gemm g, const Sched& S, const Epi& E) {
;     ...
;     const int tid = tid_l, wid = __builtin_amdgcn_readfirstlane(tid >> 6), lane = tid & 63, wr = wid >> 2, wc = wid & 3, fr = lane & 15, fq = lane >> 4;
;     const int K = g.K, nt = K / BK;
;     unsigned voffA[2], voffB[2];
; #pragma unroll
;     for (int i = 0; i < 2; ++i) { int R, C; stage_rc(tid * 16 + i * 8192, R, C); const int Rb = Epi::PERM ? ((R & ~31) + perm32(R & 31)) : R;
;         voffA[i] = (unsigned)(R * g.lda + C) * 2u; voffB[i] = (unsigned)(Rb * g.ldb + C) * 2u; }
;     ...
;     const char* cA = (const char*)g.A + (size_t)cur.pm * tstepA; const char* cB = (const char*)g.Bt + (size_t)cur.pn * tstepB;
;     S.a_ready(cur);
;     if constexpr (SP2) {
;         PG8_STAGE(PG8_SB(0, 0), cB, voffB); PG8_STAGE(PG8_SB(0, 1), cB + hstepB, voffB); PG8_STAGE(PG8_SA(0, 0), cA, voffA); PG8_STAGE(PG8_SA(0, 1), cA + hstepA, voffA);
;         if (wr == 1) PG8_BAR;
;         PG8_WAIT_V(2); PG8_BAR;
;         PG8_STAGE(PG8_SB(1, 0), cB + kstep, voffB); PG8_STAGE(PG8_SA(1, 0), cA + PG8_AK(1), voffA); PG8_STAGE(PG8_SB(1, 1), cB + hstepB + kstep, voffB);
;         PG8_WAIT_V(6); PG8_BAR;
.Lprio_ffn1_1:
	s_mov_b32 s21, s74
	s_mov_b64 s[4:5], s[0:1]
	s_mov_b32 s44, s2
	v_mov_b32_e32 v8, v254
	s_waitcnt lgkmcnt(0)
	s_barrier
	s_cmpk_gt_i32 s44, 0xaff
	v_readfirstlane_b32 s3, v8
	s_cbranch_scc1 .LBB0_1282
	v_lshlrev_b32_e32 v0, 4, v8
	v_add_u32_e32 v1, 0x2000, v0
	v_ashrrev_i32_e32 v2, 31, v1
	v_lshrrev_b32_e32 v2, 22, v2
	v_add_u32_e32 v2, v1, v2
	v_ashrrev_i32_e32 v9, 10, v2
	v_mul_i32_i24_e32 v2, 0x400, v9
	v_sub_u32_e32 v1, v1, v2
	v_lshrrev_b32_e32 v2, 4, v1
	v_bitop3_b32 v1, v2, v1, 32 bitop3:0x6c
	v_ashrrev_i32_e32 v2, 31, v1
	v_lshrrev_b32_e32 v2, 26, v2
	v_add_u32_e32 v2, v1, v2
	v_lshlrev_b32_e32 v3, 3, v9
	v_ashrrev_i32_e32 v10, 6, v2
	v_and_b32_e32 v3, -16, v3
	v_add_u32_e32 v3, v10, v3
	v_and_b32_e32 v4, 3, v10
	s_mov_b32 s6, 0x1fffe0
	v_lshrrev_b32_e32 v5, 2, v3
	v_lshlrev_b32_e32 v6, 1, v3
	v_and_b32_e32 v2, 0xc0, v2
	v_and_or_b32 v4, v3, s6, v4
	v_and_b32_e32 v5, 4, v5
	v_and_b32_e32 v6, 24, v6
	v_sub_u32_e32 v1, v1, v2
	v_mov_b32_e32 v2, 1
	v_or3_b32 v4, v4, v5, v6
	v_lshlrev_b32_e32 v5, 5, v9
	v_ashrrev_i16_sdwa v1, v2, sext(v1) dst_sel:DWORD dst_unused:UNUSED_PAD src0_sel:DWORD src1_sel:BYTE_0
	v_and_b32_e32 v5, 32, v5
	v_bfe_i32 v11, v1, 0, 16
	v_add_lshl_u32 v1, v5, v11, 1
	v_lshl_add_u32 v144, v4, 11, v1
	v_lshl_add_u32 v146, v3, 11, v1
	v_bfe_i32 v1, v8, 27, 1
	v_lshrrev_b32_e32 v1, 22, v1
	v_add_u32_e32 v1, v0, v1
	s_load_dwordx2 s[4:5], s[4:5], 0x90
	v_and_b32_e32 v1, 0xfffffc00, v1
	v_sub_u32_e32 v0, v0, v1
	v_lshrrev_b32_e32 v1, 4, v0
	v_ashrrev_i32_e32 v3, 31, v8
	v_bitop3_b32 v0, v1, v0, 32 bitop3:0x6c
	v_lshrrev_b32_e32 v3, 26, v3
	v_ashrrev_i32_e32 v1, 31, v0
	v_add_u32_e32 v3, v8, v3
	s_waitcnt lgkmcnt(0)
	s_add_u32 s45, s4, 0x2800000
	v_lshrrev_b32_e32 v1, 26, v1
	v_ashrrev_i32_e32 v13, 6, v3
	s_addc_u32 s46, s5, 0
	v_add_u32_e32 v1, v0, v1
	v_lshlrev_b32_e32 v3, 3, v13
	s_add_u32 s47, s4, 0xc00000
	v_ashrrev_i32_e32 v12, 6, v1
	v_and_b32_e32 v3, -16, v3
	s_addc_u32 s48, s5, 0
	v_add_u32_e32 v3, v12, v3
	v_and_b32_e32 v4, 3, v12
	s_ashr_i32 s50, s44, 31
	v_and_or_b32 v4, v3, s6, v4
	s_lshr_b32 s6, s50, 29
	s_add_i32 s6, s44, s6
	s_ashr_i32 s16, s3, 6
	s_ashr_i32 s7, s6, 3
	s_and_b32 s6, s6, -8
	s_ashr_i32 s19, s3, 8
	s_lshl_b32 s49, s16, 10
	s_sub_i32 s6, s44, s6
	s_cmp_lt_i32 s6, 0
	s_movk_i32 s51, 0x161
	s_cselect_b32 s8, s51, 0x160
	s_mul_i32 s6, s8, s6
	s_add_i32 s6, s6, s7
	s_mul_hi_i32 s7, s6, 0x2e8ba2e9
	s_lshr_b32 s8, s7, 31
	s_ashr_i32 s7, s7, 5
	s_add_i32 s7, s7, s8
	s_lshl_b32 s8, s7, 3
	s_mulk_i32 s7, 0xb0
	s_sub_i32 s6, s6, s7
	s_bfe_u32 s7, s6, 0x3001c
	s_add_i32 s7, s6, s7
	s_sext_i32_i16 s9, s7
	s_and_b32 s7, s7, 0xfff8
	s_sub_i32 s6, s6, s7
	s_sext_i32_i16 s6, s6
	v_lshrrev_b32_e32 v5, 2, v3
	v_lshlrev_b32_e32 v6, 1, v3
	v_and_b32_e32 v1, 0xc0, v1
	s_lshr_b32 s18, s9, 3
	s_add_i32 s30, s8, s6
	v_and_b32_e32 v5, 4, v5
	v_and_b32_e32 v6, 24, v6
	v_sub_u32_e32 v0, v0, v1
	s_ashr_i32 s31, s30, 31
	s_bfe_i64 s[8:9], s[18:19], 0x100000
	v_or3_b32 v4, v4, v5, v6
	v_lshlrev_b32_e32 v5, 5, v13
	v_ashrrev_i16_sdwa v0, v2, sext(v0) dst_sel:DWORD dst_unused:UNUSED_PAD src0_sel:DWORD src1_sel:BYTE_0
	s_lshl_b64 s[6:7], s[30:31], 19
	s_lshl_b64 s[8:9], s[8:9], 19
	v_and_b32_e32 v5, 32, v5
	v_bfe_i32 v14, v0, 0, 16
	s_add_u32 s36, s47, s8
	v_add_lshl_u32 v0, v5, v14, 1
	s_addc_u32 s37, s48, s9
	s_add_i32 s31, s49, 0
	v_lshl_add_u32 v148, v4, 11, v0
	s_add_i32 m0, s31, 0x10000
	v_lshl_add_u32 v150, v3, 11, v0
	global_load_lds_dwordx4 v148, s[36:37]
	s_add_i32 m0, s31, 0x12000
	s_add_u32 s8, s36, 0x40000
	global_load_lds_dwordx4 v144, s[36:37]
	s_addc_u32 s9, s37, 0
	s_add_i32 m0, s31, 0x14000
	v_mov_b32_e32 v149, 0
	global_load_lds_dwordx4 v148, s[8:9]
	s_add_i32 m0, s31, 0x16000
	s_add_u32 s34, s45, s6
	s_addc_u32 s35, s46, s7
	s_add_i32 s52, s31, 0x2000
	global_load_lds_dwordx4 v144, s[8:9]
	s_mov_b32 m0, s31
	s_add_u32 s6, s34, 0x40000
	global_load_lds_dwordx4 v150, s[34:35]
	s_mov_b32 m0, s52
	s_addc_u32 s7, s35, 0
	s_add_i32 s53, s31, 0x4000
	global_load_lds_dwordx4 v146, s[34:35]
	s_mov_b32 m0, s53
	s_add_i32 s54, s31, 0x6000
	global_load_lds_dwordx4 v150, s[6:7]
	s_mov_b32 m0, s54
	v_mov_b32_e32 v145, v149
	global_load_lds_dwordx4 v146, s[6:7]
	v_mov_b32_e32 v151, v149
	v_mov_b32_e32 v147, v149
	s_cmp_eq_u32 s19, 1
	s_mov_b32 s55, 0
	v_lshl_add_u64 v[6:7], s[36:37], 0, v[148:149]
	v_lshl_add_u64 v[4:5], s[36:37], 0, v[144:145]
	v_lshl_add_u64 v[0:1], s[34:35], 0, v[150:151]
	s_cselect_b64 s[6:7], -1, 0
	s_cmp_lg_u32 s19, 1
	v_lshl_add_u64 v[2:3], s[34:35], 0, v[146:147]
	s_cbranch_scc1 .LBB0_1269
	s_barrier

; #define PG8_STAGE(bufoff, gbase, voff) do { _Pragma("unroll") for (int _i = 0; _i < 2; ++_i) \
;         __builtin_amdgcn_global_load_lds((const unsigned*)((const char*)(gbase) + (voff)[_i]), (PG8_LAS unsigned*)(lds + (bufoff) + ldsw + _i * 8192), 16, 0, 0); } while (0)
; #define PG8_LDA(dst, b, h) do { _Pragma("unroll") for (int m = 0; m < 4; ++m) _Pragma("unroll") for (int k = 0; k < 2; ++k) dst[m][k] = *(const PG8_LAS bf16x8*)(lds + PG8_SA(b, h) + aoff + m * 2048 + k * 1024); } while (0)
; #define PG8_LDB(dst, b, h) do { _Pragma("unroll") for (int n = 0; n < 2; ++n) _Pragma("unroll") for (int k = 0; k < 2; ++k) dst[n][k] = *(const PG8_LAS bf16x8*)(lds + PG8_SB(b, h) + boff + n * 2048 + k * 1024); } while (0)
; #define PG8_MMA(ai, bj, At, Bt) do { __builtin_amdgcn_s_setprio(1); _Pragma("unroll") for (int m = 0; m < 4; ++m) _Pragma("unroll") for (int n = 0; n < 2; ++n) _Pragma("unroll") for (int k = 0; k < 2; ++k) \
;         acc[ai][bj][m][n] = __builtin_amdgcn_mfma_f32_16x16x32_bf16(Bt[n][k], At[m][k], acc[ai][bj][m][n], 0, 0, 0); __builtin_amdgcn_s_setprio(0); } while (0)
; #define PG8_WAIT_V(n) asm volatile("s_waitcnt vmcnt(" #n ")" ::: "memory")
; #define PG8_WAIT_L(n) asm volatile("s_waitcnt lgkmcnt(" #n ")" ::: "memory")
; template <class Epi, class Sched, bool ALIGN_EPI = false, bool SP2 = false>
; __device__ __forceinline__ void gemm_phase(PG8_LAS unsigned char* lds, const Gemm g, const Sched& S, const Epi& E) {
;     ...
;             const bool last = (t == nt - 2);
;             const char* a1 = cA + PG8_AK(t + 1);
;             const char* a2 = last ? nA : cA + PG8_AK(t + 2); const char* b2 = last ? nB : cB + (size_t)(t + 2) * kstep;
;             const char* a3 = last ? nA + PG8_AK(1) : cA + PG8_AK(t + 3); const char* b3 = b2 + kstep;
;             if (last && has_next) S.a_ready(nxt);
;             if constexpr (SP2) {
;             PG8_LDB(B0, 0, 0); PG8_LDB(B1, 0, 1); PG8_SCHED; PG8_LDA(At, 0, 0); PG8_STAGE(PG8_SA(1, 1), a1 + hstepA, voffA);
;             PG8_WAIT_V(8); PG8_WAIT_L(0); PG8_BAR; PG8_MMA(0, 0, At, B0); PG8_MMA(0, 1, At, B1); PG8_BAR; PG8_SCHED;
;             PG8_LDA(At, 0, 1); PG8_STAGE(PG8_SB(0, 0), b2, voffB); PG8_STAGE(PG8_SB(0, 1), b2 + hstepB, voffB); PG8_STAGE(PG8_SA(0, 0), a2, voffA);
;             PG8_WAIT_V(8); PG8_WAIT_L(0); PG8_BAR; PG8_MMA(1, 0, At, B0); PG8_MMA(1, 1, At, B1); PG8_BAR; PG8_SCHED;
.LBB0_1275:
	ds_read_b128 v[132:135], v171
	ds_read_b128 v[136:139], v171 offset:1024
	ds_read_b128 v[140:143], v171 offset:2048
	ds_read_b128 v[178:181], v171 offset:3072
	ds_read_b128 v[182:185], v173
	ds_read_b128 v[186:189], v173 offset:1024
	ds_read_b128 v[190:193], v173 offset:2048
	ds_read_b128 v[194:197], v173 offset:3072
	s_add_u32 s38, s34, s36
	s_addc_u32 s39, s35, s37
	s_add_u32 s42, s38, 0x100
	s_addc_u32 s43, s39, 0
	s_add_u32 s40, s66, s36
	s_addc_u32 s41, s67, s37
	s_add_u32 s38, s38, 0x180
	s_addc_u32 s39, s39, 0
	s_cmpk_eq_i32 s36, 0x700
	s_cselect_b32 s39, s65, s39
	s_cselect_b32 s38, s64, s38
	s_cselect_b32 s41, s23, s41
	s_cselect_b32 s40, s63, s40
	s_cselect_b32 s43, s3, s43
	s_cselect_b32 s42, s25, s42
	v_lshl_add_u64 v[230:231], v[130:131], 0, s[36:37]
	s_add_i32 m0, s31, 0xc000
	ds_read_b128 v[198:201], v175
	ds_read_b128 v[202:205], v175 offset:1024
	ds_read_b128 v[206:209], v175 offset:2048
	ds_read_b128 v[210:213], v175 offset:3072
	ds_read_b128 v[214:217], v175 offset:4096
	ds_read_b128 v[218:221], v175 offset:5120
	ds_read_b128 v[222:225], v175 offset:6144
	ds_read_b128 v[226:229], v175 offset:7168
	global_load_lds_dwordx4 v[230:231], off
	v_lshl_add_u64 v[230:231], v[128:129], 0, s[36:37]
	s_add_i32 m0, s31, 0xe000
	s_nop 0
	global_load_lds_dwordx4 v[230:231], off
	s_waitcnt vmcnt(8)
	s_waitcnt lgkmcnt(0)
	s_barrier
	s_waitcnt lgkmcnt(0)
	v_mfma_f32_16x16x32_bf16 v[124:127], v[132:135], v[198:201], v[124:127]
	v_mfma_f32_16x16x32_bf16 v[120:123], v[140:143], v[198:201], v[120:123]
	v_mfma_f32_16x16x32_bf16 v[116:119], v[132:135], v[206:209], v[116:119]
	v_mfma_f32_16x16x32_bf16 v[112:115], v[140:143], v[206:209], v[112:115]
	v_mfma_f32_16x16x32_bf16 v[108:111], v[132:135], v[214:217], v[108:111]
	v_mfma_f32_16x16x32_bf16 v[104:107], v[140:143], v[214:217], v[104:107]
	v_mfma_f32_16x16x32_bf16 v[100:103], v[132:135], v[222:225], v[100:103]
	v_mfma_f32_16x16x32_bf16 v[96:99], v[140:143], v[222:225], v[96:99]
	v_mfma_f32_16x16x32_bf16 v[124:127], v[136:139], v[202:205], v[124:127]
	v_mfma_f32_16x16x32_bf16 v[120:123], v[178:181], v[202:205], v[120:123]
	v_mfma_f32_16x16x32_bf16 v[116:119], v[136:139], v[210:213], v[116:119]
	v_mfma_f32_16x16x32_bf16 v[112:115], v[178:181], v[210:213], v[112:115]
	v_mfma_f32_16x16x32_bf16 v[108:111], v[136:139], v[218:221], v[108:111]
	v_mfma_f32_16x16x32_bf16 v[104:107], v[178:181], v[218:221], v[104:107]
	v_mfma_f32_16x16x32_bf16 v[100:103], v[136:139], v[226:229], v[100:103]
	v_mfma_f32_16x16x32_bf16 v[96:99], v[178:181], v[226:229], v[96:99]
	v_mfma_f32_16x16x32_bf16 v[64:67], v[182:185], v[198:201], v[64:67]
	v_mfma_f32_16x16x32_bf16 v[56:59], v[190:193], v[198:201], v[56:59]
	v_mfma_f32_16x16x32_bf16 v[52:55], v[182:185], v[206:209], v[52:55]
	v_mfma_f32_16x16x32_bf16 v[48:51], v[190:193], v[206:209], v[48:51]
	v_mfma_f32_16x16x32_bf16 v[44:47], v[182:185], v[214:217], v[44:47]
	v_mfma_f32_16x16x32_bf16 v[40:43], v[190:193], v[214:217], v[40:43]
	v_mfma_f32_16x16x32_bf16 v[36:39], v[182:185], v[222:225], v[36:39]
	v_mfma_f32_16x16x32_bf16 v[32:35], v[190:193], v[222:225], v[32:35]
	v_mfma_f32_16x16x32_bf16 v[64:67], v[186:189], v[202:205], v[64:67]
	v_mfma_f32_16x16x32_bf16 v[56:59], v[194:197], v[202:205], v[56:59]
	v_mfma_f32_16x16x32_bf16 v[52:55], v[186:189], v[210:213], v[52:55]
	v_mfma_f32_16x16x32_bf16 v[48:51], v[194:197], v[210:213], v[48:51]
	v_mfma_f32_16x16x32_bf16 v[44:47], v[186:189], v[218:221], v[44:47]
	v_mfma_f32_16x16x32_bf16 v[40:43], v[194:197], v[218:221], v[40:43]
	v_mfma_f32_16x16x32_bf16 v[36:39], v[186:189], v[226:229], v[36:39]
	v_mfma_f32_16x16x32_bf16 v[32:35], v[194:197], v[226:229], v[32:35]
	s_barrier
	s_add_i32 s69, s59, s49
	v_lshl_add_u64 v[230:231], s[40:41], 0, v[148:149]
	s_mov_b32 m0, s69
	ds_read_b128 v[198:201], v175 offset:16384
	ds_read_b128 v[202:205], v175 offset:17408
	ds_read_b128 v[206:209], v175 offset:18432
	ds_read_b128 v[210:213], v175 offset:19456
	ds_read_b128 v[214:217], v175 offset:20480
	ds_read_b128 v[218:221], v175 offset:21504
	ds_read_b128 v[222:225], v175 offset:22528
	ds_read_b128 v[226:229], v175 offset:23552
	global_load_lds_dwordx4 v[230:231], off
	s_add_i32 m0, s69, 0x2000
	s_add_u32 s70, s40, 0x40000
	v_lshl_add_u64 v[232:233], s[40:41], 0, v[144:145]
	s_addc_u32 s71, s41, 0
	s_add_i32 s69, s60, s49
	global_load_lds_dwordx4 v[232:233], off
	v_lshl_add_u64 v[234:235], s[70:71], 0, v[148:149]
	s_mov_b32 m0, s69
	s_nop 0
	global_load_lds_dwordx4 v[234:235], off
	v_lshl_add_u64 v[234:235], s[70:71], 0, v[144:145]
	s_add_i32 m0, s69, 0x2000
	s_nop 0
	global_load_lds_dwordx4 v[234:235], off
	v_lshl_add_u64 v[234:235], s[42:43], 0, v[150:151]
	s_mov_b32 m0, s31
	s_nop 0
	global_load_lds_dwordx4 v[234:235], off
	v_lshl_add_u64 v[234:235], s[42:43], 0, v[146:147]
	s_mov_b32 m0, s52
	s_nop 0
	global_load_lds_dwordx4 v[234:235], off
	s_waitcnt vmcnt(8)
	s_waitcnt lgkmcnt(0)
	s_barrier
; #define PG8_STAGE(bufoff, gbase, voff) do { _Pragma("unroll") for (int _i = 0; _i < 2; ++_i) \
;         __builtin_amdgcn_global_load_lds((const unsigned*)((const char*)(gbase) + (voff)[_i]), (PG8_LAS unsigned*)(lds + (bufoff) + ldsw + _i * 8192), 16, 0, 0); } while (0)
; #define PG8_LDA(dst, b, h) do { _Pragma("unroll") for (int m = 0; m < 4; ++m) _Pragma("unroll") for (int k = 0; k < 2; ++k) dst[m][k] = *(const PG8_LAS bf16x8*)(lds + PG8_SA(b, h) + aoff + m * 2048 + k * 1024); } while (0)
; #define PG8_LDB(dst, b, h) do { _Pragma("unroll") for (int n = 0; n < 2; ++n) _Pragma("unroll") for (int k = 0; k < 2; ++k) dst[n][k] = *(const PG8_LAS bf16x8*)(lds + PG8_SB(b, h) + boff + n * 2048 + k * 1024); } while (0)
; #define PG8_MMA(ai, bj, At, Bt) do { __builtin_amdgcn_s_setprio(1); _Pragma("unroll") for (int m = 0; m < 4; ++m) _Pragma("unroll") for (int n = 0; n < 2; ++n) _Pragma("unroll") for (int k = 0; k < 2; ++k) \
;         acc[ai][bj][m][n] = __builtin_amdgcn_mfma_f32_16x16x32_bf16(Bt[n][k], At[m][k], acc[ai][bj][m][n], 0, 0, 0); __builtin_amdgcn_s_setprio(0); } while (0)
; #define PG8_WAIT_V(n) asm volatile("s_waitcnt vmcnt(" #n ")" ::: "memory")
; #define PG8_WAIT_L(n) asm volatile("s_waitcnt lgkmcnt(" #n ")" ::: "memory")
; #define PG8_BAR __builtin_amdgcn_s_barrier()
; #define PG8_SCHED __builtin_amdgcn_sched_barrier(0)
; template <class Epi, class Sched, bool ALIGN_EPI = false, bool SP2 = false>
; __device__ __forceinline__ void gemm_phase(PG8_LAS unsigned char* lds, const Gemm g, const Sched& S, const Epi& E) {
;     ...
;             PG8_WAIT_V(8); PG8_WAIT_L(0); PG8_BAR; PG8_MMA(1, 0, At, B0); PG8_MMA(1, 1, At, B1); PG8_BAR; PG8_SCHED;
;             PG8_LDB(B0, 1, 0); PG8_LDB(B1, 1, 1); PG8_SCHED; PG8_LDA(At, 1, 0); PG8_STAGE(PG8_SA(0, 1), a2 + hstepA, voffA);
;             PG8_WAIT_V(8); PG8_WAIT_L(0); PG8_BAR; PG8_MMA(0, 0, At, B0); PG8_MMA(0, 1, At, B1); PG8_BAR; PG8_SCHED;
	s_waitcnt lgkmcnt(0)
	v_mfma_f32_16x16x32_bf16 v[92:95], v[132:135], v[198:201], v[92:95]
	v_mfma_f32_16x16x32_bf16 v[88:91], v[140:143], v[198:201], v[88:91]
	v_mfma_f32_16x16x32_bf16 v[84:87], v[132:135], v[206:209], v[84:87]
	v_mfma_f32_16x16x32_bf16 v[80:83], v[140:143], v[206:209], v[80:83]
	v_mfma_f32_16x16x32_bf16 v[76:79], v[132:135], v[214:217], v[76:79]
	v_mfma_f32_16x16x32_bf16 v[72:75], v[140:143], v[214:217], v[72:75]
	v_mfma_f32_16x16x32_bf16 v[68:71], v[132:135], v[222:225], v[68:71]
	v_mfma_f32_16x16x32_bf16 v[60:63], v[140:143], v[222:225], v[60:63]
	v_mfma_f32_16x16x32_bf16 v[92:95], v[136:139], v[202:205], v[92:95]
	v_mfma_f32_16x16x32_bf16 v[88:91], v[178:181], v[202:205], v[88:91]
	v_mfma_f32_16x16x32_bf16 v[84:87], v[136:139], v[210:213], v[84:87]
	v_mfma_f32_16x16x32_bf16 v[80:83], v[178:181], v[210:213], v[80:83]
	v_mfma_f32_16x16x32_bf16 v[76:79], v[136:139], v[218:221], v[76:79]
	v_mfma_f32_16x16x32_bf16 v[72:75], v[178:181], v[218:221], v[72:75]
	v_mfma_f32_16x16x32_bf16 v[68:71], v[136:139], v[226:229], v[68:71]
	v_mfma_f32_16x16x32_bf16 v[60:63], v[178:181], v[226:229], v[60:63]
	v_mfma_f32_16x16x32_bf16 v[28:31], v[182:185], v[198:201], v[28:31]
	v_mfma_f32_16x16x32_bf16 v[24:27], v[190:193], v[198:201], v[24:27]
	v_mfma_f32_16x16x32_bf16 v[20:23], v[182:185], v[206:209], v[20:23]
	v_mfma_f32_16x16x32_bf16 v[16:19], v[190:193], v[206:209], v[16:19]
	v_mfma_f32_16x16x32_bf16 v[12:15], v[182:185], v[214:217], v[12:15]
	v_mfma_f32_16x16x32_bf16 v[8:11], v[190:193], v[214:217], v[8:11]
	v_mfma_f32_16x16x32_bf16 v[4:7], v[182:185], v[222:225], v[4:7]
	v_mfma_f32_16x16x32_bf16 v[0:3], v[190:193], v[222:225], v[0:3]
	v_mfma_f32_16x16x32_bf16 v[28:31], v[186:189], v[202:205], v[28:31]
	v_mfma_f32_16x16x32_bf16 v[24:27], v[194:197], v[202:205], v[24:27]
	v_mfma_f32_16x16x32_bf16 v[20:23], v[186:189], v[210:213], v[20:23]
	v_mfma_f32_16x16x32_bf16 v[16:19], v[194:197], v[210:213], v[16:19]
	v_mfma_f32_16x16x32_bf16 v[12:15], v[186:189], v[218:221], v[12:15]
	v_mfma_f32_16x16x32_bf16 v[8:11], v[194:197], v[218:221], v[8:11]
	v_mfma_f32_16x16x32_bf16 v[4:7], v[186:189], v[226:229], v[4:7]
	v_mfma_f32_16x16x32_bf16 v[0:3], v[194:197], v[226:229], v[0:3]
	s_barrier
	s_add_i32 s69, 0, 0x18000
	v_add_u32_e32 v160, s69, v163
	s_add_i32 s70, 0, 0x1c000
	ds_read_b128 v[132:135], v160
	ds_read_b128 v[136:139], v160 offset:1024
	ds_read_b128 v[140:143], v160 offset:2048
	ds_read_b128 v[178:181], v160 offset:3072
	v_add_u32_e32 v160, s70, v163
	ds_read_b128 v[182:185], v160
	ds_read_b128 v[186:189], v160 offset:1024
	ds_read_b128 v[190:193], v160 offset:2048
	ds_read_b128 v[194:197], v160 offset:3072
	s_add_u32 s42, s42, 0x40000
	s_addc_u32 s43, s43, 0
	s_mov_b32 m0, s53
	v_lshl_add_u64 v[234:235], s[42:43], 0, v[150:151]
	ds_read_b128 v[198:201], v175 offset:32768
	ds_read_b128 v[202:205], v175 offset:33792
	ds_read_b128 v[206:209], v175 offset:34816
	ds_read_b128 v[210:213], v175 offset:35840
	ds_read_b128 v[214:217], v175 offset:36864
	ds_read_b128 v[218:221], v175 offset:37888
	ds_read_b128 v[222:225], v175 offset:38912
	ds_read_b128 v[226:229], v175 offset:39936
	global_load_lds_dwordx4 v[234:235], off
	v_lshl_add_u64 v[234:235], s[42:43], 0, v[146:147]
	s_mov_b32 m0, s54
	s_nop 0
	global_load_lds_dwordx4 v[234:235], off
	s_waitcnt vmcnt(8)
	s_waitcnt lgkmcnt(0)
	s_barrier
	s_waitcnt lgkmcnt(0)
	v_mfma_f32_16x16x32_bf16 v[124:127], v[132:135], v[198:201], v[124:127]
	v_mfma_f32_16x16x32_bf16 v[120:123], v[140:143], v[198:201], v[120:123]
	v_mfma_f32_16x16x32_bf16 v[116:119], v[132:135], v[206:209], v[116:119]
	v_mfma_f32_16x16x32_bf16 v[112:115], v[140:143], v[206:209], v[112:115]
	v_mfma_f32_16x16x32_bf16 v[108:111], v[132:135], v[214:217], v[108:111]
	v_mfma_f32_16x16x32_bf16 v[104:107], v[140:143], v[214:217], v[104:107]
	v_mfma_f32_16x16x32_bf16 v[100:103], v[132:135], v[222:225], v[100:103]
	v_mfma_f32_16x16x32_bf16 v[96:99], v[140:143], v[222:225], v[96:99]
	v_mfma_f32_16x16x32_bf16 v[124:127], v[136:139], v[202:205], v[124:127]
	v_mfma_f32_16x16x32_bf16 v[120:123], v[178:181], v[202:205], v[120:123]
	v_mfma_f32_16x16x32_bf16 v[116:119], v[136:139], v[210:213], v[116:119]
	v_mfma_f32_16x16x32_bf16 v[112:115], v[178:181], v[210:213], v[112:115]
	v_mfma_f32_16x16x32_bf16 v[108:111], v[136:139], v[218:221], v[108:111]
	v_mfma_f32_16x16x32_bf16 v[104:107], v[178:181], v[218:221], v[104:107]
	v_mfma_f32_16x16x32_bf16 v[100:103], v[136:139], v[226:229], v[100:103]
	v_mfma_f32_16x16x32_bf16 v[96:99], v[178:181], v[226:229], v[96:99]
	v_mfma_f32_16x16x32_bf16 v[64:67], v[182:185], v[198:201], v[64:67]
	v_mfma_f32_16x16x32_bf16 v[56:59], v[190:193], v[198:201], v[56:59]
	v_mfma_f32_16x16x32_bf16 v[52:55], v[182:185], v[206:209], v[52:55]
	v_mfma_f32_16x16x32_bf16 v[48:51], v[190:193], v[206:209], v[48:51]
	v_mfma_f32_16x16x32_bf16 v[44:47], v[182:185], v[214:217], v[44:47]
	v_mfma_f32_16x16x32_bf16 v[40:43], v[190:193], v[214:217], v[40:43]
	v_mfma_f32_16x16x32_bf16 v[36:39], v[182:185], v[222:225], v[36:39]
	v_mfma_f32_16x16x32_bf16 v[32:35], v[190:193], v[222:225], v[32:35]
	v_mfma_f32_16x16x32_bf16 v[64:67], v[186:189], v[202:205], v[64:67]
	v_mfma_f32_16x16x32_bf16 v[56:59], v[194:197], v[202:205], v[56:59]
	v_mfma_f32_16x16x32_bf16 v[52:55], v[186:189], v[210:213], v[52:55]
	v_mfma_f32_16x16x32_bf16 v[48:51], v[194:197], v[210:213], v[48:51]
	v_mfma_f32_16x16x32_bf16 v[44:47], v[186:189], v[218:221], v[44:47]
	v_mfma_f32_16x16x32_bf16 v[40:43], v[194:197], v[218:221], v[40:43]
	v_mfma_f32_16x16x32_bf16 v[36:39], v[186:189], v[226:229], v[36:39]
	v_mfma_f32_16x16x32_bf16 v[32:35], v[194:197], v[226:229], v[32:35]
	s_barrier
; #define PG8_STAGE(bufoff, gbase, voff) do { _Pragma("unroll") for (int _i = 0; _i < 2; ++_i) \
;         __builtin_amdgcn_global_load_lds((const unsigned*)((const char*)(gbase) + (voff)[_i]), (PG8_LAS unsigned*)(lds + (bufoff) + ldsw + _i * 8192), 16, 0, 0); } while (0)
; #define PG8_LDA(dst, b, h) do { _Pragma("unroll") for (int m = 0; m < 4; ++m) _Pragma("unroll") for (int k = 0; k < 2; ++k) dst[m][k] = *(const PG8_LAS bf16x8*)(lds + PG8_SA(b, h) + aoff + m * 2048 + k * 1024); } while (0)
; #define PG8_MMA(ai, bj, At, Bt) do { __builtin_amdgcn_s_setprio(1); _Pragma("unroll") for (int m = 0; m < 4; ++m) _Pragma("unroll") for (int n = 0; n < 2; ++n) _Pragma("unroll") for (int k = 0; k < 2; ++k) \
;         acc[ai][bj][m][n] = __builtin_amdgcn_mfma_f32_16x16x32_bf16(Bt[n][k], At[m][k], acc[ai][bj][m][n], 0, 0, 0); __builtin_amdgcn_s_setprio(0); } while (0)
; #define PG8_WAIT_V(n) asm volatile("s_waitcnt vmcnt(" #n ")" ::: "memory")
; #define PG8_WAIT_L(n) asm volatile("s_waitcnt lgkmcnt(" #n ")" ::: "memory")
; #define PG8_BAR __builtin_amdgcn_s_barrier()
; #define PG8_SCHED __builtin_amdgcn_sched_barrier(0)
; template <class Epi, class Sched, bool ALIGN_EPI = false, bool SP2 = false>
; __device__ __forceinline__ void gemm_phase(PG8_LAS unsigned char* lds, const Gemm g, const Sched& S, const Epi& E) {
;     ...
;         for (int t = 0; t < nt; t += 2) {
;     ...
;             PG8_LDA(At, 1, 1); PG8_STAGE(PG8_SB(1, 0), b3, voffB); PG8_STAGE(PG8_SB(1, 1), b3 + hstepB, voffB); PG8_STAGE(PG8_SA(1, 0), a3, voffA);
;             PG8_WAIT_V(8); PG8_WAIT_L(0); PG8_BAR; PG8_MMA(1, 0, At, B0); PG8_MMA(1, 1, At, B1); PG8_BAR; PG8_SCHED;
	s_add_i32 s42, s69, s49
	v_lshl_add_u64 v[230:231], v[230:231], 0, s[16:17]
	s_mov_b32 m0, s42
	ds_read_b128 v[198:201], v175 offset:49152
	ds_read_b128 v[202:205], v175 offset:50176
	ds_read_b128 v[206:209], v175 offset:51200
	ds_read_b128 v[210:213], v175 offset:52224
	ds_read_b128 v[214:217], v175 offset:53248
	ds_read_b128 v[218:221], v175 offset:54272
	ds_read_b128 v[222:225], v175 offset:55296
	ds_read_b128 v[226:229], v175 offset:56320
	global_load_lds_dwordx4 v[230:231], off
	s_add_i32 m0, s42, 0x2000
	s_add_u32 s40, s40, 0x40080
	v_lshl_add_u64 v[230:231], v[232:233], 0, s[16:17]
	s_addc_u32 s41, s41, 0
	s_add_i32 s42, s70, s49
	global_load_lds_dwordx4 v[230:231], off
	v_lshl_add_u64 v[230:231], s[40:41], 0, v[148:149]
	s_mov_b32 m0, s42
	s_nop 0
	global_load_lds_dwordx4 v[230:231], off
	v_lshl_add_u64 v[230:231], s[40:41], 0, v[144:145]
	s_add_i32 m0, s42, 0x2000
	s_nop 0
	global_load_lds_dwordx4 v[230:231], off
	v_lshl_add_u64 v[230:231], s[38:39], 0, v[150:151]
	s_mov_b32 m0, s56
	s_nop 0
	global_load_lds_dwordx4 v[230:231], off
	v_lshl_add_u64 v[230:231], s[38:39], 0, v[146:147]
	s_mov_b32 m0, s57
	s_nop 0
	global_load_lds_dwordx4 v[230:231], off
	s_waitcnt vmcnt(8)
	s_waitcnt lgkmcnt(0)
	s_barrier
	s_waitcnt lgkmcnt(0)
	v_mfma_f32_16x16x32_bf16 v[92:95], v[132:135], v[198:201], v[92:95]
	v_mfma_f32_16x16x32_bf16 v[88:91], v[140:143], v[198:201], v[88:91]
	v_mfma_f32_16x16x32_bf16 v[84:87], v[132:135], v[206:209], v[84:87]
	v_mfma_f32_16x16x32_bf16 v[80:83], v[140:143], v[206:209], v[80:83]
	v_mfma_f32_16x16x32_bf16 v[76:79], v[132:135], v[214:217], v[76:79]
	v_mfma_f32_16x16x32_bf16 v[72:75], v[140:143], v[214:217], v[72:75]
	v_mfma_f32_16x16x32_bf16 v[68:71], v[132:135], v[222:225], v[68:71]
	v_mfma_f32_16x16x32_bf16 v[60:63], v[140:143], v[222:225], v[60:63]
	v_mfma_f32_16x16x32_bf16 v[92:95], v[136:139], v[202:205], v[92:95]
	v_mfma_f32_16x16x32_bf16 v[88:91], v[178:181], v[202:205], v[88:91]
	v_mfma_f32_16x16x32_bf16 v[84:87], v[136:139], v[210:213], v[84:87]
	v_mfma_f32_16x16x32_bf16 v[80:83], v[178:181], v[210:213], v[80:83]
	v_mfma_f32_16x16x32_bf16 v[76:79], v[136:139], v[218:221], v[76:79]
	v_mfma_f32_16x16x32_bf16 v[72:75], v[178:181], v[218:221], v[72:75]
	v_mfma_f32_16x16x32_bf16 v[68:71], v[136:139], v[226:229], v[68:71]
	v_mfma_f32_16x16x32_bf16 v[60:63], v[178:181], v[226:229], v[60:63]
	v_mfma_f32_16x16x32_bf16 v[28:31], v[182:185], v[198:201], v[28:31]
	v_mfma_f32_16x16x32_bf16 v[24:27], v[190:193], v[198:201], v[24:27]
	v_mfma_f32_16x16x32_bf16 v[20:23], v[182:185], v[206:209], v[20:23]
	v_mfma_f32_16x16x32_bf16 v[16:19], v[190:193], v[206:209], v[16:19]
	v_mfma_f32_16x16x32_bf16 v[12:15], v[182:185], v[214:217], v[12:15]
	v_mfma_f32_16x16x32_bf16 v[8:11], v[190:193], v[214:217], v[8:11]
	v_mfma_f32_16x16x32_bf16 v[4:7], v[182:185], v[222:225], v[4:7]
	v_mfma_f32_16x16x32_bf16 v[0:3], v[190:193], v[222:225], v[0:3]
	v_mfma_f32_16x16x32_bf16 v[28:31], v[186:189], v[202:205], v[28:31]
	v_mfma_f32_16x16x32_bf16 v[24:27], v[194:197], v[202:205], v[24:27]
	v_mfma_f32_16x16x32_bf16 v[20:23], v[186:189], v[210:213], v[20:23]
	v_mfma_f32_16x16x32_bf16 v[16:19], v[194:197], v[210:213], v[16:19]
	v_mfma_f32_16x16x32_bf16 v[12:15], v[186:189], v[218:221], v[12:15]
	v_mfma_f32_16x16x32_bf16 v[8:11], v[194:197], v[218:221], v[8:11]
	v_mfma_f32_16x16x32_bf16 v[4:7], v[186:189], v[226:229], v[4:7]
	v_mfma_f32_16x16x32_bf16 v[0:3], v[194:197], v[226:229], v[0:3]
	s_barrier
	s_add_i32 s68, s68, 2
	s_add_u32 s36, s36, 0x100
	s_addc_u32 s37, s37, 0
	s_cmp_gt_u32 s68, 13
	s_cbranch_scc0 .LBB0_1275
	s_and_b64 vcc, exec, s[18:19]
	s_cbranch_vccz .LBB0_1278
	s_barrier

; #define PG8_STAGE(bufoff, gbase, voff) do { _Pragma("unroll") for (int _i = 0; _i < 2; ++_i) \
;         __builtin_amdgcn_global_load_lds((const unsigned*)((const char*)(gbase) + (voff)[_i]), (PG8_LAS unsigned*)(lds + (bufoff) + ldsw + _i * 8192), 16, 0, 0); } while (0)
; #define PG8_LDA(dst, b, h) do { _Pragma("unroll") for (int m = 0; m < 4; ++m) _Pragma("unroll") for (int k = 0; k < 2; ++k) dst[m][k] = *(const PG8_LAS bf16x8*)(lds + PG8_SA(b, h) + aoff + m * 2048 + k * 1024); } while (0)
; #define PG8_LDB(dst, b, h) do { _Pragma("unroll") for (int n = 0; n < 2; ++n) _Pragma("unroll") for (int k = 0; k < 2; ++k) dst[n][k] = *(const PG8_LAS bf16x8*)(lds + PG8_SB(b, h) + boff + n * 2048 + k * 1024); } while (0)
; #define PG8_MMA(ai, bj, At, Bt) do { __builtin_amdgcn_s_setprio(1); _Pragma("unroll") for (int m = 0; m < 4; ++m) _Pragma("unroll") for (int n = 0; n < 2; ++n) _Pragma("unroll") for (int k = 0; k < 2; ++k) \
;         acc[ai][bj][m][n] = __builtin_amdgcn_mfma_f32_16x16x32_bf16(Bt[n][k], At[m][k], acc[ai][bj][m][n], 0, 0, 0); __builtin_amdgcn_s_setprio(0); } while (0)
; #define PG8_WAIT_V(n) asm volatile("s_waitcnt vmcnt(" #n ")" ::: "memory")
; #define PG8_WAIT_L(n) asm volatile("s_waitcnt lgkmcnt(" #n ")" ::: "memory")
; #define PG8_BAR __builtin_amdgcn_s_barrier()
; #define PG8_SCHED __builtin_amdgcn_sched_barrier(0)
; template <class Epi, class Sched, bool ALIGN_EPI = false, bool SP2 = false>
; __device__ __forceinline__ void gemm_phase(PG8_LAS unsigned char* lds, const Gemm g, const Sched& S, const Epi& E) {
;     ...
;             const bool last = (t == nt - 2);
;             const char* a1 = cA + PG8_AK(t + 1);
;             const char* a2 = last ? nA : cA + PG8_AK(t + 2); const char* b2 = last ? nB : cB + (size_t)(t + 2) * kstep;
;             const char* a3 = last ? nA + PG8_AK(1) : cA + PG8_AK(t + 3); const char* b3 = b2 + kstep;
;             if (last && has_next) S.a_ready(nxt);
;             if constexpr (SP2) {
;             PG8_LDB(B0, 0, 0); PG8_LDB(B1, 0, 1); PG8_SCHED; PG8_LDA(At, 0, 0); PG8_STAGE(PG8_SA(1, 1), a1 + hstepA, voffA);
;             PG8_WAIT_V(8); PG8_WAIT_L(0); PG8_BAR; PG8_MMA(0, 0, At, B0); PG8_MMA(0, 1, At, B1); PG8_BAR; PG8_SCHED;
;             PG8_LDA(At, 0, 1); PG8_STAGE(PG8_SB(0, 0), b2, voffB); PG8_STAGE(PG8_SB(0, 1), b2 + hstepB, voffB); PG8_STAGE(PG8_SA(0, 0), a2, voffA);
.LBB0_1298:
	ds_read_b128 v[0:3], v145
	ds_read_b128 v[4:7], v145 offset:1024
	ds_read_b128 v[8:11], v145 offset:2048
	ds_read_b128 v[12:15], v145 offset:3072
	ds_read_b128 v[16:19], v146
	ds_read_b128 v[20:23], v146 offset:1024
	ds_read_b128 v[24:27], v146 offset:2048
	ds_read_b128 v[28:31], v146 offset:3072
	s_ashr_i32 s31, s30, 31
	s_lshl_b64 s[34:35], s[30:31], 17
	s_add_u32 s34, s49, s34
	s_addc_u32 s35, s50, s35
	s_and_b64 s[36:37], s[4:5], exec
	s_cselect_b32 s47, s35, s41
	s_cselect_b32 s46, s34, s40
	s_ashr_i32 s29, s28, 31
	s_lshl_b64 s[36:37], s[28:29], 17
	s_add_u32 s36, s51, s36
	s_addc_u32 s37, s52, s37
	s_and_b64 s[44:45], s[4:5], exec
	s_cselect_b32 s45, s37, s43
	s_cselect_b32 s44, s36, s42
	s_add_u32 s66, s40, 0x10080
	s_addc_u32 s67, s41, 0
	s_add_i32 s78, s3, 0xc000
	v_lshl_add_u64 v[64:65], s[66:67], 0, v[128:129]
	s_mov_b32 m0, s78
	s_add_i32 s29, s3, 0xe000
	ds_read_b128 v[32:35], v147
	ds_read_b128 v[36:39], v147 offset:1024
	ds_read_b128 v[40:43], v147 offset:2048
	ds_read_b128 v[44:47], v147 offset:3072
	ds_read_b128 v[48:51], v147 offset:4096
	ds_read_b128 v[52:55], v147 offset:5120
	ds_read_b128 v[56:59], v147 offset:6144
	ds_read_b128 v[60:63], v147 offset:7168
	global_load_lds_dwordx4 v[64:65], off
	v_lshl_add_u64 v[64:65], s[66:67], 0, v[132:133]
	s_mov_b32 m0, s29
	s_nop 0
	global_load_lds_dwordx4 v[64:65], off
	s_waitcnt vmcnt(8)
	s_waitcnt lgkmcnt(0)
	s_barrier
	s_waitcnt lgkmcnt(0)
	v_mfma_f32_16x16x32_bf16 v[64:67], v[0:3], v[32:35], 0
	v_mfma_f32_16x16x32_bf16 v[68:71], v[8:11], v[32:35], 0
	v_mfma_f32_16x16x32_bf16 v[72:75], v[0:3], v[40:43], 0
	v_mfma_f32_16x16x32_bf16 v[76:79], v[8:11], v[40:43], 0
	v_mfma_f32_16x16x32_bf16 v[80:83], v[0:3], v[48:51], 0
	v_mfma_f32_16x16x32_bf16 v[84:87], v[8:11], v[48:51], 0
	v_mfma_f32_16x16x32_bf16 v[88:91], v[0:3], v[56:59], 0
	v_mfma_f32_16x16x32_bf16 v[92:95], v[8:11], v[56:59], 0
	v_mfma_f32_16x16x32_bf16 v[64:67], v[4:7], v[36:39], v[64:67]
	v_mfma_f32_16x16x32_bf16 v[68:71], v[12:15], v[36:39], v[68:71]
	v_mfma_f32_16x16x32_bf16 v[72:75], v[4:7], v[44:47], v[72:75]
	v_mfma_f32_16x16x32_bf16 v[76:79], v[12:15], v[44:47], v[76:79]
	v_mfma_f32_16x16x32_bf16 v[80:83], v[4:7], v[52:55], v[80:83]
	v_mfma_f32_16x16x32_bf16 v[84:87], v[12:15], v[52:55], v[84:87]
	v_mfma_f32_16x16x32_bf16 v[88:91], v[4:7], v[60:63], v[88:91]
	v_mfma_f32_16x16x32_bf16 v[92:95], v[12:15], v[60:63], v[92:95]
	v_mfma_f32_16x16x32_bf16 v[96:99], v[16:19], v[32:35], 0
	v_mfma_f32_16x16x32_bf16 v[32:35], v[24:27], v[32:35], 0
	v_mfma_f32_16x16x32_bf16 v[96:99], v[20:23], v[36:39], v[96:99]
	v_mfma_f32_16x16x32_bf16 v[32:35], v[28:31], v[36:39], v[32:35]
	v_mfma_f32_16x16x32_bf16 v[36:39], v[16:19], v[40:43], 0
	v_mfma_f32_16x16x32_bf16 v[40:43], v[24:27], v[40:43], 0
	v_mfma_f32_16x16x32_bf16 v[36:39], v[20:23], v[44:47], v[36:39]
	v_mfma_f32_16x16x32_bf16 v[40:43], v[28:31], v[44:47], v[40:43]
	v_mfma_f32_16x16x32_bf16 v[44:47], v[16:19], v[48:51], 0
	v_mfma_f32_16x16x32_bf16 v[48:51], v[24:27], v[48:51], 0
	v_mfma_f32_16x16x32_bf16 v[44:47], v[20:23], v[52:55], v[44:47]
	v_mfma_f32_16x16x32_bf16 v[48:51], v[28:31], v[52:55], v[48:51]
	v_mfma_f32_16x16x32_bf16 v[52:55], v[16:19], v[56:59], 0
	v_mfma_f32_16x16x32_bf16 v[56:59], v[24:27], v[56:59], 0
	v_mfma_f32_16x16x32_bf16 v[52:55], v[20:23], v[60:63], v[52:55]
	v_mfma_f32_16x16x32_bf16 v[56:59], v[28:31], v[60:63], v[56:59]
	s_barrier
	s_add_i32 s68, s59, s53
	v_lshl_add_u64 v[140:141], s[42:43], 0, v[130:131]
	s_add_i32 s31, s68, 0x2000
	v_lshl_add_u64 v[148:149], v[140:141], 0, s[16:17]
	s_mov_b32 m0, s68
	v_lshl_add_u64 v[212:213], s[42:43], 0, v[134:135]
	s_add_u32 s70, s42, 0x10100
	ds_read_b128 v[60:63], v147 offset:16384
	ds_read_b128 v[100:103], v147 offset:17408
	ds_read_b128 v[104:107], v147 offset:18432
	ds_read_b128 v[108:111], v147 offset:19456
	ds_read_b128 v[112:115], v147 offset:20480
	ds_read_b128 v[116:119], v147 offset:21504
	ds_read_b128 v[120:123], v147 offset:22528
	ds_read_b128 v[124:127], v147 offset:23552
	global_load_lds_dwordx4 v[148:149], off
	v_lshl_add_u64 v[148:149], v[212:213], 0, s[16:17]
	s_mov_b32 m0, s31
	s_addc_u32 s71, s43, 0
	s_add_i32 s66, s60, s53
	global_load_lds_dwordx4 v[148:149], off
	v_lshl_add_u64 v[148:149], s[70:71], 0, v[130:131]
	s_mov_b32 m0, s66
	s_add_i32 s67, s66, 0x2000
	global_load_lds_dwordx4 v[148:149], off
	v_lshl_add_u64 v[148:149], s[70:71], 0, v[134:135]
	s_mov_b32 m0, s67
	v_lshl_add_u64 v[214:215], s[40:41], 0, v[128:129]
	global_load_lds_dwordx4 v[148:149], off
	v_lshl_add_u64 v[148:149], v[214:215], 0, s[16:17]
	s_mov_b32 m0, s3
	v_lshl_add_u64 v[216:217], s[40:41], 0, v[132:133]
	global_load_lds_dwordx4 v[148:149], off
	v_lshl_add_u64 v[148:149], v[216:217], 0, s[16:17]
	s_mov_b32 m0, s39
	s_nop 0
	global_load_lds_dwordx4 v[148:149], off
	s_waitcnt vmcnt(8)
	s_waitcnt lgkmcnt(0)
	s_barrier
; #define PG8_STAGE(bufoff, gbase, voff) do { _Pragma("unroll") for (int _i = 0; _i < 2; ++_i) \
;         __builtin_amdgcn_global_load_lds((const unsigned*)((const char*)(gbase) + (voff)[_i]), (PG8_LAS unsigned*)(lds + (bufoff) + ldsw + _i * 8192), 16, 0, 0); } while (0)
; #define PG8_LDA(dst, b, h) do { _Pragma("unroll") for (int m = 0; m < 4; ++m) _Pragma("unroll") for (int k = 0; k < 2; ++k) dst[m][k] = *(const PG8_LAS bf16x8*)(lds + PG8_SA(b, h) + aoff + m * 2048 + k * 1024); } while (0)
; #define PG8_LDB(dst, b, h) do { _Pragma("unroll") for (int n = 0; n < 2; ++n) _Pragma("unroll") for (int k = 0; k < 2; ++k) dst[n][k] = *(const PG8_LAS bf16x8*)(lds + PG8_SB(b, h) + boff + n * 2048 + k * 1024); } while (0)
; #define PG8_MMA(ai, bj, At, Bt) do { __builtin_amdgcn_s_setprio(1); _Pragma("unroll") for (int m = 0; m < 4; ++m) _Pragma("unroll") for (int n = 0; n < 2; ++n) _Pragma("unroll") for (int k = 0; k < 2; ++k) \
;         acc[ai][bj][m][n] = __builtin_amdgcn_mfma_f32_16x16x32_bf16(Bt[n][k], At[m][k], acc[ai][bj][m][n], 0, 0, 0); __builtin_amdgcn_s_setprio(0); } while (0)
; #define PG8_WAIT_V(n) asm volatile("s_waitcnt vmcnt(" #n ")" ::: "memory")
; #define PG8_WAIT_L(n) asm volatile("s_waitcnt lgkmcnt(" #n ")" ::: "memory")
; #define PG8_BAR __builtin_amdgcn_s_barrier()
; #define PG8_SCHED __builtin_amdgcn_sched_barrier(0)
; template <class Epi, class Sched, bool ALIGN_EPI = false, bool SP2 = false>
; __device__ __forceinline__ void gemm_phase(PG8_LAS unsigned char* lds, const Gemm g, const Sched& S, const Epi& E) {
;     ...
;             PG8_WAIT_V(8); PG8_WAIT_L(0); PG8_BAR; PG8_MMA(1, 0, At, B0); PG8_MMA(1, 1, At, B1); PG8_BAR; PG8_SCHED;
;             PG8_LDB(B0, 1, 0); PG8_LDB(B1, 1, 1); PG8_SCHED; PG8_LDA(At, 1, 0); PG8_STAGE(PG8_SA(0, 1), a2 + hstepA, voffA);
;             PG8_WAIT_V(8); PG8_WAIT_L(0); PG8_BAR; PG8_MMA(0, 0, At, B0); PG8_MMA(0, 1, At, B1); PG8_BAR; PG8_SCHED;
	s_waitcnt lgkmcnt(0)
	v_mfma_f32_16x16x32_bf16 v[148:151], v[0:3], v[60:63], 0
	v_mfma_f32_16x16x32_bf16 v[156:159], v[0:3], v[104:107], 0
	v_mfma_f32_16x16x32_bf16 v[164:167], v[0:3], v[112:115], 0
	v_mfma_f32_16x16x32_bf16 v[0:3], v[0:3], v[120:123], 0
	v_mfma_f32_16x16x32_bf16 v[148:151], v[4:7], v[100:103], v[148:151]
	v_mfma_f32_16x16x32_bf16 v[156:159], v[4:7], v[108:111], v[156:159]
	v_mfma_f32_16x16x32_bf16 v[164:167], v[4:7], v[116:119], v[164:167]
	v_mfma_f32_16x16x32_bf16 v[0:3], v[4:7], v[124:127], v[0:3]
	v_mfma_f32_16x16x32_bf16 v[4:7], v[8:11], v[120:123], 0
	v_mfma_f32_16x16x32_bf16 v[152:155], v[8:11], v[60:63], 0
	v_mfma_f32_16x16x32_bf16 v[160:163], v[8:11], v[104:107], 0
	v_mfma_f32_16x16x32_bf16 v[168:171], v[8:11], v[112:115], 0
	v_mfma_f32_16x16x32_bf16 v[4:7], v[12:15], v[124:127], v[4:7]
	v_mfma_f32_16x16x32_bf16 v[152:155], v[12:15], v[100:103], v[152:155]
	v_mfma_f32_16x16x32_bf16 v[160:163], v[12:15], v[108:111], v[160:163]
	v_mfma_f32_16x16x32_bf16 v[168:171], v[12:15], v[116:119], v[168:171]
	v_mfma_f32_16x16x32_bf16 v[8:11], v[16:19], v[60:63], 0
	v_mfma_f32_16x16x32_bf16 v[12:15], v[24:27], v[60:63], 0
	v_mfma_f32_16x16x32_bf16 v[8:11], v[20:23], v[100:103], v[8:11]
	v_mfma_f32_16x16x32_bf16 v[12:15], v[28:31], v[100:103], v[12:15]
	v_mfma_f32_16x16x32_bf16 v[60:63], v[16:19], v[104:107], 0
	v_mfma_f32_16x16x32_bf16 v[100:103], v[24:27], v[104:107], 0
	v_mfma_f32_16x16x32_bf16 v[104:107], v[16:19], v[112:115], 0
	v_mfma_f32_16x16x32_bf16 v[16:19], v[16:19], v[120:123], 0
	v_mfma_f32_16x16x32_bf16 v[60:63], v[20:23], v[108:111], v[60:63]
	v_mfma_f32_16x16x32_bf16 v[100:103], v[28:31], v[108:111], v[100:103]
	v_mfma_f32_16x16x32_bf16 v[104:107], v[20:23], v[116:119], v[104:107]
	v_mfma_f32_16x16x32_bf16 v[108:111], v[24:27], v[112:115], 0
	v_mfma_f32_16x16x32_bf16 v[16:19], v[20:23], v[124:127], v[16:19]
	v_mfma_f32_16x16x32_bf16 v[20:23], v[24:27], v[120:123], 0
	v_mfma_f32_16x16x32_bf16 v[108:111], v[28:31], v[116:119], v[108:111]
	v_mfma_f32_16x16x32_bf16 v[20:23], v[28:31], v[124:127], v[20:23]
	s_barrier
	s_add_i32 s79, 0, 0x18000
	s_add_i32 s80, 0, 0x1c000
	v_add_u32_e32 v224, s79, v143
	v_add_u32_e32 v232, s80, v143
	ds_read_b128 v[24:27], v224
	ds_read_b128 v[28:31], v224 offset:1024
	ds_read_b128 v[112:115], v224 offset:2048
	ds_read_b128 v[116:119], v224 offset:3072
	ds_read_b128 v[120:123], v232
	ds_read_b128 v[124:127], v232 offset:1024
	ds_read_b128 v[172:175], v232 offset:2048
	ds_read_b128 v[176:179], v232 offset:3072
	s_add_u32 s70, s40, 0x10100
	s_addc_u32 s71, s41, 0
	s_mov_b32 m0, s54
	v_lshl_add_u64 v[218:219], s[70:71], 0, v[128:129]
	ds_read_b128 v[180:183], v147 offset:32768
	ds_read_b128 v[184:187], v147 offset:33792
	ds_read_b128 v[188:191], v147 offset:34816
	ds_read_b128 v[192:195], v147 offset:35840
	ds_read_b128 v[196:199], v147 offset:36864
	ds_read_b128 v[200:203], v147 offset:37888
	ds_read_b128 v[204:207], v147 offset:38912
	ds_read_b128 v[208:211], v147 offset:39936
	global_load_lds_dwordx4 v[218:219], off
	v_lshl_add_u64 v[218:219], s[70:71], 0, v[132:133]
	s_mov_b32 m0, s55
	s_nop 0
	global_load_lds_dwordx4 v[218:219], off
	s_waitcnt vmcnt(8)
	s_waitcnt lgkmcnt(0)
	s_barrier
	s_waitcnt lgkmcnt(0)
	v_mfma_f32_16x16x32_bf16 v[64:67], v[24:27], v[180:183], v[64:67]
	v_mfma_f32_16x16x32_bf16 v[68:71], v[112:115], v[180:183], v[68:71]
	v_mfma_f32_16x16x32_bf16 v[72:75], v[24:27], v[188:191], v[72:75]
	v_mfma_f32_16x16x32_bf16 v[76:79], v[112:115], v[188:191], v[76:79]
	v_mfma_f32_16x16x32_bf16 v[80:83], v[24:27], v[196:199], v[80:83]
	v_mfma_f32_16x16x32_bf16 v[84:87], v[112:115], v[196:199], v[84:87]
	v_mfma_f32_16x16x32_bf16 v[88:91], v[24:27], v[204:207], v[88:91]
	v_mfma_f32_16x16x32_bf16 v[92:95], v[112:115], v[204:207], v[92:95]
	v_mfma_f32_16x16x32_bf16 v[64:67], v[28:31], v[184:187], v[64:67]
	v_mfma_f32_16x16x32_bf16 v[68:71], v[116:119], v[184:187], v[68:71]
	v_mfma_f32_16x16x32_bf16 v[72:75], v[28:31], v[192:195], v[72:75]
	v_mfma_f32_16x16x32_bf16 v[76:79], v[116:119], v[192:195], v[76:79]
	v_mfma_f32_16x16x32_bf16 v[80:83], v[28:31], v[200:203], v[80:83]
	v_mfma_f32_16x16x32_bf16 v[84:87], v[116:119], v[200:203], v[84:87]
	v_mfma_f32_16x16x32_bf16 v[88:91], v[28:31], v[208:211], v[88:91]
	v_mfma_f32_16x16x32_bf16 v[92:95], v[116:119], v[208:211], v[92:95]
	v_mfma_f32_16x16x32_bf16 v[96:99], v[120:123], v[180:183], v[96:99]
	v_mfma_f32_16x16x32_bf16 v[32:35], v[172:175], v[180:183], v[32:35]
	v_mfma_f32_16x16x32_bf16 v[36:39], v[120:123], v[188:191], v[36:39]
	v_mfma_f32_16x16x32_bf16 v[40:43], v[172:175], v[188:191], v[40:43]
	v_mfma_f32_16x16x32_bf16 v[44:47], v[120:123], v[196:199], v[44:47]
	v_mfma_f32_16x16x32_bf16 v[48:51], v[172:175], v[196:199], v[48:51]
	v_mfma_f32_16x16x32_bf16 v[52:55], v[120:123], v[204:207], v[52:55]
	v_mfma_f32_16x16x32_bf16 v[56:59], v[172:175], v[204:207], v[56:59]
	v_mfma_f32_16x16x32_bf16 v[96:99], v[124:127], v[184:187], v[96:99]
	v_mfma_f32_16x16x32_bf16 v[32:35], v[176:179], v[184:187], v[32:35]
	v_mfma_f32_16x16x32_bf16 v[36:39], v[124:127], v[192:195], v[36:39]
	v_mfma_f32_16x16x32_bf16 v[40:43], v[176:179], v[192:195], v[40:43]
	v_mfma_f32_16x16x32_bf16 v[44:47], v[124:127], v[200:203], v[44:47]
	v_mfma_f32_16x16x32_bf16 v[48:51], v[176:179], v[200:203], v[48:51]
	v_mfma_f32_16x16x32_bf16 v[52:55], v[124:127], v[208:211], v[52:55]
	v_mfma_f32_16x16x32_bf16 v[56:59], v[176:179], v[208:211], v[56:59]
	s_barrier
; #define PG8_STAGE(bufoff, gbase, voff) do { _Pragma("unroll") for (int _i = 0; _i < 2; ++_i) \
;         __builtin_amdgcn_global_load_lds((const unsigned*)((const char*)(gbase) + (voff)[_i]), (PG8_LAS unsigned*)(lds + (bufoff) + ldsw + _i * 8192), 16, 0, 0); } while (0)
; #define PG8_LDA(dst, b, h) do { _Pragma("unroll") for (int m = 0; m < 4; ++m) _Pragma("unroll") for (int k = 0; k < 2; ++k) dst[m][k] = *(const PG8_LAS bf16x8*)(lds + PG8_SA(b, h) + aoff + m * 2048 + k * 1024); } while (0)
; #define PG8_LDB(dst, b, h) do { _Pragma("unroll") for (int n = 0; n < 2; ++n) _Pragma("unroll") for (int k = 0; k < 2; ++k) dst[n][k] = *(const PG8_LAS bf16x8*)(lds + PG8_SB(b, h) + boff + n * 2048 + k * 1024); } while (0)
; #define PG8_MMA(ai, bj, At, Bt) do { __builtin_amdgcn_s_setprio(1); _Pragma("unroll") for (int m = 0; m < 4; ++m) _Pragma("unroll") for (int n = 0; n < 2; ++n) _Pragma("unroll") for (int k = 0; k < 2; ++k) \
;         acc[ai][bj][m][n] = __builtin_amdgcn_mfma_f32_16x16x32_bf16(Bt[n][k], At[m][k], acc[ai][bj][m][n], 0, 0, 0); __builtin_amdgcn_s_setprio(0); } while (0)
; #define PG8_WAIT_V(n) asm volatile("s_waitcnt vmcnt(" #n ")" ::: "memory")
; template <class Epi, class Sched, bool ALIGN_EPI = false, bool SP2 = false>
; __device__ __forceinline__ void gemm_phase(PG8_LAS unsigned char* lds, const Gemm g, const Sched& S, const Epi& E) {
;     ...
;             PG8_LDB(B0, 0, 0); PG8_LDB(B1, 0, 1); PG8_SCHED; PG8_LDA(At, 0, 0); PG8_STAGE(PG8_SA(1, 1), a1 + hstepA, voffA);
;             PG8_WAIT_V(8); PG8_WAIT_L(0); PG8_BAR; PG8_MMA(0, 0, At, B0); PG8_MMA(0, 1, At, B1); PG8_BAR; PG8_SCHED;
;             PG8_LDA(At, 0, 1); PG8_STAGE(PG8_SB(0, 0), b2, voffB); PG8_STAGE(PG8_SB(0, 1), b2 + hstepB, voffB); PG8_STAGE(PG8_SA(0, 0), a2, voffA);
;             PG8_WAIT_V(8); PG8_WAIT_L(0); PG8_BAR; PG8_MMA(1, 0, At, B0); PG8_MMA(1, 1, At, B1); PG8_BAR; PG8_SCHED;
;             PG8_LDB(B0, 1, 0); PG8_LDB(B1, 1, 1); PG8_SCHED; PG8_LDA(At, 1, 0); PG8_STAGE(PG8_SA(0, 1), a2 + hstepA, voffA);
;             PG8_WAIT_V(8); PG8_WAIT_L(0); PG8_BAR; PG8_MMA(0, 0, At, B0); PG8_MMA(0, 1, At, B1); PG8_BAR; PG8_SCHED;
;             PG8_LDA(At, 1, 1); PG8_STAGE(PG8_SB(1, 0), b3, voffB); PG8_STAGE(PG8_SB(1, 1), b3 + hstepB, voffB); PG8_STAGE(PG8_SA(1, 0), a3, voffA);
;             PG8_WAIT_V(8); PG8_WAIT_L(0); PG8_BAR; PG8_MMA(1, 0, At, B0); PG8_MMA(1, 1, At, B1); PG8_BAR; PG8_SCHED;
	s_add_i32 s79, s79, s53
	s_add_i32 s69, s79, 0x2000
	v_lshl_add_u64 v[140:141], v[140:141], 0, s[18:19]
	s_mov_b32 m0, s79
	s_add_u32 s70, s42, 0x10180
	ds_read_b128 v[180:183], v147 offset:49152
	ds_read_b128 v[184:187], v147 offset:50176
	ds_read_b128 v[188:191], v147 offset:51200
	ds_read_b128 v[192:195], v147 offset:52224
	ds_read_b128 v[196:199], v147 offset:53248
	ds_read_b128 v[200:203], v147 offset:54272
	ds_read_b128 v[204:207], v147 offset:55296
	ds_read_b128 v[208:211], v147 offset:56320
	global_load_lds_dwordx4 v[140:141], off
	v_lshl_add_u64 v[140:141], v[212:213], 0, s[18:19]
	s_mov_b32 m0, s69
	s_addc_u32 s71, s43, 0
	s_add_i32 s42, s80, s53
	global_load_lds_dwordx4 v[140:141], off
	v_lshl_add_u64 v[140:141], s[70:71], 0, v[130:131]
	s_mov_b32 m0, s42
	s_add_i32 s43, s42, 0x2000
	global_load_lds_dwordx4 v[140:141], off
	v_lshl_add_u64 v[140:141], s[70:71], 0, v[134:135]
	s_mov_b32 m0, s43
	s_nop 0
	global_load_lds_dwordx4 v[140:141], off
	v_lshl_add_u64 v[140:141], v[214:215], 0, s[18:19]
	s_mov_b32 m0, s56
	s_nop 0
	global_load_lds_dwordx4 v[140:141], off
	v_lshl_add_u64 v[140:141], v[216:217], 0, s[18:19]
	s_mov_b32 m0, s57
	s_nop 0
	global_load_lds_dwordx4 v[140:141], off
	s_waitcnt vmcnt(8)
	s_waitcnt lgkmcnt(0)
	s_barrier
	s_waitcnt lgkmcnt(0)
	v_mfma_f32_16x16x32_bf16 v[0:3], v[24:27], v[204:207], v[0:3]
	v_mfma_f32_16x16x32_bf16 v[4:7], v[112:115], v[204:207], v[4:7]
	v_mfma_f32_16x16x32_bf16 v[148:151], v[24:27], v[180:183], v[148:151]
	v_mfma_f32_16x16x32_bf16 v[152:155], v[112:115], v[180:183], v[152:155]
	v_mfma_f32_16x16x32_bf16 v[156:159], v[24:27], v[188:191], v[156:159]
	v_mfma_f32_16x16x32_bf16 v[160:163], v[112:115], v[188:191], v[160:163]
	v_mfma_f32_16x16x32_bf16 v[164:167], v[24:27], v[196:199], v[164:167]
	v_mfma_f32_16x16x32_bf16 v[168:171], v[112:115], v[196:199], v[168:171]
	v_mfma_f32_16x16x32_bf16 v[0:3], v[28:31], v[208:211], v[0:3]
	v_mfma_f32_16x16x32_bf16 v[4:7], v[116:119], v[208:211], v[4:7]
	v_mfma_f32_16x16x32_bf16 v[148:151], v[28:31], v[184:187], v[148:151]
	v_mfma_f32_16x16x32_bf16 v[152:155], v[116:119], v[184:187], v[152:155]
	v_mfma_f32_16x16x32_bf16 v[156:159], v[28:31], v[192:195], v[156:159]
	v_mfma_f32_16x16x32_bf16 v[160:163], v[116:119], v[192:195], v[160:163]
	v_mfma_f32_16x16x32_bf16 v[164:167], v[28:31], v[200:203], v[164:167]
	v_mfma_f32_16x16x32_bf16 v[168:171], v[116:119], v[200:203], v[168:171]
	v_mfma_f32_16x16x32_bf16 v[8:11], v[120:123], v[180:183], v[8:11]
	v_mfma_f32_16x16x32_bf16 v[12:15], v[172:175], v[180:183], v[12:15]
	v_mfma_f32_16x16x32_bf16 v[24:27], v[120:123], v[188:191], v[60:63]
	v_mfma_f32_16x16x32_bf16 v[28:31], v[172:175], v[188:191], v[100:103]
	v_mfma_f32_16x16x32_bf16 v[60:63], v[120:123], v[196:199], v[104:107]
	v_mfma_f32_16x16x32_bf16 v[100:103], v[172:175], v[196:199], v[108:111]
	v_mfma_f32_16x16x32_bf16 v[16:19], v[120:123], v[204:207], v[16:19]
	v_mfma_f32_16x16x32_bf16 v[20:23], v[172:175], v[204:207], v[20:23]
	v_mfma_f32_16x16x32_bf16 v[8:11], v[124:127], v[184:187], v[8:11]
	v_mfma_f32_16x16x32_bf16 v[12:15], v[176:179], v[184:187], v[12:15]
	v_mfma_f32_16x16x32_bf16 v[24:27], v[124:127], v[192:195], v[24:27]
	v_mfma_f32_16x16x32_bf16 v[28:31], v[176:179], v[192:195], v[28:31]
	v_mfma_f32_16x16x32_bf16 v[60:63], v[124:127], v[200:203], v[60:63]
	v_mfma_f32_16x16x32_bf16 v[100:103], v[176:179], v[200:203], v[100:103]
	v_mfma_f32_16x16x32_bf16 v[16:19], v[124:127], v[208:211], v[16:19]
	v_mfma_f32_16x16x32_bf16 v[20:23], v[176:179], v[208:211], v[20:23]
	s_barrier
	ds_read_b128 v[104:107], v145
	ds_read_b128 v[108:111], v145 offset:1024
	ds_read_b128 v[112:115], v145 offset:2048
	ds_read_b128 v[116:119], v145 offset:3072
	ds_read_b128 v[120:123], v146
	ds_read_b128 v[124:127], v146 offset:1024
	ds_read_b128 v[172:175], v146 offset:2048
	ds_read_b128 v[176:179], v146 offset:3072
	s_add_u32 s40, s40, 0x10180
	s_addc_u32 s41, s41, 0
	s_mov_b32 m0, s78
	v_lshl_add_u64 v[140:141], s[40:41], 0, v[128:129]
	ds_read_b128 v[180:183], v147
	ds_read_b128 v[184:187], v147 offset:1024
	ds_read_b128 v[188:191], v147 offset:2048
	ds_read_b128 v[192:195], v147 offset:3072
	ds_read_b128 v[196:199], v147 offset:4096
	ds_read_b128 v[200:203], v147 offset:5120
	ds_read_b128 v[204:207], v147 offset:6144
	ds_read_b128 v[208:211], v147 offset:7168
	global_load_lds_dwordx4 v[140:141], off
	v_lshl_add_u64 v[140:141], s[40:41], 0, v[132:133]
	s_mov_b32 m0, s29
	s_nop 0
	global_load_lds_dwordx4 v[140:141], off
	s_waitcnt vmcnt(8)
	s_waitcnt lgkmcnt(0)
	s_barrier
; #define PG8_STAGE(bufoff, gbase, voff) do { _Pragma("unroll") for (int _i = 0; _i < 2; ++_i) \
;         __builtin_amdgcn_global_load_lds((const unsigned*)((const char*)(gbase) + (voff)[_i]), (PG8_LAS unsigned*)(lds + (bufoff) + ldsw + _i * 8192), 16, 0, 0); } while (0)
; #define PG8_LDA(dst, b, h) do { _Pragma("unroll") for (int m = 0; m < 4; ++m) _Pragma("unroll") for (int k = 0; k < 2; ++k) dst[m][k] = *(const PG8_LAS bf16x8*)(lds + PG8_SA(b, h) + aoff + m * 2048 + k * 1024); } while (0)
; #define PG8_MMA(ai, bj, At, Bt) do { __builtin_amdgcn_s_setprio(1); _Pragma("unroll") for (int m = 0; m < 4; ++m) _Pragma("unroll") for (int n = 0; n < 2; ++n) _Pragma("unroll") for (int k = 0; k < 2; ++k) \
;         acc[ai][bj][m][n] = __builtin_amdgcn_mfma_f32_16x16x32_bf16(Bt[n][k], At[m][k], acc[ai][bj][m][n], 0, 0, 0); __builtin_amdgcn_s_setprio(0); } while (0)
; #define PG8_WAIT_V(n) asm volatile("s_waitcnt vmcnt(" #n ")" ::: "memory")
; #define PG8_WAIT_L(n) asm volatile("s_waitcnt lgkmcnt(" #n ")" ::: "memory")
; #define PG8_BAR __builtin_amdgcn_s_barrier()
; #define PG8_SCHED __builtin_amdgcn_sched_barrier(0)
; template <class Epi, class Sched, bool ALIGN_EPI = false, bool SP2 = false>
; __device__ __forceinline__ void gemm_phase(PG8_LAS unsigned char* lds, const Gemm g, const Sched& S, const Epi& E) {
;     ...
;             PG8_WAIT_V(8); PG8_WAIT_L(0); PG8_BAR; PG8_MMA(0, 0, At, B0); PG8_MMA(0, 1, At, B1); PG8_BAR; PG8_SCHED;
;             PG8_LDA(At, 0, 1); PG8_STAGE(PG8_SB(0, 0), b2, voffB); PG8_STAGE(PG8_SB(0, 1), b2 + hstepB, voffB); PG8_STAGE(PG8_SA(0, 0), a2, voffA);
;             PG8_WAIT_V(8); PG8_WAIT_L(0); PG8_BAR; PG8_MMA(1, 0, At, B0); PG8_MMA(1, 1, At, B1); PG8_BAR; PG8_SCHED;
	s_waitcnt lgkmcnt(0)
	v_mfma_f32_16x16x32_bf16 v[88:91], v[104:107], v[204:207], v[88:91]
	v_mfma_f32_16x16x32_bf16 v[64:67], v[104:107], v[180:183], v[64:67]
	v_mfma_f32_16x16x32_bf16 v[68:71], v[112:115], v[180:183], v[68:71]
	v_mfma_f32_16x16x32_bf16 v[72:75], v[104:107], v[188:191], v[72:75]
	v_mfma_f32_16x16x32_bf16 v[76:79], v[112:115], v[188:191], v[76:79]
	v_mfma_f32_16x16x32_bf16 v[80:83], v[104:107], v[196:199], v[80:83]
	v_mfma_f32_16x16x32_bf16 v[84:87], v[112:115], v[196:199], v[84:87]
	v_mfma_f32_16x16x32_bf16 v[212:215], v[108:111], v[208:211], v[88:91]
	v_mfma_f32_16x16x32_bf16 v[88:91], v[112:115], v[204:207], v[92:95]
	v_mfma_f32_16x16x32_bf16 v[64:67], v[108:111], v[184:187], v[64:67]
	v_mfma_f32_16x16x32_bf16 v[68:71], v[116:119], v[184:187], v[68:71]
	v_mfma_f32_16x16x32_bf16 v[72:75], v[108:111], v[192:195], v[72:75]
	v_mfma_f32_16x16x32_bf16 v[76:79], v[116:119], v[192:195], v[76:79]
	v_mfma_f32_16x16x32_bf16 v[80:83], v[108:111], v[200:203], v[80:83]
	v_mfma_f32_16x16x32_bf16 v[84:87], v[116:119], v[200:203], v[84:87]
	v_mfma_f32_16x16x32_bf16 v[92:95], v[116:119], v[208:211], v[88:91]
	v_mfma_f32_16x16x32_bf16 v[48:51], v[172:175], v[196:199], v[48:51]
	v_mfma_f32_16x16x32_bf16 v[88:91], v[120:123], v[180:183], v[96:99]
	v_mfma_f32_16x16x32_bf16 v[32:35], v[172:175], v[180:183], v[32:35]
	v_mfma_f32_16x16x32_bf16 v[36:39], v[120:123], v[188:191], v[36:39]
	v_mfma_f32_16x16x32_bf16 v[40:43], v[172:175], v[188:191], v[40:43]
	v_mfma_f32_16x16x32_bf16 v[44:47], v[120:123], v[196:199], v[44:47]
	v_mfma_f32_16x16x32_bf16 v[180:183], v[176:179], v[200:203], v[48:51]
	v_mfma_f32_16x16x32_bf16 v[48:51], v[120:123], v[204:207], v[52:55]
	v_mfma_f32_16x16x32_bf16 v[32:35], v[176:179], v[184:187], v[32:35]
	v_mfma_f32_16x16x32_bf16 v[36:39], v[124:127], v[192:195], v[36:39]
	v_mfma_f32_16x16x32_bf16 v[40:43], v[176:179], v[192:195], v[40:43]
	v_mfma_f32_16x16x32_bf16 v[44:47], v[124:127], v[200:203], v[44:47]
	v_mfma_f32_16x16x32_bf16 v[52:55], v[124:127], v[208:211], v[48:51]
	v_mfma_f32_16x16x32_bf16 v[48:51], v[172:175], v[204:207], v[56:59]
	v_mfma_f32_16x16x32_bf16 v[216:219], v[124:127], v[184:187], v[88:91]
	v_mfma_f32_16x16x32_bf16 v[184:187], v[176:179], v[208:211], v[48:51]
	s_barrier
	s_mov_b32 m0, s68
	v_lshl_add_u64 v[140:141], s[44:45], 0, v[130:131]
	s_add_u32 s40, s44, 0x10000
	s_nop 0
	ds_read_b128 v[48:51], v147 offset:16384
	ds_read_b128 v[56:59], v147 offset:17408
	ds_read_b128 v[88:91], v147 offset:18432
	ds_read_b128 v[96:99], v147 offset:19456
	ds_read_b128 v[188:191], v147 offset:20480
	ds_read_b128 v[192:195], v147 offset:21504
	ds_read_b128 v[196:199], v147 offset:22528
	ds_read_b128 v[200:203], v147 offset:23552
	global_load_lds_dwordx4 v[140:141], off
	v_lshl_add_u64 v[252:253], s[44:45], 0, v[134:135]
	s_mov_b32 m0, s31
	s_addc_u32 s41, s45, 0
	global_load_lds_dwordx4 v[252:253], off
	v_lshl_add_u64 v[204:205], s[40:41], 0, v[130:131]
	s_mov_b32 m0, s66
	v_lshl_add_u64 v[136:137], s[46:47], 0, v[128:129]
	global_load_lds_dwordx4 v[204:205], off
	v_lshl_add_u64 v[204:205], s[40:41], 0, v[134:135]
	s_mov_b32 m0, s67
	v_lshl_add_u64 v[138:139], s[46:47], 0, v[132:133]
	global_load_lds_dwordx4 v[204:205], off
	s_mov_b32 m0, s3
	s_nop 0
	global_load_lds_dwordx4 v[136:137], off
	s_mov_b32 m0, s39
	s_nop 0
	global_load_lds_dwordx4 v[138:139], off
	s_waitcnt vmcnt(8)
	s_waitcnt lgkmcnt(0)
	s_barrier
	s_waitcnt lgkmcnt(0)
	v_mfma_f32_16x16x32_bf16 v[0:3], v[104:107], v[196:199], v[0:3]
	v_mfma_f32_16x16x32_bf16 v[4:7], v[112:115], v[196:199], v[4:7]
	v_mfma_f32_16x16x32_bf16 v[148:151], v[104:107], v[48:51], v[148:151]
	v_mfma_f32_16x16x32_bf16 v[152:155], v[112:115], v[48:51], v[152:155]
	v_mfma_f32_16x16x32_bf16 v[156:159], v[104:107], v[88:91], v[156:159]
	v_mfma_f32_16x16x32_bf16 v[160:163], v[112:115], v[88:91], v[160:163]
	v_mfma_f32_16x16x32_bf16 v[164:167], v[104:107], v[188:191], v[164:167]
	v_mfma_f32_16x16x32_bf16 v[168:171], v[112:115], v[188:191], v[168:171]
	v_mfma_f32_16x16x32_bf16 v[0:3], v[108:111], v[200:203], v[0:3]
	v_mfma_f32_16x16x32_bf16 v[4:7], v[116:119], v[200:203], v[4:7]
	v_mfma_f32_16x16x32_bf16 v[148:151], v[108:111], v[56:59], v[148:151]
	v_mfma_f32_16x16x32_bf16 v[152:155], v[116:119], v[56:59], v[152:155]
	v_mfma_f32_16x16x32_bf16 v[156:159], v[108:111], v[96:99], v[156:159]
	v_mfma_f32_16x16x32_bf16 v[160:163], v[116:119], v[96:99], v[160:163]
	v_mfma_f32_16x16x32_bf16 v[164:167], v[108:111], v[192:195], v[164:167]
	v_mfma_f32_16x16x32_bf16 v[168:171], v[116:119], v[192:195], v[168:171]
	v_mfma_f32_16x16x32_bf16 v[12:15], v[172:175], v[48:51], v[12:15]
	v_mfma_f32_16x16x32_bf16 v[204:207], v[176:179], v[56:59], v[12:15]
	v_mfma_f32_16x16x32_bf16 v[12:15], v[120:123], v[88:91], v[24:27]
	v_mfma_f32_16x16x32_bf16 v[24:27], v[124:127], v[96:99], v[12:15]
	v_mfma_f32_16x16x32_bf16 v[12:15], v[172:175], v[88:91], v[28:31]
	v_mfma_f32_16x16x32_bf16 v[208:211], v[176:179], v[96:99], v[12:15]
	v_mfma_f32_16x16x32_bf16 v[12:15], v[120:123], v[188:191], v[60:63]
	v_mfma_f32_16x16x32_bf16 v[220:223], v[124:127], v[192:195], v[12:15]
	v_mfma_f32_16x16x32_bf16 v[12:15], v[172:175], v[188:191], v[100:103]
	v_mfma_f32_16x16x32_bf16 v[8:11], v[120:123], v[48:51], v[8:11]
	v_mfma_f32_16x16x32_bf16 v[188:191], v[176:179], v[192:195], v[12:15]
	v_mfma_f32_16x16x32_bf16 v[12:15], v[120:123], v[196:199], v[16:19]
	v_mfma_f32_16x16x32_bf16 v[8:11], v[124:127], v[56:59], v[8:11]
	v_mfma_f32_16x16x32_bf16 v[192:195], v[124:127], v[200:203], v[12:15]
	v_mfma_f32_16x16x32_bf16 v[12:15], v[172:175], v[196:199], v[20:23]
	v_mfma_f32_16x16x32_bf16 v[172:175], v[176:179], v[200:203], v[12:15]
	s_barrier
; #define PG8_STAGE(bufoff, gbase, voff) do { _Pragma("unroll") for (int _i = 0; _i < 2; ++_i) \
;         __builtin_amdgcn_global_load_lds((const unsigned*)((const char*)(gbase) + (voff)[_i]), (PG8_LAS unsigned*)(lds + (bufoff) + ldsw + _i * 8192), 16, 0, 0); } while (0)
; #define PG8_LDA(dst, b, h) do { _Pragma("unroll") for (int m = 0; m < 4; ++m) _Pragma("unroll") for (int k = 0; k < 2; ++k) dst[m][k] = *(const PG8_LAS bf16x8*)(lds + PG8_SA(b, h) + aoff + m * 2048 + k * 1024); } while (0)
; #define PG8_LDB(dst, b, h) do { _Pragma("unroll") for (int n = 0; n < 2; ++n) _Pragma("unroll") for (int k = 0; k < 2; ++k) dst[n][k] = *(const PG8_LAS bf16x8*)(lds + PG8_SB(b, h) + boff + n * 2048 + k * 1024); } while (0)
; #define PG8_MMA(ai, bj, At, Bt) do { __builtin_amdgcn_s_setprio(1); _Pragma("unroll") for (int m = 0; m < 4; ++m) _Pragma("unroll") for (int n = 0; n < 2; ++n) _Pragma("unroll") for (int k = 0; k < 2; ++k) \
;         acc[ai][bj][m][n] = __builtin_amdgcn_mfma_f32_16x16x32_bf16(Bt[n][k], At[m][k], acc[ai][bj][m][n], 0, 0, 0); __builtin_amdgcn_s_setprio(0); } while (0)
; #define PG8_WAIT_V(n) asm volatile("s_waitcnt vmcnt(" #n ")" ::: "memory")
; #define PG8_WAIT_L(n) asm volatile("s_waitcnt lgkmcnt(" #n ")" ::: "memory")
; #define PG8_BAR __builtin_amdgcn_s_barrier()
; #define PG8_SCHED __builtin_amdgcn_sched_barrier(0)
; template <class Epi, class Sched, bool ALIGN_EPI = false, bool SP2 = false>
; __device__ __forceinline__ void gemm_phase(PG8_LAS unsigned char* lds, const Gemm g, const Sched& S, const Epi& E) {
;     ...
;             PG8_LDB(B0, 1, 0); PG8_LDB(B1, 1, 1); PG8_SCHED; PG8_LDA(At, 1, 0); PG8_STAGE(PG8_SA(0, 1), a2 + hstepA, voffA);
;             PG8_WAIT_V(8); PG8_WAIT_L(0); PG8_BAR; PG8_MMA(0, 0, At, B0); PG8_MMA(0, 1, At, B1); PG8_BAR; PG8_SCHED;
;             PG8_LDA(At, 1, 1); PG8_STAGE(PG8_SB(1, 0), b3, voffB); PG8_STAGE(PG8_SB(1, 1), b3 + hstepB, voffB); PG8_STAGE(PG8_SA(1, 0), a3, voffA);
;             PG8_WAIT_V(8); PG8_WAIT_L(0); PG8_BAR; PG8_MMA(1, 0, At, B0); PG8_MMA(1, 1, At, B1); PG8_BAR; PG8_SCHED;
;     ...
;         if (!has_next) break;
	s_nop 4
	ds_read_b128 v[12:15], v224
	ds_read_b128 v[16:19], v224 offset:1024
	ds_read_b128 v[176:179], v224 offset:2048
	ds_read_b128 v[196:199], v224 offset:3072
	ds_read_b128 v[200:203], v232
	ds_read_b128 v[224:227], v232 offset:1024
	ds_read_b128 v[228:231], v232 offset:2048
	ds_read_b128 v[232:235], v232 offset:3072
	s_add_u32 s40, s46, 0x10000
	s_addc_u32 s41, s47, 0
	s_mov_b32 m0, s54
	v_lshl_add_u64 v[48:49], s[40:41], 0, v[128:129]
	ds_read_b128 v[20:23], v147 offset:32768
	ds_read_b128 v[28:31], v147 offset:33792
	ds_read_b128 v[60:63], v147 offset:34816
	ds_read_b128 v[100:103], v147 offset:35840
	ds_read_b128 v[236:239], v147 offset:36864
	ds_read_b128 v[240:243], v147 offset:37888
	ds_read_b128 v[244:247], v147 offset:38912
	ds_read_b128 v[248:251], v147 offset:39936
	global_load_lds_dwordx4 v[48:49], off
	v_lshl_add_u64 v[48:49], s[40:41], 0, v[132:133]
	s_mov_b32 m0, s55
	s_nop 0
	global_load_lds_dwordx4 v[48:49], off
	s_waitcnt vmcnt(8)
	s_waitcnt lgkmcnt(0)
	s_barrier
	s_waitcnt lgkmcnt(0)
	v_mfma_f32_16x16x32_bf16 v[48:51], v[12:15], v[20:23], v[64:67]
	v_mfma_f32_16x16x32_bf16 v[120:123], v[16:19], v[28:31], v[48:51]
	v_mfma_f32_16x16x32_bf16 v[48:51], v[176:179], v[20:23], v[68:71]
	v_mfma_f32_16x16x32_bf16 v[112:115], v[196:199], v[28:31], v[48:51]
	v_mfma_f32_16x16x32_bf16 v[48:51], v[12:15], v[60:63], v[72:75]
	v_mfma_f32_16x16x32_bf16 v[104:107], v[16:19], v[100:103], v[48:51]
	v_mfma_f32_16x16x32_bf16 v[48:51], v[176:179], v[60:63], v[76:79]
	v_mfma_f32_16x16x32_bf16 v[96:99], v[196:199], v[100:103], v[48:51]
	v_mfma_f32_16x16x32_bf16 v[48:51], v[12:15], v[236:239], v[80:83]
	v_mfma_f32_16x16x32_bf16 v[88:91], v[16:19], v[240:243], v[48:51]
	v_mfma_f32_16x16x32_bf16 v[48:51], v[176:179], v[236:239], v[84:87]
	v_mfma_f32_16x16x32_bf16 v[80:83], v[196:199], v[240:243], v[48:51]
	v_mfma_f32_16x16x32_bf16 v[48:51], v[12:15], v[244:247], v[212:215]
	v_mfma_f32_16x16x32_bf16 v[56:59], v[16:19], v[248:251], v[48:51]
	v_mfma_f32_16x16x32_bf16 v[48:51], v[176:179], v[244:247], v[92:95]
	v_mfma_f32_16x16x32_bf16 v[48:51], v[196:199], v[248:251], v[48:51]
	v_mfma_f32_16x16x32_bf16 v[64:67], v[200:203], v[20:23], v[216:219]
	v_mfma_f32_16x16x32_bf16 v[20:23], v[228:231], v[20:23], v[32:35]
	v_mfma_f32_16x16x32_bf16 v[116:119], v[232:235], v[28:31], v[20:23]
	v_mfma_f32_16x16x32_bf16 v[20:23], v[200:203], v[60:63], v[36:39]
	v_mfma_f32_16x16x32_bf16 v[108:111], v[224:227], v[100:103], v[20:23]
	v_mfma_f32_16x16x32_bf16 v[20:23], v[228:231], v[60:63], v[40:43]
	v_mfma_f32_16x16x32_bf16 v[100:103], v[232:235], v[100:103], v[20:23]
	v_mfma_f32_16x16x32_bf16 v[20:23], v[200:203], v[236:239], v[44:47]
	v_mfma_f32_16x16x32_bf16 v[92:95], v[224:227], v[240:243], v[20:23]
	v_mfma_f32_16x16x32_bf16 v[20:23], v[228:231], v[236:239], v[180:183]
	v_mfma_f32_16x16x32_bf16 v[84:87], v[232:235], v[240:243], v[20:23]
	v_mfma_f32_16x16x32_bf16 v[20:23], v[200:203], v[244:247], v[52:55]
	v_mfma_f32_16x16x32_bf16 v[60:63], v[224:227], v[248:251], v[20:23]
	v_mfma_f32_16x16x32_bf16 v[20:23], v[228:231], v[244:247], v[184:187]
	v_mfma_f32_16x16x32_bf16 v[124:127], v[224:227], v[28:31], v[64:67]
	v_mfma_f32_16x16x32_bf16 v[52:55], v[232:235], v[248:251], v[20:23]
	s_barrier
	s_mov_b32 m0, s79
	s_nop 2
	v_lshl_add_u64 v[20:21], v[140:141], 0, s[10:11]
	s_add_u32 s40, s44, 0x10080
	ds_read_b128 v[32:35], v147 offset:49152
	ds_read_b128 v[40:43], v147 offset:50176
	ds_read_b128 v[180:183], v147 offset:51200
	ds_read_b128 v[184:187], v147 offset:52224
	ds_read_b128 v[212:215], v147 offset:53248
	ds_read_b128 v[216:219], v147 offset:54272
	ds_read_b128 v[236:239], v147 offset:55296
	ds_read_b128 v[240:243], v147 offset:56320
	global_load_lds_dwordx4 v[20:21], off
	v_lshl_add_u64 v[20:21], v[252:253], 0, s[10:11]
	s_mov_b32 m0, s69
	s_addc_u32 s41, s45, 0
	global_load_lds_dwordx4 v[20:21], off
	v_lshl_add_u64 v[20:21], s[40:41], 0, v[130:131]
	s_mov_b32 m0, s42
	s_nop 0
	global_load_lds_dwordx4 v[20:21], off
	v_lshl_add_u64 v[20:21], s[40:41], 0, v[134:135]
	s_mov_b32 m0, s43
	s_nop 0
	global_load_lds_dwordx4 v[20:21], off
	v_lshl_add_u64 v[20:21], v[136:137], 0, s[10:11]
	s_mov_b32 m0, s56
	s_nop 0
	global_load_lds_dwordx4 v[20:21], off
	v_lshl_add_u64 v[20:21], v[138:139], 0, s[10:11]
	s_mov_b32 m0, s57
	s_nop 0
	global_load_lds_dwordx4 v[20:21], off
	s_waitcnt vmcnt(8)
	s_waitcnt lgkmcnt(0)
	s_barrier
	s_waitcnt lgkmcnt(0)
	v_mfma_f32_16x16x32_bf16 v[20:23], v[12:15], v[32:35], v[148:151]
	v_mfma_f32_16x16x32_bf16 v[76:79], v[16:19], v[40:43], v[20:23]
	v_mfma_f32_16x16x32_bf16 v[20:23], v[176:179], v[32:35], v[152:155]
	v_mfma_f32_16x16x32_bf16 v[68:71], v[196:199], v[40:43], v[20:23]
	v_mfma_f32_16x16x32_bf16 v[20:23], v[12:15], v[180:183], v[156:159]
	v_mfma_f32_16x16x32_bf16 v[44:47], v[16:19], v[184:187], v[20:23]
	v_mfma_f32_16x16x32_bf16 v[20:23], v[176:179], v[180:183], v[160:163]
	v_mfma_f32_16x16x32_bf16 v[36:39], v[196:199], v[184:187], v[20:23]
	v_mfma_f32_16x16x32_bf16 v[20:23], v[12:15], v[212:215], v[164:167]
	v_mfma_f32_16x16x32_bf16 v[0:3], v[12:15], v[236:239], v[0:3]
	v_mfma_f32_16x16x32_bf16 v[28:31], v[16:19], v[216:219], v[20:23]
	v_mfma_f32_16x16x32_bf16 v[20:23], v[176:179], v[212:215], v[168:171]
	v_mfma_f32_16x16x32_bf16 v[12:15], v[16:19], v[240:243], v[0:3]
	v_mfma_f32_16x16x32_bf16 v[0:3], v[176:179], v[236:239], v[4:7]
	v_mfma_f32_16x16x32_bf16 v[20:23], v[196:199], v[216:219], v[20:23]
	v_mfma_f32_16x16x32_bf16 v[4:7], v[196:199], v[240:243], v[0:3]
	v_mfma_f32_16x16x32_bf16 v[0:3], v[200:203], v[32:35], v[8:11]
	v_mfma_f32_16x16x32_bf16 v[72:75], v[224:227], v[40:43], v[0:3]
	v_mfma_f32_16x16x32_bf16 v[0:3], v[228:231], v[32:35], v[204:207]
	v_mfma_f32_16x16x32_bf16 v[64:67], v[232:235], v[40:43], v[0:3]
	v_mfma_f32_16x16x32_bf16 v[0:3], v[200:203], v[180:183], v[24:27]
	v_mfma_f32_16x16x32_bf16 v[40:43], v[224:227], v[184:187], v[0:3]
	v_mfma_f32_16x16x32_bf16 v[0:3], v[228:231], v[180:183], v[208:211]
	v_mfma_f32_16x16x32_bf16 v[32:35], v[232:235], v[184:187], v[0:3]
	v_mfma_f32_16x16x32_bf16 v[0:3], v[200:203], v[212:215], v[220:223]
	v_mfma_f32_16x16x32_bf16 v[24:27], v[224:227], v[216:219], v[0:3]
	v_mfma_f32_16x16x32_bf16 v[0:3], v[228:231], v[212:215], v[188:191]
	v_mfma_f32_16x16x32_bf16 v[16:19], v[232:235], v[216:219], v[0:3]
	v_mfma_f32_16x16x32_bf16 v[0:3], v[200:203], v[236:239], v[192:195]
	v_mfma_f32_16x16x32_bf16 v[8:11], v[224:227], v[240:243], v[0:3]
	v_mfma_f32_16x16x32_bf16 v[0:3], v[228:231], v[236:239], v[172:175]
	v_mfma_f32_16x16x32_bf16 v[0:3], v[232:235], v[240:243], v[0:3]
	s_barrier
	s_andn2_b64 vcc, exec, s[12:13]
	s_cbranch_vccnz .LBB0_1300
	s_barrier

;     __host__ __device__ bool next(int i, Unit& u) const {
;         const long L = (long)i * G + c; if (L >= nwg) return false;
;         int wgid = (int)L; { const int q = nwg / NXCD, r = nwg % NXCD, xcd = wgid % NXCD, off = wgid / NXCD; wgid = (xcd < r ? xcd * (q + 1) : r * (q + 1) + (xcd - r) * q) + off; }
;         const int nig = WGM * nN, gid = wgid / nig, fm = gid * WGM, gsz = (nM - fm) < WGM ? (nM - fm) : WGM;
;         u.pm = fm + ((wgid % nig) % gsz); u.pn = (wgid % nig) / gsz; return true;
.Lprio_ffn2_1:
	s_mov_b32 s31, s74
	s_mov_b64 s[8:9], s[0:1]
	s_mov_b32 s35, s2
	s_waitcnt lgkmcnt(0)
	s_barrier
	v_mov_b32_e32 v8, v254
	s_cmpk_lt_i32 s35, 0x200
	s_cselect_b64 s[10:11], -1, 0
	s_cmpk_gt_i32 s35, 0x1ff
	v_readfirstlane_b32 s3, v8
	s_cbranch_scc1 .LBB0_1362
	s_ashr_i32 s4, s35, 31
	s_lshr_b32 s4, s4, 29
	s_add_i32 s12, s35, s4
	s_and_b32 s4, s12, -8
	s_sub_i32 s6, s35, s4
	s_cmp_gt_i32 s6, -1
	s_cbranch_scc0 .LBB0_1359
	s_lshl_b32 s7, s6, 6
	s_ashr_i32 s4, s12, 3
	s_cbranch_execz .LBB0_1360
	s_branch .LBB0_1361

; #define PG8_STAGE(bufoff, gbase, voff) do { _Pragma("unroll") for (int _i = 0; _i < 2; ++_i) \
;         __builtin_amdgcn_global_load_lds((const unsigned*)((const char*)(gbase) + (voff)[_i]), (PG8_LAS unsigned*)(lds + (bufoff) + ldsw + _i * 8192), 16, 0, 0); } while (0)
; #define PG8_LDA(dst, b, h) do { _Pragma("unroll") for (int m = 0; m < 4; ++m) _Pragma("unroll") for (int k = 0; k < 2; ++k) dst[m][k] = *(const PG8_LAS bf16x8*)(lds + PG8_SA(b, h) + aoff + m * 2048 + k * 1024); } while (0)
; #define PG8_LDB(dst, b, h) do { _Pragma("unroll") for (int n = 0; n < 2; ++n) _Pragma("unroll") for (int k = 0; k < 2; ++k) dst[n][k] = *(const PG8_LAS bf16x8*)(lds + PG8_SB(b, h) + boff + n * 2048 + k * 1024); } while (0)
; #define PG8_MMA(ai, bj, At, Bt) do { __builtin_amdgcn_s_setprio(1); _Pragma("unroll") for (int m = 0; m < 4; ++m) _Pragma("unroll") for (int n = 0; n < 2; ++n) _Pragma("unroll") for (int k = 0; k < 2; ++k) \
;         acc[ai][bj][m][n] = __builtin_amdgcn_mfma_f32_16x16x32_bf16(Bt[n][k], At[m][k], acc[ai][bj][m][n], 0, 0, 0); __builtin_amdgcn_s_setprio(0); } while (0)
; #define PG8_WAIT_V(n) asm volatile("s_waitcnt vmcnt(" #n ")" ::: "memory")
; #define PG8_WAIT_L(n) asm volatile("s_waitcnt lgkmcnt(" #n ")" ::: "memory")
; template <class Epi, class Sched, bool ALIGN_EPI = false, bool SP2 = false>
; __device__ __forceinline__ void gemm_phase(PG8_LAS unsigned char* lds, const Gemm g, const Sched& S, const Epi& E) {
;     ...
;             const bool last = (t == nt - 2);
;             const char* a1 = cA + PG8_AK(t + 1);
;             const char* a2 = last ? nA : cA + PG8_AK(t + 2); const char* b2 = last ? nB : cB + (size_t)(t + 2) * kstep;
;             const char* a3 = last ? nA + PG8_AK(1) : cA + PG8_AK(t + 3); const char* b3 = b2 + kstep;
;             if (last && has_next) S.a_ready(nxt);
;             if constexpr (SP2) {
;             PG8_LDB(B0, 0, 0); PG8_LDB(B1, 0, 1); PG8_SCHED; PG8_LDA(At, 0, 0); PG8_STAGE(PG8_SA(1, 1), a1 + hstepA, voffA);
;             PG8_WAIT_V(8); PG8_WAIT_L(0); PG8_BAR; PG8_MMA(0, 0, At, B0); PG8_MMA(0, 1, At, B1); PG8_BAR; PG8_SCHED;
;             PG8_LDA(At, 0, 1); PG8_STAGE(PG8_SB(0, 0), b2, voffB); PG8_STAGE(PG8_SB(0, 1), b2 + hstepB, voffB); PG8_STAGE(PG8_SA(0, 0), a2, voffA);
;             PG8_WAIT_V(8); PG8_WAIT_L(0); PG8_BAR; PG8_MMA(1, 0, At, B0); PG8_MMA(1, 1, At, B1); PG8_BAR; PG8_SCHED;
.LBB0_1379:
	ds_read_b128 v[124:127], v210
	ds_read_b128 v[128:131], v210 offset:1024
	ds_read_b128 v[132:135], v210 offset:2048
	ds_read_b128 v[144:147], v210 offset:3072
	ds_read_b128 v[148:151], v211
	ds_read_b128 v[170:173], v211 offset:1024
	ds_read_b128 v[174:177], v211 offset:2048
	ds_read_b128 v[178:181], v211 offset:3072
	s_add_u32 s42, s38, s40
	s_addc_u32 s43, s39, s41
	s_add_u32 s46, s42, 0x100
	s_addc_u32 s47, s43, 0
	s_add_u32 s44, s78, s40
	s_addc_u32 s45, s79, s41
	s_add_u32 s42, s42, 0x180
	s_addc_u32 s43, s43, 0
	s_cmpk_eq_i32 s40, 0x1500
	s_cselect_b32 s43, s10, s43
	s_cselect_b32 s42, s3, s42
	s_cselect_b32 s45, s37, s45
	s_cselect_b32 s44, s36, s44
	s_cselect_b32 s47, s9, s47
	s_cselect_b32 s46, s8, s46
	v_lshl_add_u64 v[206:207], v[122:123], 0, s[40:41]
	s_add_i32 m0, s53, 0xc000
	ds_read_b128 v[212:215], v191
	ds_read_b128 v[216:219], v191 offset:1024
	ds_read_b128 v[220:223], v191 offset:2048
	ds_read_b128 v[224:227], v191 offset:3072
	ds_read_b128 v[228:231], v191 offset:4096
	ds_read_b128 v[232:235], v191 offset:5120
	ds_read_b128 v[236:239], v191 offset:6144
	ds_read_b128 v[240:243], v191 offset:7168
	global_load_lds_dwordx4 v[206:207], off
	v_lshl_add_u64 v[206:207], v[120:121], 0, s[40:41]
	s_add_i32 m0, s53, 0xe000
	s_nop 0
	global_load_lds_dwordx4 v[206:207], off
	s_waitcnt vmcnt(8)
	s_waitcnt lgkmcnt(0)
	s_barrier
	s_waitcnt lgkmcnt(0)
	v_mfma_f32_16x16x32_bf16 v[140:143], v[124:127], v[212:215], v[140:143]
	v_mfma_f32_16x16x32_bf16 v[136:139], v[132:135], v[212:215], v[136:139]
	v_mfma_f32_16x16x32_bf16 v[116:119], v[124:127], v[220:223], v[116:119]
	v_mfma_f32_16x16x32_bf16 v[112:115], v[132:135], v[220:223], v[112:115]
	v_mfma_f32_16x16x32_bf16 v[108:111], v[124:127], v[228:231], v[108:111]
	v_mfma_f32_16x16x32_bf16 v[104:107], v[132:135], v[228:231], v[104:107]
	v_mfma_f32_16x16x32_bf16 v[100:103], v[124:127], v[236:239], v[100:103]
	v_mfma_f32_16x16x32_bf16 v[96:99], v[132:135], v[236:239], v[96:99]
	v_mfma_f32_16x16x32_bf16 v[140:143], v[128:131], v[216:219], v[140:143]
	v_mfma_f32_16x16x32_bf16 v[136:139], v[144:147], v[216:219], v[136:139]
	v_mfma_f32_16x16x32_bf16 v[116:119], v[128:131], v[224:227], v[116:119]
	v_mfma_f32_16x16x32_bf16 v[112:115], v[144:147], v[224:227], v[112:115]
	v_mfma_f32_16x16x32_bf16 v[108:111], v[128:131], v[232:235], v[108:111]
	v_mfma_f32_16x16x32_bf16 v[104:107], v[144:147], v[232:235], v[104:107]
	v_mfma_f32_16x16x32_bf16 v[100:103], v[128:131], v[240:243], v[100:103]
	v_mfma_f32_16x16x32_bf16 v[96:99], v[144:147], v[240:243], v[96:99]
	v_mfma_f32_16x16x32_bf16 v[60:63], v[148:151], v[212:215], v[60:63]
	v_mfma_f32_16x16x32_bf16 v[56:59], v[174:177], v[212:215], v[56:59]
	v_mfma_f32_16x16x32_bf16 v[52:55], v[148:151], v[220:223], v[52:55]
	v_mfma_f32_16x16x32_bf16 v[48:51], v[174:177], v[220:223], v[48:51]
	v_mfma_f32_16x16x32_bf16 v[44:47], v[148:151], v[228:231], v[44:47]
	v_mfma_f32_16x16x32_bf16 v[40:43], v[174:177], v[228:231], v[40:43]
	v_mfma_f32_16x16x32_bf16 v[36:39], v[148:151], v[236:239], v[36:39]
	v_mfma_f32_16x16x32_bf16 v[32:35], v[174:177], v[236:239], v[32:35]
	v_mfma_f32_16x16x32_bf16 v[60:63], v[170:173], v[216:219], v[60:63]
	v_mfma_f32_16x16x32_bf16 v[56:59], v[178:181], v[216:219], v[56:59]
	v_mfma_f32_16x16x32_bf16 v[52:55], v[170:173], v[224:227], v[52:55]
	v_mfma_f32_16x16x32_bf16 v[48:51], v[178:181], v[224:227], v[48:51]
	v_mfma_f32_16x16x32_bf16 v[44:47], v[170:173], v[232:235], v[44:47]
	v_mfma_f32_16x16x32_bf16 v[40:43], v[178:181], v[232:235], v[40:43]
	v_mfma_f32_16x16x32_bf16 v[36:39], v[170:173], v[240:243], v[36:39]
	v_mfma_f32_16x16x32_bf16 v[32:35], v[178:181], v[240:243], v[32:35]
	s_barrier
	s_add_i32 s70, s67, s52
	v_lshl_add_u64 v[206:207], s[44:45], 0, v[154:155]
	s_mov_b32 m0, s70
	ds_read_b128 v[212:215], v191 offset:16384
	ds_read_b128 v[216:219], v191 offset:17408
	ds_read_b128 v[220:223], v191 offset:18432
	ds_read_b128 v[224:227], v191 offset:19456
	ds_read_b128 v[228:231], v191 offset:20480
	ds_read_b128 v[232:235], v191 offset:21504
	ds_read_b128 v[236:239], v191 offset:22528
	ds_read_b128 v[240:243], v191 offset:23552
	global_load_lds_dwordx4 v[206:207], off
	s_add_i32 m0, s70, 0x2000
	s_add_u32 s70, s44, 0xb0000
	v_lshl_add_u64 v[244:245], s[44:45], 0, v[158:159]
	s_addc_u32 s71, s45, 0
	s_add_i32 s85, s68, s52
	global_load_lds_dwordx4 v[244:245], off
	v_lshl_add_u64 v[246:247], s[70:71], 0, v[154:155]
	s_mov_b32 m0, s85
	s_nop 0
	global_load_lds_dwordx4 v[246:247], off
	v_lshl_add_u64 v[246:247], s[70:71], 0, v[158:159]
	s_add_i32 m0, s85, 0x2000
	s_nop 0
	global_load_lds_dwordx4 v[246:247], off
	v_lshl_add_u64 v[246:247], s[46:47], 0, v[152:153]
	s_mov_b32 m0, s53
	s_nop 0
	global_load_lds_dwordx4 v[246:247], off
	v_lshl_add_u64 v[246:247], s[46:47], 0, v[156:157]
	s_mov_b32 m0, s54
	s_nop 0
	global_load_lds_dwordx4 v[246:247], off
	s_waitcnt vmcnt(8)
	s_waitcnt lgkmcnt(0)
	s_barrier
; #define PG8_STAGE(bufoff, gbase, voff) do { _Pragma("unroll") for (int _i = 0; _i < 2; ++_i) \
;         __builtin_amdgcn_global_load_lds((const unsigned*)((const char*)(gbase) + (voff)[_i]), (PG8_LAS unsigned*)(lds + (bufoff) + ldsw + _i * 8192), 16, 0, 0); } while (0)
; #define PG8_LDA(dst, b, h) do { _Pragma("unroll") for (int m = 0; m < 4; ++m) _Pragma("unroll") for (int k = 0; k < 2; ++k) dst[m][k] = *(const PG8_LAS bf16x8*)(lds + PG8_SA(b, h) + aoff + m * 2048 + k * 1024); } while (0)
; #define PG8_LDB(dst, b, h) do { _Pragma("unroll") for (int n = 0; n < 2; ++n) _Pragma("unroll") for (int k = 0; k < 2; ++k) dst[n][k] = *(const PG8_LAS bf16x8*)(lds + PG8_SB(b, h) + boff + n * 2048 + k * 1024); } while (0)
; #define PG8_MMA(ai, bj, At, Bt) do { __builtin_amdgcn_s_setprio(1); _Pragma("unroll") for (int m = 0; m < 4; ++m) _Pragma("unroll") for (int n = 0; n < 2; ++n) _Pragma("unroll") for (int k = 0; k < 2; ++k) \
;         acc[ai][bj][m][n] = __builtin_amdgcn_mfma_f32_16x16x32_bf16(Bt[n][k], At[m][k], acc[ai][bj][m][n], 0, 0, 0); __builtin_amdgcn_s_setprio(0); } while (0)
; #define PG8_WAIT_V(n) asm volatile("s_waitcnt vmcnt(" #n ")" ::: "memory")
; #define PG8_WAIT_L(n) asm volatile("s_waitcnt lgkmcnt(" #n ")" ::: "memory")
; #define PG8_BAR __builtin_amdgcn_s_barrier()
; #define PG8_SCHED __builtin_amdgcn_sched_barrier(0)
; template <class Epi, class Sched, bool ALIGN_EPI = false, bool SP2 = false>
; __device__ __forceinline__ void gemm_phase(PG8_LAS unsigned char* lds, const Gemm g, const Sched& S, const Epi& E) {
;     ...
;             PG8_WAIT_V(8); PG8_WAIT_L(0); PG8_BAR; PG8_MMA(1, 0, At, B0); PG8_MMA(1, 1, At, B1); PG8_BAR; PG8_SCHED;
;             PG8_LDB(B0, 1, 0); PG8_LDB(B1, 1, 1); PG8_SCHED; PG8_LDA(At, 1, 0); PG8_STAGE(PG8_SA(0, 1), a2 + hstepA, voffA);
;             PG8_WAIT_V(8); PG8_WAIT_L(0); PG8_BAR; PG8_MMA(0, 0, At, B0); PG8_MMA(0, 1, At, B1); PG8_BAR; PG8_SCHED;
	s_waitcnt lgkmcnt(0)
	v_mfma_f32_16x16x32_bf16 v[92:95], v[124:127], v[212:215], v[92:95]
	v_mfma_f32_16x16x32_bf16 v[88:91], v[132:135], v[212:215], v[88:91]
	v_mfma_f32_16x16x32_bf16 v[84:87], v[124:127], v[220:223], v[84:87]
	v_mfma_f32_16x16x32_bf16 v[80:83], v[132:135], v[220:223], v[80:83]
	v_mfma_f32_16x16x32_bf16 v[76:79], v[124:127], v[228:231], v[76:79]
	v_mfma_f32_16x16x32_bf16 v[72:75], v[132:135], v[228:231], v[72:75]
	v_mfma_f32_16x16x32_bf16 v[68:71], v[124:127], v[236:239], v[68:71]
	v_mfma_f32_16x16x32_bf16 v[64:67], v[132:135], v[236:239], v[64:67]
	v_mfma_f32_16x16x32_bf16 v[92:95], v[128:131], v[216:219], v[92:95]
	v_mfma_f32_16x16x32_bf16 v[88:91], v[144:147], v[216:219], v[88:91]
	v_mfma_f32_16x16x32_bf16 v[84:87], v[128:131], v[224:227], v[84:87]
	v_mfma_f32_16x16x32_bf16 v[80:83], v[144:147], v[224:227], v[80:83]
	v_mfma_f32_16x16x32_bf16 v[76:79], v[128:131], v[232:235], v[76:79]
	v_mfma_f32_16x16x32_bf16 v[72:75], v[144:147], v[232:235], v[72:75]
	v_mfma_f32_16x16x32_bf16 v[68:71], v[128:131], v[240:243], v[68:71]
	v_mfma_f32_16x16x32_bf16 v[64:67], v[144:147], v[240:243], v[64:67]
	v_mfma_f32_16x16x32_bf16 v[28:31], v[148:151], v[212:215], v[28:31]
	v_mfma_f32_16x16x32_bf16 v[24:27], v[174:177], v[212:215], v[24:27]
	v_mfma_f32_16x16x32_bf16 v[20:23], v[148:151], v[220:223], v[20:23]
	v_mfma_f32_16x16x32_bf16 v[16:19], v[174:177], v[220:223], v[16:19]
	v_mfma_f32_16x16x32_bf16 v[12:15], v[148:151], v[228:231], v[12:15]
	v_mfma_f32_16x16x32_bf16 v[8:11], v[174:177], v[228:231], v[8:11]
	v_mfma_f32_16x16x32_bf16 v[4:7], v[148:151], v[236:239], v[4:7]
	v_mfma_f32_16x16x32_bf16 v[0:3], v[174:177], v[236:239], v[0:3]
	v_mfma_f32_16x16x32_bf16 v[28:31], v[170:173], v[216:219], v[28:31]
	v_mfma_f32_16x16x32_bf16 v[24:27], v[178:181], v[216:219], v[24:27]
	v_mfma_f32_16x16x32_bf16 v[20:23], v[170:173], v[224:227], v[20:23]
	v_mfma_f32_16x16x32_bf16 v[16:19], v[178:181], v[224:227], v[16:19]
	v_mfma_f32_16x16x32_bf16 v[12:15], v[170:173], v[232:235], v[12:15]
	v_mfma_f32_16x16x32_bf16 v[8:11], v[178:181], v[232:235], v[8:11]
	v_mfma_f32_16x16x32_bf16 v[4:7], v[170:173], v[240:243], v[4:7]
	v_mfma_f32_16x16x32_bf16 v[0:3], v[178:181], v[240:243], v[0:3]
	s_barrier
	s_add_i32 s70, 0, 0x18000
	s_add_i32 s71, 0, 0x1c000
	v_add_u32_e32 v144, s70, v185
	v_add_u32_e32 v161, s71, v185
	ds_read_b128 v[124:127], v144
	ds_read_b128 v[128:131], v144 offset:1024
	ds_read_b128 v[132:135], v144 offset:2048
	ds_read_b128 v[144:147], v144 offset:3072
	ds_read_b128 v[148:151], v161
	ds_read_b128 v[170:173], v161 offset:1024
	ds_read_b128 v[174:177], v161 offset:2048
	ds_read_b128 v[178:181], v161 offset:3072
	s_add_u32 s46, s46, 0xb0000
	s_addc_u32 s47, s47, 0
	s_mov_b32 m0, s55
	v_lshl_add_u64 v[246:247], s[46:47], 0, v[152:153]
	ds_read_b128 v[212:215], v191 offset:32768
	ds_read_b128 v[216:219], v191 offset:33792
	ds_read_b128 v[220:223], v191 offset:34816
	ds_read_b128 v[224:227], v191 offset:35840
	ds_read_b128 v[228:231], v191 offset:36864
	ds_read_b128 v[232:235], v191 offset:37888
	ds_read_b128 v[236:239], v191 offset:38912
	ds_read_b128 v[240:243], v191 offset:39936
	global_load_lds_dwordx4 v[246:247], off
	v_lshl_add_u64 v[246:247], s[46:47], 0, v[156:157]
	s_mov_b32 m0, s56
	s_nop 0
	global_load_lds_dwordx4 v[246:247], off
	s_waitcnt vmcnt(8)
	s_waitcnt lgkmcnt(0)
	s_barrier
	s_waitcnt lgkmcnt(0)
	v_mfma_f32_16x16x32_bf16 v[140:143], v[124:127], v[212:215], v[140:143]
	v_mfma_f32_16x16x32_bf16 v[136:139], v[132:135], v[212:215], v[136:139]
	v_mfma_f32_16x16x32_bf16 v[116:119], v[124:127], v[220:223], v[116:119]
	v_mfma_f32_16x16x32_bf16 v[112:115], v[132:135], v[220:223], v[112:115]
	v_mfma_f32_16x16x32_bf16 v[108:111], v[124:127], v[228:231], v[108:111]
	v_mfma_f32_16x16x32_bf16 v[104:107], v[132:135], v[228:231], v[104:107]
	v_mfma_f32_16x16x32_bf16 v[100:103], v[124:127], v[236:239], v[100:103]
	v_mfma_f32_16x16x32_bf16 v[96:99], v[132:135], v[236:239], v[96:99]
	v_mfma_f32_16x16x32_bf16 v[140:143], v[128:131], v[216:219], v[140:143]
	v_mfma_f32_16x16x32_bf16 v[136:139], v[144:147], v[216:219], v[136:139]
	v_mfma_f32_16x16x32_bf16 v[116:119], v[128:131], v[224:227], v[116:119]
	v_mfma_f32_16x16x32_bf16 v[112:115], v[144:147], v[224:227], v[112:115]
	v_mfma_f32_16x16x32_bf16 v[108:111], v[128:131], v[232:235], v[108:111]
	v_mfma_f32_16x16x32_bf16 v[104:107], v[144:147], v[232:235], v[104:107]
	v_mfma_f32_16x16x32_bf16 v[100:103], v[128:131], v[240:243], v[100:103]
	v_mfma_f32_16x16x32_bf16 v[96:99], v[144:147], v[240:243], v[96:99]
	v_mfma_f32_16x16x32_bf16 v[60:63], v[148:151], v[212:215], v[60:63]
	v_mfma_f32_16x16x32_bf16 v[56:59], v[174:177], v[212:215], v[56:59]
	v_mfma_f32_16x16x32_bf16 v[52:55], v[148:151], v[220:223], v[52:55]
	v_mfma_f32_16x16x32_bf16 v[48:51], v[174:177], v[220:223], v[48:51]
	v_mfma_f32_16x16x32_bf16 v[44:47], v[148:151], v[228:231], v[44:47]
	v_mfma_f32_16x16x32_bf16 v[40:43], v[174:177], v[228:231], v[40:43]
	v_mfma_f32_16x16x32_bf16 v[36:39], v[148:151], v[236:239], v[36:39]
	v_mfma_f32_16x16x32_bf16 v[32:35], v[174:177], v[236:239], v[32:35]
	v_mfma_f32_16x16x32_bf16 v[60:63], v[170:173], v[216:219], v[60:63]
	v_mfma_f32_16x16x32_bf16 v[56:59], v[178:181], v[216:219], v[56:59]
	v_mfma_f32_16x16x32_bf16 v[52:55], v[170:173], v[224:227], v[52:55]
	v_mfma_f32_16x16x32_bf16 v[48:51], v[178:181], v[224:227], v[48:51]
	v_mfma_f32_16x16x32_bf16 v[44:47], v[170:173], v[232:235], v[44:47]
	v_mfma_f32_16x16x32_bf16 v[40:43], v[178:181], v[232:235], v[40:43]
	v_mfma_f32_16x16x32_bf16 v[36:39], v[170:173], v[240:243], v[36:39]
	v_mfma_f32_16x16x32_bf16 v[32:35], v[178:181], v[240:243], v[32:35]
	s_barrier
; #define PG8_STAGE(bufoff, gbase, voff) do { _Pragma("unroll") for (int _i = 0; _i < 2; ++_i) \
;         __builtin_amdgcn_global_load_lds((const unsigned*)((const char*)(gbase) + (voff)[_i]), (PG8_LAS unsigned*)(lds + (bufoff) + ldsw + _i * 8192), 16, 0, 0); } while (0)
; #define PG8_LDA(dst, b, h) do { _Pragma("unroll") for (int m = 0; m < 4; ++m) _Pragma("unroll") for (int k = 0; k < 2; ++k) dst[m][k] = *(const PG8_LAS bf16x8*)(lds + PG8_SA(b, h) + aoff + m * 2048 + k * 1024); } while (0)
; #define PG8_MMA(ai, bj, At, Bt) do { __builtin_amdgcn_s_setprio(1); _Pragma("unroll") for (int m = 0; m < 4; ++m) _Pragma("unroll") for (int n = 0; n < 2; ++n) _Pragma("unroll") for (int k = 0; k < 2; ++k) \
;         acc[ai][bj][m][n] = __builtin_amdgcn_mfma_f32_16x16x32_bf16(Bt[n][k], At[m][k], acc[ai][bj][m][n], 0, 0, 0); __builtin_amdgcn_s_setprio(0); } while (0)
; #define PG8_WAIT_V(n) asm volatile("s_waitcnt vmcnt(" #n ")" ::: "memory")
; #define PG8_WAIT_L(n) asm volatile("s_waitcnt lgkmcnt(" #n ")" ::: "memory")
; #define PG8_BAR __builtin_amdgcn_s_barrier()
; #define PG8_SCHED __builtin_amdgcn_sched_barrier(0)
; template <class Epi, class Sched, bool ALIGN_EPI = false, bool SP2 = false>
; __device__ __forceinline__ void gemm_phase(PG8_LAS unsigned char* lds, const Gemm g, const Sched& S, const Epi& E) {
;     ...
;         for (int t = 0; t < nt; t += 2) {
;     ...
;             PG8_LDA(At, 1, 1); PG8_STAGE(PG8_SB(1, 0), b3, voffB); PG8_STAGE(PG8_SB(1, 1), b3 + hstepB, voffB); PG8_STAGE(PG8_SA(1, 0), a3, voffA);
;             PG8_WAIT_V(8); PG8_WAIT_L(0); PG8_BAR; PG8_MMA(1, 0, At, B0); PG8_MMA(1, 1, At, B1); PG8_BAR; PG8_SCHED;
	s_add_i32 s46, s70, s52
	v_lshl_add_u64 v[206:207], v[206:207], 0, s[26:27]
	s_mov_b32 m0, s46
	ds_read_b128 v[212:215], v191 offset:49152
	ds_read_b128 v[216:219], v191 offset:50176
	ds_read_b128 v[220:223], v191 offset:51200
	ds_read_b128 v[224:227], v191 offset:52224
	ds_read_b128 v[228:231], v191 offset:53248
	ds_read_b128 v[232:235], v191 offset:54272
	ds_read_b128 v[236:239], v191 offset:55296
	ds_read_b128 v[240:243], v191 offset:56320
	global_load_lds_dwordx4 v[206:207], off
	s_add_i32 m0, s46, 0x2000
	s_add_u32 s44, s44, 0xb0080
	v_lshl_add_u64 v[206:207], v[244:245], 0, s[26:27]
	s_addc_u32 s45, s45, 0
	s_add_i32 s46, s71, s52
	global_load_lds_dwordx4 v[206:207], off
	v_lshl_add_u64 v[206:207], s[44:45], 0, v[154:155]
	s_mov_b32 m0, s46
	s_nop 0
	global_load_lds_dwordx4 v[206:207], off
	v_lshl_add_u64 v[206:207], s[44:45], 0, v[158:159]
	s_add_i32 m0, s46, 0x2000
	s_nop 0
	global_load_lds_dwordx4 v[206:207], off
	v_lshl_add_u64 v[206:207], s[42:43], 0, v[152:153]
	s_mov_b32 m0, s63
	s_nop 0
	global_load_lds_dwordx4 v[206:207], off
	v_lshl_add_u64 v[206:207], s[42:43], 0, v[156:157]
	s_mov_b32 m0, s64
	s_nop 0
	global_load_lds_dwordx4 v[206:207], off
	s_waitcnt vmcnt(8)
	s_waitcnt lgkmcnt(0)
	s_barrier
	s_waitcnt lgkmcnt(0)
	v_mfma_f32_16x16x32_bf16 v[92:95], v[124:127], v[212:215], v[92:95]
	v_mfma_f32_16x16x32_bf16 v[88:91], v[132:135], v[212:215], v[88:91]
	v_mfma_f32_16x16x32_bf16 v[84:87], v[124:127], v[220:223], v[84:87]
	v_mfma_f32_16x16x32_bf16 v[80:83], v[132:135], v[220:223], v[80:83]
	v_mfma_f32_16x16x32_bf16 v[76:79], v[124:127], v[228:231], v[76:79]
	v_mfma_f32_16x16x32_bf16 v[72:75], v[132:135], v[228:231], v[72:75]
	v_mfma_f32_16x16x32_bf16 v[68:71], v[124:127], v[236:239], v[68:71]
	v_mfma_f32_16x16x32_bf16 v[64:67], v[132:135], v[236:239], v[64:67]
	v_mfma_f32_16x16x32_bf16 v[92:95], v[128:131], v[216:219], v[92:95]
	v_mfma_f32_16x16x32_bf16 v[88:91], v[144:147], v[216:219], v[88:91]
	v_mfma_f32_16x16x32_bf16 v[84:87], v[128:131], v[224:227], v[84:87]
	v_mfma_f32_16x16x32_bf16 v[80:83], v[144:147], v[224:227], v[80:83]
	v_mfma_f32_16x16x32_bf16 v[76:79], v[128:131], v[232:235], v[76:79]
	v_mfma_f32_16x16x32_bf16 v[72:75], v[144:147], v[232:235], v[72:75]
	v_mfma_f32_16x16x32_bf16 v[68:71], v[128:131], v[240:243], v[68:71]
	v_mfma_f32_16x16x32_bf16 v[64:67], v[144:147], v[240:243], v[64:67]
	v_mfma_f32_16x16x32_bf16 v[28:31], v[148:151], v[212:215], v[28:31]
	v_mfma_f32_16x16x32_bf16 v[24:27], v[174:177], v[212:215], v[24:27]
	v_mfma_f32_16x16x32_bf16 v[20:23], v[148:151], v[220:223], v[20:23]
	v_mfma_f32_16x16x32_bf16 v[16:19], v[174:177], v[220:223], v[16:19]
	v_mfma_f32_16x16x32_bf16 v[12:15], v[148:151], v[228:231], v[12:15]
	v_mfma_f32_16x16x32_bf16 v[8:11], v[174:177], v[228:231], v[8:11]
	v_mfma_f32_16x16x32_bf16 v[4:7], v[148:151], v[236:239], v[4:7]
	v_mfma_f32_16x16x32_bf16 v[0:3], v[174:177], v[236:239], v[0:3]
	v_mfma_f32_16x16x32_bf16 v[28:31], v[170:173], v[216:219], v[28:31]
	v_mfma_f32_16x16x32_bf16 v[24:27], v[178:181], v[216:219], v[24:27]
	v_mfma_f32_16x16x32_bf16 v[20:23], v[170:173], v[224:227], v[20:23]
	v_mfma_f32_16x16x32_bf16 v[16:19], v[178:181], v[224:227], v[16:19]
	v_mfma_f32_16x16x32_bf16 v[12:15], v[170:173], v[232:235], v[12:15]
	v_mfma_f32_16x16x32_bf16 v[8:11], v[178:181], v[232:235], v[8:11]
	v_mfma_f32_16x16x32_bf16 v[4:7], v[170:173], v[240:243], v[4:7]
	v_mfma_f32_16x16x32_bf16 v[0:3], v[178:181], v[240:243], v[0:3]
	s_barrier
	s_add_i32 s84, s84, 2
	s_add_u32 s40, s40, 0x100
	s_addc_u32 s41, s41, 0
	s_cmp_gt_u32 s84, 41
	s_cbranch_scc0 .LBB0_1379
	s_and_b64 vcc, exec, s[28:29]
	s_cbranch_vccz .LBB0_1382
	s_barrier

;     __host__ __device__ bool next(int i, Unit& u) const {
;         const long L = (long)i * G + c; if (L >= nwg) return false;
;         int wgid = (int)L; { const int q = nwg / NXCD, r = nwg % NXCD, xcd = wgid % NXCD, off = wgid / NXCD; wgid = (xcd < r ? xcd * (q + 1) : r * (q + 1) + (xcd - r) * q) + off; }
;         const int nig = WGM * nN, gid = wgid / nig, fm = gid * WGM, gsz = (nM - fm) < WGM ? (nM - fm) : WGM;
;         u.pm = fm + ((wgid % nig) % gsz); u.pn = (wgid % nig) / gsz; return true;
.Lprio_gate1:
	s_mov_b32 s27, s74
	s_mov_b64 s[12:13], s[0:1]
	s_mov_b32 s50, s2
	v_mov_b32_e32 v9, v254
	s_waitcnt lgkmcnt(0)
	s_barrier
	s_cmpk_gt_i32 s50, 0x1ff
	v_readfirstlane_b32 s3, v9
	s_cbranch_scc1 .LBB0_1478
	s_ashr_i32 s51, s50, 31
	s_lshr_b32 s4, s51, 29
	s_add_i32 s14, s50, s4
	s_and_b32 s4, s14, -8
	s_sub_i32 s7, s50, s4
	s_cmp_gt_i32 s7, -1
	s_cbranch_scc0 .LBB0_1457
	s_lshl_b32 s6, s7, 6
	s_load_dwordx4 s[8:11], s[12:13], 0x88
	s_ashr_i32 s4, s14, 3
	s_cbranch_execz .LBB0_1458
	s_branch .LBB0_1459

; #define PG8_STAGE(bufoff, gbase, voff) do { _Pragma("unroll") for (int _i = 0; _i < 2; ++_i) \
;         __builtin_amdgcn_global_load_lds((const unsigned*)((const char*)(gbase) + (voff)[_i]), (PG8_LAS unsigned*)(lds + (bufoff) + ldsw + _i * 8192), 16, 0, 0); } while (0)
; #define PG8_LDA(dst, b, h) do { _Pragma("unroll") for (int m = 0; m < 4; ++m) _Pragma("unroll") for (int k = 0; k < 2; ++k) dst[m][k] = *(const PG8_LAS bf16x8*)(lds + PG8_SA(b, h) + aoff + m * 2048 + k * 1024); } while (0)
; #define PG8_LDB(dst, b, h) do { _Pragma("unroll") for (int n = 0; n < 2; ++n) _Pragma("unroll") for (int k = 0; k < 2; ++k) dst[n][k] = *(const PG8_LAS bf16x8*)(lds + PG8_SB(b, h) + boff + n * 2048 + k * 1024); } while (0)
; #define PG8_MMA(ai, bj, At, Bt) do { __builtin_amdgcn_s_setprio(1); _Pragma("unroll") for (int m = 0; m < 4; ++m) _Pragma("unroll") for (int n = 0; n < 2; ++n) _Pragma("unroll") for (int k = 0; k < 2; ++k) \
;         acc[ai][bj][m][n] = __builtin_amdgcn_mfma_f32_16x16x32_bf16(Bt[n][k], At[m][k], acc[ai][bj][m][n], 0, 0, 0); __builtin_amdgcn_s_setprio(0); } while (0)
; #define PG8_WAIT_V(n) asm volatile("s_waitcnt vmcnt(" #n ")" ::: "memory")
; #define PG8_WAIT_L(n) asm volatile("s_waitcnt lgkmcnt(" #n ")" ::: "memory")
; template <class Epi, class Sched, bool ALIGN_EPI = false, bool SP2 = false>
; __device__ __forceinline__ void gemm_phase(PG8_LAS unsigned char* lds, const Gemm g, const Sched& S, const Epi& E) {
;     ...
;             const bool last = (t == nt - 2);
;             const char* a1 = cA + PG8_AK(t + 1);
;             const char* a2 = last ? nA : cA + PG8_AK(t + 2); const char* b2 = last ? nB : cB + (size_t)(t + 2) * kstep;
;             const char* a3 = last ? nA + PG8_AK(1) : cA + PG8_AK(t + 3); const char* b3 = b2 + kstep;
;             if (last && has_next) S.a_ready(nxt);
;             if constexpr (SP2) {
;             PG8_LDB(B0, 0, 0); PG8_LDB(B1, 0, 1); PG8_SCHED; PG8_LDA(At, 0, 0); PG8_STAGE(PG8_SA(1, 1), a1 + hstepA, voffA);
;             PG8_WAIT_V(8); PG8_WAIT_L(0); PG8_BAR; PG8_MMA(0, 0, At, B0); PG8_MMA(0, 1, At, B1); PG8_BAR; PG8_SCHED;
;             PG8_LDA(At, 0, 1); PG8_STAGE(PG8_SB(0, 0), b2, voffB); PG8_STAGE(PG8_SB(0, 1), b2 + hstepB, voffB); PG8_STAGE(PG8_SA(0, 0), a2, voffA);
;             PG8_WAIT_V(8); PG8_WAIT_L(0); PG8_BAR; PG8_MMA(1, 0, At, B0); PG8_MMA(1, 1, At, B1); PG8_BAR; PG8_SCHED;
.LBB0_1471:
	ds_read_b128 v[100:103], v222
	ds_read_b128 v[104:107], v222 offset:1024
	ds_read_b128 v[108:111], v222 offset:2048
	ds_read_b128 v[120:123], v222 offset:3072
	ds_read_b128 v[124:127], v223
	ds_read_b128 v[128:131], v223 offset:1024
	ds_read_b128 v[132:135], v223 offset:2048
	ds_read_b128 v[160:163], v223 offset:3072
	s_add_u32 s44, s40, s42
	s_addc_u32 s45, s41, s43
	s_add_u32 s48, s44, 0x100
	s_addc_u32 s49, s45, 0
	s_add_u32 s46, s83, s42
	s_addc_u32 s47, s84, s43
	s_add_u32 s44, s44, 0x180
	s_addc_u32 s45, s45, 0
	s_cmpk_eq_i32 s42, 0x700
	s_cselect_b32 s45, s82, s45
	s_cselect_b32 s44, s79, s44
	s_cselect_b32 s47, s29, s47
	s_cselect_b32 s46, s78, s46
	s_cselect_b32 s49, s3, s49
	s_cselect_b32 s48, s31, s48
	v_lshl_add_u64 v[200:201], v[98:99], 0, s[42:43]
	s_add_i32 m0, s57, 0xc000
	ds_read_b128 v[164:167], v203
	ds_read_b128 v[168:171], v203 offset:1024
	ds_read_b128 v[192:195], v203 offset:2048
	ds_read_b128 v[196:199], v203 offset:3072
	ds_read_b128 v[224:227], v203 offset:4096
	ds_read_b128 v[228:231], v203 offset:5120
	ds_read_b128 v[232:235], v203 offset:6144
	ds_read_b128 v[236:239], v203 offset:7168
	global_load_lds_dwordx4 v[200:201], off
	v_lshl_add_u64 v[200:201], v[96:97], 0, s[42:43]
	s_add_i32 m0, s57, 0xe000
	s_nop 0
	global_load_lds_dwordx4 v[200:201], off
	s_waitcnt vmcnt(8)
	s_waitcnt lgkmcnt(0)
	s_barrier
	s_waitcnt lgkmcnt(0)
	v_mfma_f32_16x16x32_bf16 v[156:159], v[100:103], v[164:167], v[156:159]
	v_mfma_f32_16x16x32_bf16 v[152:155], v[108:111], v[164:167], v[152:155]
	v_mfma_f32_16x16x32_bf16 v[148:151], v[100:103], v[192:195], v[148:151]
	v_mfma_f32_16x16x32_bf16 v[144:147], v[108:111], v[192:195], v[144:147]
	v_mfma_f32_16x16x32_bf16 v[140:143], v[100:103], v[224:227], v[140:143]
	v_mfma_f32_16x16x32_bf16 v[136:139], v[108:111], v[224:227], v[136:139]
	v_mfma_f32_16x16x32_bf16 v[116:119], v[100:103], v[232:235], v[116:119]
	v_mfma_f32_16x16x32_bf16 v[112:115], v[108:111], v[232:235], v[112:115]
	v_mfma_f32_16x16x32_bf16 v[156:159], v[104:107], v[168:171], v[156:159]
	v_mfma_f32_16x16x32_bf16 v[152:155], v[120:123], v[168:171], v[152:155]
	v_mfma_f32_16x16x32_bf16 v[148:151], v[104:107], v[196:199], v[148:151]
	v_mfma_f32_16x16x32_bf16 v[144:147], v[120:123], v[196:199], v[144:147]
	v_mfma_f32_16x16x32_bf16 v[140:143], v[104:107], v[228:231], v[140:143]
	v_mfma_f32_16x16x32_bf16 v[136:139], v[120:123], v[228:231], v[136:139]
	v_mfma_f32_16x16x32_bf16 v[116:119], v[104:107], v[236:239], v[116:119]
	v_mfma_f32_16x16x32_bf16 v[112:115], v[120:123], v[236:239], v[112:115]
	v_mfma_f32_16x16x32_bf16 v[60:63], v[124:127], v[164:167], v[60:63]
	v_mfma_f32_16x16x32_bf16 v[56:59], v[132:135], v[164:167], v[56:59]
	v_mfma_f32_16x16x32_bf16 v[52:55], v[124:127], v[192:195], v[52:55]
	v_mfma_f32_16x16x32_bf16 v[48:51], v[132:135], v[192:195], v[48:51]
	v_mfma_f32_16x16x32_bf16 v[44:47], v[124:127], v[224:227], v[44:47]
	v_mfma_f32_16x16x32_bf16 v[40:43], v[132:135], v[224:227], v[40:43]
	v_mfma_f32_16x16x32_bf16 v[36:39], v[124:127], v[232:235], v[36:39]
	v_mfma_f32_16x16x32_bf16 v[32:35], v[132:135], v[232:235], v[32:35]
	v_mfma_f32_16x16x32_bf16 v[60:63], v[128:131], v[168:171], v[60:63]
	v_mfma_f32_16x16x32_bf16 v[56:59], v[160:163], v[168:171], v[56:59]
	v_mfma_f32_16x16x32_bf16 v[52:55], v[128:131], v[196:199], v[52:55]
	v_mfma_f32_16x16x32_bf16 v[48:51], v[160:163], v[196:199], v[48:51]
	v_mfma_f32_16x16x32_bf16 v[44:47], v[128:131], v[228:231], v[44:47]
	v_mfma_f32_16x16x32_bf16 v[40:43], v[160:163], v[228:231], v[40:43]
	v_mfma_f32_16x16x32_bf16 v[36:39], v[128:131], v[236:239], v[36:39]
	v_mfma_f32_16x16x32_bf16 v[32:35], v[160:163], v[236:239], v[32:35]
	s_barrier
	s_add_i32 s70, s69, s56
	v_lshl_add_u64 v[200:201], s[46:47], 0, v[174:175]
	s_mov_b32 m0, s70
	ds_read_b128 v[164:167], v203 offset:16384
	ds_read_b128 v[168:171], v203 offset:17408
	ds_read_b128 v[192:195], v203 offset:18432
	ds_read_b128 v[196:199], v203 offset:19456
	ds_read_b128 v[224:227], v203 offset:20480
	ds_read_b128 v[228:231], v203 offset:21504
	ds_read_b128 v[232:235], v203 offset:22528
	ds_read_b128 v[236:239], v203 offset:23552
	global_load_lds_dwordx4 v[200:201], off
	s_add_i32 m0, s70, 0x2000
	s_add_u32 s70, s46, 0x40000
	v_lshl_add_u64 v[206:207], s[46:47], 0, v[178:179]
	s_addc_u32 s71, s47, 0
	s_add_i32 s86, s80, s56
	global_load_lds_dwordx4 v[206:207], off
	v_lshl_add_u64 v[240:241], s[70:71], 0, v[174:175]
	s_mov_b32 m0, s86
	s_nop 0
	global_load_lds_dwordx4 v[240:241], off
	v_lshl_add_u64 v[240:241], s[70:71], 0, v[178:179]
	s_add_i32 m0, s86, 0x2000
	s_nop 0
	global_load_lds_dwordx4 v[240:241], off
	v_lshl_add_u64 v[240:241], s[48:49], 0, v[172:173]
	s_mov_b32 m0, s57
	s_nop 0
	global_load_lds_dwordx4 v[240:241], off
	v_lshl_add_u64 v[240:241], s[48:49], 0, v[176:177]
	s_mov_b32 m0, s58
	s_nop 0
	global_load_lds_dwordx4 v[240:241], off
	s_waitcnt vmcnt(8)
	s_waitcnt lgkmcnt(0)
	s_barrier
; #define PG8_STAGE(bufoff, gbase, voff) do { _Pragma("unroll") for (int _i = 0; _i < 2; ++_i) \
;         __builtin_amdgcn_global_load_lds((const unsigned*)((const char*)(gbase) + (voff)[_i]), (PG8_LAS unsigned*)(lds + (bufoff) + ldsw + _i * 8192), 16, 0, 0); } while (0)
; #define PG8_LDA(dst, b, h) do { _Pragma("unroll") for (int m = 0; m < 4; ++m) _Pragma("unroll") for (int k = 0; k < 2; ++k) dst[m][k] = *(const PG8_LAS bf16x8*)(lds + PG8_SA(b, h) + aoff + m * 2048 + k * 1024); } while (0)
; #define PG8_LDB(dst, b, h) do { _Pragma("unroll") for (int n = 0; n < 2; ++n) _Pragma("unroll") for (int k = 0; k < 2; ++k) dst[n][k] = *(const PG8_LAS bf16x8*)(lds + PG8_SB(b, h) + boff + n * 2048 + k * 1024); } while (0)
; #define PG8_MMA(ai, bj, At, Bt) do { __builtin_amdgcn_s_setprio(1); _Pragma("unroll") for (int m = 0; m < 4; ++m) _Pragma("unroll") for (int n = 0; n < 2; ++n) _Pragma("unroll") for (int k = 0; k < 2; ++k) \
;         acc[ai][bj][m][n] = __builtin_amdgcn_mfma_f32_16x16x32_bf16(Bt[n][k], At[m][k], acc[ai][bj][m][n], 0, 0, 0); __builtin_amdgcn_s_setprio(0); } while (0)
; #define PG8_WAIT_V(n) asm volatile("s_waitcnt vmcnt(" #n ")" ::: "memory")
; #define PG8_WAIT_L(n) asm volatile("s_waitcnt lgkmcnt(" #n ")" ::: "memory")
; #define PG8_BAR __builtin_amdgcn_s_barrier()
; #define PG8_SCHED __builtin_amdgcn_sched_barrier(0)
; template <class Epi, class Sched, bool ALIGN_EPI = false, bool SP2 = false>
; __device__ __forceinline__ void gemm_phase(PG8_LAS unsigned char* lds, const Gemm g, const Sched& S, const Epi& E) {
;     ...
;             PG8_WAIT_V(8); PG8_WAIT_L(0); PG8_BAR; PG8_MMA(1, 0, At, B0); PG8_MMA(1, 1, At, B1); PG8_BAR; PG8_SCHED;
;             PG8_LDB(B0, 1, 0); PG8_LDB(B1, 1, 1); PG8_SCHED; PG8_LDA(At, 1, 0); PG8_STAGE(PG8_SA(0, 1), a2 + hstepA, voffA);
;             PG8_WAIT_V(8); PG8_WAIT_L(0); PG8_BAR; PG8_MMA(0, 0, At, B0); PG8_MMA(0, 1, At, B1); PG8_BAR; PG8_SCHED;
	s_waitcnt lgkmcnt(0)
	v_mfma_f32_16x16x32_bf16 v[92:95], v[100:103], v[164:167], v[92:95]
	v_mfma_f32_16x16x32_bf16 v[88:91], v[108:111], v[164:167], v[88:91]
	v_mfma_f32_16x16x32_bf16 v[84:87], v[100:103], v[192:195], v[84:87]
	v_mfma_f32_16x16x32_bf16 v[80:83], v[108:111], v[192:195], v[80:83]
	v_mfma_f32_16x16x32_bf16 v[76:79], v[100:103], v[224:227], v[76:79]
	v_mfma_f32_16x16x32_bf16 v[72:75], v[108:111], v[224:227], v[72:75]
	v_mfma_f32_16x16x32_bf16 v[68:71], v[100:103], v[232:235], v[68:71]
	v_mfma_f32_16x16x32_bf16 v[64:67], v[108:111], v[232:235], v[64:67]
	v_mfma_f32_16x16x32_bf16 v[92:95], v[104:107], v[168:171], v[92:95]
	v_mfma_f32_16x16x32_bf16 v[88:91], v[120:123], v[168:171], v[88:91]
	v_mfma_f32_16x16x32_bf16 v[84:87], v[104:107], v[196:199], v[84:87]
	v_mfma_f32_16x16x32_bf16 v[80:83], v[120:123], v[196:199], v[80:83]
	v_mfma_f32_16x16x32_bf16 v[76:79], v[104:107], v[228:231], v[76:79]
	v_mfma_f32_16x16x32_bf16 v[72:75], v[120:123], v[228:231], v[72:75]
	v_mfma_f32_16x16x32_bf16 v[68:71], v[104:107], v[236:239], v[68:71]
	v_mfma_f32_16x16x32_bf16 v[64:67], v[120:123], v[236:239], v[64:67]
	v_mfma_f32_16x16x32_bf16 v[28:31], v[124:127], v[164:167], v[28:31]
	v_mfma_f32_16x16x32_bf16 v[24:27], v[132:135], v[164:167], v[24:27]
	v_mfma_f32_16x16x32_bf16 v[20:23], v[124:127], v[192:195], v[20:23]
	v_mfma_f32_16x16x32_bf16 v[16:19], v[132:135], v[192:195], v[16:19]
	v_mfma_f32_16x16x32_bf16 v[12:15], v[124:127], v[224:227], v[12:15]
	v_mfma_f32_16x16x32_bf16 v[8:11], v[132:135], v[224:227], v[8:11]
	v_mfma_f32_16x16x32_bf16 v[4:7], v[124:127], v[232:235], v[4:7]
	v_mfma_f32_16x16x32_bf16 v[0:3], v[132:135], v[232:235], v[0:3]
	v_mfma_f32_16x16x32_bf16 v[28:31], v[128:131], v[168:171], v[28:31]
	v_mfma_f32_16x16x32_bf16 v[24:27], v[160:163], v[168:171], v[24:27]
	v_mfma_f32_16x16x32_bf16 v[20:23], v[128:131], v[196:199], v[20:23]
	v_mfma_f32_16x16x32_bf16 v[16:19], v[160:163], v[196:199], v[16:19]
	v_mfma_f32_16x16x32_bf16 v[12:15], v[128:131], v[228:231], v[12:15]
	v_mfma_f32_16x16x32_bf16 v[8:11], v[160:163], v[228:231], v[8:11]
	v_mfma_f32_16x16x32_bf16 v[4:7], v[128:131], v[236:239], v[4:7]
	v_mfma_f32_16x16x32_bf16 v[0:3], v[160:163], v[236:239], v[0:3]
	s_barrier
	s_add_i32 s70, 0, 0x18000
	s_add_i32 s71, 0, 0x1c000
	v_add_u32_e32 v120, s70, v189
	v_add_u32_e32 v160, s71, v189
	ds_read_b128 v[100:103], v120
	ds_read_b128 v[104:107], v120 offset:1024
	ds_read_b128 v[108:111], v120 offset:2048
	ds_read_b128 v[120:123], v120 offset:3072
	ds_read_b128 v[124:127], v160
	ds_read_b128 v[128:131], v160 offset:1024
	ds_read_b128 v[132:135], v160 offset:2048
	ds_read_b128 v[160:163], v160 offset:3072
	s_add_u32 s48, s48, 0x40000
	s_addc_u32 s49, s49, 0
	s_mov_b32 m0, s59
	v_lshl_add_u64 v[240:241], s[48:49], 0, v[172:173]
	ds_read_b128 v[164:167], v203 offset:32768
	ds_read_b128 v[168:171], v203 offset:33792
	ds_read_b128 v[192:195], v203 offset:34816
	ds_read_b128 v[196:199], v203 offset:35840
	ds_read_b128 v[224:227], v203 offset:36864
	ds_read_b128 v[228:231], v203 offset:37888
	ds_read_b128 v[232:235], v203 offset:38912
	ds_read_b128 v[236:239], v203 offset:39936
	global_load_lds_dwordx4 v[240:241], off
	v_lshl_add_u64 v[240:241], s[48:49], 0, v[176:177]
	s_mov_b32 m0, s60
	s_nop 0
	global_load_lds_dwordx4 v[240:241], off
	s_waitcnt vmcnt(8)
	s_waitcnt lgkmcnt(0)
	s_barrier
	s_waitcnt lgkmcnt(0)
	v_mfma_f32_16x16x32_bf16 v[156:159], v[100:103], v[164:167], v[156:159]
	v_mfma_f32_16x16x32_bf16 v[152:155], v[108:111], v[164:167], v[152:155]
	v_mfma_f32_16x16x32_bf16 v[148:151], v[100:103], v[192:195], v[148:151]
	v_mfma_f32_16x16x32_bf16 v[144:147], v[108:111], v[192:195], v[144:147]
	v_mfma_f32_16x16x32_bf16 v[140:143], v[100:103], v[224:227], v[140:143]
	v_mfma_f32_16x16x32_bf16 v[136:139], v[108:111], v[224:227], v[136:139]
	v_mfma_f32_16x16x32_bf16 v[116:119], v[100:103], v[232:235], v[116:119]
	v_mfma_f32_16x16x32_bf16 v[112:115], v[108:111], v[232:235], v[112:115]
	v_mfma_f32_16x16x32_bf16 v[156:159], v[104:107], v[168:171], v[156:159]
	v_mfma_f32_16x16x32_bf16 v[152:155], v[120:123], v[168:171], v[152:155]
	v_mfma_f32_16x16x32_bf16 v[148:151], v[104:107], v[196:199], v[148:151]
	v_mfma_f32_16x16x32_bf16 v[144:147], v[120:123], v[196:199], v[144:147]
	v_mfma_f32_16x16x32_bf16 v[140:143], v[104:107], v[228:231], v[140:143]
	v_mfma_f32_16x16x32_bf16 v[136:139], v[120:123], v[228:231], v[136:139]
	v_mfma_f32_16x16x32_bf16 v[116:119], v[104:107], v[236:239], v[116:119]
	v_mfma_f32_16x16x32_bf16 v[112:115], v[120:123], v[236:239], v[112:115]
	v_mfma_f32_16x16x32_bf16 v[60:63], v[124:127], v[164:167], v[60:63]
	v_mfma_f32_16x16x32_bf16 v[56:59], v[132:135], v[164:167], v[56:59]
	v_mfma_f32_16x16x32_bf16 v[52:55], v[124:127], v[192:195], v[52:55]
	v_mfma_f32_16x16x32_bf16 v[48:51], v[132:135], v[192:195], v[48:51]
	v_mfma_f32_16x16x32_bf16 v[44:47], v[124:127], v[224:227], v[44:47]
	v_mfma_f32_16x16x32_bf16 v[40:43], v[132:135], v[224:227], v[40:43]
	v_mfma_f32_16x16x32_bf16 v[36:39], v[124:127], v[232:235], v[36:39]
	v_mfma_f32_16x16x32_bf16 v[32:35], v[132:135], v[232:235], v[32:35]
	v_mfma_f32_16x16x32_bf16 v[60:63], v[128:131], v[168:171], v[60:63]
	v_mfma_f32_16x16x32_bf16 v[56:59], v[160:163], v[168:171], v[56:59]
	v_mfma_f32_16x16x32_bf16 v[52:55], v[128:131], v[196:199], v[52:55]
	v_mfma_f32_16x16x32_bf16 v[48:51], v[160:163], v[196:199], v[48:51]
	v_mfma_f32_16x16x32_bf16 v[44:47], v[128:131], v[228:231], v[44:47]
	v_mfma_f32_16x16x32_bf16 v[40:43], v[160:163], v[228:231], v[40:43]
	v_mfma_f32_16x16x32_bf16 v[36:39], v[128:131], v[236:239], v[36:39]
	v_mfma_f32_16x16x32_bf16 v[32:35], v[160:163], v[236:239], v[32:35]
	s_barrier
; #define PG8_STAGE(bufoff, gbase, voff) do { _Pragma("unroll") for (int _i = 0; _i < 2; ++_i) \
;         __builtin_amdgcn_global_load_lds((const unsigned*)((const char*)(gbase) + (voff)[_i]), (PG8_LAS unsigned*)(lds + (bufoff) + ldsw + _i * 8192), 16, 0, 0); } while (0)
; #define PG8_LDA(dst, b, h) do { _Pragma("unroll") for (int m = 0; m < 4; ++m) _Pragma("unroll") for (int k = 0; k < 2; ++k) dst[m][k] = *(const PG8_LAS bf16x8*)(lds + PG8_SA(b, h) + aoff + m * 2048 + k * 1024); } while (0)
; #define PG8_MMA(ai, bj, At, Bt) do { __builtin_amdgcn_s_setprio(1); _Pragma("unroll") for (int m = 0; m < 4; ++m) _Pragma("unroll") for (int n = 0; n < 2; ++n) _Pragma("unroll") for (int k = 0; k < 2; ++k) \
;         acc[ai][bj][m][n] = __builtin_amdgcn_mfma_f32_16x16x32_bf16(Bt[n][k], At[m][k], acc[ai][bj][m][n], 0, 0, 0); __builtin_amdgcn_s_setprio(0); } while (0)
; #define PG8_WAIT_V(n) asm volatile("s_waitcnt vmcnt(" #n ")" ::: "memory")
; #define PG8_WAIT_L(n) asm volatile("s_waitcnt lgkmcnt(" #n ")" ::: "memory")
; #define PG8_BAR __builtin_amdgcn_s_barrier()
; #define PG8_SCHED __builtin_amdgcn_sched_barrier(0)
; template <class Epi, class Sched, bool ALIGN_EPI = false, bool SP2 = false>
; __device__ __forceinline__ void gemm_phase(PG8_LAS unsigned char* lds, const Gemm g, const Sched& S, const Epi& E) {
;     ...
;         for (int t = 0; t < nt; t += 2) {
;     ...
;             PG8_LDA(At, 1, 1); PG8_STAGE(PG8_SB(1, 0), b3, voffB); PG8_STAGE(PG8_SB(1, 1), b3 + hstepB, voffB); PG8_STAGE(PG8_SA(1, 0), a3, voffA);
;             PG8_WAIT_V(8); PG8_WAIT_L(0); PG8_BAR; PG8_MMA(1, 0, At, B0); PG8_MMA(1, 1, At, B1); PG8_BAR; PG8_SCHED;
	s_add_i32 s48, s70, s56
	v_lshl_add_u64 v[200:201], v[200:201], 0, s[10:11]
	s_mov_b32 m0, s48
	ds_read_b128 v[164:167], v203 offset:49152
	ds_read_b128 v[168:171], v203 offset:50176
	ds_read_b128 v[192:195], v203 offset:51200
	ds_read_b128 v[196:199], v203 offset:52224
	ds_read_b128 v[224:227], v203 offset:53248
	ds_read_b128 v[228:231], v203 offset:54272
	ds_read_b128 v[232:235], v203 offset:55296
	ds_read_b128 v[236:239], v203 offset:56320
	global_load_lds_dwordx4 v[200:201], off
	s_add_i32 m0, s48, 0x2000
	s_add_u32 s46, s46, 0x40080
	v_lshl_add_u64 v[200:201], v[206:207], 0, s[10:11]
	s_addc_u32 s47, s47, 0
	s_add_i32 s48, s71, s56
	global_load_lds_dwordx4 v[200:201], off
	v_lshl_add_u64 v[200:201], s[46:47], 0, v[174:175]
	s_mov_b32 m0, s48
	s_nop 0
	global_load_lds_dwordx4 v[200:201], off
	v_lshl_add_u64 v[200:201], s[46:47], 0, v[178:179]
	s_add_i32 m0, s48, 0x2000
	s_nop 0
	global_load_lds_dwordx4 v[200:201], off
	v_lshl_add_u64 v[200:201], s[44:45], 0, v[172:173]
	s_mov_b32 m0, s66
	s_nop 0
	global_load_lds_dwordx4 v[200:201], off
	v_lshl_add_u64 v[200:201], s[44:45], 0, v[176:177]
	s_mov_b32 m0, s67
	s_nop 0
	global_load_lds_dwordx4 v[200:201], off
	s_waitcnt vmcnt(8)
	s_waitcnt lgkmcnt(0)
	s_barrier
	s_waitcnt lgkmcnt(0)
	v_mfma_f32_16x16x32_bf16 v[92:95], v[100:103], v[164:167], v[92:95]
	v_mfma_f32_16x16x32_bf16 v[88:91], v[108:111], v[164:167], v[88:91]
	v_mfma_f32_16x16x32_bf16 v[84:87], v[100:103], v[192:195], v[84:87]
	v_mfma_f32_16x16x32_bf16 v[80:83], v[108:111], v[192:195], v[80:83]
	v_mfma_f32_16x16x32_bf16 v[76:79], v[100:103], v[224:227], v[76:79]
	v_mfma_f32_16x16x32_bf16 v[72:75], v[108:111], v[224:227], v[72:75]
	v_mfma_f32_16x16x32_bf16 v[68:71], v[100:103], v[232:235], v[68:71]
	v_mfma_f32_16x16x32_bf16 v[64:67], v[108:111], v[232:235], v[64:67]
	v_mfma_f32_16x16x32_bf16 v[92:95], v[104:107], v[168:171], v[92:95]
	v_mfma_f32_16x16x32_bf16 v[88:91], v[120:123], v[168:171], v[88:91]
	v_mfma_f32_16x16x32_bf16 v[84:87], v[104:107], v[196:199], v[84:87]
	v_mfma_f32_16x16x32_bf16 v[80:83], v[120:123], v[196:199], v[80:83]
	v_mfma_f32_16x16x32_bf16 v[76:79], v[104:107], v[228:231], v[76:79]
	v_mfma_f32_16x16x32_bf16 v[72:75], v[120:123], v[228:231], v[72:75]
	v_mfma_f32_16x16x32_bf16 v[68:71], v[104:107], v[236:239], v[68:71]
	v_mfma_f32_16x16x32_bf16 v[64:67], v[120:123], v[236:239], v[64:67]
	v_mfma_f32_16x16x32_bf16 v[28:31], v[124:127], v[164:167], v[28:31]
	v_mfma_f32_16x16x32_bf16 v[24:27], v[132:135], v[164:167], v[24:27]
	v_mfma_f32_16x16x32_bf16 v[20:23], v[124:127], v[192:195], v[20:23]
	v_mfma_f32_16x16x32_bf16 v[16:19], v[132:135], v[192:195], v[16:19]
	v_mfma_f32_16x16x32_bf16 v[12:15], v[124:127], v[224:227], v[12:15]
	v_mfma_f32_16x16x32_bf16 v[8:11], v[132:135], v[224:227], v[8:11]
	v_mfma_f32_16x16x32_bf16 v[4:7], v[124:127], v[232:235], v[4:7]
	v_mfma_f32_16x16x32_bf16 v[0:3], v[132:135], v[232:235], v[0:3]
	v_mfma_f32_16x16x32_bf16 v[28:31], v[128:131], v[168:171], v[28:31]
	v_mfma_f32_16x16x32_bf16 v[24:27], v[160:163], v[168:171], v[24:27]
	v_mfma_f32_16x16x32_bf16 v[20:23], v[128:131], v[196:199], v[20:23]
	v_mfma_f32_16x16x32_bf16 v[16:19], v[160:163], v[196:199], v[16:19]
	v_mfma_f32_16x16x32_bf16 v[12:15], v[128:131], v[228:231], v[12:15]
	v_mfma_f32_16x16x32_bf16 v[8:11], v[160:163], v[228:231], v[8:11]
	v_mfma_f32_16x16x32_bf16 v[4:7], v[128:131], v[236:239], v[4:7]
	v_mfma_f32_16x16x32_bf16 v[0:3], v[160:163], v[236:239], v[0:3]
	s_barrier
	s_add_i32 s85, s85, 2
	s_add_u32 s42, s42, 0x100
	s_addc_u32 s43, s43, 0
	s_cmp_gt_u32 s85, 13
	s_cbranch_scc0 .LBB0_1471
	s_and_b64 vcc, exec, s[24:25]
	s_cbranch_vccz .LBB0_1474
	s_barrier

; __device__ __forceinline__ void wconv_phase(KP Pk, int L, unsigned char* lds, int G, int blk) {
;     ...
;     int tid_l = threadIdx.x; asm volatile("" : "+v"(tid_l)); const int tid = tid_l, lane = tid & 63, wid = __builtin_amdgcn_readfirstlane(tid >> 6), j = L >> 1; const bool att = (L & 1) == 0;
;     float* scr = (float*)(lds + wid * 16384);
;     unsigned char* ws = P.ws;
;     bf16_t *WIN = (bf16_t*)(ws + WS_WIN), *WOUT = (bf16_t*)(ws + WS_WOUT), *W1 = (bf16_t*)(ws + WS_W1), *W2 = (bf16_t*)(ws + WS_W2), *WG = (bf16_t*)(ws + WS_WG), *WP = (bf16_t*)(ws + WS_WP);
;     float* vecp = (float*)(ws + WS_VECP);
;     const int nin = att ? NQKV / 32 : HIN / 32;
;     const int I0 = nin * 16, I1 = I0 + 32 * 16, I2 = I1 + 176 * 16, I3 = I2 + 32 * 44, I4 = I3 + 32 * 16, I5 = I4 + 32 * 4;
;     for (int it = wid * G + blk; it < I5; it += 8 * G) {
.LBB0_1530:
	s_or_b64 exec, exec, s[4:5]
	s_setprio 0
	s_mov_b64 s[12:13], s[0:1]
	s_mov_b32 s10, s2
	s_mov_b32 s8, s74
	s_waitcnt lgkmcnt(0)
	v_mov_b32_e32 v0, v254
	s_barrier
	s_load_dwordx2 s[14:15], s[12:13], 0x90
	v_readfirstlane_b32 s3, v0
	s_ashr_i32 s3, s3, 6
	s_mul_i32 s4, s3, s8
	s_add_i32 s9, s4, s10
	s_cmpk_gt_i32 s9, 0x17ff
	s_cbranch_scc1 .LBB0_1569
	s_waitcnt lgkmcnt(0)
	s_add_u32 s11, s14, 0x1fd00000
	v_lshlrev_b32_e32 v18, 3, v0
	s_addc_u32 s24, s15, 0
	s_lshl_b32 s3, s3, 14
	v_and_b32_e32 v4, 56, v18
	v_bfe_u32 v3, v0, 3, 3
	s_add_i32 s4, s3, 0
	v_mul_u32_u24_e32 v5, 0x84, v4
	v_lshlrev_b32_e32 v6, 2, v3
	v_add3_u32 v86, s4, v5, v6
	v_lshlrev_b32_e32 v4, 1, v4
	v_mov_b32_e32 v5, 0
	v_bfe_u32 v2, v0, 5, 1
	v_lshl_add_u64 v[6:7], s[14:15], 0, v[4:5]
	s_mov_b64 s[4:5], 0x1f00000
	v_and_b32_e32 v4, 1, v0
	v_and_b32_e32 v12, 63, v0
	v_and_b32_e32 v1, 31, v0
	v_lshl_add_u64 v[8:9], v[6:7], 0, s[4:5]
	s_mov_b64 s[4:5], 0x1d00000
	s_mov_b64 s[6:7], 0x1700000
	v_cmp_eq_u32_e32 vcc, 1, v4
	v_mul_u32_u24_e32 v4, 0x84, v2
	v_lshl_add_u64 v[10:11], v[6:7], 0, s[4:5]
	v_cmp_gt_u32_e64 s[4:5], 32, v12
	v_lshl_add_u64 v[12:13], v[6:7], 0, s[6:7]
	v_mov_b32_e32 v14, 0xb00
	s_mov_b64 s[6:7], 0xc00000
	v_and_b32_e32 v91, 8, v18
	v_or_b32_e32 v4, s3, v4
	v_lshlrev_b32_e32 v18, 2, v1
	v_cndmask_b32_e32 v90, 0, v14, vcc
	v_lshl_add_u64 v[14:15], v[6:7], 0, s[6:7]
	s_mov_b64 s[6:7], 0xa00000
	v_add3_u32 v92, v4, v18, 0
	s_lshl_b32 s3, s9, 3
	s_add_i32 s34, s9, 0xfffffb00
	v_mbcnt_lo_u32_b32 v4, -1, 0
	s_mov_b32 s17, 0
	v_or_b32_e32 v87, 8, v3
	v_or_b32_e32 v88, 16, v3
	v_or_b32_e32 v89, 24, v3
	v_lshl_add_u64 v[16:17], v[6:7], 0, s[6:7]
	s_lshl_b32 s25, s8, 3
	s_add_i32 s26, s3, 0xffff4400
	s_lshl_b32 s27, s8, 6
	v_or_b32_e32 v93, 14, v2
	s_lshl_b32 s28, s9, 6
	s_lshl_b32 s29, s8, 9
	v_or_b32_e32 v94, 12, v2
	v_or_b32_e32 v95, 10, v2
	v_or_b32_e32 v96, 8, v2
	v_or_b32_e32 v97, 6, v2
	v_or_b32_e32 v98, 4, v2
	v_or_b32_e32 v99, 2, v2
	v_or_b32_e32 v100, 0xffffd500, v1
	s_lshl_b32 s30, s9, 1
	s_lshl_b32 s31, s8, 4
	s_lshl_b32 s35, s34, 1
	v_or_b32_e32 v101, 0xfffffa00, v1
	s_mov_b64 s[18:19], 0x10000
	s_movk_i32 s36, 0x5800
	s_mov_b64 s[20:21], 0x2c00000
	s_mov_b64 s[22:23], 0x58000
	s_movk_i32 s37, 0x1800
	s_movk_i32 s38, 0x500
	v_mov_b32_e32 v102, 0x800000
	v_mbcnt_hi_u32_b32 v103, -1, v4
	v_mov_b64_e32 v[18:19], 0x2c00000
	s_mov_b32 s39, s9
	s_branch .LBB0_1533

; __device__ __forceinline__ void vec_finalize(unsigned char* ws, int G, int blk) {
;     const float* vecp = (const float*)(ws + WS_VECP); float* vec = (float*)(ws + WS_VEC);
;     for (int i = blk * 512 + threadIdx.x; i < 13312; i += G * 512) { float a = 0.f;
; #pragma unroll
;         for (int kb = 0; kb < 16; ++kb) a += vecp[(size_t)kb * 13312 + i];
;         vec[i] = a; }
.Lprio_qkv2:
	s_mov_b32 s44, s74
	s_mov_b64 s[4:5], s[0:1]
	s_mov_b32 s45, s2
	s_waitcnt lgkmcnt(0)
	s_barrier
	s_load_dwordx2 s[8:9], s[4:5], 0x90
	v_lshl_add_u32 v0, s45, 9, v254
	s_movk_i32 s3, 0x3400
	v_cmp_gt_i32_e32 vcc, s3, v0
	s_and_saveexec_b64 s[4:5], vcc
	s_cbranch_execz .LBB0_1627
	s_lshl_b32 s6, s44, 9
	v_ashrrev_i32_e32 v1, 31, v0
	s_waitcnt lgkmcnt(0)
	v_lshl_add_u64 v[2:3], v[0:1], 2, s[8:9]
	s_mov_b64 s[10:11], 0x1fdc3000
	s_ashr_i32 s7, s6, 31
	v_lshl_add_u64 v[2:3], v[2:3], 0, s[10:11]
	s_lshl_b64 s[10:11], s[6:7], 2
	s_mov_b64 s[12:13], 0
	s_movk_i32 s3, 0x33ff

; #define PG8_STAGE(bufoff, gbase, voff) do { _Pragma("unroll") for (int _i = 0; _i < 2; ++_i) \
;         __builtin_amdgcn_global_load_lds((const unsigned*)((const char*)(gbase) + (voff)[_i]), (PG8_LAS unsigned*)(lds + (bufoff) + ldsw + _i * 8192), 16, 0, 0); } while (0)
; #define PG8_LDA(dst, b, h) do { _Pragma("unroll") for (int m = 0; m < 4; ++m) _Pragma("unroll") for (int k = 0; k < 2; ++k) dst[m][k] = *(const PG8_LAS bf16x8*)(lds + PG8_SA(b, h) + aoff + m * 2048 + k * 1024); } while (0)
; #define PG8_LDB(dst, b, h) do { _Pragma("unroll") for (int n = 0; n < 2; ++n) _Pragma("unroll") for (int k = 0; k < 2; ++k) dst[n][k] = *(const PG8_LAS bf16x8*)(lds + PG8_SB(b, h) + boff + n * 2048 + k * 1024); } while (0)
; #define PG8_MMA(ai, bj, At, Bt) do { __builtin_amdgcn_s_setprio(1); _Pragma("unroll") for (int m = 0; m < 4; ++m) _Pragma("unroll") for (int n = 0; n < 2; ++n) _Pragma("unroll") for (int k = 0; k < 2; ++k) \
;         acc[ai][bj][m][n] = __builtin_amdgcn_mfma_f32_16x16x32_bf16(Bt[n][k], At[m][k], acc[ai][bj][m][n], 0, 0, 0); __builtin_amdgcn_s_setprio(0); } while (0)
; #define PG8_WAIT_V(n) asm volatile("s_waitcnt vmcnt(" #n ")" ::: "memory")
; #define PG8_WAIT_L(n) asm volatile("s_waitcnt lgkmcnt(" #n ")" ::: "memory")
; template <class Epi, class Sched, bool ALIGN_EPI = false, bool SP2 = false>
; __device__ __forceinline__ void gemm_phase(PG8_LAS unsigned char* lds, const Gemm g, const Sched& S, const Epi& E) {
;     ...
;             const bool last = (t == nt - 2);
;             const char* a1 = cA + PG8_AK(t + 1);
;             const char* a2 = last ? nA : cA + PG8_AK(t + 2); const char* b2 = last ? nB : cB + (size_t)(t + 2) * kstep;
;             const char* a3 = last ? nA + PG8_AK(1) : cA + PG8_AK(t + 3); const char* b3 = b2 + kstep;
;             if (last && has_next) S.a_ready(nxt);
;             if constexpr (SP2) {
;             PG8_LDB(B0, 0, 0); PG8_LDB(B1, 0, 1); PG8_SCHED; PG8_LDA(At, 0, 0); PG8_STAGE(PG8_SA(1, 1), a1 + hstepA, voffA);
;             PG8_WAIT_V(8); PG8_WAIT_L(0); PG8_BAR; PG8_MMA(0, 0, At, B0); PG8_MMA(0, 1, At, B1); PG8_BAR; PG8_SCHED;
;             PG8_LDA(At, 0, 1); PG8_STAGE(PG8_SB(0, 0), b2, voffB); PG8_STAGE(PG8_SB(0, 1), b2 + hstepB, voffB); PG8_STAGE(PG8_SA(0, 0), a2, voffA);
;             PG8_WAIT_V(8); PG8_WAIT_L(0); PG8_BAR; PG8_MMA(1, 0, At, B0); PG8_MMA(1, 1, At, B1); PG8_BAR; PG8_SCHED;
.LBB0_1638:
	ds_read_b128 v[132:135], v172
	ds_read_b128 v[158:161], v172 offset:1024
	ds_read_b128 v[176:179], v172 offset:2048
	ds_read_b128 v[180:183], v172 offset:3072
	ds_read_b128 v[184:187], v173
	ds_read_b128 v[188:191], v173 offset:1024
	ds_read_b128 v[192:195], v173 offset:2048
	ds_read_b128 v[196:199], v173 offset:3072
	s_add_u32 s38, s28, s34
	s_addc_u32 s39, s29, s35
	s_add_u32 s42, s38, 0x100
	s_addc_u32 s43, s39, 0
	s_add_u32 s40, s62, s34
	s_addc_u32 s41, s63, s35
	s_add_u32 s38, s38, 0x180
	s_addc_u32 s39, s39, 0
	s_cmpk_eq_i32 s34, 0x700
	s_cselect_b32 s39, s37, s39
	s_cselect_b32 s38, s31, s38
	s_cselect_b32 s41, s21, s41
	s_cselect_b32 s40, s23, s40
	s_cselect_b32 s43, s3, s43
	s_cselect_b32 s42, s10, s42
	v_lshl_add_u64 v[232:233], v[130:131], 0, s[34:35]
	s_add_i32 m0, s49, 0xc000
	ds_read_b128 v[200:203], v174
	ds_read_b128 v[204:207], v174 offset:1024
	ds_read_b128 v[208:211], v174 offset:2048
	ds_read_b128 v[212:215], v174 offset:3072
	ds_read_b128 v[216:219], v174 offset:4096
	ds_read_b128 v[220:223], v174 offset:5120
	ds_read_b128 v[224:227], v174 offset:6144
	ds_read_b128 v[228:231], v174 offset:7168
	global_load_lds_dwordx4 v[232:233], off
	v_lshl_add_u64 v[232:233], v[128:129], 0, s[34:35]
	s_add_i32 m0, s49, 0xe000
	s_nop 0
	global_load_lds_dwordx4 v[232:233], off
	s_waitcnt vmcnt(8)
	s_waitcnt lgkmcnt(0)
	s_barrier
	s_waitcnt lgkmcnt(0)
	v_mfma_f32_16x16x32_bf16 v[124:127], v[132:135], v[200:203], v[124:127]
	v_mfma_f32_16x16x32_bf16 v[120:123], v[176:179], v[200:203], v[120:123]
	v_mfma_f32_16x16x32_bf16 v[108:111], v[132:135], v[208:211], v[108:111]
	v_mfma_f32_16x16x32_bf16 v[104:107], v[176:179], v[208:211], v[104:107]
	v_mfma_f32_16x16x32_bf16 v[92:95], v[132:135], v[216:219], v[92:95]
	v_mfma_f32_16x16x32_bf16 v[88:91], v[176:179], v[216:219], v[88:91]
	v_mfma_f32_16x16x32_bf16 v[76:79], v[132:135], v[224:227], v[76:79]
	v_mfma_f32_16x16x32_bf16 v[72:75], v[176:179], v[224:227], v[72:75]
	v_mfma_f32_16x16x32_bf16 v[124:127], v[158:161], v[204:207], v[124:127]
	v_mfma_f32_16x16x32_bf16 v[120:123], v[180:183], v[204:207], v[120:123]
	v_mfma_f32_16x16x32_bf16 v[108:111], v[158:161], v[212:215], v[108:111]
	v_mfma_f32_16x16x32_bf16 v[104:107], v[180:183], v[212:215], v[104:107]
	v_mfma_f32_16x16x32_bf16 v[92:95], v[158:161], v[220:223], v[92:95]
	v_mfma_f32_16x16x32_bf16 v[88:91], v[180:183], v[220:223], v[88:91]
	v_mfma_f32_16x16x32_bf16 v[76:79], v[158:161], v[228:231], v[76:79]
	v_mfma_f32_16x16x32_bf16 v[72:75], v[180:183], v[228:231], v[72:75]
	v_mfma_f32_16x16x32_bf16 v[116:119], v[184:187], v[200:203], v[116:119]
	v_mfma_f32_16x16x32_bf16 v[112:115], v[192:195], v[200:203], v[112:115]
	v_mfma_f32_16x16x32_bf16 v[100:103], v[184:187], v[208:211], v[100:103]
	v_mfma_f32_16x16x32_bf16 v[96:99], v[192:195], v[208:211], v[96:99]
	v_mfma_f32_16x16x32_bf16 v[84:87], v[184:187], v[216:219], v[84:87]
	v_mfma_f32_16x16x32_bf16 v[80:83], v[192:195], v[216:219], v[80:83]
	v_mfma_f32_16x16x32_bf16 v[68:71], v[184:187], v[224:227], v[68:71]
	v_mfma_f32_16x16x32_bf16 v[64:67], v[192:195], v[224:227], v[64:67]
	v_mfma_f32_16x16x32_bf16 v[116:119], v[188:191], v[204:207], v[116:119]
	v_mfma_f32_16x16x32_bf16 v[112:115], v[196:199], v[204:207], v[112:115]
	v_mfma_f32_16x16x32_bf16 v[100:103], v[188:191], v[212:215], v[100:103]
	v_mfma_f32_16x16x32_bf16 v[96:99], v[196:199], v[212:215], v[96:99]
	v_mfma_f32_16x16x32_bf16 v[84:87], v[188:191], v[220:223], v[84:87]
	v_mfma_f32_16x16x32_bf16 v[80:83], v[196:199], v[220:223], v[80:83]
	v_mfma_f32_16x16x32_bf16 v[68:71], v[188:191], v[228:231], v[68:71]
	v_mfma_f32_16x16x32_bf16 v[64:67], v[196:199], v[228:231], v[64:67]
	s_barrier
	s_add_i32 s65, s58, s48
	v_lshl_add_u64 v[232:233], s[40:41], 0, v[138:139]
	s_mov_b32 m0, s65
	ds_read_b128 v[200:203], v174 offset:16384
	ds_read_b128 v[204:207], v174 offset:17408
	ds_read_b128 v[208:211], v174 offset:18432
	ds_read_b128 v[212:215], v174 offset:19456
	ds_read_b128 v[216:219], v174 offset:20480
	ds_read_b128 v[220:223], v174 offset:21504
	ds_read_b128 v[224:227], v174 offset:22528
	ds_read_b128 v[228:231], v174 offset:23552
	global_load_lds_dwordx4 v[232:233], off
	s_add_i32 m0, s65, 0x2000
	s_add_u32 s66, s40, 0x40000
	v_lshl_add_u64 v[234:235], s[40:41], 0, v[142:143]
	s_addc_u32 s67, s41, 0
	s_add_i32 s65, s59, s48
	global_load_lds_dwordx4 v[234:235], off
	v_lshl_add_u64 v[236:237], s[66:67], 0, v[138:139]
	s_mov_b32 m0, s65
	s_nop 0
	global_load_lds_dwordx4 v[236:237], off
	v_lshl_add_u64 v[236:237], s[66:67], 0, v[142:143]
	s_add_i32 m0, s65, 0x2000
	s_nop 0
	global_load_lds_dwordx4 v[236:237], off
	v_lshl_add_u64 v[236:237], s[42:43], 0, v[136:137]
	s_mov_b32 m0, s49
	s_nop 0
	global_load_lds_dwordx4 v[236:237], off
	v_lshl_add_u64 v[236:237], s[42:43], 0, v[140:141]
	s_mov_b32 m0, s50
	s_nop 0
	global_load_lds_dwordx4 v[236:237], off
	s_waitcnt vmcnt(8)
	s_waitcnt lgkmcnt(0)
	s_barrier
; #define PG8_STAGE(bufoff, gbase, voff) do { _Pragma("unroll") for (int _i = 0; _i < 2; ++_i) \
;         __builtin_amdgcn_global_load_lds((const unsigned*)((const char*)(gbase) + (voff)[_i]), (PG8_LAS unsigned*)(lds + (bufoff) + ldsw + _i * 8192), 16, 0, 0); } while (0)
; #define PG8_LDA(dst, b, h) do { _Pragma("unroll") for (int m = 0; m < 4; ++m) _Pragma("unroll") for (int k = 0; k < 2; ++k) dst[m][k] = *(const PG8_LAS bf16x8*)(lds + PG8_SA(b, h) + aoff + m * 2048 + k * 1024); } while (0)
; #define PG8_LDB(dst, b, h) do { _Pragma("unroll") for (int n = 0; n < 2; ++n) _Pragma("unroll") for (int k = 0; k < 2; ++k) dst[n][k] = *(const PG8_LAS bf16x8*)(lds + PG8_SB(b, h) + boff + n * 2048 + k * 1024); } while (0)
; #define PG8_MMA(ai, bj, At, Bt) do { __builtin_amdgcn_s_setprio(1); _Pragma("unroll") for (int m = 0; m < 4; ++m) _Pragma("unroll") for (int n = 0; n < 2; ++n) _Pragma("unroll") for (int k = 0; k < 2; ++k) \
;         acc[ai][bj][m][n] = __builtin_amdgcn_mfma_f32_16x16x32_bf16(Bt[n][k], At[m][k], acc[ai][bj][m][n], 0, 0, 0); __builtin_amdgcn_s_setprio(0); } while (0)
; #define PG8_WAIT_V(n) asm volatile("s_waitcnt vmcnt(" #n ")" ::: "memory")
; #define PG8_WAIT_L(n) asm volatile("s_waitcnt lgkmcnt(" #n ")" ::: "memory")
; #define PG8_BAR __builtin_amdgcn_s_barrier()
; #define PG8_SCHED __builtin_amdgcn_sched_barrier(0)
; template <class Epi, class Sched, bool ALIGN_EPI = false, bool SP2 = false>
; __device__ __forceinline__ void gemm_phase(PG8_LAS unsigned char* lds, const Gemm g, const Sched& S, const Epi& E) {
;     ...
;             PG8_WAIT_V(8); PG8_WAIT_L(0); PG8_BAR; PG8_MMA(1, 0, At, B0); PG8_MMA(1, 1, At, B1); PG8_BAR; PG8_SCHED;
;             PG8_LDB(B0, 1, 0); PG8_LDB(B1, 1, 1); PG8_SCHED; PG8_LDA(At, 1, 0); PG8_STAGE(PG8_SA(0, 1), a2 + hstepA, voffA);
;             PG8_WAIT_V(8); PG8_WAIT_L(0); PG8_BAR; PG8_MMA(0, 0, At, B0); PG8_MMA(0, 1, At, B1); PG8_BAR; PG8_SCHED;
	s_waitcnt lgkmcnt(0)
	v_mfma_f32_16x16x32_bf16 v[60:63], v[132:135], v[200:203], v[60:63]
	v_mfma_f32_16x16x32_bf16 v[56:59], v[176:179], v[200:203], v[56:59]
	v_mfma_f32_16x16x32_bf16 v[44:47], v[132:135], v[208:211], v[44:47]
	v_mfma_f32_16x16x32_bf16 v[40:43], v[176:179], v[208:211], v[40:43]
	v_mfma_f32_16x16x32_bf16 v[28:31], v[132:135], v[216:219], v[28:31]
	v_mfma_f32_16x16x32_bf16 v[24:27], v[176:179], v[216:219], v[24:27]
	v_mfma_f32_16x16x32_bf16 v[12:15], v[132:135], v[224:227], v[12:15]
	v_mfma_f32_16x16x32_bf16 v[8:11], v[176:179], v[224:227], v[8:11]
	v_mfma_f32_16x16x32_bf16 v[60:63], v[158:161], v[204:207], v[60:63]
	v_mfma_f32_16x16x32_bf16 v[56:59], v[180:183], v[204:207], v[56:59]
	v_mfma_f32_16x16x32_bf16 v[44:47], v[158:161], v[212:215], v[44:47]
	v_mfma_f32_16x16x32_bf16 v[40:43], v[180:183], v[212:215], v[40:43]
	v_mfma_f32_16x16x32_bf16 v[28:31], v[158:161], v[220:223], v[28:31]
	v_mfma_f32_16x16x32_bf16 v[24:27], v[180:183], v[220:223], v[24:27]
	v_mfma_f32_16x16x32_bf16 v[12:15], v[158:161], v[228:231], v[12:15]
	v_mfma_f32_16x16x32_bf16 v[8:11], v[180:183], v[228:231], v[8:11]
	v_mfma_f32_16x16x32_bf16 v[52:55], v[184:187], v[200:203], v[52:55]
	v_mfma_f32_16x16x32_bf16 v[48:51], v[192:195], v[200:203], v[48:51]
	v_mfma_f32_16x16x32_bf16 v[36:39], v[184:187], v[208:211], v[36:39]
	v_mfma_f32_16x16x32_bf16 v[32:35], v[192:195], v[208:211], v[32:35]
	v_mfma_f32_16x16x32_bf16 v[20:23], v[184:187], v[216:219], v[20:23]
	v_mfma_f32_16x16x32_bf16 v[16:19], v[192:195], v[216:219], v[16:19]
	v_mfma_f32_16x16x32_bf16 v[4:7], v[184:187], v[224:227], v[4:7]
	v_mfma_f32_16x16x32_bf16 v[0:3], v[192:195], v[224:227], v[0:3]
	v_mfma_f32_16x16x32_bf16 v[52:55], v[188:191], v[204:207], v[52:55]
	v_mfma_f32_16x16x32_bf16 v[48:51], v[196:199], v[204:207], v[48:51]
	v_mfma_f32_16x16x32_bf16 v[36:39], v[188:191], v[212:215], v[36:39]
	v_mfma_f32_16x16x32_bf16 v[32:35], v[196:199], v[212:215], v[32:35]
	v_mfma_f32_16x16x32_bf16 v[20:23], v[188:191], v[220:223], v[20:23]
	v_mfma_f32_16x16x32_bf16 v[16:19], v[196:199], v[220:223], v[16:19]
	v_mfma_f32_16x16x32_bf16 v[4:7], v[188:191], v[228:231], v[4:7]
	v_mfma_f32_16x16x32_bf16 v[0:3], v[196:199], v[228:231], v[0:3]
	s_barrier
	s_add_i32 s65, 0, 0x18000
	v_add_u32_e32 v144, s65, v163
	s_add_i32 s66, 0, 0x1c000
	ds_read_b128 v[132:135], v144
	ds_read_b128 v[158:161], v144 offset:1024
	ds_read_b128 v[176:179], v144 offset:2048
	ds_read_b128 v[180:183], v144 offset:3072
	v_add_u32_e32 v144, s66, v163
	ds_read_b128 v[184:187], v144
	ds_read_b128 v[188:191], v144 offset:1024
	ds_read_b128 v[192:195], v144 offset:2048
	ds_read_b128 v[196:199], v144 offset:3072
	s_add_u32 s42, s42, 0x40000
	s_addc_u32 s43, s43, 0
	s_mov_b32 m0, s51
	v_lshl_add_u64 v[236:237], s[42:43], 0, v[136:137]
	ds_read_b128 v[200:203], v174 offset:32768
	ds_read_b128 v[204:207], v174 offset:33792
	ds_read_b128 v[208:211], v174 offset:34816
	ds_read_b128 v[212:215], v174 offset:35840
	ds_read_b128 v[216:219], v174 offset:36864
	ds_read_b128 v[220:223], v174 offset:37888
	ds_read_b128 v[224:227], v174 offset:38912
	ds_read_b128 v[228:231], v174 offset:39936
	global_load_lds_dwordx4 v[236:237], off
	v_lshl_add_u64 v[236:237], s[42:43], 0, v[140:141]
	s_mov_b32 m0, s52
	s_nop 0
	global_load_lds_dwordx4 v[236:237], off
	s_waitcnt vmcnt(8)
	s_waitcnt lgkmcnt(0)
	s_barrier
	s_waitcnt lgkmcnt(0)
	v_mfma_f32_16x16x32_bf16 v[124:127], v[132:135], v[200:203], v[124:127]
	v_mfma_f32_16x16x32_bf16 v[120:123], v[176:179], v[200:203], v[120:123]
	v_mfma_f32_16x16x32_bf16 v[108:111], v[132:135], v[208:211], v[108:111]
	v_mfma_f32_16x16x32_bf16 v[104:107], v[176:179], v[208:211], v[104:107]
	v_mfma_f32_16x16x32_bf16 v[92:95], v[132:135], v[216:219], v[92:95]
	v_mfma_f32_16x16x32_bf16 v[88:91], v[176:179], v[216:219], v[88:91]
	v_mfma_f32_16x16x32_bf16 v[76:79], v[132:135], v[224:227], v[76:79]
	v_mfma_f32_16x16x32_bf16 v[72:75], v[176:179], v[224:227], v[72:75]
	v_mfma_f32_16x16x32_bf16 v[124:127], v[158:161], v[204:207], v[124:127]
	v_mfma_f32_16x16x32_bf16 v[120:123], v[180:183], v[204:207], v[120:123]
	v_mfma_f32_16x16x32_bf16 v[108:111], v[158:161], v[212:215], v[108:111]
	v_mfma_f32_16x16x32_bf16 v[104:107], v[180:183], v[212:215], v[104:107]
	v_mfma_f32_16x16x32_bf16 v[92:95], v[158:161], v[220:223], v[92:95]
	v_mfma_f32_16x16x32_bf16 v[88:91], v[180:183], v[220:223], v[88:91]
	v_mfma_f32_16x16x32_bf16 v[76:79], v[158:161], v[228:231], v[76:79]
	v_mfma_f32_16x16x32_bf16 v[72:75], v[180:183], v[228:231], v[72:75]
	v_mfma_f32_16x16x32_bf16 v[116:119], v[184:187], v[200:203], v[116:119]
	v_mfma_f32_16x16x32_bf16 v[112:115], v[192:195], v[200:203], v[112:115]
	v_mfma_f32_16x16x32_bf16 v[100:103], v[184:187], v[208:211], v[100:103]
	v_mfma_f32_16x16x32_bf16 v[96:99], v[192:195], v[208:211], v[96:99]
	v_mfma_f32_16x16x32_bf16 v[84:87], v[184:187], v[216:219], v[84:87]
	v_mfma_f32_16x16x32_bf16 v[80:83], v[192:195], v[216:219], v[80:83]
	v_mfma_f32_16x16x32_bf16 v[68:71], v[184:187], v[224:227], v[68:71]
	v_mfma_f32_16x16x32_bf16 v[64:67], v[192:195], v[224:227], v[64:67]
	v_mfma_f32_16x16x32_bf16 v[116:119], v[188:191], v[204:207], v[116:119]
	v_mfma_f32_16x16x32_bf16 v[112:115], v[196:199], v[204:207], v[112:115]
	v_mfma_f32_16x16x32_bf16 v[100:103], v[188:191], v[212:215], v[100:103]
	v_mfma_f32_16x16x32_bf16 v[96:99], v[196:199], v[212:215], v[96:99]
	v_mfma_f32_16x16x32_bf16 v[84:87], v[188:191], v[220:223], v[84:87]
	v_mfma_f32_16x16x32_bf16 v[80:83], v[196:199], v[220:223], v[80:83]
	v_mfma_f32_16x16x32_bf16 v[68:71], v[188:191], v[228:231], v[68:71]
	v_mfma_f32_16x16x32_bf16 v[64:67], v[196:199], v[228:231], v[64:67]
	s_barrier
; #define PG8_STAGE(bufoff, gbase, voff) do { _Pragma("unroll") for (int _i = 0; _i < 2; ++_i) \
;         __builtin_amdgcn_global_load_lds((const unsigned*)((const char*)(gbase) + (voff)[_i]), (PG8_LAS unsigned*)(lds + (bufoff) + ldsw + _i * 8192), 16, 0, 0); } while (0)
; #define PG8_LDA(dst, b, h) do { _Pragma("unroll") for (int m = 0; m < 4; ++m) _Pragma("unroll") for (int k = 0; k < 2; ++k) dst[m][k] = *(const PG8_LAS bf16x8*)(lds + PG8_SA(b, h) + aoff + m * 2048 + k * 1024); } while (0)
; #define PG8_MMA(ai, bj, At, Bt) do { __builtin_amdgcn_s_setprio(1); _Pragma("unroll") for (int m = 0; m < 4; ++m) _Pragma("unroll") for (int n = 0; n < 2; ++n) _Pragma("unroll") for (int k = 0; k < 2; ++k) \
;         acc[ai][bj][m][n] = __builtin_amdgcn_mfma_f32_16x16x32_bf16(Bt[n][k], At[m][k], acc[ai][bj][m][n], 0, 0, 0); __builtin_amdgcn_s_setprio(0); } while (0)
; #define PG8_WAIT_V(n) asm volatile("s_waitcnt vmcnt(" #n ")" ::: "memory")
; #define PG8_WAIT_L(n) asm volatile("s_waitcnt lgkmcnt(" #n ")" ::: "memory")
; #define PG8_BAR __builtin_amdgcn_s_barrier()
; #define PG8_SCHED __builtin_amdgcn_sched_barrier(0)
; template <class Epi, class Sched, bool ALIGN_EPI = false, bool SP2 = false>
; __device__ __forceinline__ void gemm_phase(PG8_LAS unsigned char* lds, const Gemm g, const Sched& S, const Epi& E) {
;     ...
;         for (int t = 0; t < nt; t += 2) {
;     ...
;             PG8_LDA(At, 1, 1); PG8_STAGE(PG8_SB(1, 0), b3, voffB); PG8_STAGE(PG8_SB(1, 1), b3 + hstepB, voffB); PG8_STAGE(PG8_SA(1, 0), a3, voffA);
;             PG8_WAIT_V(8); PG8_WAIT_L(0); PG8_BAR; PG8_MMA(1, 0, At, B0); PG8_MMA(1, 1, At, B1); PG8_BAR; PG8_SCHED;
;     __device__ __forceinline__ void operator()(const f32x4 (&acc)[2][2][4][2], const Unit& u, int wr, int wc, int fr, int fq) const {
;     ...
;         if (u.pn < 4) { base = Q; ldc = 1024; colt = u.pn * 256; sc = 0.125f * LOG2E; } else if (u.pn == 4) { base = K; ldc = 256; colt = 0; sc = 1.f; } else { base = V; ldc = 256; colt = 0; sc = 1.f; }
	s_add_i32 s42, s65, s48
	v_lshl_add_u64 v[232:233], v[232:233], 0, s[14:15]
	s_mov_b32 m0, s42
	ds_read_b128 v[200:203], v174 offset:49152
	ds_read_b128 v[204:207], v174 offset:50176
	ds_read_b128 v[208:211], v174 offset:51200
	ds_read_b128 v[212:215], v174 offset:52224
	ds_read_b128 v[216:219], v174 offset:53248
	ds_read_b128 v[220:223], v174 offset:54272
	ds_read_b128 v[224:227], v174 offset:55296
	ds_read_b128 v[228:231], v174 offset:56320
	global_load_lds_dwordx4 v[232:233], off
	s_add_i32 m0, s42, 0x2000
	s_add_u32 s40, s40, 0x40080
	v_lshl_add_u64 v[232:233], v[234:235], 0, s[14:15]
	s_addc_u32 s41, s41, 0
	s_add_i32 s42, s66, s48
	global_load_lds_dwordx4 v[232:233], off
	v_lshl_add_u64 v[232:233], s[40:41], 0, v[138:139]
	s_mov_b32 m0, s42
	s_nop 0
	global_load_lds_dwordx4 v[232:233], off
	v_lshl_add_u64 v[232:233], s[40:41], 0, v[142:143]
	s_add_i32 m0, s42, 0x2000
	s_nop 0
	global_load_lds_dwordx4 v[232:233], off
	v_lshl_add_u64 v[232:233], s[38:39], 0, v[136:137]
	s_mov_b32 m0, s53
	s_nop 0
	global_load_lds_dwordx4 v[232:233], off
	v_lshl_add_u64 v[232:233], s[38:39], 0, v[140:141]
	s_mov_b32 m0, s54
	s_nop 0
	global_load_lds_dwordx4 v[232:233], off
	s_waitcnt vmcnt(8)
	s_waitcnt lgkmcnt(0)
	s_barrier
	s_waitcnt lgkmcnt(0)
	v_mfma_f32_16x16x32_bf16 v[60:63], v[132:135], v[200:203], v[60:63]
	v_mfma_f32_16x16x32_bf16 v[56:59], v[176:179], v[200:203], v[56:59]
	v_mfma_f32_16x16x32_bf16 v[44:47], v[132:135], v[208:211], v[44:47]
	v_mfma_f32_16x16x32_bf16 v[40:43], v[176:179], v[208:211], v[40:43]
	v_mfma_f32_16x16x32_bf16 v[28:31], v[132:135], v[216:219], v[28:31]
	v_mfma_f32_16x16x32_bf16 v[24:27], v[176:179], v[216:219], v[24:27]
	v_mfma_f32_16x16x32_bf16 v[12:15], v[132:135], v[224:227], v[12:15]
	v_mfma_f32_16x16x32_bf16 v[8:11], v[176:179], v[224:227], v[8:11]
	v_mfma_f32_16x16x32_bf16 v[60:63], v[158:161], v[204:207], v[60:63]
	v_mfma_f32_16x16x32_bf16 v[56:59], v[180:183], v[204:207], v[56:59]
	v_mfma_f32_16x16x32_bf16 v[44:47], v[158:161], v[212:215], v[44:47]
	v_mfma_f32_16x16x32_bf16 v[40:43], v[180:183], v[212:215], v[40:43]
	v_mfma_f32_16x16x32_bf16 v[28:31], v[158:161], v[220:223], v[28:31]
	v_mfma_f32_16x16x32_bf16 v[24:27], v[180:183], v[220:223], v[24:27]
	v_mfma_f32_16x16x32_bf16 v[12:15], v[158:161], v[228:231], v[12:15]
	v_mfma_f32_16x16x32_bf16 v[8:11], v[180:183], v[228:231], v[8:11]
	v_mfma_f32_16x16x32_bf16 v[52:55], v[184:187], v[200:203], v[52:55]
	v_mfma_f32_16x16x32_bf16 v[48:51], v[192:195], v[200:203], v[48:51]
	v_mfma_f32_16x16x32_bf16 v[36:39], v[184:187], v[208:211], v[36:39]
	v_mfma_f32_16x16x32_bf16 v[32:35], v[192:195], v[208:211], v[32:35]
	v_mfma_f32_16x16x32_bf16 v[20:23], v[184:187], v[216:219], v[20:23]
	v_mfma_f32_16x16x32_bf16 v[16:19], v[192:195], v[216:219], v[16:19]
	v_mfma_f32_16x16x32_bf16 v[4:7], v[184:187], v[224:227], v[4:7]
	v_mfma_f32_16x16x32_bf16 v[0:3], v[192:195], v[224:227], v[0:3]
	v_mfma_f32_16x16x32_bf16 v[52:55], v[188:191], v[204:207], v[52:55]
	v_mfma_f32_16x16x32_bf16 v[48:51], v[196:199], v[204:207], v[48:51]
	v_mfma_f32_16x16x32_bf16 v[36:39], v[188:191], v[212:215], v[36:39]
	v_mfma_f32_16x16x32_bf16 v[32:35], v[196:199], v[212:215], v[32:35]
	v_mfma_f32_16x16x32_bf16 v[20:23], v[188:191], v[220:223], v[20:23]
	v_mfma_f32_16x16x32_bf16 v[16:19], v[196:199], v[220:223], v[16:19]
	v_mfma_f32_16x16x32_bf16 v[4:7], v[188:191], v[228:231], v[4:7]
	v_mfma_f32_16x16x32_bf16 v[0:3], v[196:199], v[228:231], v[0:3]
	s_barrier
	s_add_i32 s64, s64, 2
	s_add_u32 s34, s34, 0x100
	s_addc_u32 s35, s35, 0
	s_cmp_gt_u32 s64, 13
	s_cbranch_scc0 .LBB0_1638
	s_and_b64 vcc, exec, s[16:17]
	s_cbranch_vccz .LBB0_1643
	s_barrier
	s_cmp_gt_i32 s30, 3
	s_mov_b64 s[28:29], -1
	s_cbranch_scc1 .LBB0_1644

; __device__ __forceinline__ void attn_phase(unsigned char* lds, const bf16_t* Q, const bf16_t* Kb, const bf16_t* Vb, bf16_t* O, const float* sink, int G, int blk) {
;     int tid_l = threadIdx.x; asm volatile("" : "+v"(tid_l)); const int tid = tid_l, lane = tid & 63, wid = __builtin_amdgcn_readfirstlane(tid >> 6), r32 = lane & 31, hi = lane >> 5;
;     bf16_t* Ks = (bf16_t*)lds; bf16_t* Vt = (bf16_t*)(lds + 384 * 72 * 2);
;     for (int unit = blk; unit < 1024; unit += G) {
;         const int b = unit >> 9, kvh = (unit >> 7) & 3, qb = unit & 127, start = qb * 128;
;         asm volatile("s_waitcnt lgkmcnt(0)\n\ts_barrier" ::: "memory");
;         for (int idx = tid; idx < 384 * 8; idx += 512) {
;             const int key = idx >> 3, ch = idx & 7, kpos = start - 128 + key;
;             if (kpos >= 0 && kpos < SEQ) {
;                 const size_t gofs = ((size_t)(b * SEQ + kpos)) * 256 + kvh * 64 + ch * 8;
;                 const u32x4 kv = *(const u32x4*)(Kb + gofs); *(u32x4*)(Ks + key * 72 + ch * 8) = kv;
;                 const u32x4 vv = *(const u32x4*)(Vb + gofs);
; #pragma unroll
;                 for (int jj = 0; jj < 4; ++jj) { const unsigned w = vv[jj]; Vt[(ch * 8 + 2 * jj) * 392 + key] = (bf16_t)(w & 0xffffu); Vt[(ch * 8 + 2 * jj + 1) * 392 + key] = (bf16_t)(w >> 16); }
;             }
;         }
;         __syncthreads();
;         const int g = wid >> 1, half = wid & 1, head = kvh * 4 + g;
;         const float sk = sink[head] * LOG2E;
;         for (int sb = 0; sb < 2; ++sb) {
;             const int r0 = 64 * half + 32 * sb; const size_t tok = (size_t)b * SEQ + start + r0 + r32;
;             bf16x8 qf[4];
; #pragma unroll
;             for (int ks = 0; ks < 4; ++ks) qf[ks] = *(const bf16x8*)(Q + tok * 1024 + head * 64 + 16 * ks + 8 * hi);
;             float m = sk, l = 1.f; f32x16 o0 = {}, o1 = {};
;             const int base_pos = start - 128 + r0;
;             const int jlo = base_pos < 0 ? ((-base_pos + 31) >> 5) : 0, jhi = (SEQ - base_pos) >= 288 ? 9 : ((SEQ - base_pos) >> 5);
.LBB0_1750:
	s_or_b64 exec, exec, s[4:5]
	s_setprio 0
	s_mov_b64 s[4:5], s[0:1]
	s_mov_b32 s94, s2
	s_mov_b32 s95, s74
	v_mov_b32_e32 v107, v254
	s_waitcnt lgkmcnt(0)
	s_barrier
	s_cmpk_gt_i32 s94, 0x3ff
	v_readfirstlane_b32 s3, v107
	s_cbranch_scc1 .LBB0_1770
	s_load_dwordx2 s[6:7], s[4:5], 0x90
	s_load_dwordx2 s[80:81], s[4:5], 0x18
	v_bfe_u32 v4, v107, 5, 1
	v_mov_b32_e32 v103, 0
	v_lshlrev_b32_e32 v0, 4, v4
	s_waitcnt lgkmcnt(0)
	s_add_u32 s82, s6, 0x13800000
	s_addc_u32 s83, s7, 0
	v_mov_b32_e32 v1, v103
	s_add_u32 s84, s6, 0x14800000
	v_lshlrev_b32_e32 v102, 3, v4
	v_lshl_add_u64 v[2:3], s[6:7], 0, v[0:1]
	s_mov_b64 s[8:9], 0xf800000
	s_addc_u32 s85, s7, 0
	v_lshl_add_u64 v[104:105], v[2:3], 0, s[8:9]
	v_add_u32_e32 v106, 0, v0
	v_lshlrev_b32_e32 v2, 2, v4
	v_lshl_add_u64 v[0:1], s[6:7], 0, v[102:103]
	s_mov_b64 s[6:7], 0x15800000
	v_and_b32_e32 v100, 31, v107
	s_ashr_i32 s96, s3, 7
	s_and_b32 s97, s3, 64
	v_lshl_add_u64 v[108:109], v[0:1], 0, s[6:7]
	v_or_b32_e32 v0, 1, v2
	s_lshl_b32 s3, s3, 1
	v_cmp_lt_u32_e64 s[8:9], v0, v100
	v_or_b32_e32 v0, 2, v2
	s_and_b32 s3, s3, 0x80
	v_cmp_lt_u32_e64 s[10:11], v0, v100
	v_cmp_gt_u32_e64 s[42:43], v0, v100
	s_movk_i32 s70, 0x310
	v_mov_b32_e32 v0, s3
	v_mad_u32_u24 v0, v100, s70, v0
	v_or_b32_e32 v0, v0, v102
	v_add_u32_e32 v118, 0, v0
	v_mbcnt_lo_u32_b32 v0, -1, 0
	v_mbcnt_hi_u32_b32 v119, -1, v0
	v_writelane_b32 v255, s90, 4
	s_movk_i32 s4, 0xc00
	v_or_b32_e32 v1, 3, v2
	v_or_b32_e32 v3, 8, v2
	v_or_b32_e32 v4, 9, v2
	v_or_b32_e32 v5, 10, v2
	v_or_b32_e32 v6, 11, v2
	v_or_b32_e32 v7, 16, v2
	v_or_b32_e32 v8, 17, v2
	v_or_b32_e32 v9, 18, v2
	v_or_b32_e32 v10, 19, v2
	v_or_b32_e32 v11, 24, v2
	v_or_b32_e32 v12, 25, v2
	v_or_b32_e32 v13, 26, v2
	v_or_b32_e32 v14, 27, v2
	v_and_b32_e32 v0, 64, v119
	v_writelane_b32 v255, s91, 5
	s_mov_b64 s[0:1], s[76:77]
	s_mov_b32 s76, s88
	v_cmp_gt_i32_e64 s[4:5], s4, v107
	v_cmp_lt_u32_e64 s[6:7], v2, v100
	v_cmp_lt_u32_e64 s[12:13], v1, v100
	v_cmp_lt_u32_e64 s[14:15], v3, v100
	v_cmp_lt_u32_e64 s[16:17], v4, v100
	v_cmp_lt_u32_e64 s[18:19], v5, v100
	v_cmp_lt_u32_e64 s[20:21], v6, v100
	v_cmp_lt_u32_e64 s[22:23], v7, v100
	v_cmp_lt_u32_e64 s[24:25], v8, v100
	v_cmp_lt_u32_e64 s[26:27], v9, v100
	v_cmp_lt_u32_e64 s[28:29], v10, v100
	v_cmp_lt_u32_e64 s[30:31], v11, v100
	v_cmp_lt_u32_e64 s[34:35], v12, v100
	v_cmp_lt_u32_e64 s[36:37], v13, v100
	v_cmp_lt_u32_e64 s[38:39], v14, v100
	v_cmp_gt_u32_e64 s[40:41], v2, v100
	v_cmp_gt_u32_e64 s[44:45], v1, v100
	v_cmp_gt_u32_e64 s[46:47], v3, v100
	v_cmp_gt_u32_e64 s[48:49], v4, v100
	v_cmp_gt_u32_e64 s[50:51], v5, v100
	v_cmp_gt_u32_e64 s[52:53], v6, v100
	v_cmp_gt_u32_e64 s[54:55], v7, v100
	v_cmp_gt_u32_e64 s[56:57], v8, v100
	v_cmp_gt_u32_e64 s[58:59], v9, v100
	v_cmp_gt_u32_e64 s[60:61], v10, v100
	v_cmp_gt_u32_e64 s[62:63], v11, v100
	v_cmp_gt_u32_e64 s[64:65], v12, v100
	v_cmp_gt_u32_e64 s[66:67], v13, v100
	v_cmp_gt_u32_e64 s[68:69], v14, v100
	v_or_b32_e32 v116, s97, v100
	v_lshlrev_b32_e32 v117, 3, v107
	s_movk_i32 s3, 0x90
	v_xor_b32_e32 v120, 32, v119
	v_add_u32_e32 v121, 64, v0
	v_mov_b32_e32 v122, 0xff800000
	s_branch .LBB0_1753

;     __host__ __device__ bool next(int i, Unit& u) const {
;         const long L = (long)i * G + c; if (L >= nwg) return false;
;         int wgid = (int)L; { const int q = nwg / NXCD, r = nwg % NXCD, xcd = wgid % NXCD, off = wgid / NXCD; wgid = (xcd < r ? xcd * (q + 1) : r * (q + 1) + (xcd - r) * q) + off; }
;         const int nig = WGM * nN, gid = wgid / nig, fm = gid * WGM, gsz = (nM - fm) < WGM ? (nM - fm) : WGM;
;         u.pm = fm + ((wgid % nig) % gsz); u.pn = (wgid % nig) / gsz; return true;
.Lprio_out2:
	s_mov_b64 s[4:5], s[0:1]
	s_mov_b32 s23, s2
	s_mov_b32 s46, s74
	s_waitcnt lgkmcnt(0)
	s_barrier
	v_mov_b32_e32 v8, v254
	s_cmpk_lt_i32 s23, 0x200
	s_cselect_b64 s[6:7], -1, 0
	s_cmpk_gt_i32 s23, 0x1ff
	v_readfirstlane_b32 s3, v8
	s_cbranch_scc1 .LBB0_1828
	s_ashr_i32 s8, s23, 31
	s_lshr_b32 s8, s8, 29
	s_add_i32 s12, s23, s8
	s_and_b32 s8, s12, -8
	s_sub_i32 s10, s23, s8
	s_cmp_gt_i32 s10, -1
	s_cbranch_scc0 .LBB0_1825
	s_lshl_b32 s11, s10, 6
	s_ashr_i32 s8, s12, 3
	s_cbranch_execz .LBB0_1826
	s_branch .LBB0_1827

; #define PG8_STAGE(bufoff, gbase, voff) do { _Pragma("unroll") for (int _i = 0; _i < 2; ++_i) \
;         __builtin_amdgcn_global_load_lds((const unsigned*)((const char*)(gbase) + (voff)[_i]), (PG8_LAS unsigned*)(lds + (bufoff) + ldsw + _i * 8192), 16, 0, 0); } while (0)
; #define PG8_LDA(dst, b, h) do { _Pragma("unroll") for (int m = 0; m < 4; ++m) _Pragma("unroll") for (int k = 0; k < 2; ++k) dst[m][k] = *(const PG8_LAS bf16x8*)(lds + PG8_SA(b, h) + aoff + m * 2048 + k * 1024); } while (0)
; #define PG8_LDB(dst, b, h) do { _Pragma("unroll") for (int n = 0; n < 2; ++n) _Pragma("unroll") for (int k = 0; k < 2; ++k) dst[n][k] = *(const PG8_LAS bf16x8*)(lds + PG8_SB(b, h) + boff + n * 2048 + k * 1024); } while (0)
; #define PG8_MMA(ai, bj, At, Bt) do { __builtin_amdgcn_s_setprio(1); _Pragma("unroll") for (int m = 0; m < 4; ++m) _Pragma("unroll") for (int n = 0; n < 2; ++n) _Pragma("unroll") for (int k = 0; k < 2; ++k) \
;         acc[ai][bj][m][n] = __builtin_amdgcn_mfma_f32_16x16x32_bf16(Bt[n][k], At[m][k], acc[ai][bj][m][n], 0, 0, 0); __builtin_amdgcn_s_setprio(0); } while (0)
; #define PG8_WAIT_V(n) asm volatile("s_waitcnt vmcnt(" #n ")" ::: "memory")
; #define PG8_WAIT_L(n) asm volatile("s_waitcnt lgkmcnt(" #n ")" ::: "memory")
; template <class Epi, class Sched, bool ALIGN_EPI = false, bool SP2 = false>
; __device__ __forceinline__ void gemm_phase(PG8_LAS unsigned char* lds, const Gemm g, const Sched& S, const Epi& E) {
;     ...
;             const bool last = (t == nt - 2);
;             const char* a1 = cA + PG8_AK(t + 1);
;             const char* a2 = last ? nA : cA + PG8_AK(t + 2); const char* b2 = last ? nB : cB + (size_t)(t + 2) * kstep;
;             const char* a3 = last ? nA + PG8_AK(1) : cA + PG8_AK(t + 3); const char* b3 = b2 + kstep;
;             if (last && has_next) S.a_ready(nxt);
;             if constexpr (SP2) {
;             PG8_LDB(B0, 0, 0); PG8_LDB(B1, 0, 1); PG8_SCHED; PG8_LDA(At, 0, 0); PG8_STAGE(PG8_SA(1, 1), a1 + hstepA, voffA);
;             PG8_WAIT_V(8); PG8_WAIT_L(0); PG8_BAR; PG8_MMA(0, 0, At, B0); PG8_MMA(0, 1, At, B1); PG8_BAR; PG8_SCHED;
;             PG8_LDA(At, 0, 1); PG8_STAGE(PG8_SB(0, 0), b2, voffB); PG8_STAGE(PG8_SB(0, 1), b2 + hstepB, voffB); PG8_STAGE(PG8_SA(0, 0), a2, voffA);
;             PG8_WAIT_V(8); PG8_WAIT_L(0); PG8_BAR; PG8_MMA(1, 0, At, B0); PG8_MMA(1, 1, At, B1); PG8_BAR; PG8_SCHED;
.LBB0_1841:
	ds_read_b128 v[132:135], v191
	ds_read_b128 v[136:139], v191 offset:1024
	ds_read_b128 v[140:143], v191 offset:2048
	ds_read_b128 v[162:165], v191 offset:3072
	ds_read_b128 v[166:169], v192
	ds_read_b128 v[194:197], v192 offset:1024
	ds_read_b128 v[198:201], v192 offset:2048
	ds_read_b128 v[202:205], v192 offset:3072
	s_add_u32 s40, s36, s38
	s_addc_u32 s41, s37, s39
	s_add_u32 s42, s40, 0x100
	s_addc_u32 s43, s41, 0
	s_add_u32 s70, s69, s38
	s_addc_u32 s71, s78, s39
	s_add_u32 s40, s40, 0x180
	s_addc_u32 s41, s41, 0
	s_cmpk_eq_i32 s38, 0x700
	s_cselect_b32 s45, s3, s43
	s_cselect_b32 s44, s27, s42
	s_cselect_b32 s43, s25, s71
	s_cselect_b32 s42, s35, s70
	s_cselect_b32 s41, s68, s41
	s_cselect_b32 s40, s67, s40
	v_lshl_add_u64 v[170:171], v[130:131], 0, s[38:39]
	s_add_i32 m0, s52, 0xc000
	ds_read_b128 v[206:209], v174
	ds_read_b128 v[210:213], v174 offset:1024
	ds_read_b128 v[214:217], v174 offset:2048
	ds_read_b128 v[218:221], v174 offset:3072
	ds_read_b128 v[222:225], v174 offset:4096
	ds_read_b128 v[226:229], v174 offset:5120
	ds_read_b128 v[230:233], v174 offset:6144
	ds_read_b128 v[234:237], v174 offset:7168
	global_load_lds_dwordx4 v[170:171], off
	v_lshl_add_u64 v[170:171], v[128:129], 0, s[38:39]
	s_add_i32 m0, s52, 0xe000
	s_nop 0
	global_load_lds_dwordx4 v[170:171], off
	s_waitcnt vmcnt(8)
	s_waitcnt lgkmcnt(0)
	s_barrier
	s_waitcnt lgkmcnt(0)
	v_mfma_f32_16x16x32_bf16 v[124:127], v[132:135], v[206:209], v[124:127]
	v_mfma_f32_16x16x32_bf16 v[120:123], v[140:143], v[206:209], v[120:123]
	v_mfma_f32_16x16x32_bf16 v[116:119], v[132:135], v[214:217], v[116:119]
	v_mfma_f32_16x16x32_bf16 v[112:115], v[140:143], v[214:217], v[112:115]
	v_mfma_f32_16x16x32_bf16 v[108:111], v[132:135], v[222:225], v[108:111]
	v_mfma_f32_16x16x32_bf16 v[104:107], v[140:143], v[222:225], v[104:107]
	v_mfma_f32_16x16x32_bf16 v[100:103], v[132:135], v[230:233], v[100:103]
	v_mfma_f32_16x16x32_bf16 v[96:99], v[140:143], v[230:233], v[96:99]
	v_mfma_f32_16x16x32_bf16 v[124:127], v[136:139], v[210:213], v[124:127]
	v_mfma_f32_16x16x32_bf16 v[120:123], v[162:165], v[210:213], v[120:123]
	v_mfma_f32_16x16x32_bf16 v[116:119], v[136:139], v[218:221], v[116:119]
	v_mfma_f32_16x16x32_bf16 v[112:115], v[162:165], v[218:221], v[112:115]
	v_mfma_f32_16x16x32_bf16 v[108:111], v[136:139], v[226:229], v[108:111]
	v_mfma_f32_16x16x32_bf16 v[104:107], v[162:165], v[226:229], v[104:107]
	v_mfma_f32_16x16x32_bf16 v[100:103], v[136:139], v[234:237], v[100:103]
	v_mfma_f32_16x16x32_bf16 v[96:99], v[162:165], v[234:237], v[96:99]
	v_mfma_f32_16x16x32_bf16 v[60:63], v[166:169], v[206:209], v[60:63]
	v_mfma_f32_16x16x32_bf16 v[56:59], v[198:201], v[206:209], v[56:59]
	v_mfma_f32_16x16x32_bf16 v[52:55], v[166:169], v[214:217], v[52:55]
	v_mfma_f32_16x16x32_bf16 v[48:51], v[198:201], v[214:217], v[48:51]
	v_mfma_f32_16x16x32_bf16 v[44:47], v[166:169], v[222:225], v[44:47]
	v_mfma_f32_16x16x32_bf16 v[40:43], v[198:201], v[222:225], v[40:43]
	v_mfma_f32_16x16x32_bf16 v[36:39], v[166:169], v[230:233], v[36:39]
	v_mfma_f32_16x16x32_bf16 v[32:35], v[198:201], v[230:233], v[32:35]
	v_mfma_f32_16x16x32_bf16 v[60:63], v[194:197], v[210:213], v[60:63]
	v_mfma_f32_16x16x32_bf16 v[56:59], v[202:205], v[210:213], v[56:59]
	v_mfma_f32_16x16x32_bf16 v[52:55], v[194:197], v[218:221], v[52:55]
	v_mfma_f32_16x16x32_bf16 v[48:51], v[202:205], v[218:221], v[48:51]
	v_mfma_f32_16x16x32_bf16 v[44:47], v[194:197], v[226:229], v[44:47]
	v_mfma_f32_16x16x32_bf16 v[40:43], v[202:205], v[226:229], v[40:43]
	v_mfma_f32_16x16x32_bf16 v[36:39], v[194:197], v[234:237], v[36:39]
	v_mfma_f32_16x16x32_bf16 v[32:35], v[202:205], v[234:237], v[32:35]
	s_barrier
	s_add_i32 s70, s64, s51
	v_lshl_add_u64 v[170:171], s[42:43], 0, v[146:147]
	s_mov_b32 m0, s70
	ds_read_b128 v[206:209], v174 offset:16384
	ds_read_b128 v[210:213], v174 offset:17408
	ds_read_b128 v[214:217], v174 offset:18432
	ds_read_b128 v[218:221], v174 offset:19456
	ds_read_b128 v[222:225], v174 offset:20480
	ds_read_b128 v[226:229], v174 offset:21504
	ds_read_b128 v[230:233], v174 offset:22528
	ds_read_b128 v[234:237], v174 offset:23552
	global_load_lds_dwordx4 v[170:171], off
	s_add_i32 m0, s70, 0x2000
	s_add_u32 s70, s42, 0x40000
	v_lshl_add_u64 v[238:239], s[42:43], 0, v[150:151]
	s_addc_u32 s71, s43, 0
	s_add_i32 s80, s65, s51
	global_load_lds_dwordx4 v[238:239], off
	v_lshl_add_u64 v[240:241], s[70:71], 0, v[146:147]
	s_mov_b32 m0, s80
	s_nop 0
	global_load_lds_dwordx4 v[240:241], off
	v_lshl_add_u64 v[240:241], s[70:71], 0, v[150:151]
	s_add_i32 m0, s80, 0x2000
	s_nop 0
	global_load_lds_dwordx4 v[240:241], off
	v_lshl_add_u64 v[240:241], s[44:45], 0, v[144:145]
	s_mov_b32 m0, s52
	s_nop 0
	global_load_lds_dwordx4 v[240:241], off
	v_lshl_add_u64 v[240:241], s[44:45], 0, v[148:149]
	s_mov_b32 m0, s53
	s_nop 0
	global_load_lds_dwordx4 v[240:241], off
	s_waitcnt vmcnt(8)
	s_waitcnt lgkmcnt(0)
	s_barrier
; #define PG8_STAGE(bufoff, gbase, voff) do { _Pragma("unroll") for (int _i = 0; _i < 2; ++_i) \
;         __builtin_amdgcn_global_load_lds((const unsigned*)((const char*)(gbase) + (voff)[_i]), (PG8_LAS unsigned*)(lds + (bufoff) + ldsw + _i * 8192), 16, 0, 0); } while (0)
; #define PG8_LDA(dst, b, h) do { _Pragma("unroll") for (int m = 0; m < 4; ++m) _Pragma("unroll") for (int k = 0; k < 2; ++k) dst[m][k] = *(const PG8_LAS bf16x8*)(lds + PG8_SA(b, h) + aoff + m * 2048 + k * 1024); } while (0)
; #define PG8_LDB(dst, b, h) do { _Pragma("unroll") for (int n = 0; n < 2; ++n) _Pragma("unroll") for (int k = 0; k < 2; ++k) dst[n][k] = *(const PG8_LAS bf16x8*)(lds + PG8_SB(b, h) + boff + n * 2048 + k * 1024); } while (0)
; #define PG8_MMA(ai, bj, At, Bt) do { __builtin_amdgcn_s_setprio(1); _Pragma("unroll") for (int m = 0; m < 4; ++m) _Pragma("unroll") for (int n = 0; n < 2; ++n) _Pragma("unroll") for (int k = 0; k < 2; ++k) \
;         acc[ai][bj][m][n] = __builtin_amdgcn_mfma_f32_16x16x32_bf16(Bt[n][k], At[m][k], acc[ai][bj][m][n], 0, 0, 0); __builtin_amdgcn_s_setprio(0); } while (0)
; #define PG8_WAIT_V(n) asm volatile("s_waitcnt vmcnt(" #n ")" ::: "memory")
; #define PG8_WAIT_L(n) asm volatile("s_waitcnt lgkmcnt(" #n ")" ::: "memory")
; #define PG8_BAR __builtin_amdgcn_s_barrier()
; #define PG8_SCHED __builtin_amdgcn_sched_barrier(0)
; template <class Epi, class Sched, bool ALIGN_EPI = false, bool SP2 = false>
; __device__ __forceinline__ void gemm_phase(PG8_LAS unsigned char* lds, const Gemm g, const Sched& S, const Epi& E) {
;     ...
;             PG8_WAIT_V(8); PG8_WAIT_L(0); PG8_BAR; PG8_MMA(1, 0, At, B0); PG8_MMA(1, 1, At, B1); PG8_BAR; PG8_SCHED;
;             PG8_LDB(B0, 1, 0); PG8_LDB(B1, 1, 1); PG8_SCHED; PG8_LDA(At, 1, 0); PG8_STAGE(PG8_SA(0, 1), a2 + hstepA, voffA);
;             PG8_WAIT_V(8); PG8_WAIT_L(0); PG8_BAR; PG8_MMA(0, 0, At, B0); PG8_MMA(0, 1, At, B1); PG8_BAR; PG8_SCHED;
	s_waitcnt lgkmcnt(0)
	v_mfma_f32_16x16x32_bf16 v[92:95], v[132:135], v[206:209], v[92:95]
	v_mfma_f32_16x16x32_bf16 v[88:91], v[140:143], v[206:209], v[88:91]
	v_mfma_f32_16x16x32_bf16 v[84:87], v[132:135], v[214:217], v[84:87]
	v_mfma_f32_16x16x32_bf16 v[80:83], v[140:143], v[214:217], v[80:83]
	v_mfma_f32_16x16x32_bf16 v[76:79], v[132:135], v[222:225], v[76:79]
	v_mfma_f32_16x16x32_bf16 v[72:75], v[140:143], v[222:225], v[72:75]
	v_mfma_f32_16x16x32_bf16 v[68:71], v[132:135], v[230:233], v[68:71]
	v_mfma_f32_16x16x32_bf16 v[64:67], v[140:143], v[230:233], v[64:67]
	v_mfma_f32_16x16x32_bf16 v[92:95], v[136:139], v[210:213], v[92:95]
	v_mfma_f32_16x16x32_bf16 v[88:91], v[162:165], v[210:213], v[88:91]
	v_mfma_f32_16x16x32_bf16 v[84:87], v[136:139], v[218:221], v[84:87]
	v_mfma_f32_16x16x32_bf16 v[80:83], v[162:165], v[218:221], v[80:83]
	v_mfma_f32_16x16x32_bf16 v[76:79], v[136:139], v[226:229], v[76:79]
	v_mfma_f32_16x16x32_bf16 v[72:75], v[162:165], v[226:229], v[72:75]
	v_mfma_f32_16x16x32_bf16 v[68:71], v[136:139], v[234:237], v[68:71]
	v_mfma_f32_16x16x32_bf16 v[64:67], v[162:165], v[234:237], v[64:67]
	v_mfma_f32_16x16x32_bf16 v[28:31], v[166:169], v[206:209], v[28:31]
	v_mfma_f32_16x16x32_bf16 v[24:27], v[198:201], v[206:209], v[24:27]
	v_mfma_f32_16x16x32_bf16 v[20:23], v[166:169], v[214:217], v[20:23]
	v_mfma_f32_16x16x32_bf16 v[16:19], v[198:201], v[214:217], v[16:19]
	v_mfma_f32_16x16x32_bf16 v[12:15], v[166:169], v[222:225], v[12:15]
	v_mfma_f32_16x16x32_bf16 v[8:11], v[198:201], v[222:225], v[8:11]
	v_mfma_f32_16x16x32_bf16 v[4:7], v[166:169], v[230:233], v[4:7]
	v_mfma_f32_16x16x32_bf16 v[0:3], v[198:201], v[230:233], v[0:3]
	v_mfma_f32_16x16x32_bf16 v[28:31], v[194:197], v[210:213], v[28:31]
	v_mfma_f32_16x16x32_bf16 v[24:27], v[202:205], v[210:213], v[24:27]
	v_mfma_f32_16x16x32_bf16 v[20:23], v[194:197], v[218:221], v[20:23]
	v_mfma_f32_16x16x32_bf16 v[16:19], v[202:205], v[218:221], v[16:19]
	v_mfma_f32_16x16x32_bf16 v[12:15], v[194:197], v[226:229], v[12:15]
	v_mfma_f32_16x16x32_bf16 v[8:11], v[202:205], v[226:229], v[8:11]
	v_mfma_f32_16x16x32_bf16 v[4:7], v[194:197], v[234:237], v[4:7]
	v_mfma_f32_16x16x32_bf16 v[0:3], v[202:205], v[234:237], v[0:3]
	s_barrier
	s_add_i32 s70, 0, 0x18000
	v_add_u32_e32 v153, s70, v173
	s_add_i32 s71, 0, 0x1c000
	ds_read_b128 v[132:135], v153
	ds_read_b128 v[136:139], v153 offset:1024
	ds_read_b128 v[140:143], v153 offset:2048
	ds_read_b128 v[162:165], v153 offset:3072
	v_add_u32_e32 v153, s71, v173
	ds_read_b128 v[166:169], v153
	ds_read_b128 v[194:197], v153 offset:1024
	ds_read_b128 v[198:201], v153 offset:2048
	ds_read_b128 v[202:205], v153 offset:3072
	s_add_u32 s44, s44, 0x40000
	s_addc_u32 s45, s45, 0
	s_mov_b32 m0, s54
	v_lshl_add_u64 v[240:241], s[44:45], 0, v[144:145]
	ds_read_b128 v[206:209], v174 offset:32768
	ds_read_b128 v[210:213], v174 offset:33792
	ds_read_b128 v[214:217], v174 offset:34816
	ds_read_b128 v[218:221], v174 offset:35840
	ds_read_b128 v[222:225], v174 offset:36864
	ds_read_b128 v[226:229], v174 offset:37888
	ds_read_b128 v[230:233], v174 offset:38912
	ds_read_b128 v[234:237], v174 offset:39936
	global_load_lds_dwordx4 v[240:241], off
	v_lshl_add_u64 v[240:241], s[44:45], 0, v[148:149]
	s_mov_b32 m0, s55
	s_nop 0
	global_load_lds_dwordx4 v[240:241], off
	s_waitcnt vmcnt(8)
	s_waitcnt lgkmcnt(0)
	s_barrier
	s_waitcnt lgkmcnt(0)
	v_mfma_f32_16x16x32_bf16 v[124:127], v[132:135], v[206:209], v[124:127]
	v_mfma_f32_16x16x32_bf16 v[120:123], v[140:143], v[206:209], v[120:123]
	v_mfma_f32_16x16x32_bf16 v[116:119], v[132:135], v[214:217], v[116:119]
	v_mfma_f32_16x16x32_bf16 v[112:115], v[140:143], v[214:217], v[112:115]
	v_mfma_f32_16x16x32_bf16 v[108:111], v[132:135], v[222:225], v[108:111]
	v_mfma_f32_16x16x32_bf16 v[104:107], v[140:143], v[222:225], v[104:107]
	v_mfma_f32_16x16x32_bf16 v[100:103], v[132:135], v[230:233], v[100:103]
	v_mfma_f32_16x16x32_bf16 v[96:99], v[140:143], v[230:233], v[96:99]
	v_mfma_f32_16x16x32_bf16 v[124:127], v[136:139], v[210:213], v[124:127]
	v_mfma_f32_16x16x32_bf16 v[120:123], v[162:165], v[210:213], v[120:123]
	v_mfma_f32_16x16x32_bf16 v[116:119], v[136:139], v[218:221], v[116:119]
	v_mfma_f32_16x16x32_bf16 v[112:115], v[162:165], v[218:221], v[112:115]
	v_mfma_f32_16x16x32_bf16 v[108:111], v[136:139], v[226:229], v[108:111]
	v_mfma_f32_16x16x32_bf16 v[104:107], v[162:165], v[226:229], v[104:107]
	v_mfma_f32_16x16x32_bf16 v[100:103], v[136:139], v[234:237], v[100:103]
	v_mfma_f32_16x16x32_bf16 v[96:99], v[162:165], v[234:237], v[96:99]
	v_mfma_f32_16x16x32_bf16 v[60:63], v[166:169], v[206:209], v[60:63]
	v_mfma_f32_16x16x32_bf16 v[56:59], v[198:201], v[206:209], v[56:59]
	v_mfma_f32_16x16x32_bf16 v[52:55], v[166:169], v[214:217], v[52:55]
	v_mfma_f32_16x16x32_bf16 v[48:51], v[198:201], v[214:217], v[48:51]
	v_mfma_f32_16x16x32_bf16 v[44:47], v[166:169], v[222:225], v[44:47]
	v_mfma_f32_16x16x32_bf16 v[40:43], v[198:201], v[222:225], v[40:43]
	v_mfma_f32_16x16x32_bf16 v[36:39], v[166:169], v[230:233], v[36:39]
	v_mfma_f32_16x16x32_bf16 v[32:35], v[198:201], v[230:233], v[32:35]
	v_mfma_f32_16x16x32_bf16 v[60:63], v[194:197], v[210:213], v[60:63]
	v_mfma_f32_16x16x32_bf16 v[56:59], v[202:205], v[210:213], v[56:59]
	v_mfma_f32_16x16x32_bf16 v[52:55], v[194:197], v[218:221], v[52:55]
	v_mfma_f32_16x16x32_bf16 v[48:51], v[202:205], v[218:221], v[48:51]
	v_mfma_f32_16x16x32_bf16 v[44:47], v[194:197], v[226:229], v[44:47]
	v_mfma_f32_16x16x32_bf16 v[40:43], v[202:205], v[226:229], v[40:43]
	v_mfma_f32_16x16x32_bf16 v[36:39], v[194:197], v[234:237], v[36:39]
	v_mfma_f32_16x16x32_bf16 v[32:35], v[202:205], v[234:237], v[32:35]
	s_barrier
; #define PG8_STAGE(bufoff, gbase, voff) do { _Pragma("unroll") for (int _i = 0; _i < 2; ++_i) \
;         __builtin_amdgcn_global_load_lds((const unsigned*)((const char*)(gbase) + (voff)[_i]), (PG8_LAS unsigned*)(lds + (bufoff) + ldsw + _i * 8192), 16, 0, 0); } while (0)
; #define PG8_LDA(dst, b, h) do { _Pragma("unroll") for (int m = 0; m < 4; ++m) _Pragma("unroll") for (int k = 0; k < 2; ++k) dst[m][k] = *(const PG8_LAS bf16x8*)(lds + PG8_SA(b, h) + aoff + m * 2048 + k * 1024); } while (0)
; #define PG8_MMA(ai, bj, At, Bt) do { __builtin_amdgcn_s_setprio(1); _Pragma("unroll") for (int m = 0; m < 4; ++m) _Pragma("unroll") for (int n = 0; n < 2; ++n) _Pragma("unroll") for (int k = 0; k < 2; ++k) \
;         acc[ai][bj][m][n] = __builtin_amdgcn_mfma_f32_16x16x32_bf16(Bt[n][k], At[m][k], acc[ai][bj][m][n], 0, 0, 0); __builtin_amdgcn_s_setprio(0); } while (0)
; #define PG8_WAIT_V(n) asm volatile("s_waitcnt vmcnt(" #n ")" ::: "memory")
; #define PG8_WAIT_L(n) asm volatile("s_waitcnt lgkmcnt(" #n ")" ::: "memory")
; #define PG8_BAR __builtin_amdgcn_s_barrier()
; #define PG8_SCHED __builtin_amdgcn_sched_barrier(0)
; template <class Epi, class Sched, bool ALIGN_EPI = false, bool SP2 = false>
; __device__ __forceinline__ void gemm_phase(PG8_LAS unsigned char* lds, const Gemm g, const Sched& S, const Epi& E) {
;     ...
;             PG8_LDA(At, 1, 1); PG8_STAGE(PG8_SB(1, 0), b3, voffB); PG8_STAGE(PG8_SB(1, 1), b3 + hstepB, voffB); PG8_STAGE(PG8_SA(1, 0), a3, voffA);
;             PG8_WAIT_V(8); PG8_WAIT_L(0); PG8_BAR; PG8_MMA(1, 0, At, B0); PG8_MMA(1, 1, At, B1); PG8_BAR; PG8_SCHED;
	s_add_i32 s44, s70, s51
	v_lshl_add_u64 v[170:171], v[170:171], 0, s[18:19]
	s_mov_b32 m0, s44
	ds_read_b128 v[206:209], v174 offset:49152
	ds_read_b128 v[210:213], v174 offset:50176
	ds_read_b128 v[214:217], v174 offset:51200
	ds_read_b128 v[218:221], v174 offset:52224
	ds_read_b128 v[222:225], v174 offset:53248
	ds_read_b128 v[226:229], v174 offset:54272
	ds_read_b128 v[230:233], v174 offset:55296
	ds_read_b128 v[234:237], v174 offset:56320
	global_load_lds_dwordx4 v[170:171], off
	s_add_i32 m0, s44, 0x2000
	s_add_u32 s42, s42, 0x40080
	v_lshl_add_u64 v[170:171], v[238:239], 0, s[18:19]
	s_addc_u32 s43, s43, 0
	s_add_i32 s44, s71, s51
	global_load_lds_dwordx4 v[170:171], off
	v_lshl_add_u64 v[170:171], s[42:43], 0, v[146:147]
	s_mov_b32 m0, s44
	s_nop 0
	global_load_lds_dwordx4 v[170:171], off
	v_lshl_add_u64 v[170:171], s[42:43], 0, v[150:151]
	s_add_i32 m0, s44, 0x2000
	s_nop 0
	global_load_lds_dwordx4 v[170:171], off
	v_lshl_add_u64 v[170:171], s[40:41], 0, v[144:145]
	s_mov_b32 m0, s60
	s_nop 0
	global_load_lds_dwordx4 v[170:171], off
	v_lshl_add_u64 v[170:171], s[40:41], 0, v[148:149]
	s_mov_b32 m0, s61
	s_nop 0
	global_load_lds_dwordx4 v[170:171], off
	s_waitcnt vmcnt(8)
	s_waitcnt lgkmcnt(0)
	s_barrier
	s_waitcnt lgkmcnt(0)
	v_mfma_f32_16x16x32_bf16 v[92:95], v[132:135], v[206:209], v[92:95]
	v_mfma_f32_16x16x32_bf16 v[88:91], v[140:143], v[206:209], v[88:91]
	v_mfma_f32_16x16x32_bf16 v[84:87], v[132:135], v[214:217], v[84:87]
	v_mfma_f32_16x16x32_bf16 v[80:83], v[140:143], v[214:217], v[80:83]
	v_mfma_f32_16x16x32_bf16 v[76:79], v[132:135], v[222:225], v[76:79]
	v_mfma_f32_16x16x32_bf16 v[72:75], v[140:143], v[222:225], v[72:75]
	v_mfma_f32_16x16x32_bf16 v[68:71], v[132:135], v[230:233], v[68:71]
	v_mfma_f32_16x16x32_bf16 v[64:67], v[140:143], v[230:233], v[64:67]
	v_mfma_f32_16x16x32_bf16 v[92:95], v[136:139], v[210:213], v[92:95]
	v_mfma_f32_16x16x32_bf16 v[88:91], v[162:165], v[210:213], v[88:91]
	v_mfma_f32_16x16x32_bf16 v[84:87], v[136:139], v[218:221], v[84:87]
	v_mfma_f32_16x16x32_bf16 v[80:83], v[162:165], v[218:221], v[80:83]
	v_mfma_f32_16x16x32_bf16 v[76:79], v[136:139], v[226:229], v[76:79]
	v_mfma_f32_16x16x32_bf16 v[72:75], v[162:165], v[226:229], v[72:75]
	v_mfma_f32_16x16x32_bf16 v[68:71], v[136:139], v[234:237], v[68:71]
	v_mfma_f32_16x16x32_bf16 v[64:67], v[162:165], v[234:237], v[64:67]
	v_mfma_f32_16x16x32_bf16 v[28:31], v[166:169], v[206:209], v[28:31]
	v_mfma_f32_16x16x32_bf16 v[24:27], v[198:201], v[206:209], v[24:27]
	v_mfma_f32_16x16x32_bf16 v[20:23], v[166:169], v[214:217], v[20:23]
	v_mfma_f32_16x16x32_bf16 v[16:19], v[198:201], v[214:217], v[16:19]
	v_mfma_f32_16x16x32_bf16 v[12:15], v[166:169], v[222:225], v[12:15]
	v_mfma_f32_16x16x32_bf16 v[8:11], v[198:201], v[222:225], v[8:11]
	v_mfma_f32_16x16x32_bf16 v[4:7], v[166:169], v[230:233], v[4:7]
	v_mfma_f32_16x16x32_bf16 v[0:3], v[198:201], v[230:233], v[0:3]
	v_mfma_f32_16x16x32_bf16 v[28:31], v[194:197], v[210:213], v[28:31]
	v_mfma_f32_16x16x32_bf16 v[24:27], v[202:205], v[210:213], v[24:27]
	v_mfma_f32_16x16x32_bf16 v[20:23], v[194:197], v[218:221], v[20:23]
	v_mfma_f32_16x16x32_bf16 v[16:19], v[202:205], v[218:221], v[16:19]
	v_mfma_f32_16x16x32_bf16 v[12:15], v[194:197], v[226:229], v[12:15]
	v_mfma_f32_16x16x32_bf16 v[8:11], v[202:205], v[226:229], v[8:11]
	v_mfma_f32_16x16x32_bf16 v[4:7], v[194:197], v[234:237], v[4:7]
	v_mfma_f32_16x16x32_bf16 v[0:3], v[202:205], v[234:237], v[0:3]
	s_barrier
	s_add_i32 s79, s79, 2
	s_add_u32 s38, s38, 0x100
	s_addc_u32 s39, s39, 0
	s_cmp_gt_u32 s79, 13
	s_cbranch_scc0 .LBB0_1841
	s_and_b64 vcc, exec, s[20:21]
	s_cbranch_vccz .LBB0_1844
	s_barrier

; #define GEMM_PHASE(EPI, Aptr, LDA, Bptr, LDB, NN, KK, Eobj) GEMM_PHASE_H(EPI, Aptr, LDA, 0, Bptr, LDB, NN, KK, Eobj)
;     __host__ __device__ bool next(int i, Unit& u) const {
;         const long L = (long)i * G + c; if (L >= nwg) return false;
;         int wgid = (int)L; { const int q = nwg / NXCD, r = nwg % NXCD, xcd = wgid % NXCD, off = wgid / NXCD; wgid = (xcd < r ? xcd * (q + 1) : r * (q + 1) + (xcd - r) * q) + off; }
;         const int nig = WGM * nN, gid = wgid / nig, fm = gid * WGM, gsz = (nM - fm) < WGM ? (nM - fm) : WGM;
;         u.pm = fm + ((wgid % nig) % gsz); u.pn = (wgid % nig) / gsz; return true;
; template <int L> __device__ __forceinline__ void layer_fwd(unsigned char* lds, const XcdBarrier& bar) {
;     ...
;           using ER_ = EpiRes<true, false>; ER_ E{nullptr, (const bf16_t*)(ws + WS_XBX), LOA, (bf16_t*)(ws + WS_XBY), LOW, (f32x2*)(ws + WS_ST2), (const f32x2*)(ws + WS_ST1), kp->lnm_g + L * D, kp->lnm_b + L * D}; GEMM_PHASE(ER_, ws + WS_H, DFF, ws + WS_W2, DFF, D, DFF, E); }
.Lprio_ffn2_2:
	s_mov_b32 s31, s2
	s_mov_b32 s35, s74
	s_mov_b64 s[8:9], s[0:1]
	s_waitcnt lgkmcnt(0)
	s_barrier
	v_mov_b32_e32 v8, v254
	s_cmpk_lt_i32 s31, 0x200
	s_cselect_b64 s[10:11], -1, 0
	s_cmpk_gt_i32 s31, 0x1ff
	v_readfirstlane_b32 s3, v8
	s_cbranch_scc1 .LBB0_2012
	s_ashr_i32 s4, s31, 31
	s_lshr_b32 s4, s4, 29
	s_add_i32 s12, s31, s4
	s_and_b32 s4, s12, -8
	s_sub_i32 s6, s31, s4
	s_cmp_gt_i32 s6, -1
	s_cbranch_scc0 .LBB0_2009
	s_lshl_b32 s7, s6, 6
	s_ashr_i32 s4, s12, 3
	s_cbranch_execz .LBB0_2010
	s_branch .LBB0_2011

; #define GEMM_PHASE(EPI, Aptr, LDA, Bptr, LDB, NN, KK, Eobj) GEMM_PHASE_H(EPI, Aptr, LDA, 0, Bptr, LDB, NN, KK, Eobj)
; #define KPTR() KP kp = (KP)__builtin_amdgcn_kernarg_segment_ptr(); int G = gridDim.x, blk = blockIdx.x; asm volatile("" : "+s"(kp), "+s"(G), "+s"(blk)); unsigned char* ws = kp->ws; (void)ws
;     __host__ __device__ bool next(int i, Unit& u) const {
;         const long L = (long)i * G + c; if (L >= nwg) return false;
;         int wgid = (int)L; { const int q = nwg / NXCD, r = nwg % NXCD, xcd = wgid % NXCD, off = wgid / NXCD; wgid = (xcd < r ? xcd * (q + 1) : r * (q + 1) + (xcd - r) * q) + off; }
;         const int nig = WGM * nN, gid = wgid / nig, fm = gid * WGM, gsz = (nM - fm) < WGM ? (nM - fm) : WGM;
;         u.pm = fm + ((wgid % nig) % gsz); u.pn = (wgid % nig) / gsz; return true;
; template <int L> __device__ __forceinline__ void layer_fwd(unsigned char* lds, const XcdBarrier& bar) {
;     ...
;         { KPTR(); float* vec = (float*)(ws + WS_VEC); bf16_t* LOA = (bf16_t*)kp->out; const bf16_t* LOR = (L == DEPTH - 1) ? (const bf16_t*)(ws + WS_SB) : LOA;
;           EpiPle<L == DEPTH - 1> E{kp->out, (const bf16_t*)(ws + WS_XBY), LOR, (bf16_t*)(ws + WS_XBX), LOA, (const f32x2*)(ws + WS_ST2), kp->lnf_g + L * D, kp->lnf_b + L * D, vec + 11264, vec + 12288, (const bf16_t*)(ws + WS_PP)}; GEMM_PHASE(EpiPle<L == DEPTH - 1>, ws + WS_XBY, D, ws + WS_WG, D, D, D, E); }
.Lprio_gate2:
	s_mov_b64 s[12:13], s[0:1]
	s_mov_b32 s27, s2
	s_mov_b32 s50, s74
	v_mov_b32_e32 v9, v254
	s_waitcnt lgkmcnt(0)
	s_barrier
	s_cmpk_gt_i32 s27, 0x1ff
	v_readfirstlane_b32 s3, v9
	s_cbranch_scc1 .LBB0_2128
	s_ashr_i32 s51, s27, 31
	s_lshr_b32 s4, s51, 29
	s_add_i32 s14, s27, s4
	s_and_b32 s4, s14, -8
	s_sub_i32 s7, s27, s4
	s_cmp_gt_i32 s7, -1
	s_cbranch_scc0 .LBB0_2107
	s_lshl_b32 s6, s7, 6
	s_load_dwordx4 s[8:11], s[12:13], 0x88
	s_ashr_i32 s4, s14, 3
	s_cbranch_execz .LBB0_2108
	s_branch .LBB0_2109

; __device__ __forceinline__ void wconv_phase(KP Pk, int L, unsigned char* lds, int G, int blk) {
;     ...
;     int tid_l = threadIdx.x; asm volatile("" : "+v"(tid_l)); const int tid = tid_l, lane = tid & 63, wid = __builtin_amdgcn_readfirstlane(tid >> 6), j = L >> 1; const bool att = (L & 1) == 0;
;     float* scr = (float*)(lds + wid * 16384);
;     unsigned char* ws = P.ws;
;     bf16_t *WIN = (bf16_t*)(ws + WS_WIN), *WOUT = (bf16_t*)(ws + WS_WOUT), *W1 = (bf16_t*)(ws + WS_W1), *W2 = (bf16_t*)(ws + WS_W2), *WG = (bf16_t*)(ws + WS_WG), *WP = (bf16_t*)(ws + WS_WP);
;     float* vecp = (float*)(ws + WS_VECP);
;     const int nin = att ? NQKV / 32 : HIN / 32;
;     const int I0 = nin * 16, I1 = I0 + 32 * 16, I2 = I1 + 176 * 16, I3 = I2 + 32 * 44, I4 = I3 + 32 * 16, I5 = I4 + 32 * 4;
;     for (int it = wid * G + blk; it < I5; it += 8 * G) {
.LBB0_2180:
	s_or_b64 exec, exec, s[4:5]
	s_setprio 0
	s_mov_b32 s6, s74
	s_mov_b64 s[10:11], s[0:1]
	s_mov_b32 s8, s2
	s_waitcnt lgkmcnt(0)
	v_mov_b32_e32 v0, v254
	s_barrier
	s_load_dwordx2 s[12:13], s[10:11], 0x90
	v_readfirstlane_b32 s3, v0
	s_ashr_i32 s3, s3, 6
	s_mul_i32 s4, s3, s6
	s_add_i32 s7, s4, s8
	s_cmpk_gt_i32 s7, 0x1eff
	s_cbranch_scc1 .LBB0_2219
	s_waitcnt lgkmcnt(0)
	s_add_u32 s9, s12, 0x1fd00000
	v_lshlrev_b32_e32 v3, 3, v0
	s_addc_u32 s24, s13, 0
	s_lshl_b32 s3, s3, 14
	v_and_b32_e32 v4, 56, v3
	v_bfe_u32 v3, v0, 3, 3
	s_add_i32 s4, s3, 0
	v_mul_u32_u24_e32 v5, 0x84, v4
	v_lshlrev_b32_e32 v6, 2, v3
	v_add3_u32 v86, s4, v5, v6
	v_lshlrev_b32_e32 v4, 1, v4
	v_mov_b32_e32 v5, 0
	v_bfe_u32 v2, v0, 5, 1
	v_lshl_add_u64 v[6:7], s[12:13], 0, v[4:5]
	s_mov_b64 s[4:5], 0x1f00000
	v_and_b32_e32 v4, 1, v0
	v_and_b32_e32 v12, 63, v0
	v_and_b32_e32 v1, 31, v0
	v_lshl_add_u64 v[8:9], v[6:7], 0, s[4:5]
	s_mov_b64 s[4:5], 0x1d00000
	s_mov_b64 s[16:17], 0x1700000
	v_cmp_eq_u32_e32 vcc, 1, v4
	v_mul_u32_u24_e32 v4, 0x84, v2
	v_lshl_add_u64 v[10:11], v[6:7], 0, s[4:5]
	v_cmp_gt_u32_e64 s[4:5], 32, v12
	v_lshl_add_u64 v[12:13], v[6:7], 0, s[16:17]
	v_mov_b32_e32 v14, 0xb00
	s_mov_b64 s[16:17], 0xc00000
	v_or_b32_e32 v4, s3, v4
	v_lshlrev_b32_e32 v18, 2, v1
	v_cndmask_b32_e32 v90, 0, v14, vcc
	v_lshl_add_u64 v[14:15], v[6:7], 0, s[16:17]
	s_mov_b64 s[16:17], 0xa00000
	v_add3_u32 v91, v4, v18, 0
	s_lshl_b32 s3, s7, 3
	s_add_i32 s34, s7, 0xfffff400
	v_mbcnt_lo_u32_b32 v4, -1, 0
	s_mov_b32 s15, 0
	v_or_b32_e32 v87, 8, v3
	v_or_b32_e32 v88, 16, v3
	v_or_b32_e32 v89, 24, v3
	v_lshl_add_u64 v[16:17], v[6:7], 0, s[16:17]
	s_lshl_b32 s25, s6, 3
	s_add_i32 s26, s3, 0xffff0c00
	s_lshl_b32 s27, s6, 6
	v_or_b32_e32 v92, 14, v2
	s_lshl_b32 s28, s7, 6
	s_lshl_b32 s29, s6, 9
	v_or_b32_e32 v93, 12, v2
	v_or_b32_e32 v94, 10, v2
	v_or_b32_e32 v95, 8, v2
	v_or_b32_e32 v96, 6, v2
	v_or_b32_e32 v97, 4, v2
	v_or_b32_e32 v98, 2, v2
	v_or_b32_e32 v99, 0xffffc700, v1
	s_lshl_b32 s30, s7, 1
	s_lshl_b32 s31, s6, 4
	s_lshl_b32 s35, s34, 1
	v_or_b32_e32 v100, 0xffffec00, v1
	s_mov_b64 s[16:17], 0x10000
	s_movk_i32 s36, 0x5800
	s_mov_b64 s[18:19], 0x4200000
	s_mov_b64 s[20:21], 0x58000
	s_movk_i32 s37, 0x5000
	v_mov_b32_e32 v101, 0xc00000
	v_mbcnt_hi_u32_b32 v102, -1, v4
	v_mov_b64_e32 v[18:19], 0x4200000
	s_mov_b32 s38, s7
	s_branch .LBB0_2183

; #define GEMM_PHASE(EPI, Aptr, LDA, Bptr, LDB, NN, KK, Eobj) GEMM_PHASE_H(EPI, Aptr, LDA, 0, Bptr, LDB, NN, KK, Eobj)
; #define KPTR() KP kp = (KP)__builtin_amdgcn_kernarg_segment_ptr(); int G = gridDim.x, blk = blockIdx.x; asm volatile("" : "+s"(kp), "+s"(G), "+s"(blk)); unsigned char* ws = kp->ws; (void)ws
; __device__ __forceinline__ void vec_finalize(unsigned char* ws, int G, int blk) {
;     const float* vecp = (const float*)(ws + WS_VECP); float* vec = (float*)(ws + WS_VEC);
;     for (int i = blk * 512 + threadIdx.x; i < 13312; i += G * 512) { float a = 0.f;
; #pragma unroll
;         for (int kb = 0; kb < 16; ++kb) a += vecp[(size_t)kb * 13312 + i];
;         vec[i] = a; }
; template <int L> __device__ __forceinline__ void layer_fwd(unsigned char* lds, const XcdBarrier& bar) {
;     ...
;             REP_HIN({ KPTR(); vec_finalize(ws, G, blk); EpiHin E{(bf16_t*)(ws + WS_Z), (const float*)(ws + WS_LB)}; GEMM_PHASE(EpiHin, ws + WS_XBX, D, ws + WS_WIN, D, HIN, D, E); })
.Lprio_hin3:
	s_mov_b32 s42, s74
	s_mov_b64 s[4:5], s[0:1]
	s_mov_b32 s43, s2
	s_waitcnt lgkmcnt(0)
	s_barrier
	s_load_dwordx2 s[10:11], s[4:5], 0x90
	v_lshl_add_u32 v0, s43, 9, v254
	s_movk_i32 s3, 0x3400
	v_cmp_gt_i32_e32 vcc, s3, v0
	s_and_saveexec_b64 s[4:5], vcc
	s_cbranch_execz .LBB0_2280
	s_lshl_b32 s6, s42, 9
	v_ashrrev_i32_e32 v1, 31, v0
	s_waitcnt lgkmcnt(0)
	v_lshl_add_u64 v[2:3], v[0:1], 2, s[10:11]
	s_mov_b64 s[8:9], 0x1fdc3000
	s_ashr_i32 s7, s6, 31
	v_lshl_add_u64 v[2:3], v[2:3], 0, s[8:9]
	s_lshl_b64 s[8:9], s[6:7], 2
	s_mov_b64 s[12:13], 0
	s_movk_i32 s3, 0x33ff

; __device__ __forceinline__ void h1_phase(unsigned char* lds, unsigned char* ws, bf16_t* SF, int G, int blk) {
;     int tid_l = threadIdx.x; asm volatile("" : "+v"(tid_l)); const int tid = tid_l, lane = tid & 63, wid = __builtin_amdgcn_readfirstlane(tid >> 6), r = lane & 15, kq = lane >> 4;
;     const bf16_t* Z = (const bf16_t*)(ws + WS_Z); bf16_t* VT = (bf16_t*)(lds + L_VT);
;     for (int unit = blk; unit < 2048; unit += G) {
;         const int b = unit >> 10, c = (unit >> 3) & 127, h = unit & 7, chain = b * 8 + h;
;         const bf16_t* zrow = Z + ((size_t)h * M + (size_t)b * SEQ + c * 128 + 16 * wid + r) * 128;
.LBB0_2450:
	s_or_b64 exec, exec, s[4:5]
	s_setprio 0
	s_mov_b32 s20, s74
	s_mov_b64 s[4:5], s[0:1]
	s_mov_b32 s21, s2
	s_waitcnt lgkmcnt(0)
	v_mov_b32_e32 v0, v254
	s_barrier
	s_cmpk_gt_i32 s21, 0x7ff
	v_readfirstlane_b32 s3, v0
	s_cbranch_scc1 .LBB0_2497
	s_load_dwordx4 s[8:11], s[4:5], 0x88
	v_and_b32_e32 v1, 15, v0
	v_lshrrev_b32_e32 v0, 1, v0
	v_and_b32_e32 v0, 24, v0
	v_lshlrev_b32_e32 v2, 1, v1
	s_waitcnt lgkmcnt(0)
	s_add_u32 s22, s8, 0x4000000
	s_addc_u32 s23, s9, 0
	s_add_u32 s6, s10, 0x6800000
	s_addc_u32 s7, s11, 0
	s_ashr_i32 s3, s3, 2
	s_and_b32 s3, s3, -16
	s_lshl_b32 s8, s3, 1
	s_add_i32 s8, s8, 0
	s_ashr_i32 s9, s3, 31
	s_add_u32 s24, s10, 0x1fa00000
	s_addc_u32 s25, s11, 0
	v_or_b32_e32 v32, s3, v1
	s_add_u32 s26, s10, 0x1a800000
	v_mul_u32_u24_e32 v1, 0x88, v0
	s_addc_u32 s27, s11, 0
	v_lshlrev_b32_e32 v1, 1, v1
	s_add_i32 s8, s8, 0x13000
	v_mov_b32_e32 v35, 0
	v_add3_u32 v81, v1, s8, v2
	s_mov_b64 s[4:5], 0x4000000
	v_mov_b32_e32 v33, s9
	v_add3_u32 v80, s8, v2, v1
	v_add_u32_e32 v82, 0x220, v81
	v_add_u32_e32 v83, 0x440, v81
	v_add_u32_e32 v84, 0x660, v81
	v_add_u32_e32 v85, 0x2200, v81
	v_add_u32_e32 v86, 0x2420, v81
	v_add_u32_e32 v87, 0x2640, v81
	v_add_u32_e32 v88, 0x2860, v81
	v_add_u32_e32 v89, 0x4400, v81
	v_add_u32_e32 v90, 0x4620, v81
	v_add_u32_e32 v91, 0x4840, v81
	v_add_u32_e32 v92, 0x4a60, v81
	v_add_u32_e32 v93, 0x6600, v81
	v_add_u32_e32 v94, 0x6820, v81
	v_add_u32_e32 v95, 0x6a40, v81
	v_add_u32_e32 v96, 0x6c60, v81
	v_lshlrev_b32_e32 v36, 1, v0
	v_mov_b32_e32 v37, v35
	s_mov_b64 s[8:9], 0xc000000
	s_brev_b32 s28, 48
	s_brev_b32 s29, 32
	s_movk_i32 s30, 0x110
	s_mov_b64 s[10:11], 0x8000000
	s_brev_b32 s31, 16
	s_mov_b64 s[12:13], 0x100000
	s_mov_b32 s34, 0x100000
	s_add_i32 s35, 0, 0x13000
	s_branch .LBB0_2453

; __device__ __forceinline__ void h2_phase(unsigned char* ws, bf16_t* SF, int G, int blk) {
;     int tid_l = threadIdx.x; asm volatile("" : "+v"(tid_l));
;     const size_t gt = (size_t)blk * 512 + tid_l, GT = (size_t)G * 512;
;     for (size_t w = gt; w < (size_t)32 * 4096; w += GT) {
;         const int ch32 = (int)(w >> 12), dir = ch32 >> 4, chain = ch32 & 15, e4 = (int)(w & 4095);
;         bf16_t* base = (dir ? (bf16_t*)(ws + WS_SB) : SF) + (size_t)chain * 128 * 16384 + (size_t)e4 * 4;
;         const float* dbase = (const float*)(ws + WS_DEC) + ((size_t)(dir * 16 + chain) * 128) * 128 + ((e4 * 4) & 127);
;         f32x4 S = {0.f, 0.f, 0.f, 0.f};
.LBB0_2549:
	s_or_b64 exec, exec, s[4:5]
	s_setprio 0
	s_mov_b32 s10, s74
	s_mov_b64 s[6:7], s[0:1]
	s_mov_b32 s4, s2
	s_waitcnt lgkmcnt(0)
	s_barrier
	v_mov_b32_e32 v0, v254
	s_ashr_i32 s5, s4, 31
	s_lshl_b64 s[4:5], s[4:5], 9
	v_ashrrev_i32_e32 v1, 31, v0
	v_lshl_add_u64 v[0:1], s[4:5], 0, v[0:1]
	s_mov_b64 s[4:5], 0x20000
	v_cmp_gt_u64_e32 vcc, s[4:5], v[0:1]
	s_and_saveexec_b64 s[4:5], vcc
	s_cbranch_execz .LBB0_2554
	s_load_dwordx4 s[12:15], s[6:7], 0x88
	s_mov_b64 s[6:7], 0
	s_mov_b64 s[8:9], 0x10000
	v_mov_b32_e32 v3, 0
	s_waitcnt lgkmcnt(0)
	s_add_u32 s3, s12, 0x4000000
	s_addc_u32 s16, s13, 0
	s_ashr_i32 s11, s10, 31
	s_lshl_b64 s[10:11], s[10:11], 9
	s_add_u32 s17, s14, 0x1a800000
	s_addc_u32 s18, s15, 0
	s_add_u32 s12, s14, 0x1fa00000
	s_addc_u32 s13, s15, 0
	v_mov_b32_e32 v26, s18
	v_mov_b32_e32 v27, s16
	v_mov_b32_e32 v28, s17
	v_mov_b32_e32 v29, s3
	s_mov_b64 s[14:15], 0x1ffff

; template <bool STORE> __device__ __forceinline__ void h3_phase(unsigned char* lds, unsigned char* ws, const bf16_t* SF, const float* norm_g, int G, int blk) {
;     int tid_l = threadIdx.x; asm volatile("" : "+v"(tid_l)); const int tid = tid_l, lane = tid & 63, wid = __builtin_amdgcn_readfirstlane(tid >> 6), r = lane & 15, kq = lane >> 4;
;     bf16_t* Z = (bf16_t*)(ws + WS_Z); bf16_t* VT = (bf16_t*)(lds + L_VT); float* STGF = (float*)(lds + L_KO) + wid * 16 * 132;
;     for (int unit = blk; unit < 2048; unit += G) {
;         const int b = unit >> 10, c = (unit >> 3) & 127, h = unit & 7, chain = b * 8 + h;
;         const size_t tok0 = (size_t)b * SEQ + c * 128 + 16 * wid;
;         const bf16_t* zrow = Z + ((size_t)h * M + tok0 + r) * 128;
.LBB0_2606:
	s_or_b64 exec, exec, s[4:5]
	s_setprio 0
	s_mov_b32 s16, s74
	s_mov_b64 s[4:5], s[0:1]
	s_mov_b32 s17, s2
	s_waitcnt lgkmcnt(0)
	v_mov_b32_e32 v0, v254
	s_barrier
	s_cmpk_gt_i32 s17, 0x7ff
	v_readfirstlane_b32 s3, v0
	s_cbranch_scc1 .LBB0_2629
	s_load_dwordx4 s[12:15], s[4:5], 0x88
	s_load_dwordx2 s[6:7], s[4:5], 0x38
	v_and_b32_e32 v112, 15, v0
	v_bfe_u32 v114, v0, 4, 2
	v_lshlrev_b32_e32 v0, 3, v0
	s_waitcnt lgkmcnt(0)
	s_add_u32 s18, s12, 0x4000000
	s_addc_u32 s19, s13, 0
	s_add_u32 s10, s14, 0x6800000
	s_addc_u32 s11, s15, 0
	s_ashr_i32 s3, s3, 2
	s_and_b32 s20, s3, -16
	s_mul_i32 s3, s20, 0x210
	s_lshl_b32 s5, s20, 1
	v_and_b32_e32 v0, 0x78, v0
	s_mov_b32 s4, 0
	s_add_i32 s3, s3, 0
	v_mov_b32_e32 v117, 0
	s_add_i32 s5, s5, 0
	v_lshlrev_b32_e32 v116, 2, v0
	v_mul_u32_u24_e32 v5, 0x440, v114
	s_ashr_i32 s21, s20, 31
	s_add_i32 s5, s5, 0x13000
	v_lshlrev_b32_e32 v1, 1, v112
	v_add_u32_e32 v4, s3, v116
	v_lshl_add_u64 v[118:119], s[6:7], 0, v[116:117]
	v_lshlrev_b32_e32 v116, 1, v0
	v_mul_u32_u24_e32 v0, 0x210, v114
	v_lshlrev_b32_e32 v5, 1, v5
	v_or_b32_e32 v122, 4, v114
	s_mov_b32 s6, s4
	s_mov_b32 s7, s4
	v_lshlrev_b32_e32 v2, 3, v114
	s_add_u32 s22, s14, 0x1a800000
	v_lshl_add_u32 v3, v112, 2, s3
	v_add3_u32 v113, s5, v1, v5
	v_add3_u32 v115, s5, v5, v1
	v_mul_u32_u24_e32 v1, 0x840, v114
	v_mul_u32_u24_e32 v5, 0x210, v122
	s_mov_b32 s5, s4
	v_mov_b64_e32 v[186:187], s[6:7]
	v_add_u32_e32 v145, v4, v0
	v_mbcnt_lo_u32_b32 v0, -1, 0
	s_mov_b64 s[8:9], 0x4000000
	s_addc_u32 s23, s15, 0
	v_lshl_add_u64 v[120:121], s[10:11], 0, v[116:117]
	s_movk_i32 s24, 0x440
	v_add_u32_e32 v123, 0x220, v113
	v_add_u32_e32 v125, 0x440, v113
	v_add_u32_e32 v127, 0x660, v113
	v_add_u32_e32 v130, 0x2200, v113
	v_add_u32_e32 v131, 0x2420, v113
	v_add_u32_e32 v132, 0x2640, v113
	v_add_u32_e32 v133, 0x2860, v113
	v_add_u32_e32 v134, 0x4400, v113
	v_add_u32_e32 v135, 0x4620, v113
	v_add_u32_e32 v136, 0x4840, v113
	v_add_u32_e32 v137, 0x4a60, v113
	v_add_u32_e32 v138, 0x6600, v113
	v_add_u32_e32 v139, 0x6820, v113
	v_add_u32_e32 v140, 0x6a40, v113
	v_add_u32_e32 v141, 0x6c60, v113
	v_or_b32_e32 v124, 8, v114
	v_or_b32_e32 v126, 12, v114
	v_lshlrev_b32_e32 v128, 1, v2
	v_mov_b32_e32 v129, v117
	s_mov_b64 s[12:13], 0xc000000
	s_brev_b32 s25, 48
	s_brev_b32 s26, 32
	s_movk_i32 s27, 0x110
	v_mov_b64_e32 v[184:185], s[4:5]
	s_mov_b64 s[14:15], 0x8000000
	s_brev_b32 s28, 16
	v_mov_b32_e32 v142, 0x3727c5ac
	s_mov_b32 s29, 0xf800000
	v_mov_b32_e32 v143, 0x260
	v_add_u32_e32 v144, v3, v1
	s_brev_b32 s30, 8
	v_add_u32_e32 v146, v4, v5
	v_mbcnt_hi_u32_b32 v147, -1, v0
	s_branch .LBB0_2609

; #define GEMM_PHASE_H(EPI, Aptr, LDA, AHS, Bptr, LDB, NN, KK, Eobj) do { pg8::Gemm g_{(const bf16_t*)(Aptr), (const bf16_t*)(Bptr), M, (NN), (KK), (LDA), (LDB), (size_t)(AHS)}; pg8::StaticOrder S_; S_.init(M, (NN), G, blk); \
;     pg8::gemm_phase<EPI, pg8::StaticOrder, true, true>((PG8_LAS unsigned char*)lds, g_, S_, (Eobj)); } while (0)
; #define KPTR() KP kp = (KP)__builtin_amdgcn_kernarg_segment_ptr(); int G = gridDim.x, blk = blockIdx.x; asm volatile("" : "+s"(kp), "+s"(G), "+s"(blk)); unsigned char* ws = kp->ws; (void)ws
;     __host__ __device__ bool next(int i, Unit& u) const {
;         const long L = (long)i * G + c; if (L >= nwg) return false;
;         int wgid = (int)L; { const int q = nwg / NXCD, r = nwg % NXCD, xcd = wgid % NXCD, off = wgid / NXCD; wgid = (xcd < r ? xcd * (q + 1) : r * (q + 1) + (xcd - r) * q) + off; }
;         const int nig = WGM * nN, gid = wgid / nig, fm = gid * WGM, gsz = (nM - fm) < WGM ? (nM - fm) : WGM;
;         u.pm = fm + ((wgid % nig) % gsz); u.pn = (wgid % nig) / gsz; return true;
; template <int L> __device__ __forceinline__ void layer_fwd(unsigned char* lds, const XcdBarrier& bar) {
;     ...
;             { KPTR(); bf16_t* LOA = (bf16_t*)kp->out; using ER_ = EpiRes<false, false>; ER_ E{nullptr, (const bf16_t*)(ws + WS_XBX), LOA, (bf16_t*)(ws + WS_XBX), LOA, (f32x2*)(ws + WS_ST1), nullptr, nullptr, nullptr}; GEMM_PHASE_H(ER_, ws + WS_Z, 128, (size_t)M * 128 * 2, ws + WS_WOUT, D, D, D, E); }
.Lprio_out3:
	s_mov_b32 s23, s2
	s_mov_b32 s44, s74
	s_mov_b64 s[4:5], s[0:1]
	s_waitcnt lgkmcnt(0)
	s_barrier
	v_mov_b32_e32 v8, v254
	s_cmpk_lt_i32 s23, 0x200
	s_cselect_b64 s[6:7], -1, 0
	s_cmpk_gt_i32 s23, 0x1ff
	v_readfirstlane_b32 s3, v8
	s_cbranch_scc1 .LBB0_2687
	s_ashr_i32 s8, s23, 31
	s_lshr_b32 s8, s8, 29
	s_add_i32 s12, s23, s8
	s_and_b32 s8, s12, -8
	s_sub_i32 s10, s23, s8
	s_cmp_gt_i32 s10, -1
	s_cbranch_scc0 .LBB0_2684
	s_lshl_b32 s11, s10, 6
	s_ashr_i32 s8, s12, 3
	s_cbranch_execz .LBB0_2685
	s_branch .LBB0_2686

; #define GEMM_PHASE(EPI, Aptr, LDA, Bptr, LDB, NN, KK, Eobj) GEMM_PHASE_H(EPI, Aptr, LDA, 0, Bptr, LDB, NN, KK, Eobj)
;     __host__ __device__ bool next(int i, Unit& u) const {
;         const long L = (long)i * G + c; if (L >= nwg) return false;
;         int wgid = (int)L; { const int q = nwg / NXCD, r = nwg % NXCD, xcd = wgid % NXCD, off = wgid / NXCD; wgid = (xcd < r ? xcd * (q + 1) : r * (q + 1) + (xcd - r) * q) + off; }
;         const int nig = WGM * nN, gid = wgid / nig, fm = gid * WGM, gsz = (nM - fm) < WGM ? (nM - fm) : WGM;
;         u.pm = fm + ((wgid % nig) % gsz); u.pn = (wgid % nig) / gsz; return true;
; template <int L> __device__ __forceinline__ void layer_fwd(unsigned char* lds, const XcdBarrier& bar) {
;     ...
;           using ER_ = EpiRes<true, false>; ER_ E{nullptr, (const bf16_t*)(ws + WS_XBX), LOA, (bf16_t*)(ws + WS_XBY), LOW, (f32x2*)(ws + WS_ST2), (const f32x2*)(ws + WS_ST1), kp->lnm_g + L * D, kp->lnm_b + L * D}; GEMM_PHASE(ER_, ws + WS_H, DFF, ws + WS_W2, DFF, D, DFF, E); }
.Lprio_ffn2_3:
	s_mov_b64 s[8:9], s[0:1]
	s_mov_b32 s31, s2
	s_mov_b32 s35, s74
	s_waitcnt lgkmcnt(0)
	s_barrier
	v_mov_b32_e32 v8, v254
	s_cmpk_lt_i32 s31, 0x200
	s_cselect_b64 s[10:11], -1, 0
	s_cmpk_gt_i32 s31, 0x1ff
	v_readfirstlane_b32 s3, v8
	s_cbranch_scc1 .LBB0_2871
	s_ashr_i32 s4, s31, 31
	s_lshr_b32 s4, s4, 29
	s_add_i32 s12, s31, s4
	s_and_b32 s4, s12, -8
	s_sub_i32 s6, s31, s4
	s_cmp_gt_i32 s6, -1
	s_cbranch_scc0 .LBB0_2868
	s_lshl_b32 s7, s6, 6
	s_ashr_i32 s4, s12, 3
	s_cbranch_execz .LBB0_2869
	s_branch .LBB0_2870

; #define PG8_STAGE(bufoff, gbase, voff) do { _Pragma("unroll") for (int _i = 0; _i < 2; ++_i) \
;         __builtin_amdgcn_global_load_lds((const unsigned*)((const char*)(gbase) + (voff)[_i]), (PG8_LAS unsigned*)(lds + (bufoff) + ldsw + _i * 8192), 16, 0, 0); } while (0)
; #define PG8_LDA(dst, b, h) do { _Pragma("unroll") for (int m = 0; m < 4; ++m) _Pragma("unroll") for (int k = 0; k < 2; ++k) dst[m][k] = *(const PG8_LAS bf16x8*)(lds + PG8_SA(b, h) + aoff + m * 2048 + k * 1024); } while (0)
; #define PG8_LDB(dst, b, h) do { _Pragma("unroll") for (int n = 0; n < 2; ++n) _Pragma("unroll") for (int k = 0; k < 2; ++k) dst[n][k] = *(const PG8_LAS bf16x8*)(lds + PG8_SB(b, h) + boff + n * 2048 + k * 1024); } while (0)
; #define PG8_MMA(ai, bj, At, Bt) do { __builtin_amdgcn_s_setprio(1); _Pragma("unroll") for (int m = 0; m < 4; ++m) _Pragma("unroll") for (int n = 0; n < 2; ++n) _Pragma("unroll") for (int k = 0; k < 2; ++k) \
;         acc[ai][bj][m][n] = __builtin_amdgcn_mfma_f32_16x16x32_bf16(Bt[n][k], At[m][k], acc[ai][bj][m][n], 0, 0, 0); __builtin_amdgcn_s_setprio(0); } while (0)
; #define PG8_WAIT_V(n) asm volatile("s_waitcnt vmcnt(" #n ")" ::: "memory")
; #define PG8_WAIT_L(n) asm volatile("s_waitcnt lgkmcnt(" #n ")" ::: "memory")
; #define PG8_BAR __builtin_amdgcn_s_barrier()
; #define PG8_SCHED __builtin_amdgcn_sched_barrier(0)
; template <class Epi, class Sched, bool ALIGN_EPI = false, bool SP2 = false>
; __device__ __forceinline__ void gemm_phase(PG8_LAS unsigned char* lds, const Gemm g, const Sched& S, const Epi& E) {
;     ...
;             PG8_LDB(B0, 0, 0); PG8_LDB(B1, 0, 1); PG8_SCHED; PG8_LDA(At, 0, 0); PG8_STAGE(PG8_SA(1, 1), a1 + hstepA, voffA);
;             PG8_WAIT_V(8); PG8_WAIT_L(0); PG8_BAR; PG8_MMA(0, 0, At, B0); PG8_MMA(0, 1, At, B1); PG8_BAR; PG8_SCHED;
;             PG8_LDA(At, 0, 1); PG8_STAGE(PG8_SB(0, 0), b2, voffB); PG8_STAGE(PG8_SB(0, 1), b2 + hstepB, voffB); PG8_STAGE(PG8_SA(0, 0), a2, voffA);
;             PG8_WAIT_V(8); PG8_WAIT_L(0); PG8_BAR; PG8_MMA(1, 0, At, B0); PG8_MMA(1, 1, At, B1); PG8_BAR; PG8_SCHED;
.LBB0_2888:
	ds_read_b128 v[124:127], v210
	ds_read_b128 v[128:131], v210 offset:1024
	ds_read_b128 v[132:135], v210 offset:2048
	ds_read_b128 v[144:147], v210 offset:3072
	ds_read_b128 v[148:151], v211
	ds_read_b128 v[170:173], v211 offset:1024
	ds_read_b128 v[174:177], v211 offset:2048
	ds_read_b128 v[178:181], v211 offset:3072
	s_add_u32 s42, s38, s40
	s_addc_u32 s43, s39, s41
	s_add_u32 s46, s42, 0x100
	s_addc_u32 s47, s43, 0
	s_add_u32 s44, s78, s40
	s_addc_u32 s45, s79, s41
	s_add_u32 s42, s42, 0x180
	s_addc_u32 s43, s43, 0
	s_cmpk_eq_i32 s40, 0x1500
	s_cselect_b32 s43, s10, s43
	s_cselect_b32 s42, s3, s42
	s_cselect_b32 s45, s37, s45
	s_cselect_b32 s44, s36, s44
	s_cselect_b32 s47, s9, s47
	s_cselect_b32 s46, s8, s46
	v_lshl_add_u64 v[206:207], v[122:123], 0, s[40:41]
	s_add_i32 m0, s53, 0xc000
	ds_read_b128 v[212:215], v191
	ds_read_b128 v[216:219], v191 offset:1024
	ds_read_b128 v[220:223], v191 offset:2048
	ds_read_b128 v[224:227], v191 offset:3072
	ds_read_b128 v[228:231], v191 offset:4096
	ds_read_b128 v[232:235], v191 offset:5120
	ds_read_b128 v[236:239], v191 offset:6144
	ds_read_b128 v[240:243], v191 offset:7168
	global_load_lds_dwordx4 v[206:207], off
	v_lshl_add_u64 v[206:207], v[120:121], 0, s[40:41]
	s_add_i32 m0, s53, 0xe000
	s_nop 0
	global_load_lds_dwordx4 v[206:207], off
	s_waitcnt vmcnt(8)
	s_waitcnt lgkmcnt(0)
	s_barrier
	s_waitcnt lgkmcnt(0)
	v_mfma_f32_16x16x32_bf16 v[140:143], v[124:127], v[212:215], v[140:143]
	v_mfma_f32_16x16x32_bf16 v[136:139], v[132:135], v[212:215], v[136:139]
	v_mfma_f32_16x16x32_bf16 v[116:119], v[124:127], v[220:223], v[116:119]
	v_mfma_f32_16x16x32_bf16 v[112:115], v[132:135], v[220:223], v[112:115]
	v_mfma_f32_16x16x32_bf16 v[108:111], v[124:127], v[228:231], v[108:111]
	v_mfma_f32_16x16x32_bf16 v[104:107], v[132:135], v[228:231], v[104:107]
	v_mfma_f32_16x16x32_bf16 v[100:103], v[124:127], v[236:239], v[100:103]
	v_mfma_f32_16x16x32_bf16 v[96:99], v[132:135], v[236:239], v[96:99]
	v_mfma_f32_16x16x32_bf16 v[140:143], v[128:131], v[216:219], v[140:143]
	v_mfma_f32_16x16x32_bf16 v[136:139], v[144:147], v[216:219], v[136:139]
	v_mfma_f32_16x16x32_bf16 v[116:119], v[128:131], v[224:227], v[116:119]
	v_mfma_f32_16x16x32_bf16 v[112:115], v[144:147], v[224:227], v[112:115]
	v_mfma_f32_16x16x32_bf16 v[108:111], v[128:131], v[232:235], v[108:111]
	v_mfma_f32_16x16x32_bf16 v[104:107], v[144:147], v[232:235], v[104:107]
	v_mfma_f32_16x16x32_bf16 v[100:103], v[128:131], v[240:243], v[100:103]
	v_mfma_f32_16x16x32_bf16 v[96:99], v[144:147], v[240:243], v[96:99]
	v_mfma_f32_16x16x32_bf16 v[60:63], v[148:151], v[212:215], v[60:63]
	v_mfma_f32_16x16x32_bf16 v[56:59], v[174:177], v[212:215], v[56:59]
	v_mfma_f32_16x16x32_bf16 v[52:55], v[148:151], v[220:223], v[52:55]
	v_mfma_f32_16x16x32_bf16 v[48:51], v[174:177], v[220:223], v[48:51]
	v_mfma_f32_16x16x32_bf16 v[44:47], v[148:151], v[228:231], v[44:47]
	v_mfma_f32_16x16x32_bf16 v[40:43], v[174:177], v[228:231], v[40:43]
	v_mfma_f32_16x16x32_bf16 v[36:39], v[148:151], v[236:239], v[36:39]
	v_mfma_f32_16x16x32_bf16 v[32:35], v[174:177], v[236:239], v[32:35]
	v_mfma_f32_16x16x32_bf16 v[60:63], v[170:173], v[216:219], v[60:63]
	v_mfma_f32_16x16x32_bf16 v[56:59], v[178:181], v[216:219], v[56:59]
	v_mfma_f32_16x16x32_bf16 v[52:55], v[170:173], v[224:227], v[52:55]
	v_mfma_f32_16x16x32_bf16 v[48:51], v[178:181], v[224:227], v[48:51]
	v_mfma_f32_16x16x32_bf16 v[44:47], v[170:173], v[232:235], v[44:47]
	v_mfma_f32_16x16x32_bf16 v[40:43], v[178:181], v[232:235], v[40:43]
	v_mfma_f32_16x16x32_bf16 v[36:39], v[170:173], v[240:243], v[36:39]
	v_mfma_f32_16x16x32_bf16 v[32:35], v[178:181], v[240:243], v[32:35]
	s_barrier
	s_add_i32 s70, s69, s52
	v_lshl_add_u64 v[206:207], s[44:45], 0, v[154:155]
	s_mov_b32 m0, s70
	ds_read_b128 v[212:215], v191 offset:16384
	ds_read_b128 v[216:219], v191 offset:17408
	ds_read_b128 v[220:223], v191 offset:18432
	ds_read_b128 v[224:227], v191 offset:19456
	ds_read_b128 v[228:231], v191 offset:20480
	ds_read_b128 v[232:235], v191 offset:21504
	ds_read_b128 v[236:239], v191 offset:22528
	ds_read_b128 v[240:243], v191 offset:23552
	global_load_lds_dwordx4 v[206:207], off
	s_add_i32 m0, s70, 0x2000
	s_add_u32 s70, s44, 0xb0000
	v_lshl_add_u64 v[244:245], s[44:45], 0, v[158:159]
	s_addc_u32 s71, s45, 0
	s_add_i32 s87, s80, s52
	global_load_lds_dwordx4 v[244:245], off
	v_lshl_add_u64 v[246:247], s[70:71], 0, v[154:155]
	s_mov_b32 m0, s87
	s_nop 0
	global_load_lds_dwordx4 v[246:247], off
	v_lshl_add_u64 v[246:247], s[70:71], 0, v[158:159]
	s_add_i32 m0, s87, 0x2000
	s_nop 0
	global_load_lds_dwordx4 v[246:247], off
	v_lshl_add_u64 v[246:247], s[46:47], 0, v[152:153]
	s_mov_b32 m0, s53
	s_nop 0
	global_load_lds_dwordx4 v[246:247], off
	v_lshl_add_u64 v[246:247], s[46:47], 0, v[156:157]
	s_mov_b32 m0, s54
	s_nop 0
	global_load_lds_dwordx4 v[246:247], off
	s_waitcnt vmcnt(8)
	s_waitcnt lgkmcnt(0)
	s_barrier
; #define PG8_STAGE(bufoff, gbase, voff) do { _Pragma("unroll") for (int _i = 0; _i < 2; ++_i) \
;         __builtin_amdgcn_global_load_lds((const unsigned*)((const char*)(gbase) + (voff)[_i]), (PG8_LAS unsigned*)(lds + (bufoff) + ldsw + _i * 8192), 16, 0, 0); } while (0)
; #define PG8_LDA(dst, b, h) do { _Pragma("unroll") for (int m = 0; m < 4; ++m) _Pragma("unroll") for (int k = 0; k < 2; ++k) dst[m][k] = *(const PG8_LAS bf16x8*)(lds + PG8_SA(b, h) + aoff + m * 2048 + k * 1024); } while (0)
; #define PG8_LDB(dst, b, h) do { _Pragma("unroll") for (int n = 0; n < 2; ++n) _Pragma("unroll") for (int k = 0; k < 2; ++k) dst[n][k] = *(const PG8_LAS bf16x8*)(lds + PG8_SB(b, h) + boff + n * 2048 + k * 1024); } while (0)
; #define PG8_MMA(ai, bj, At, Bt) do { __builtin_amdgcn_s_setprio(1); _Pragma("unroll") for (int m = 0; m < 4; ++m) _Pragma("unroll") for (int n = 0; n < 2; ++n) _Pragma("unroll") for (int k = 0; k < 2; ++k) \
;         acc[ai][bj][m][n] = __builtin_amdgcn_mfma_f32_16x16x32_bf16(Bt[n][k], At[m][k], acc[ai][bj][m][n], 0, 0, 0); __builtin_amdgcn_s_setprio(0); } while (0)
; #define PG8_WAIT_V(n) asm volatile("s_waitcnt vmcnt(" #n ")" ::: "memory")
; #define PG8_WAIT_L(n) asm volatile("s_waitcnt lgkmcnt(" #n ")" ::: "memory")
; #define PG8_BAR __builtin_amdgcn_s_barrier()
; #define PG8_SCHED __builtin_amdgcn_sched_barrier(0)
; template <class Epi, class Sched, bool ALIGN_EPI = false, bool SP2 = false>
; __device__ __forceinline__ void gemm_phase(PG8_LAS unsigned char* lds, const Gemm g, const Sched& S, const Epi& E) {
;     ...
;             PG8_WAIT_V(8); PG8_WAIT_L(0); PG8_BAR; PG8_MMA(1, 0, At, B0); PG8_MMA(1, 1, At, B1); PG8_BAR; PG8_SCHED;
;             PG8_LDB(B0, 1, 0); PG8_LDB(B1, 1, 1); PG8_SCHED; PG8_LDA(At, 1, 0); PG8_STAGE(PG8_SA(0, 1), a2 + hstepA, voffA);
;             PG8_WAIT_V(8); PG8_WAIT_L(0); PG8_BAR; PG8_MMA(0, 0, At, B0); PG8_MMA(0, 1, At, B1); PG8_BAR; PG8_SCHED;
	s_waitcnt lgkmcnt(0)
	v_mfma_f32_16x16x32_bf16 v[92:95], v[124:127], v[212:215], v[92:95]
	v_mfma_f32_16x16x32_bf16 v[88:91], v[132:135], v[212:215], v[88:91]
	v_mfma_f32_16x16x32_bf16 v[84:87], v[124:127], v[220:223], v[84:87]
	v_mfma_f32_16x16x32_bf16 v[80:83], v[132:135], v[220:223], v[80:83]
	v_mfma_f32_16x16x32_bf16 v[76:79], v[124:127], v[228:231], v[76:79]
	v_mfma_f32_16x16x32_bf16 v[72:75], v[132:135], v[228:231], v[72:75]
	v_mfma_f32_16x16x32_bf16 v[68:71], v[124:127], v[236:239], v[68:71]
	v_mfma_f32_16x16x32_bf16 v[64:67], v[132:135], v[236:239], v[64:67]
	v_mfma_f32_16x16x32_bf16 v[92:95], v[128:131], v[216:219], v[92:95]
	v_mfma_f32_16x16x32_bf16 v[88:91], v[144:147], v[216:219], v[88:91]
	v_mfma_f32_16x16x32_bf16 v[84:87], v[128:131], v[224:227], v[84:87]
	v_mfma_f32_16x16x32_bf16 v[80:83], v[144:147], v[224:227], v[80:83]
	v_mfma_f32_16x16x32_bf16 v[76:79], v[128:131], v[232:235], v[76:79]
	v_mfma_f32_16x16x32_bf16 v[72:75], v[144:147], v[232:235], v[72:75]
	v_mfma_f32_16x16x32_bf16 v[68:71], v[128:131], v[240:243], v[68:71]
	v_mfma_f32_16x16x32_bf16 v[64:67], v[144:147], v[240:243], v[64:67]
	v_mfma_f32_16x16x32_bf16 v[28:31], v[148:151], v[212:215], v[28:31]
	v_mfma_f32_16x16x32_bf16 v[24:27], v[174:177], v[212:215], v[24:27]
	v_mfma_f32_16x16x32_bf16 v[20:23], v[148:151], v[220:223], v[20:23]
	v_mfma_f32_16x16x32_bf16 v[16:19], v[174:177], v[220:223], v[16:19]
	v_mfma_f32_16x16x32_bf16 v[12:15], v[148:151], v[228:231], v[12:15]
	v_mfma_f32_16x16x32_bf16 v[8:11], v[174:177], v[228:231], v[8:11]
	v_mfma_f32_16x16x32_bf16 v[4:7], v[148:151], v[236:239], v[4:7]
	v_mfma_f32_16x16x32_bf16 v[0:3], v[174:177], v[236:239], v[0:3]
	v_mfma_f32_16x16x32_bf16 v[28:31], v[170:173], v[216:219], v[28:31]
	v_mfma_f32_16x16x32_bf16 v[24:27], v[178:181], v[216:219], v[24:27]
	v_mfma_f32_16x16x32_bf16 v[20:23], v[170:173], v[224:227], v[20:23]
	v_mfma_f32_16x16x32_bf16 v[16:19], v[178:181], v[224:227], v[16:19]
	v_mfma_f32_16x16x32_bf16 v[12:15], v[170:173], v[232:235], v[12:15]
	v_mfma_f32_16x16x32_bf16 v[8:11], v[178:181], v[232:235], v[8:11]
	v_mfma_f32_16x16x32_bf16 v[4:7], v[170:173], v[240:243], v[4:7]
	v_mfma_f32_16x16x32_bf16 v[0:3], v[178:181], v[240:243], v[0:3]
	s_barrier
	s_add_i32 s70, 0, 0x18000
	s_add_i32 s71, 0, 0x1c000
	v_add_u32_e32 v144, s70, v185
	v_add_u32_e32 v161, s71, v185
	ds_read_b128 v[124:127], v144
	ds_read_b128 v[128:131], v144 offset:1024
	ds_read_b128 v[132:135], v144 offset:2048
	ds_read_b128 v[144:147], v144 offset:3072
	ds_read_b128 v[148:151], v161
	ds_read_b128 v[170:173], v161 offset:1024
	ds_read_b128 v[174:177], v161 offset:2048
	ds_read_b128 v[178:181], v161 offset:3072
	s_add_u32 s46, s46, 0xb0000
	s_addc_u32 s47, s47, 0
	s_mov_b32 m0, s55
	v_lshl_add_u64 v[246:247], s[46:47], 0, v[152:153]
	ds_read_b128 v[212:215], v191 offset:32768
	ds_read_b128 v[216:219], v191 offset:33792
	ds_read_b128 v[220:223], v191 offset:34816
	ds_read_b128 v[224:227], v191 offset:35840
	ds_read_b128 v[228:231], v191 offset:36864
	ds_read_b128 v[232:235], v191 offset:37888
	ds_read_b128 v[236:239], v191 offset:38912
	ds_read_b128 v[240:243], v191 offset:39936
	global_load_lds_dwordx4 v[246:247], off
	v_lshl_add_u64 v[246:247], s[46:47], 0, v[156:157]
	s_mov_b32 m0, s56
	s_nop 0
	global_load_lds_dwordx4 v[246:247], off
	s_waitcnt vmcnt(8)
	s_waitcnt lgkmcnt(0)
	s_barrier
	s_waitcnt lgkmcnt(0)
	v_mfma_f32_16x16x32_bf16 v[140:143], v[124:127], v[212:215], v[140:143]
	v_mfma_f32_16x16x32_bf16 v[136:139], v[132:135], v[212:215], v[136:139]
	v_mfma_f32_16x16x32_bf16 v[116:119], v[124:127], v[220:223], v[116:119]
	v_mfma_f32_16x16x32_bf16 v[112:115], v[132:135], v[220:223], v[112:115]
	v_mfma_f32_16x16x32_bf16 v[108:111], v[124:127], v[228:231], v[108:111]
	v_mfma_f32_16x16x32_bf16 v[104:107], v[132:135], v[228:231], v[104:107]
	v_mfma_f32_16x16x32_bf16 v[100:103], v[124:127], v[236:239], v[100:103]
	v_mfma_f32_16x16x32_bf16 v[96:99], v[132:135], v[236:239], v[96:99]
	v_mfma_f32_16x16x32_bf16 v[140:143], v[128:131], v[216:219], v[140:143]
	v_mfma_f32_16x16x32_bf16 v[136:139], v[144:147], v[216:219], v[136:139]
	v_mfma_f32_16x16x32_bf16 v[116:119], v[128:131], v[224:227], v[116:119]
	v_mfma_f32_16x16x32_bf16 v[112:115], v[144:147], v[224:227], v[112:115]
	v_mfma_f32_16x16x32_bf16 v[108:111], v[128:131], v[232:235], v[108:111]
	v_mfma_f32_16x16x32_bf16 v[104:107], v[144:147], v[232:235], v[104:107]
	v_mfma_f32_16x16x32_bf16 v[100:103], v[128:131], v[240:243], v[100:103]
	v_mfma_f32_16x16x32_bf16 v[96:99], v[144:147], v[240:243], v[96:99]
	v_mfma_f32_16x16x32_bf16 v[60:63], v[148:151], v[212:215], v[60:63]
	v_mfma_f32_16x16x32_bf16 v[56:59], v[174:177], v[212:215], v[56:59]
	v_mfma_f32_16x16x32_bf16 v[52:55], v[148:151], v[220:223], v[52:55]
	v_mfma_f32_16x16x32_bf16 v[48:51], v[174:177], v[220:223], v[48:51]
	v_mfma_f32_16x16x32_bf16 v[44:47], v[148:151], v[228:231], v[44:47]
	v_mfma_f32_16x16x32_bf16 v[40:43], v[174:177], v[228:231], v[40:43]
	v_mfma_f32_16x16x32_bf16 v[36:39], v[148:151], v[236:239], v[36:39]
	v_mfma_f32_16x16x32_bf16 v[32:35], v[174:177], v[236:239], v[32:35]
	v_mfma_f32_16x16x32_bf16 v[60:63], v[170:173], v[216:219], v[60:63]
	v_mfma_f32_16x16x32_bf16 v[56:59], v[178:181], v[216:219], v[56:59]
	v_mfma_f32_16x16x32_bf16 v[52:55], v[170:173], v[224:227], v[52:55]
	v_mfma_f32_16x16x32_bf16 v[48:51], v[178:181], v[224:227], v[48:51]
	v_mfma_f32_16x16x32_bf16 v[44:47], v[170:173], v[232:235], v[44:47]
	v_mfma_f32_16x16x32_bf16 v[40:43], v[178:181], v[232:235], v[40:43]
	v_mfma_f32_16x16x32_bf16 v[36:39], v[170:173], v[240:243], v[36:39]
	v_mfma_f32_16x16x32_bf16 v[32:35], v[178:181], v[240:243], v[32:35]
	s_barrier
; #define PG8_STAGE(bufoff, gbase, voff) do { _Pragma("unroll") for (int _i = 0; _i < 2; ++_i) \
;         __builtin_amdgcn_global_load_lds((const unsigned*)((const char*)(gbase) + (voff)[_i]), (PG8_LAS unsigned*)(lds + (bufoff) + ldsw + _i * 8192), 16, 0, 0); } while (0)
; #define PG8_LDA(dst, b, h) do { _Pragma("unroll") for (int m = 0; m < 4; ++m) _Pragma("unroll") for (int k = 0; k < 2; ++k) dst[m][k] = *(const PG8_LAS bf16x8*)(lds + PG8_SA(b, h) + aoff + m * 2048 + k * 1024); } while (0)
; #define PG8_MMA(ai, bj, At, Bt) do { __builtin_amdgcn_s_setprio(1); _Pragma("unroll") for (int m = 0; m < 4; ++m) _Pragma("unroll") for (int n = 0; n < 2; ++n) _Pragma("unroll") for (int k = 0; k < 2; ++k) \
;         acc[ai][bj][m][n] = __builtin_amdgcn_mfma_f32_16x16x32_bf16(Bt[n][k], At[m][k], acc[ai][bj][m][n], 0, 0, 0); __builtin_amdgcn_s_setprio(0); } while (0)
; #define PG8_WAIT_V(n) asm volatile("s_waitcnt vmcnt(" #n ")" ::: "memory")
; #define PG8_WAIT_L(n) asm volatile("s_waitcnt lgkmcnt(" #n ")" ::: "memory")
; #define PG8_BAR __builtin_amdgcn_s_barrier()
; #define PG8_SCHED __builtin_amdgcn_sched_barrier(0)
; template <class Epi, class Sched, bool ALIGN_EPI = false, bool SP2 = false>
; __device__ __forceinline__ void gemm_phase(PG8_LAS unsigned char* lds, const Gemm g, const Sched& S, const Epi& E) {
;     ...
;             PG8_LDA(At, 1, 1); PG8_STAGE(PG8_SB(1, 0), b3, voffB); PG8_STAGE(PG8_SB(1, 1), b3 + hstepB, voffB); PG8_STAGE(PG8_SA(1, 0), a3, voffA);
;             PG8_WAIT_V(8); PG8_WAIT_L(0); PG8_BAR; PG8_MMA(1, 0, At, B0); PG8_MMA(1, 1, At, B1); PG8_BAR; PG8_SCHED;
	s_add_i32 s46, s70, s52
	v_lshl_add_u64 v[206:207], v[206:207], 0, s[26:27]
	s_mov_b32 m0, s46
	ds_read_b128 v[212:215], v191 offset:49152
	ds_read_b128 v[216:219], v191 offset:50176
	ds_read_b128 v[220:223], v191 offset:51200
	ds_read_b128 v[224:227], v191 offset:52224
	ds_read_b128 v[228:231], v191 offset:53248
	ds_read_b128 v[232:235], v191 offset:54272
	ds_read_b128 v[236:239], v191 offset:55296
	ds_read_b128 v[240:243], v191 offset:56320
	global_load_lds_dwordx4 v[206:207], off
	s_add_i32 m0, s46, 0x2000
	s_add_u32 s44, s44, 0xb0080
	v_lshl_add_u64 v[206:207], v[244:245], 0, s[26:27]
	s_addc_u32 s45, s45, 0
	s_add_i32 s46, s71, s52
	global_load_lds_dwordx4 v[206:207], off
	v_lshl_add_u64 v[206:207], s[44:45], 0, v[154:155]
	s_mov_b32 m0, s46
	s_nop 0
	global_load_lds_dwordx4 v[206:207], off
	v_lshl_add_u64 v[206:207], s[44:45], 0, v[158:159]
	s_add_i32 m0, s46, 0x2000
	s_nop 0
	global_load_lds_dwordx4 v[206:207], off
	v_lshl_add_u64 v[206:207], s[42:43], 0, v[152:153]
	s_mov_b32 m0, s65
	s_nop 0
	global_load_lds_dwordx4 v[206:207], off
	v_lshl_add_u64 v[206:207], s[42:43], 0, v[156:157]
	s_mov_b32 m0, s66
	s_nop 0
	global_load_lds_dwordx4 v[206:207], off
	s_waitcnt vmcnt(8)
	s_waitcnt lgkmcnt(0)
	s_barrier
	s_waitcnt lgkmcnt(0)
	v_mfma_f32_16x16x32_bf16 v[92:95], v[124:127], v[212:215], v[92:95]
	v_mfma_f32_16x16x32_bf16 v[88:91], v[132:135], v[212:215], v[88:91]
	v_mfma_f32_16x16x32_bf16 v[84:87], v[124:127], v[220:223], v[84:87]
	v_mfma_f32_16x16x32_bf16 v[80:83], v[132:135], v[220:223], v[80:83]
	v_mfma_f32_16x16x32_bf16 v[76:79], v[124:127], v[228:231], v[76:79]
	v_mfma_f32_16x16x32_bf16 v[72:75], v[132:135], v[228:231], v[72:75]
	v_mfma_f32_16x16x32_bf16 v[68:71], v[124:127], v[236:239], v[68:71]
	v_mfma_f32_16x16x32_bf16 v[64:67], v[132:135], v[236:239], v[64:67]
	v_mfma_f32_16x16x32_bf16 v[92:95], v[128:131], v[216:219], v[92:95]
	v_mfma_f32_16x16x32_bf16 v[88:91], v[144:147], v[216:219], v[88:91]
	v_mfma_f32_16x16x32_bf16 v[84:87], v[128:131], v[224:227], v[84:87]
	v_mfma_f32_16x16x32_bf16 v[80:83], v[144:147], v[224:227], v[80:83]
	v_mfma_f32_16x16x32_bf16 v[76:79], v[128:131], v[232:235], v[76:79]
	v_mfma_f32_16x16x32_bf16 v[72:75], v[144:147], v[232:235], v[72:75]
	v_mfma_f32_16x16x32_bf16 v[68:71], v[128:131], v[240:243], v[68:71]
	v_mfma_f32_16x16x32_bf16 v[64:67], v[144:147], v[240:243], v[64:67]
	v_mfma_f32_16x16x32_bf16 v[28:31], v[148:151], v[212:215], v[28:31]
	v_mfma_f32_16x16x32_bf16 v[24:27], v[174:177], v[212:215], v[24:27]
	v_mfma_f32_16x16x32_bf16 v[20:23], v[148:151], v[220:223], v[20:23]
	v_mfma_f32_16x16x32_bf16 v[16:19], v[174:177], v[220:223], v[16:19]
	v_mfma_f32_16x16x32_bf16 v[12:15], v[148:151], v[228:231], v[12:15]
	v_mfma_f32_16x16x32_bf16 v[8:11], v[174:177], v[228:231], v[8:11]
	v_mfma_f32_16x16x32_bf16 v[4:7], v[148:151], v[236:239], v[4:7]
	v_mfma_f32_16x16x32_bf16 v[0:3], v[174:177], v[236:239], v[0:3]
	v_mfma_f32_16x16x32_bf16 v[28:31], v[170:173], v[216:219], v[28:31]
	v_mfma_f32_16x16x32_bf16 v[24:27], v[178:181], v[216:219], v[24:27]
	v_mfma_f32_16x16x32_bf16 v[20:23], v[170:173], v[224:227], v[20:23]
	v_mfma_f32_16x16x32_bf16 v[16:19], v[178:181], v[224:227], v[16:19]
	v_mfma_f32_16x16x32_bf16 v[12:15], v[170:173], v[232:235], v[12:15]
	v_mfma_f32_16x16x32_bf16 v[8:11], v[178:181], v[232:235], v[8:11]
	v_mfma_f32_16x16x32_bf16 v[4:7], v[170:173], v[240:243], v[4:7]
	v_mfma_f32_16x16x32_bf16 v[0:3], v[178:181], v[240:243], v[0:3]
	s_barrier
	s_add_i32 s86, s86, 2
	s_add_u32 s40, s40, 0x100
	s_addc_u32 s41, s41, 0
	s_cmp_gt_u32 s86, 41
	s_cbranch_scc0 .LBB0_2888
	s_and_b64 vcc, exec, s[28:29]
	s_cbranch_vccz .LBB0_2891
	s_barrier

; #define GEMM_PHASE(EPI, Aptr, LDA, Bptr, LDB, NN, KK, Eobj) GEMM_PHASE_H(EPI, Aptr, LDA, 0, Bptr, LDB, NN, KK, Eobj)
; #define KPTR() KP kp = (KP)__builtin_amdgcn_kernarg_segment_ptr(); int G = gridDim.x, blk = blockIdx.x; asm volatile("" : "+s"(kp), "+s"(G), "+s"(blk)); unsigned char* ws = kp->ws; (void)ws
;     __host__ __device__ bool next(int i, Unit& u) const {
;         const long L = (long)i * G + c; if (L >= nwg) return false;
;         int wgid = (int)L; { const int q = nwg / NXCD, r = nwg % NXCD, xcd = wgid % NXCD, off = wgid / NXCD; wgid = (xcd < r ? xcd * (q + 1) : r * (q + 1) + (xcd - r) * q) + off; }
;         const int nig = WGM * nN, gid = wgid / nig, fm = gid * WGM, gsz = (nM - fm) < WGM ? (nM - fm) : WGM;
;         u.pm = fm + ((wgid % nig) % gsz); u.pn = (wgid % nig) / gsz; return true;
; template <int L> __device__ __forceinline__ void layer_fwd(unsigned char* lds, const XcdBarrier& bar) {
;     ...
;         { KPTR(); float* vec = (float*)(ws + WS_VEC); bf16_t* LOA = (bf16_t*)kp->out; const bf16_t* LOR = (L == DEPTH - 1) ? (const bf16_t*)(ws + WS_SB) : LOA;
;           EpiPle<L == DEPTH - 1> E{kp->out, (const bf16_t*)(ws + WS_XBY), LOR, (bf16_t*)(ws + WS_XBX), LOA, (const f32x2*)(ws + WS_ST2), kp->lnf_g + L * D, kp->lnf_b + L * D, vec + 11264, vec + 12288, (const bf16_t*)(ws + WS_PP)}; GEMM_PHASE(EpiPle<L == DEPTH - 1>, ws + WS_XBY, D, ws + WS_WG, D, D, D, E); }
.Lprio_gate3:
	s_mov_b32 s25, s74
	s_waitcnt lgkmcnt(0)
	s_barrier
	s_cmpk_gt_i32 s2, 0x1ff
	v_readfirstlane_b32 s3, v254
	s_cbranch_scc1 .LBB0_2987
	s_ashr_i32 s48, s2, 31
	s_lshr_b32 s4, s48, 29
	s_add_i32 s12, s2, s4
	s_and_b32 s4, s12, -8
	s_sub_i32 s11, s2, s4
	s_cmp_gt_i32 s11, -1
	s_cbranch_scc0 .LBB0_2966
	s_lshl_b32 s10, s11, 6
	s_load_dwordx4 s[4:7], s[0:1], 0x88
	s_ashr_i32 s8, s12, 3
	s_cbranch_execz .LBB0_2967
	s_branch .LBB0_2968

; #define PG8_STAGE(bufoff, gbase, voff) do { _Pragma("unroll") for (int _i = 0; _i < 2; ++_i) \
;         __builtin_amdgcn_global_load_lds((const unsigned*)((const char*)(gbase) + (voff)[_i]), (PG8_LAS unsigned*)(lds + (bufoff) + ldsw + _i * 8192), 16, 0, 0); } while (0)
; #define PG8_LDA(dst, b, h) do { _Pragma("unroll") for (int m = 0; m < 4; ++m) _Pragma("unroll") for (int k = 0; k < 2; ++k) dst[m][k] = *(const PG8_LAS bf16x8*)(lds + PG8_SA(b, h) + aoff + m * 2048 + k * 1024); } while (0)
; #define PG8_LDB(dst, b, h) do { _Pragma("unroll") for (int n = 0; n < 2; ++n) _Pragma("unroll") for (int k = 0; k < 2; ++k) dst[n][k] = *(const PG8_LAS bf16x8*)(lds + PG8_SB(b, h) + boff + n * 2048 + k * 1024); } while (0)
; #define PG8_MMA(ai, bj, At, Bt) do { __builtin_amdgcn_s_setprio(1); _Pragma("unroll") for (int m = 0; m < 4; ++m) _Pragma("unroll") for (int n = 0; n < 2; ++n) _Pragma("unroll") for (int k = 0; k < 2; ++k) \
;         acc[ai][bj][m][n] = __builtin_amdgcn_mfma_f32_16x16x32_bf16(Bt[n][k], At[m][k], acc[ai][bj][m][n], 0, 0, 0); __builtin_amdgcn_s_setprio(0); } while (0)
; #define PG8_WAIT_V(n) asm volatile("s_waitcnt vmcnt(" #n ")" ::: "memory")
; #define PG8_WAIT_L(n) asm volatile("s_waitcnt lgkmcnt(" #n ")" ::: "memory")
; #define PG8_BAR __builtin_amdgcn_s_barrier()
; #define PG8_SCHED __builtin_amdgcn_sched_barrier(0)
; template <class Epi, class Sched, bool ALIGN_EPI = false, bool SP2 = false>
; __device__ __forceinline__ void gemm_phase(PG8_LAS unsigned char* lds, const Gemm g, const Sched& S, const Epi& E) {
;     ...
;             PG8_LDB(B0, 0, 0); PG8_LDB(B1, 0, 1); PG8_SCHED; PG8_LDA(At, 0, 0); PG8_STAGE(PG8_SA(1, 1), a1 + hstepA, voffA);
;             PG8_WAIT_V(8); PG8_WAIT_L(0); PG8_BAR; PG8_MMA(0, 0, At, B0); PG8_MMA(0, 1, At, B1); PG8_BAR; PG8_SCHED;
;             PG8_LDA(At, 0, 1); PG8_STAGE(PG8_SB(0, 0), b2, voffB); PG8_STAGE(PG8_SB(0, 1), b2 + hstepB, voffB); PG8_STAGE(PG8_SA(0, 0), a2, voffA);
;             PG8_WAIT_V(8); PG8_WAIT_L(0); PG8_BAR; PG8_MMA(1, 0, At, B0); PG8_MMA(1, 1, At, B1); PG8_BAR; PG8_SCHED;
.LBB0_2980:
	ds_read_b128 v[108:111], v191
	ds_read_b128 v[112:115], v191 offset:1024
	ds_read_b128 v[116:119], v191 offset:2048
	ds_read_b128 v[120:123], v191 offset:3072
	ds_read_b128 v[124:127], v193
	ds_read_b128 v[128:131], v193 offset:1024
	ds_read_b128 v[132:135], v193 offset:2048
	ds_read_b128 v[160:163], v193 offset:3072
	s_add_u32 s42, s38, s40
	s_addc_u32 s43, s39, s41
	s_add_u32 s46, s42, 0x100
	s_addc_u32 s47, s43, 0
	s_add_u32 s44, s80, s40
	s_addc_u32 s45, s81, s41
	s_add_u32 s42, s42, 0x180
	s_addc_u32 s43, s43, 0
	s_cmpk_eq_i32 s40, 0x700
	s_cselect_b32 s43, s79, s43
	s_cselect_b32 s42, s78, s42
	s_cselect_b32 s45, s27, s45
	s_cselect_b32 s44, s69, s44
	s_cselect_b32 s47, s3, s47
	s_cselect_b32 s46, s29, s46
	v_lshl_add_u64 v[242:243], v[106:107], 0, s[40:41]
	s_add_i32 m0, s54, 0xc000
	ds_read_b128 v[164:167], v187
	ds_read_b128 v[168:171], v187 offset:1024
	ds_read_b128 v[218:221], v187 offset:2048
	ds_read_b128 v[222:225], v187 offset:3072
	ds_read_b128 v[226:229], v187 offset:4096
	ds_read_b128 v[230:233], v187 offset:5120
	ds_read_b128 v[234:237], v187 offset:6144
	ds_read_b128 v[238:241], v187 offset:7168
	global_load_lds_dwordx4 v[242:243], off
	v_lshl_add_u64 v[242:243], v[104:105], 0, s[40:41]
	s_add_i32 m0, s54, 0xe000
	s_nop 0
	global_load_lds_dwordx4 v[242:243], off
	s_waitcnt vmcnt(8)
	s_waitcnt lgkmcnt(0)
	s_barrier
	s_waitcnt lgkmcnt(0)
	v_mfma_f32_16x16x32_bf16 v[156:159], v[108:111], v[164:167], v[156:159]
	v_mfma_f32_16x16x32_bf16 v[152:155], v[116:119], v[164:167], v[152:155]
	v_mfma_f32_16x16x32_bf16 v[148:151], v[108:111], v[218:221], v[148:151]
	v_mfma_f32_16x16x32_bf16 v[144:147], v[116:119], v[218:221], v[144:147]
	v_mfma_f32_16x16x32_bf16 v[140:143], v[108:111], v[226:229], v[140:143]
	v_mfma_f32_16x16x32_bf16 v[136:139], v[116:119], v[226:229], v[136:139]
	v_mfma_f32_16x16x32_bf16 v[100:103], v[108:111], v[234:237], v[100:103]
	v_mfma_f32_16x16x32_bf16 v[96:99], v[116:119], v[234:237], v[96:99]
	v_mfma_f32_16x16x32_bf16 v[156:159], v[112:115], v[168:171], v[156:159]
	v_mfma_f32_16x16x32_bf16 v[152:155], v[120:123], v[168:171], v[152:155]
	v_mfma_f32_16x16x32_bf16 v[148:151], v[112:115], v[222:225], v[148:151]
	v_mfma_f32_16x16x32_bf16 v[144:147], v[120:123], v[222:225], v[144:147]
	v_mfma_f32_16x16x32_bf16 v[140:143], v[112:115], v[230:233], v[140:143]
	v_mfma_f32_16x16x32_bf16 v[136:139], v[120:123], v[230:233], v[136:139]
	v_mfma_f32_16x16x32_bf16 v[100:103], v[112:115], v[238:241], v[100:103]
	v_mfma_f32_16x16x32_bf16 v[96:99], v[120:123], v[238:241], v[96:99]
	v_mfma_f32_16x16x32_bf16 v[60:63], v[124:127], v[164:167], v[60:63]
	v_mfma_f32_16x16x32_bf16 v[56:59], v[132:135], v[164:167], v[56:59]
	v_mfma_f32_16x16x32_bf16 v[52:55], v[124:127], v[218:221], v[52:55]
	v_mfma_f32_16x16x32_bf16 v[48:51], v[132:135], v[218:221], v[48:51]
	v_mfma_f32_16x16x32_bf16 v[44:47], v[124:127], v[226:229], v[44:47]
	v_mfma_f32_16x16x32_bf16 v[40:43], v[132:135], v[226:229], v[40:43]
	v_mfma_f32_16x16x32_bf16 v[36:39], v[124:127], v[234:237], v[36:39]
	v_mfma_f32_16x16x32_bf16 v[32:35], v[132:135], v[234:237], v[32:35]
	v_mfma_f32_16x16x32_bf16 v[60:63], v[128:131], v[168:171], v[60:63]
	v_mfma_f32_16x16x32_bf16 v[56:59], v[160:163], v[168:171], v[56:59]
	v_mfma_f32_16x16x32_bf16 v[52:55], v[128:131], v[222:225], v[52:55]
	v_mfma_f32_16x16x32_bf16 v[48:51], v[160:163], v[222:225], v[48:51]
	v_mfma_f32_16x16x32_bf16 v[44:47], v[128:131], v[230:233], v[44:47]
	v_mfma_f32_16x16x32_bf16 v[40:43], v[160:163], v[230:233], v[40:43]
	v_mfma_f32_16x16x32_bf16 v[36:39], v[128:131], v[238:241], v[36:39]
	v_mfma_f32_16x16x32_bf16 v[32:35], v[160:163], v[238:241], v[32:35]
	s_barrier
	s_add_i32 s70, s66, s53
	v_lshl_add_u64 v[242:243], s[44:45], 0, v[174:175]
	s_mov_b32 m0, s70
	ds_read_b128 v[164:167], v187 offset:16384
	ds_read_b128 v[168:171], v187 offset:17408
	ds_read_b128 v[218:221], v187 offset:18432
	ds_read_b128 v[222:225], v187 offset:19456
	ds_read_b128 v[226:229], v187 offset:20480
	ds_read_b128 v[230:233], v187 offset:21504
	ds_read_b128 v[234:237], v187 offset:22528
	ds_read_b128 v[238:241], v187 offset:23552
	global_load_lds_dwordx4 v[242:243], off
	s_add_i32 m0, s70, 0x2000
	s_add_u32 s70, s44, 0x40000
	v_lshl_add_u64 v[244:245], s[44:45], 0, v[178:179]
	s_addc_u32 s71, s45, 0
	s_add_i32 s83, s67, s53
	global_load_lds_dwordx4 v[244:245], off
	v_lshl_add_u64 v[246:247], s[70:71], 0, v[174:175]
	s_mov_b32 m0, s83
	s_nop 0
	global_load_lds_dwordx4 v[246:247], off
	v_lshl_add_u64 v[246:247], s[70:71], 0, v[178:179]
	s_add_i32 m0, s83, 0x2000
	s_nop 0
	global_load_lds_dwordx4 v[246:247], off
	v_lshl_add_u64 v[246:247], s[46:47], 0, v[172:173]
	s_mov_b32 m0, s54
	s_nop 0
	global_load_lds_dwordx4 v[246:247], off
	v_lshl_add_u64 v[246:247], s[46:47], 0, v[176:177]
	s_mov_b32 m0, s55
	s_nop 0
	global_load_lds_dwordx4 v[246:247], off
	s_waitcnt vmcnt(8)
	s_waitcnt lgkmcnt(0)
	s_barrier
; #define PG8_STAGE(bufoff, gbase, voff) do { _Pragma("unroll") for (int _i = 0; _i < 2; ++_i) \
;         __builtin_amdgcn_global_load_lds((const unsigned*)((const char*)(gbase) + (voff)[_i]), (PG8_LAS unsigned*)(lds + (bufoff) + ldsw + _i * 8192), 16, 0, 0); } while (0)
; #define PG8_LDA(dst, b, h) do { _Pragma("unroll") for (int m = 0; m < 4; ++m) _Pragma("unroll") for (int k = 0; k < 2; ++k) dst[m][k] = *(const PG8_LAS bf16x8*)(lds + PG8_SA(b, h) + aoff + m * 2048 + k * 1024); } while (0)
; #define PG8_LDB(dst, b, h) do { _Pragma("unroll") for (int n = 0; n < 2; ++n) _Pragma("unroll") for (int k = 0; k < 2; ++k) dst[n][k] = *(const PG8_LAS bf16x8*)(lds + PG8_SB(b, h) + boff + n * 2048 + k * 1024); } while (0)
; #define PG8_MMA(ai, bj, At, Bt) do { __builtin_amdgcn_s_setprio(1); _Pragma("unroll") for (int m = 0; m < 4; ++m) _Pragma("unroll") for (int n = 0; n < 2; ++n) _Pragma("unroll") for (int k = 0; k < 2; ++k) \
;         acc[ai][bj][m][n] = __builtin_amdgcn_mfma_f32_16x16x32_bf16(Bt[n][k], At[m][k], acc[ai][bj][m][n], 0, 0, 0); __builtin_amdgcn_s_setprio(0); } while (0)
; #define PG8_WAIT_V(n) asm volatile("s_waitcnt vmcnt(" #n ")" ::: "memory")
; #define PG8_WAIT_L(n) asm volatile("s_waitcnt lgkmcnt(" #n ")" ::: "memory")
; #define PG8_BAR __builtin_amdgcn_s_barrier()
; #define PG8_SCHED __builtin_amdgcn_sched_barrier(0)
; template <class Epi, class Sched, bool ALIGN_EPI = false, bool SP2 = false>
; __device__ __forceinline__ void gemm_phase(PG8_LAS unsigned char* lds, const Gemm g, const Sched& S, const Epi& E) {
;     ...
;             PG8_WAIT_V(8); PG8_WAIT_L(0); PG8_BAR; PG8_MMA(1, 0, At, B0); PG8_MMA(1, 1, At, B1); PG8_BAR; PG8_SCHED;
;             PG8_LDB(B0, 1, 0); PG8_LDB(B1, 1, 1); PG8_SCHED; PG8_LDA(At, 1, 0); PG8_STAGE(PG8_SA(0, 1), a2 + hstepA, voffA);
;             PG8_WAIT_V(8); PG8_WAIT_L(0); PG8_BAR; PG8_MMA(0, 0, At, B0); PG8_MMA(0, 1, At, B1); PG8_BAR; PG8_SCHED;
	s_waitcnt lgkmcnt(0)
	v_mfma_f32_16x16x32_bf16 v[92:95], v[108:111], v[164:167], v[92:95]
	v_mfma_f32_16x16x32_bf16 v[88:91], v[116:119], v[164:167], v[88:91]
	v_mfma_f32_16x16x32_bf16 v[84:87], v[108:111], v[218:221], v[84:87]
	v_mfma_f32_16x16x32_bf16 v[80:83], v[116:119], v[218:221], v[80:83]
	v_mfma_f32_16x16x32_bf16 v[76:79], v[108:111], v[226:229], v[76:79]
	v_mfma_f32_16x16x32_bf16 v[72:75], v[116:119], v[226:229], v[72:75]
	v_mfma_f32_16x16x32_bf16 v[68:71], v[108:111], v[234:237], v[68:71]
	v_mfma_f32_16x16x32_bf16 v[64:67], v[116:119], v[234:237], v[64:67]
	v_mfma_f32_16x16x32_bf16 v[92:95], v[112:115], v[168:171], v[92:95]
	v_mfma_f32_16x16x32_bf16 v[88:91], v[120:123], v[168:171], v[88:91]
	v_mfma_f32_16x16x32_bf16 v[84:87], v[112:115], v[222:225], v[84:87]
	v_mfma_f32_16x16x32_bf16 v[80:83], v[120:123], v[222:225], v[80:83]
	v_mfma_f32_16x16x32_bf16 v[76:79], v[112:115], v[230:233], v[76:79]
	v_mfma_f32_16x16x32_bf16 v[72:75], v[120:123], v[230:233], v[72:75]
	v_mfma_f32_16x16x32_bf16 v[68:71], v[112:115], v[238:241], v[68:71]
	v_mfma_f32_16x16x32_bf16 v[64:67], v[120:123], v[238:241], v[64:67]
	v_mfma_f32_16x16x32_bf16 v[28:31], v[124:127], v[164:167], v[28:31]
	v_mfma_f32_16x16x32_bf16 v[24:27], v[132:135], v[164:167], v[24:27]
	v_mfma_f32_16x16x32_bf16 v[20:23], v[124:127], v[218:221], v[20:23]
	v_mfma_f32_16x16x32_bf16 v[16:19], v[132:135], v[218:221], v[16:19]
	v_mfma_f32_16x16x32_bf16 v[12:15], v[124:127], v[226:229], v[12:15]
	v_mfma_f32_16x16x32_bf16 v[8:11], v[132:135], v[226:229], v[8:11]
	v_mfma_f32_16x16x32_bf16 v[4:7], v[124:127], v[234:237], v[4:7]
	v_mfma_f32_16x16x32_bf16 v[0:3], v[132:135], v[234:237], v[0:3]
	v_mfma_f32_16x16x32_bf16 v[28:31], v[128:131], v[168:171], v[28:31]
	v_mfma_f32_16x16x32_bf16 v[24:27], v[160:163], v[168:171], v[24:27]
	v_mfma_f32_16x16x32_bf16 v[20:23], v[128:131], v[222:225], v[20:23]
	v_mfma_f32_16x16x32_bf16 v[16:19], v[160:163], v[222:225], v[16:19]
	v_mfma_f32_16x16x32_bf16 v[12:15], v[128:131], v[230:233], v[12:15]
	v_mfma_f32_16x16x32_bf16 v[8:11], v[160:163], v[230:233], v[8:11]
	v_mfma_f32_16x16x32_bf16 v[4:7], v[128:131], v[238:241], v[4:7]
	v_mfma_f32_16x16x32_bf16 v[0:3], v[160:163], v[238:241], v[0:3]
	s_barrier
	s_add_i32 s70, 0, 0x18000
	s_add_i32 s71, 0, 0x1c000
	v_add_u32_e32 v120, s70, v181
	v_add_u32_e32 v160, s71, v181
	ds_read_b128 v[108:111], v120
	ds_read_b128 v[112:115], v120 offset:1024
	ds_read_b128 v[116:119], v120 offset:2048
	ds_read_b128 v[120:123], v120 offset:3072
	ds_read_b128 v[124:127], v160
	ds_read_b128 v[128:131], v160 offset:1024
	ds_read_b128 v[132:135], v160 offset:2048
	ds_read_b128 v[160:163], v160 offset:3072
	s_add_u32 s46, s46, 0x40000
	s_addc_u32 s47, s47, 0
	s_mov_b32 m0, s56
	v_lshl_add_u64 v[246:247], s[46:47], 0, v[172:173]
	ds_read_b128 v[164:167], v187 offset:32768
	ds_read_b128 v[168:171], v187 offset:33792
	ds_read_b128 v[218:221], v187 offset:34816
	ds_read_b128 v[222:225], v187 offset:35840
	ds_read_b128 v[226:229], v187 offset:36864
	ds_read_b128 v[230:233], v187 offset:37888
	ds_read_b128 v[234:237], v187 offset:38912
	ds_read_b128 v[238:241], v187 offset:39936
	global_load_lds_dwordx4 v[246:247], off
	v_lshl_add_u64 v[246:247], s[46:47], 0, v[176:177]
	s_mov_b32 m0, s57
	s_nop 0
	global_load_lds_dwordx4 v[246:247], off
	s_waitcnt vmcnt(8)
	s_waitcnt lgkmcnt(0)
	s_barrier
	s_waitcnt lgkmcnt(0)
	v_mfma_f32_16x16x32_bf16 v[156:159], v[108:111], v[164:167], v[156:159]
	v_mfma_f32_16x16x32_bf16 v[152:155], v[116:119], v[164:167], v[152:155]
	v_mfma_f32_16x16x32_bf16 v[148:151], v[108:111], v[218:221], v[148:151]
	v_mfma_f32_16x16x32_bf16 v[144:147], v[116:119], v[218:221], v[144:147]
	v_mfma_f32_16x16x32_bf16 v[140:143], v[108:111], v[226:229], v[140:143]
	v_mfma_f32_16x16x32_bf16 v[136:139], v[116:119], v[226:229], v[136:139]
	v_mfma_f32_16x16x32_bf16 v[100:103], v[108:111], v[234:237], v[100:103]
	v_mfma_f32_16x16x32_bf16 v[96:99], v[116:119], v[234:237], v[96:99]
	v_mfma_f32_16x16x32_bf16 v[156:159], v[112:115], v[168:171], v[156:159]
	v_mfma_f32_16x16x32_bf16 v[152:155], v[120:123], v[168:171], v[152:155]
	v_mfma_f32_16x16x32_bf16 v[148:151], v[112:115], v[222:225], v[148:151]
	v_mfma_f32_16x16x32_bf16 v[144:147], v[120:123], v[222:225], v[144:147]
	v_mfma_f32_16x16x32_bf16 v[140:143], v[112:115], v[230:233], v[140:143]
	v_mfma_f32_16x16x32_bf16 v[136:139], v[120:123], v[230:233], v[136:139]
	v_mfma_f32_16x16x32_bf16 v[100:103], v[112:115], v[238:241], v[100:103]
	v_mfma_f32_16x16x32_bf16 v[96:99], v[120:123], v[238:241], v[96:99]
	v_mfma_f32_16x16x32_bf16 v[60:63], v[124:127], v[164:167], v[60:63]
	v_mfma_f32_16x16x32_bf16 v[56:59], v[132:135], v[164:167], v[56:59]
	v_mfma_f32_16x16x32_bf16 v[52:55], v[124:127], v[218:221], v[52:55]
	v_mfma_f32_16x16x32_bf16 v[48:51], v[132:135], v[218:221], v[48:51]
	v_mfma_f32_16x16x32_bf16 v[44:47], v[124:127], v[226:229], v[44:47]
	v_mfma_f32_16x16x32_bf16 v[40:43], v[132:135], v[226:229], v[40:43]
	v_mfma_f32_16x16x32_bf16 v[36:39], v[124:127], v[234:237], v[36:39]
	v_mfma_f32_16x16x32_bf16 v[32:35], v[132:135], v[234:237], v[32:35]
	v_mfma_f32_16x16x32_bf16 v[60:63], v[128:131], v[168:171], v[60:63]
	v_mfma_f32_16x16x32_bf16 v[56:59], v[160:163], v[168:171], v[56:59]
	v_mfma_f32_16x16x32_bf16 v[52:55], v[128:131], v[222:225], v[52:55]
	v_mfma_f32_16x16x32_bf16 v[48:51], v[160:163], v[222:225], v[48:51]
	v_mfma_f32_16x16x32_bf16 v[44:47], v[128:131], v[230:233], v[44:47]
	v_mfma_f32_16x16x32_bf16 v[40:43], v[160:163], v[230:233], v[40:43]
	v_mfma_f32_16x16x32_bf16 v[36:39], v[128:131], v[238:241], v[36:39]
	v_mfma_f32_16x16x32_bf16 v[32:35], v[160:163], v[238:241], v[32:35]
	s_barrier
; #define PG8_STAGE(bufoff, gbase, voff) do { _Pragma("unroll") for (int _i = 0; _i < 2; ++_i) \
;         __builtin_amdgcn_global_load_lds((const unsigned*)((const char*)(gbase) + (voff)[_i]), (PG8_LAS unsigned*)(lds + (bufoff) + ldsw + _i * 8192), 16, 0, 0); } while (0)
; #define PG8_LDA(dst, b, h) do { _Pragma("unroll") for (int m = 0; m < 4; ++m) _Pragma("unroll") for (int k = 0; k < 2; ++k) dst[m][k] = *(const PG8_LAS bf16x8*)(lds + PG8_SA(b, h) + aoff + m * 2048 + k * 1024); } while (0)
; #define PG8_MMA(ai, bj, At, Bt) do { __builtin_amdgcn_s_setprio(1); _Pragma("unroll") for (int m = 0; m < 4; ++m) _Pragma("unroll") for (int n = 0; n < 2; ++n) _Pragma("unroll") for (int k = 0; k < 2; ++k) \
;         acc[ai][bj][m][n] = __builtin_amdgcn_mfma_f32_16x16x32_bf16(Bt[n][k], At[m][k], acc[ai][bj][m][n], 0, 0, 0); __builtin_amdgcn_s_setprio(0); } while (0)
; #define PG8_WAIT_V(n) asm volatile("s_waitcnt vmcnt(" #n ")" ::: "memory")
; #define PG8_WAIT_L(n) asm volatile("s_waitcnt lgkmcnt(" #n ")" ::: "memory")
; #define PG8_BAR __builtin_amdgcn_s_barrier()
; #define PG8_SCHED __builtin_amdgcn_sched_barrier(0)
; template <class Epi, class Sched, bool ALIGN_EPI = false, bool SP2 = false>
; __device__ __forceinline__ void gemm_phase(PG8_LAS unsigned char* lds, const Gemm g, const Sched& S, const Epi& E) {
;     ...
;             PG8_LDA(At, 1, 1); PG8_STAGE(PG8_SB(1, 0), b3, voffB); PG8_STAGE(PG8_SB(1, 1), b3 + hstepB, voffB); PG8_STAGE(PG8_SA(1, 0), a3, voffA);
;             PG8_WAIT_V(8); PG8_WAIT_L(0); PG8_BAR; PG8_MMA(1, 0, At, B0); PG8_MMA(1, 1, At, B1); PG8_BAR; PG8_SCHED;
	s_add_i32 s46, s70, s53
	v_lshl_add_u64 v[242:243], v[242:243], 0, s[6:7]
	s_mov_b32 m0, s46
	ds_read_b128 v[164:167], v187 offset:49152
	ds_read_b128 v[168:171], v187 offset:50176
	ds_read_b128 v[218:221], v187 offset:51200
	ds_read_b128 v[222:225], v187 offset:52224
	ds_read_b128 v[226:229], v187 offset:53248
	ds_read_b128 v[230:233], v187 offset:54272
	ds_read_b128 v[234:237], v187 offset:55296
	ds_read_b128 v[238:241], v187 offset:56320
	global_load_lds_dwordx4 v[242:243], off
	s_add_i32 m0, s46, 0x2000
	s_add_u32 s44, s44, 0x40080
	v_lshl_add_u64 v[242:243], v[244:245], 0, s[6:7]
	s_addc_u32 s45, s45, 0
	s_add_i32 s46, s71, s53
	global_load_lds_dwordx4 v[242:243], off
	v_lshl_add_u64 v[242:243], s[44:45], 0, v[174:175]
	s_mov_b32 m0, s46
	s_nop 0
	global_load_lds_dwordx4 v[242:243], off
	v_lshl_add_u64 v[242:243], s[44:45], 0, v[178:179]
	s_add_i32 m0, s46, 0x2000
	s_nop 0
	global_load_lds_dwordx4 v[242:243], off
	v_lshl_add_u64 v[242:243], s[42:43], 0, v[172:173]
	s_mov_b32 m0, s63
	s_nop 0
	global_load_lds_dwordx4 v[242:243], off
	v_lshl_add_u64 v[242:243], s[42:43], 0, v[176:177]
	s_mov_b32 m0, s64
	s_nop 0
	global_load_lds_dwordx4 v[242:243], off
	s_waitcnt vmcnt(8)
	s_waitcnt lgkmcnt(0)
	s_barrier
	s_waitcnt lgkmcnt(0)
	v_mfma_f32_16x16x32_bf16 v[92:95], v[108:111], v[164:167], v[92:95]
	v_mfma_f32_16x16x32_bf16 v[88:91], v[116:119], v[164:167], v[88:91]
	v_mfma_f32_16x16x32_bf16 v[84:87], v[108:111], v[218:221], v[84:87]
	v_mfma_f32_16x16x32_bf16 v[80:83], v[116:119], v[218:221], v[80:83]
	v_mfma_f32_16x16x32_bf16 v[76:79], v[108:111], v[226:229], v[76:79]
	v_mfma_f32_16x16x32_bf16 v[72:75], v[116:119], v[226:229], v[72:75]
	v_mfma_f32_16x16x32_bf16 v[68:71], v[108:111], v[234:237], v[68:71]
	v_mfma_f32_16x16x32_bf16 v[64:67], v[116:119], v[234:237], v[64:67]
	v_mfma_f32_16x16x32_bf16 v[92:95], v[112:115], v[168:171], v[92:95]
	v_mfma_f32_16x16x32_bf16 v[88:91], v[120:123], v[168:171], v[88:91]
	v_mfma_f32_16x16x32_bf16 v[84:87], v[112:115], v[222:225], v[84:87]
	v_mfma_f32_16x16x32_bf16 v[80:83], v[120:123], v[222:225], v[80:83]
	v_mfma_f32_16x16x32_bf16 v[76:79], v[112:115], v[230:233], v[76:79]
	v_mfma_f32_16x16x32_bf16 v[72:75], v[120:123], v[230:233], v[72:75]
	v_mfma_f32_16x16x32_bf16 v[68:71], v[112:115], v[238:241], v[68:71]
	v_mfma_f32_16x16x32_bf16 v[64:67], v[120:123], v[238:241], v[64:67]
	v_mfma_f32_16x16x32_bf16 v[28:31], v[124:127], v[164:167], v[28:31]
	v_mfma_f32_16x16x32_bf16 v[24:27], v[132:135], v[164:167], v[24:27]
	v_mfma_f32_16x16x32_bf16 v[20:23], v[124:127], v[218:221], v[20:23]
	v_mfma_f32_16x16x32_bf16 v[16:19], v[132:135], v[218:221], v[16:19]
	v_mfma_f32_16x16x32_bf16 v[12:15], v[124:127], v[226:229], v[12:15]
	v_mfma_f32_16x16x32_bf16 v[8:11], v[132:135], v[226:229], v[8:11]
	v_mfma_f32_16x16x32_bf16 v[4:7], v[124:127], v[234:237], v[4:7]
	v_mfma_f32_16x16x32_bf16 v[0:3], v[132:135], v[234:237], v[0:3]
	v_mfma_f32_16x16x32_bf16 v[28:31], v[128:131], v[168:171], v[28:31]
	v_mfma_f32_16x16x32_bf16 v[24:27], v[160:163], v[168:171], v[24:27]
	v_mfma_f32_16x16x32_bf16 v[20:23], v[128:131], v[222:225], v[20:23]
	v_mfma_f32_16x16x32_bf16 v[16:19], v[160:163], v[222:225], v[16:19]
	v_mfma_f32_16x16x32_bf16 v[12:15], v[128:131], v[230:233], v[12:15]
	v_mfma_f32_16x16x32_bf16 v[8:11], v[160:163], v[230:233], v[8:11]
	v_mfma_f32_16x16x32_bf16 v[4:7], v[128:131], v[238:241], v[4:7]
	v_mfma_f32_16x16x32_bf16 v[0:3], v[160:163], v[238:241], v[0:3]
	s_barrier
	s_add_i32 s82, s82, 2
	s_add_u32 s40, s40, 0x100
	s_addc_u32 s41, s41, 0
	s_cmp_gt_u32 s82, 13
	s_cbranch_scc0 .LBB0_2980
	s_and_b64 vcc, exec, s[22:23]
	s_cbranch_vccz .LBB0_2983
	s_barrier

; #define LAS __attribute__((address_space(3)))
; __global__ void __launch_bounds__(512, 2) mk_fwd(Ptrs Parg) {
;     extern __shared__ __attribute__((aligned(16))) unsigned char lds[];
;     cg::grid_group grid = cg::this_grid();
;     volatile LAS unsigned* bst = (volatile LAS unsigned*)((LAS unsigned char*)lds + (LDS_BYTES - 16));
;     if (threadIdx.x < 4) bst[threadIdx.x] = 0u;
;     __syncthreads();
;     XcdBarrier bar = xcd_barrier_post((unsigned*)(Parg.ws + WS_CTL), bst);
;     grid.sync();
;     layer_fwd<0>(lds, bar); layer_fwd<1>(lds, bar); layer_fwd<2>(lds, bar); layer_fwd<3>(lds, bar);
; }
	.amdhsa_kernel _Z6mk_fwd4Ptrs
		.amdhsa_group_segment_fixed_size 0
		.amdhsa_private_segment_fixed_size 0
		.amdhsa_kernarg_size 408
		.amdhsa_user_sgpr_count 2
		.amdhsa_user_sgpr_dispatch_ptr 0
		.amdhsa_user_sgpr_queue_ptr 0
		.amdhsa_user_sgpr_kernarg_segment_ptr 1
		.amdhsa_user_sgpr_dispatch_id 0
		.amdhsa_user_sgpr_kernarg_preload_length 0
		.amdhsa_user_sgpr_kernarg_preload_offset 0
		.amdhsa_user_sgpr_private_segment_size 0
		.amdhsa_uses_dynamic_stack 0
		.amdhsa_enable_private_segment 0
		.amdhsa_system_sgpr_workgroup_id_x 1
		.amdhsa_system_sgpr_workgroup_id_y 0
		.amdhsa_system_sgpr_workgroup_id_z 0
		.amdhsa_system_sgpr_workgroup_info 0
		.amdhsa_system_vgpr_workitem_id 2
		.amdhsa_next_free_vgpr 256
		.amdhsa_next_free_sgpr 100
		.amdhsa_accum_offset 256
		.amdhsa_reserve_vcc 1
		.amdhsa_float_round_mode_32 0
		.amdhsa_float_round_mode_16_64 0
		.amdhsa_float_denorm_mode_32 3
		.amdhsa_float_denorm_mode_16_64 3
		.amdhsa_dx10_clamp 1
		.amdhsa_ieee_mode 1
		.amdhsa_fp16_overflow 0
		.amdhsa_tg_split 0
		.amdhsa_exception_fp_ieee_invalid_op 0
		.amdhsa_exception_fp_denorm_src 0
		.amdhsa_exception_fp_ieee_div_zero 0
		.amdhsa_exception_fp_ieee_overflow 0
		.amdhsa_exception_fp_ieee_underflow 0
		.amdhsa_exception_fp_ieee_inexact 0
		.amdhsa_exception_int_div_zero 0
	.end_amdhsa_kernel

; #define LAS __attribute__((address_space(3)))
; __global__ void __launch_bounds__(512, 2) mk_fwd(Ptrs Parg) {
;     extern __shared__ __attribute__((aligned(16))) unsigned char lds[];
;     cg::grid_group grid = cg::this_grid();
;     volatile LAS unsigned* bst = (volatile LAS unsigned*)((LAS unsigned char*)lds + (LDS_BYTES - 16));
;     if (threadIdx.x < 4) bst[threadIdx.x] = 0u;
;     __syncthreads();
;     XcdBarrier bar = xcd_barrier_post((unsigned*)(Parg.ws + WS_CTL), bst);
;     grid.sync();
;     layer_fwd<0>(lds, bar); layer_fwd<1>(lds, bar); layer_fwd<2>(lds, bar); layer_fwd<3>(lds, bar);
; }
amdhsa.kernels:
  - .agpr_count:     0
    .args:
      - .offset:         0
        .size:           152
        .value_kind:     by_value
      - .offset:         152
        .size:           4
        .value_kind:     hidden_block_count_x
      - .offset:         156
        .size:           4
        .value_kind:     hidden_block_count_y
      - .offset:         160
        .size:           4
        .value_kind:     hidden_block_count_z
      - .offset:         164
        .size:           2
        .value_kind:     hidden_group_size_x
      - .offset:         166
        .size:           2
        .value_kind:     hidden_group_size_y
      - .offset:         168
        .size:           2
        .value_kind:     hidden_group_size_z
      - .offset:         170
        .size:           2
        .value_kind:     hidden_remainder_x
      - .offset:         172
        .size:           2
        .value_kind:     hidden_remainder_y
      - .offset:         174
        .size:           2
        .value_kind:     hidden_remainder_z
      - .offset:         192
        .size:           8
        .value_kind:     hidden_global_offset_x
      - .offset:         200
        .size:           8
        .value_kind:     hidden_global_offset_y
      - .offset:         208
        .size:           8
        .value_kind:     hidden_global_offset_z
      - .offset:         216
        .size:           2
        .value_kind:     hidden_grid_dims
      - .offset:         240
        .size:           8
        .value_kind:     hidden_multigrid_sync_arg
      - .offset:         272
        .size:           4
        .value_kind:     hidden_dynamic_lds_size
    .group_segment_fixed_size: 0
    .kernarg_segment_align: 8
    .kernarg_segment_size: 408
    .language:       OpenCL C
    .language_version:
      - 2
      - 0
    .max_flat_workgroup_size: 512
    .name:           _Z6mk_fwd4Ptrs
    .private_segment_fixed_size: 0
    .sgpr_count:     106
    .sgpr_spill_count: 6
    .symbol:         _Z6mk_fwd4Ptrs.kd
    .uniform_work_group_size: 1
    .uses_dynamic_stack: false
    .vgpr_count:     256
    .vgpr_spill_count: 0
    .wavefront_size: 64
